# trailing half's re-offset barrier moved after its scheduler arithmetic and accumulator zeroing (12 GEMM phases)
# speedup vs baseline: 1.0107x; 1.0069x over previous
.LBB0_138:
	s_or_b64 exec, exec, s[0:1]
	v_mov_b32_e32 v1, 0x3780
	global_load_dword v1, v1, s[38:39] sc1
	s_waitcnt vmcnt(0)
	v_readfirstlane_b32 s98, v1
	s_nop 3
	s_cmp_eq_u32 s98, 0
	s_cselect_b32 s101, 1, 0
	s_mov_b32 s100, 0
	v_mov_b32_e32 v1, 0x20008
	ds_read_b32 v1, v1
	s_waitcnt lgkmcnt(0)
	v_readfirstlane_b32 s98, v1
	s_nop 3
	s_lshl_b32 s98, s98, 3
	s_add_i32 s98, s98, s3
	s_cmp_lg_u32 s101, 0
	s_cselect_b32 s2, s98, s2
	s_cmpk_lt_i32 s2, 0x200
	s_cselect_b64 s[4:5], -1, 0
	v_writelane_b32 v253, s4, 50
	s_lshl_b32 s1, s2, 6
	s_and_b32 s1, s1, 0x1c0
	v_writelane_b32 v253, s5, 51
	s_ashr_i32 s4, s2, 3
	s_add_i32 s1, s1, s4
	s_ashr_i32 s5, s1, 2
	s_lshl_b32 s1, s4, 1
	s_and_b32 s1, s1, 6
	v_writelane_b32 v253, s1, 52
	s_ashr_i32 s1, s5, 31
	s_add_u32 s68, s26, 0x280200
	s_addc_u32 s69, s27, 0
	s_add_u32 s70, s26, 0x280400
	s_addc_u32 s71, s27, 0
	s_add_u32 s66, s26, 0x280500
	s_addc_u32 s67, s27, 0
	s_add_u32 s34, s26, 0x280600
	s_addc_u32 s35, s27, 0
	s_add_u32 s36, s26, 0x280700
	s_addc_u32 s37, s27, 0
	s_add_u32 s56, s26, 0x280800
	s_addc_u32 s57, s27, 0
	s_add_u32 s58, s26, 0x280900
	s_addc_u32 s59, s27, 0
	s_add_u32 s60, s26, 0x280a00
	s_addc_u32 s61, s27, 0
	s_add_u32 s76, s26, 0x280b00
	s_addc_u32 s77, s27, 0
	s_add_u32 s78, s26, 0x280c00
	s_addc_u32 s79, s27, 0
	s_add_u32 s80, s26, 0x280d00
	s_addc_u32 s81, s27, 0
	s_add_u32 s82, s26, 0x280e00
	s_addc_u32 s83, s27, 0
	s_add_u32 s84, s26, 0x280f00
	s_addc_u32 s85, s27, 0
	s_add_u32 s86, s26, 0x281000
	s_addc_u32 s87, s27, 0
	s_add_u32 s88, s26, 0x281100
	s_addc_u32 s89, s27, 0
	s_add_u32 s90, s26, 0x281200
	s_addc_u32 s91, s27, 0
	s_add_u32 s92, s26, 0x281300
	s_addc_u32 s93, s27, 0
	s_mul_i32 s0, s73, s72
	v_writelane_b32 v253, s5, 54
	s_cmp_eq_u32 s3, 15
	v_writelane_b32 v253, s1, 56
	s_mul_i32 s94, s0, s33
	s_cselect_b64 s[0:1], -1, 0
	v_writelane_b32 v253, s0, 58
	s_cmp_eq_u32 s3, 14
	s_movk_i32 s53, 0x161
	v_writelane_b32 v253, s1, 59
	s_cselect_b64 s[0:1], -1, 0
	v_writelane_b32 v253, s0, 60
	s_cmp_eq_u32 s3, 13
	v_mov_b32_e32 v177, 0
	v_writelane_b32 v253, s1, 61
	s_cselect_b64 s[0:1], -1, 0
	v_writelane_b32 v253, s0, 62
	s_cmp_eq_u32 s3, 12
	v_mov_b32_e32 v220, 0x358637bd
	v_writelane_b32 v253, s1, 63
	s_cselect_b64 s[0:1], -1, 0
	v_writelane_b32 v254, s0, 0
	s_cmp_eq_u32 s3, 11
	v_writelane_b32 v253, s60, 16
	v_writelane_b32 v254, s1, 1
	s_cselect_b64 s[0:1], -1, 0
	v_writelane_b32 v254, s0, 2
	s_cmp_eq_u32 s3, 10
	v_mov_b32_e32 v221, 1
	v_writelane_b32 v254, s1, 3
	s_cselect_b64 s[0:1], -1, 0
	v_writelane_b32 v254, s0, 4
	s_cmp_eq_u32 s3, 9
	v_mbcnt_hi_u32_b32 v219, -1, v51
	v_writelane_b32 v254, s1, 5
	s_cselect_b64 s[0:1], -1, 0
	v_writelane_b32 v254, s0, 6
	s_cmp_eq_u32 s3, 8
	v_mov_b64_e32 v[178:179], 0x1ff
	v_writelane_b32 v254, s1, 7
	s_cselect_b64 s[0:1], -1, 0
	v_writelane_b32 v254, s0, 8
	s_cmp_eq_u32 s3, 7
	v_mov_b64_e32 v[180:181], 0x200
	v_writelane_b32 v254, s1, 9
	s_cselect_b64 s[0:1], -1, 0
	v_writelane_b32 v254, s0, 10
	s_cmp_eq_u32 s3, 6
	v_mov_b64_e32 v[182:183], 0xb00
	v_writelane_b32 v254, s1, 11
	s_cselect_b64 s[0:1], -1, 0
	v_writelane_b32 v254, s0, 12
	s_cmp_eq_u32 s3, 5
	v_mov_b64_e32 v[184:185], 0xaff
	v_writelane_b32 v254, s1, 13
	s_cselect_b64 s[0:1], -1, 0
	v_writelane_b32 v254, s0, 14
	s_cmp_eq_u32 s3, 4
	s_mov_b32 s17, 0
	v_writelane_b32 v254, s1, 15
	s_cselect_b64 s[0:1], -1, 0
	v_writelane_b32 v254, s0, 16
	s_cmp_eq_u32 s3, 3
	s_mov_b64 s[14:15], 0x80
	v_writelane_b32 v254, s1, 17
	s_cselect_b64 s[0:1], -1, 0
	v_writelane_b32 v254, s0, 18
	s_cmp_eq_u32 s3, 2
	v_writelane_b32 v253, s61, 17
	v_writelane_b32 v254, s1, 19
	s_cselect_b64 s[0:1], -1, 0
	v_writelane_b32 v254, s0, 20
	s_cmp_eq_u32 s3, 1
	s_barrier
	v_writelane_b32 v254, s1, 21
	s_cselect_b64 s[0:1], -1, 0
	v_writelane_b32 v254, s0, 22
	s_cmp_eq_u32 s3, 0
	s_nop 0
	v_writelane_b32 v254, s1, 23
	s_cselect_b64 s[0:1], -1, 0
	v_writelane_b32 v254, s0, 24
	s_nop 1
	v_writelane_b32 v254, s1, 25
	s_lshl_b32 s0, s3, 8
	s_add_u32 s0, s38, s0
	s_addc_u32 s1, s39, 0
	s_add_u32 s4, s0, 0x1400
	s_addc_u32 s5, s1, 0
	v_writelane_b32 v254, s4, 26
	s_add_u32 s0, s0, 0x2400
	s_addc_u32 s1, s1, 0
	v_writelane_b32 v254, s5, 27
	v_writelane_b32 v254, s0, 28
	s_nop 1
	v_writelane_b32 v254, s1, 29
	s_add_u32 s0, s26, 0x283400
	s_addc_u32 s1, s27, 0
	v_writelane_b32 v254, s0, 30
	s_nop 1
	v_writelane_b32 v254, s1, 31
	s_add_u32 s0, s26, 0x283500
	s_addc_u32 s1, s27, 0
	v_writelane_b32 v254, s0, 32
	s_ashr_i32 s3, s2, 31
	s_ashr_i32 s73, s72, 31
	v_writelane_b32 v254, s1, 33
	s_lshr_b32 s0, s3, 29
	s_add_i32 s0, s2, s0
	s_ashr_i32 s7, s0, 3
	s_and_b32 s0, s0, -8
	s_sub_i32 s8, s2, s0
	s_cmp_gt_i32 s8, -1
	s_cselect_b64 s[0:1], -1, 0
	s_lshl_b32 s4, s8, 6
	v_writelane_b32 v254, s0, 34
	s_cmpk_lt_i32 s2, 0xb00
	s_nop 0
	v_writelane_b32 v254, s1, 35
	s_cselect_b64 s[0:1], -1, 0
	v_writelane_b32 v254, s0, 36
	s_cmp_lt_i32 s8, 0
	s_nop 0
	v_writelane_b32 v254, s1, 37
	s_cselect_b64 s[0:1], -1, 0
	v_writelane_b32 v254, s0, 38
	s_nop 1
	v_writelane_b32 v254, s1, 39
	s_and_b64 s[0:1], s[0:1], exec
	s_mul_i32 s0, s8, 0x41
	s_cselect_b32 s0, s0, s4
	s_cselect_b32 s1, s53, 0x160
	s_add_i32 s5, s0, s7
	s_ashr_i32 s0, s5, 31
	v_writelane_b32 v254, s0, 40
	s_lshr_b32 s0, s0, 27
	s_add_i32 s0, s5, s0
	s_and_b32 s4, s0, 0xffe0
	s_sub_i32 s4, s5, s4
	v_writelane_b32 v254, s5, 42
	s_bfe_i32 s5, s4, 0x80000
	s_bfe_u32 s5, s5, 0x3000c
	s_add_i32 s5, s4, s5
	s_and_b32 s6, s5, 0xf8
	s_sub_i32 s4, s4, s6
	s_ashr_i32 s0, s0, 5
	s_lshl_b32 s0, s0, 3
	s_sext_i32_i8 s4, s4
	s_add_i32 s95, s0, s4
	s_mul_i32 s0, s8, s1
	s_add_i32 s0, s0, s7
	s_mul_hi_i32 s1, s0, 0x2e8ba2e9
	s_lshr_b32 s4, s1, 31
	s_ashr_i32 s1, s1, 5
	s_add_i32 s1, s1, s4
	s_mul_i32 s4, s1, 0xb0
	s_sub_i32 s0, s0, s4
	s_bfe_u32 s4, s0, 0x3001c
	s_add_i32 s4, s0, s4
	s_and_b32 s6, s4, 0xfff8
	s_sub_i32 s0, s0, s6
	s_lshl_b32 s1, s1, 3
	s_sext_i32_i16 s0, s0
	v_writelane_b32 v254, s8, 44
	s_add_i32 s8, s1, s0
	s_bfe_i32 s0, s5, 0x80000
	s_sext_i32_i16 s1, s0
	s_sext_i32_i16 s0, s4
	v_writelane_b32 v254, s7, 45
	s_ashr_i32 s4, s0, 3
	s_lshr_b32 s0, s0, 3
	v_writelane_b32 v254, s4, 46
	s_bfe_i64 s[4:5], s[0:1], 0x100000
	v_writelane_b32 v254, s4, 47
	s_ashr_i32 s0, s1, 3
	s_mov_b64 s[6:7], -1
	v_writelane_b32 v254, s5, 48
	v_writelane_b32 v254, s0, 49
	s_lshr_b32 s0, s1, 3
	s_bfe_i64 s[0:1], s[0:1], 0x100000
	v_writelane_b32 v254, s0, 50
	s_nop 1
	v_writelane_b32 v254, s1, 51
	s_ashr_i32 s0, s8, 31
	v_writelane_b32 v254, s0, 52
	s_ashr_i32 s0, s95, 31
	v_writelane_b32 v254, s0, 53
	s_add_i32 s0, 0, 0x20000
	v_writelane_b32 v254, s0, 54
	s_add_i32 s0, 0, 0x20004
	v_writelane_b32 v254, s0, 55
	v_writelane_b32 v254, s94, 56
	v_writelane_b32 v254, s68, 57
	s_mov_b32 s0, 0
	s_nop 0
	v_writelane_b32 v254, s69, 58
	v_writelane_b32 v254, s70, 59
	s_nop 1
	v_writelane_b32 v254, s71, 60
	v_writelane_b32 v254, s66, 61
	s_nop 1
	v_writelane_b32 v254, s67, 62
	v_writelane_b32 v254, s34, 63
	s_nop 1
	v_writelane_b32 v255, s35, 0
	v_writelane_b32 v255, s56, 1
	s_nop 1
	v_writelane_b32 v255, s57, 2
	v_writelane_b32 v255, s58, 3
	s_nop 1
	v_writelane_b32 v255, s59, 4
	v_writelane_b32 v255, s95, 5
	v_writelane_b32 v255, s8, 6
	v_writelane_b32 v255, s36, 7
	s_nop 1
	v_writelane_b32 v255, s37, 8
	s_branch .LBB0_141

.LBB0_153:
	v_mov_b32_e32 v123, 0
	s_andn2_b64 vcc, exec, s[36:37]
	v_mov_b32_e32 v122, v123
	v_mov_b32_e32 v121, v123
	v_mov_b32_e32 v120, v123
	v_mov_b32_e32 v119, v123
	v_mov_b32_e32 v118, v123
	v_mov_b32_e32 v117, v123
	v_mov_b32_e32 v116, v123
	v_mov_b32_e32 v111, v123
	v_mov_b32_e32 v110, v123
	v_mov_b32_e32 v109, v123
	v_mov_b32_e32 v108, v123
	v_mov_b32_e32 v103, v123
	v_mov_b32_e32 v102, v123
	v_mov_b32_e32 v101, v123
	v_mov_b32_e32 v100, v123
	v_mov_b32_e32 v95, v123
	v_mov_b32_e32 v94, v123
	v_mov_b32_e32 v93, v123
	v_mov_b32_e32 v92, v123
	v_mov_b32_e32 v87, v123
	v_mov_b32_e32 v86, v123
	v_mov_b32_e32 v85, v123
	v_mov_b32_e32 v84, v123
	v_mov_b32_e32 v79, v123
	v_mov_b32_e32 v78, v123
	v_mov_b32_e32 v77, v123
	v_mov_b32_e32 v76, v123
	v_mov_b32_e32 v71, v123
	v_mov_b32_e32 v70, v123
	v_mov_b32_e32 v69, v123
	v_mov_b32_e32 v68, v123
	v_mov_b32_e32 v127, v123
	v_mov_b32_e32 v126, v123
	v_mov_b32_e32 v125, v123
	v_mov_b32_e32 v124, v123
	v_mov_b32_e32 v115, v123
	v_mov_b32_e32 v114, v123
	v_mov_b32_e32 v113, v123
	v_mov_b32_e32 v112, v123
	v_mov_b32_e32 v107, v123
	v_mov_b32_e32 v106, v123
	v_mov_b32_e32 v105, v123
	v_mov_b32_e32 v104, v123
	v_mov_b32_e32 v99, v123
	v_mov_b32_e32 v98, v123
	v_mov_b32_e32 v97, v123
	v_mov_b32_e32 v96, v123
	v_mov_b32_e32 v91, v123
	v_mov_b32_e32 v90, v123
	v_mov_b32_e32 v89, v123
	v_mov_b32_e32 v88, v123
	v_mov_b32_e32 v83, v123
	v_mov_b32_e32 v82, v123
	v_mov_b32_e32 v81, v123
	v_mov_b32_e32 v80, v123
	v_mov_b32_e32 v75, v123
	v_mov_b32_e32 v74, v123
	v_mov_b32_e32 v73, v123
	v_mov_b32_e32 v72, v123
	v_mov_b32_e32 v67, v123
	v_mov_b32_e32 v66, v123
	v_mov_b32_e32 v65, v123
	v_mov_b32_e32 v64, v123
	v_mov_b32_e32 v63, v123
	v_mov_b32_e32 v62, v123
	v_mov_b32_e32 v61, v123
	v_mov_b32_e32 v60, v123
	v_mov_b32_e32 v55, v123
	v_mov_b32_e32 v54, v123
	v_mov_b32_e32 v53, v123
	v_mov_b32_e32 v52, v123
	v_mov_b32_e32 v47, v123
	v_mov_b32_e32 v46, v123
	v_mov_b32_e32 v45, v123
	v_mov_b32_e32 v44, v123
	v_mov_b32_e32 v39, v123
	v_mov_b32_e32 v38, v123
	v_mov_b32_e32 v37, v123
	v_mov_b32_e32 v36, v123
	v_mov_b32_e32 v31, v123
	v_mov_b32_e32 v30, v123
	v_mov_b32_e32 v29, v123
	v_mov_b32_e32 v28, v123
	v_mov_b32_e32 v23, v123
	v_mov_b32_e32 v22, v123
	v_mov_b32_e32 v21, v123
	v_mov_b32_e32 v20, v123
	v_mov_b32_e32 v15, v123
	v_mov_b32_e32 v14, v123
	v_mov_b32_e32 v13, v123
	v_mov_b32_e32 v12, v123
	v_mov_b32_e32 v7, v123
	v_mov_b32_e32 v6, v123
	v_mov_b32_e32 v5, v123
	v_mov_b32_e32 v4, v123
	v_mov_b32_e32 v59, v123
	v_mov_b32_e32 v58, v123
	v_mov_b32_e32 v57, v123
	v_mov_b32_e32 v56, v123
	v_mov_b32_e32 v51, v123
	v_mov_b32_e32 v50, v123
	v_mov_b32_e32 v49, v123
	v_mov_b32_e32 v48, v123
	v_mov_b32_e32 v43, v123
	v_mov_b32_e32 v42, v123
	v_mov_b32_e32 v41, v123
	v_mov_b32_e32 v40, v123
	v_mov_b32_e32 v35, v123
	v_mov_b32_e32 v34, v123
	v_mov_b32_e32 v33, v123
	v_mov_b32_e32 v32, v123
	v_mov_b32_e32 v27, v123
	v_mov_b32_e32 v26, v123
	v_mov_b32_e32 v25, v123
	v_mov_b32_e32 v24, v123
	v_mov_b32_e32 v19, v123
	v_mov_b32_e32 v18, v123
	v_mov_b32_e32 v17, v123
	v_mov_b32_e32 v16, v123
	v_mov_b32_e32 v11, v123
	v_mov_b32_e32 v10, v123
	v_mov_b32_e32 v9, v123
	v_mov_b32_e32 v8, v123
	v_mov_b32_e32 v3, v123
	v_mov_b32_e32 v2, v123
	v_mov_b32_e32 v1, v123
	v_mov_b32_e32 v0, v123
	s_cbranch_vccnz .LBB0_156
	s_add_u32 s42, s42, 0x80
	s_addc_u32 s43, s43, 0
	s_add_u32 s10, s44, 0x100
	s_addc_u32 s11, s45, 0
	s_mov_b32 s44, 0
	s_cmp_lg_u32 s100, 0
	s_cbranch_scc0 .Llbb_0
	s_barrier
	s_mov_b32 s100, 0
.Llbb_0:
.LBB0_155:
	s_add_i32 s47, s44, 2
	s_add_u32 s4, s42, 0x80
	s_addc_u32 s5, s43, 0
	s_add_i32 s54, 0, 0x10000
	s_cmp_eq_u32 s69, s44
	s_cselect_b32 s45, s13, s5
	s_cselect_b32 s44, s12, s4
	s_cselect_b32 vcc_hi, s1, s11
	s_cselect_b32 vcc_lo, s0, s10
	s_add_i32 s4, 0, 0x14000
	v_add_u32_e32 v140, s54, v223
	v_add_u32_e32 v156, s4, v223
	s_waitcnt lgkmcnt(0)
	ds_read_b128 v[128:131], v140
	ds_read_b128 v[132:135], v140 offset:1024
	ds_read_b128 v[136:139], v140 offset:2048
	ds_read_b128 v[140:143], v140 offset:3072
	ds_read_b128 v[144:147], v156
	ds_read_b128 v[148:151], v156 offset:1024
	ds_read_b128 v[152:155], v156 offset:2048
	ds_read_b128 v[156:159], v156 offset:3072
	v_lshl_add_u64 v[214:215], s[42:43], 0, v[194:195]
	s_add_i32 m0, s59, 0xc000
	ds_read_b128 v[160:163], v228
	ds_read_b128 v[164:167], v228 offset:1024
	ds_read_b128 v[168:171], v228 offset:2048
	ds_read_b128 v[172:175], v228 offset:3072
	ds_read_b128 v[198:201], v228 offset:4096
	ds_read_b128 v[202:205], v228 offset:5120
	ds_read_b128 v[206:209], v228 offset:6144
	ds_read_b128 v[210:213], v228 offset:7168
	global_load_lds_dwordx4 v[214:215], off
	v_lshl_add_u64 v[214:215], s[42:43], 0, v[196:197]
	s_add_i32 m0, s59, 0xe000
	s_nop 0
	global_load_lds_dwordx4 v[214:215], off
	s_waitcnt vmcnt(8)
	s_waitcnt lgkmcnt(0)
	s_barrier
	s_waitcnt lgkmcnt(0)
	v_mfma_f32_16x16x32_bf16 v[120:123], v[128:131], v[160:163], v[120:123]
	v_mfma_f32_16x16x32_bf16 v[116:119], v[136:139], v[160:163], v[116:119]
	v_mfma_f32_16x16x32_bf16 v[108:111], v[128:131], v[168:171], v[108:111]
	v_mfma_f32_16x16x32_bf16 v[100:103], v[136:139], v[168:171], v[100:103]
	v_mfma_f32_16x16x32_bf16 v[92:95], v[128:131], v[198:201], v[92:95]
	v_mfma_f32_16x16x32_bf16 v[84:87], v[136:139], v[198:201], v[84:87]
	v_mfma_f32_16x16x32_bf16 v[76:79], v[128:131], v[206:209], v[76:79]
	v_mfma_f32_16x16x32_bf16 v[68:71], v[136:139], v[206:209], v[68:71]
	v_mfma_f32_16x16x32_bf16 v[120:123], v[132:135], v[164:167], v[120:123]
	v_mfma_f32_16x16x32_bf16 v[116:119], v[140:143], v[164:167], v[116:119]
	v_mfma_f32_16x16x32_bf16 v[108:111], v[132:135], v[172:175], v[108:111]
	v_mfma_f32_16x16x32_bf16 v[100:103], v[140:143], v[172:175], v[100:103]
	v_mfma_f32_16x16x32_bf16 v[92:95], v[132:135], v[202:205], v[92:95]
	v_mfma_f32_16x16x32_bf16 v[84:87], v[140:143], v[202:205], v[84:87]
	v_mfma_f32_16x16x32_bf16 v[76:79], v[132:135], v[210:213], v[76:79]
	v_mfma_f32_16x16x32_bf16 v[68:71], v[140:143], v[210:213], v[68:71]
	v_mfma_f32_16x16x32_bf16 v[124:127], v[144:147], v[160:163], v[124:127]
	v_mfma_f32_16x16x32_bf16 v[112:115], v[152:155], v[160:163], v[112:115]
	v_mfma_f32_16x16x32_bf16 v[104:107], v[144:147], v[168:171], v[104:107]
	v_mfma_f32_16x16x32_bf16 v[96:99], v[152:155], v[168:171], v[96:99]
	v_mfma_f32_16x16x32_bf16 v[88:91], v[144:147], v[198:201], v[88:91]
	v_mfma_f32_16x16x32_bf16 v[80:83], v[152:155], v[198:201], v[80:83]
	v_mfma_f32_16x16x32_bf16 v[72:75], v[144:147], v[206:209], v[72:75]
	v_mfma_f32_16x16x32_bf16 v[64:67], v[152:155], v[206:209], v[64:67]
	v_mfma_f32_16x16x32_bf16 v[124:127], v[148:151], v[164:167], v[124:127]
	v_mfma_f32_16x16x32_bf16 v[112:115], v[156:159], v[164:167], v[112:115]
	v_mfma_f32_16x16x32_bf16 v[104:107], v[148:151], v[172:175], v[104:107]
	v_mfma_f32_16x16x32_bf16 v[96:99], v[156:159], v[172:175], v[96:99]
	v_mfma_f32_16x16x32_bf16 v[88:91], v[148:151], v[202:205], v[88:91]
	v_mfma_f32_16x16x32_bf16 v[80:83], v[156:159], v[202:205], v[80:83]
	v_mfma_f32_16x16x32_bf16 v[72:75], v[148:151], v[210:213], v[72:75]
	v_mfma_f32_16x16x32_bf16 v[64:67], v[156:159], v[210:213], v[64:67]
	s_barrier
	s_add_i32 s5, s54, s58
	v_lshl_add_u64 v[214:215], vcc, 0, v[190:191]
	s_mov_b32 m0, s5
	ds_read_b128 v[160:163], v228 offset:16384
	ds_read_b128 v[164:167], v228 offset:17408
	ds_read_b128 v[168:171], v228 offset:18432
	ds_read_b128 v[172:175], v228 offset:19456
	ds_read_b128 v[198:201], v228 offset:20480
	ds_read_b128 v[202:205], v228 offset:21504
	ds_read_b128 v[206:209], v228 offset:22528
	ds_read_b128 v[210:213], v228 offset:23552
	global_load_lds_dwordx4 v[214:215], off
	s_add_i32 m0, s5, 0x2000
	v_lshl_add_u64 v[216:217], vcc, 0, v[186:187]
	s_add_u32 vcc_lo, vcc_lo, s24
	s_addc_u32 vcc_hi, vcc_hi, s25
	s_add_i32 s4, s4, s58
	global_load_lds_dwordx4 v[216:217], off
	v_lshl_add_u64 v[230:231], vcc, 0, v[190:191]
	s_mov_b32 m0, s4
	v_lshl_add_u64 v[232:233], vcc, 0, v[186:187]
	global_load_lds_dwordx4 v[230:231], off
	s_add_i32 m0, s4, 0x2000
	v_lshl_add_u64 v[234:235], s[44:45], 0, v[192:193]
	global_load_lds_dwordx4 v[232:233], off
	s_mov_b32 m0, s59
	v_lshl_add_u64 v[236:237], s[44:45], 0, v[188:189]
	global_load_lds_dwordx4 v[234:235], off
	s_mov_b32 m0, s60
	s_nop 0
	global_load_lds_dwordx4 v[236:237], off
	s_waitcnt vmcnt(8)
	s_waitcnt lgkmcnt(0)
	s_barrier
	s_waitcnt lgkmcnt(0)
	v_mfma_f32_16x16x32_bf16 v[60:63], v[128:131], v[160:163], v[60:63]
	v_mfma_f32_16x16x32_bf16 v[52:55], v[136:139], v[160:163], v[52:55]
	v_mfma_f32_16x16x32_bf16 v[44:47], v[128:131], v[168:171], v[44:47]
	v_mfma_f32_16x16x32_bf16 v[36:39], v[136:139], v[168:171], v[36:39]
	v_mfma_f32_16x16x32_bf16 v[28:31], v[128:131], v[198:201], v[28:31]
	v_mfma_f32_16x16x32_bf16 v[20:23], v[136:139], v[198:201], v[20:23]
	v_mfma_f32_16x16x32_bf16 v[12:15], v[128:131], v[206:209], v[12:15]
	v_mfma_f32_16x16x32_bf16 v[4:7], v[136:139], v[206:209], v[4:7]
	v_mfma_f32_16x16x32_bf16 v[60:63], v[132:135], v[164:167], v[60:63]
	v_mfma_f32_16x16x32_bf16 v[52:55], v[140:143], v[164:167], v[52:55]
	v_mfma_f32_16x16x32_bf16 v[44:47], v[132:135], v[172:175], v[44:47]
	v_mfma_f32_16x16x32_bf16 v[36:39], v[140:143], v[172:175], v[36:39]
	v_mfma_f32_16x16x32_bf16 v[28:31], v[132:135], v[202:205], v[28:31]
	v_mfma_f32_16x16x32_bf16 v[20:23], v[140:143], v[202:205], v[20:23]
	v_mfma_f32_16x16x32_bf16 v[12:15], v[132:135], v[210:213], v[12:15]
	v_mfma_f32_16x16x32_bf16 v[4:7], v[140:143], v[210:213], v[4:7]
	v_mfma_f32_16x16x32_bf16 v[56:59], v[144:147], v[160:163], v[56:59]
	v_mfma_f32_16x16x32_bf16 v[48:51], v[152:155], v[160:163], v[48:51]
	v_mfma_f32_16x16x32_bf16 v[40:43], v[144:147], v[168:171], v[40:43]
	v_mfma_f32_16x16x32_bf16 v[32:35], v[152:155], v[168:171], v[32:35]
	v_mfma_f32_16x16x32_bf16 v[24:27], v[144:147], v[198:201], v[24:27]
	v_mfma_f32_16x16x32_bf16 v[16:19], v[152:155], v[198:201], v[16:19]
	v_mfma_f32_16x16x32_bf16 v[8:11], v[144:147], v[206:209], v[8:11]
	v_mfma_f32_16x16x32_bf16 v[0:3], v[152:155], v[206:209], v[0:3]
	v_mfma_f32_16x16x32_bf16 v[56:59], v[148:151], v[164:167], v[56:59]
	v_mfma_f32_16x16x32_bf16 v[48:51], v[156:159], v[164:167], v[48:51]
	v_mfma_f32_16x16x32_bf16 v[40:43], v[148:151], v[172:175], v[40:43]
	v_mfma_f32_16x16x32_bf16 v[32:35], v[156:159], v[172:175], v[32:35]
	v_mfma_f32_16x16x32_bf16 v[24:27], v[148:151], v[202:205], v[24:27]
	v_mfma_f32_16x16x32_bf16 v[16:19], v[156:159], v[202:205], v[16:19]
	v_mfma_f32_16x16x32_bf16 v[8:11], v[148:151], v[210:213], v[8:11]
	v_mfma_f32_16x16x32_bf16 v[0:3], v[156:159], v[210:213], v[0:3]
	s_barrier
	s_add_i32 s4, 0, 0x18000
	s_add_i32 s5, 0, 0x1c000
	v_add_u32_e32 v140, s4, v223
	v_add_u32_e32 v156, s5, v223
	ds_read_b128 v[128:131], v140
	ds_read_b128 v[132:135], v140 offset:1024
	ds_read_b128 v[136:139], v140 offset:2048
	ds_read_b128 v[140:143], v140 offset:3072
	ds_read_b128 v[144:147], v156
	ds_read_b128 v[148:151], v156 offset:1024
	ds_read_b128 v[152:155], v156 offset:2048
	ds_read_b128 v[156:159], v156 offset:3072
	s_add_u32 s44, s44, s24
	s_addc_u32 s45, s45, s25
	s_mov_b32 m0, s61
	v_lshl_add_u64 v[238:239], s[44:45], 0, v[192:193]
	ds_read_b128 v[160:163], v228 offset:32768
	ds_read_b128 v[164:167], v228 offset:33792
	ds_read_b128 v[168:171], v228 offset:34816
	ds_read_b128 v[172:175], v228 offset:35840
	ds_read_b128 v[198:201], v228 offset:36864
	ds_read_b128 v[202:205], v228 offset:37888
	ds_read_b128 v[206:209], v228 offset:38912
	ds_read_b128 v[210:213], v228 offset:39936
	global_load_lds_dwordx4 v[238:239], off
	v_lshl_add_u64 v[238:239], s[44:45], 0, v[188:189]
	s_mov_b32 m0, s62
	s_nop 0
	global_load_lds_dwordx4 v[238:239], off
	s_waitcnt vmcnt(8)
	s_waitcnt lgkmcnt(0)
	s_barrier
	s_waitcnt lgkmcnt(0)
	v_mfma_f32_16x16x32_bf16 v[120:123], v[128:131], v[160:163], v[120:123]
	v_mfma_f32_16x16x32_bf16 v[116:119], v[136:139], v[160:163], v[116:119]
	v_mfma_f32_16x16x32_bf16 v[108:111], v[128:131], v[168:171], v[108:111]
	v_mfma_f32_16x16x32_bf16 v[100:103], v[136:139], v[168:171], v[100:103]
	v_mfma_f32_16x16x32_bf16 v[92:95], v[128:131], v[198:201], v[92:95]
	v_mfma_f32_16x16x32_bf16 v[84:87], v[136:139], v[198:201], v[84:87]
	v_mfma_f32_16x16x32_bf16 v[76:79], v[128:131], v[206:209], v[76:79]
	v_mfma_f32_16x16x32_bf16 v[68:71], v[136:139], v[206:209], v[68:71]
	v_mfma_f32_16x16x32_bf16 v[120:123], v[132:135], v[164:167], v[120:123]
	v_mfma_f32_16x16x32_bf16 v[116:119], v[140:143], v[164:167], v[116:119]
	v_mfma_f32_16x16x32_bf16 v[108:111], v[132:135], v[172:175], v[108:111]
	v_mfma_f32_16x16x32_bf16 v[100:103], v[140:143], v[172:175], v[100:103]
	v_mfma_f32_16x16x32_bf16 v[92:95], v[132:135], v[202:205], v[92:95]
	v_mfma_f32_16x16x32_bf16 v[84:87], v[140:143], v[202:205], v[84:87]
	v_mfma_f32_16x16x32_bf16 v[76:79], v[132:135], v[210:213], v[76:79]
	v_mfma_f32_16x16x32_bf16 v[68:71], v[140:143], v[210:213], v[68:71]
	v_mfma_f32_16x16x32_bf16 v[124:127], v[144:147], v[160:163], v[124:127]
	v_mfma_f32_16x16x32_bf16 v[112:115], v[152:155], v[160:163], v[112:115]
	v_mfma_f32_16x16x32_bf16 v[104:107], v[144:147], v[168:171], v[104:107]
	v_mfma_f32_16x16x32_bf16 v[96:99], v[152:155], v[168:171], v[96:99]
	v_mfma_f32_16x16x32_bf16 v[88:91], v[144:147], v[198:201], v[88:91]
	v_mfma_f32_16x16x32_bf16 v[80:83], v[152:155], v[198:201], v[80:83]
	v_mfma_f32_16x16x32_bf16 v[72:75], v[144:147], v[206:209], v[72:75]
	v_mfma_f32_16x16x32_bf16 v[64:67], v[152:155], v[206:209], v[64:67]
	v_mfma_f32_16x16x32_bf16 v[124:127], v[148:151], v[164:167], v[124:127]
	v_mfma_f32_16x16x32_bf16 v[112:115], v[156:159], v[164:167], v[112:115]
	v_mfma_f32_16x16x32_bf16 v[104:107], v[148:151], v[172:175], v[104:107]
	v_mfma_f32_16x16x32_bf16 v[96:99], v[156:159], v[172:175], v[96:99]
	v_mfma_f32_16x16x32_bf16 v[88:91], v[148:151], v[202:205], v[88:91]
	v_mfma_f32_16x16x32_bf16 v[80:83], v[156:159], v[202:205], v[80:83]
	v_mfma_f32_16x16x32_bf16 v[72:75], v[148:151], v[210:213], v[72:75]
	v_mfma_f32_16x16x32_bf16 v[64:67], v[156:159], v[210:213], v[64:67]
	s_barrier
	s_add_i32 s4, s4, s58
	v_lshl_add_u64 v[214:215], v[214:215], 0, s[14:15]
	s_mov_b32 m0, s4
	ds_read_b128 v[160:163], v228 offset:49152
	ds_read_b128 v[164:167], v228 offset:50176
	ds_read_b128 v[168:171], v228 offset:51200
	ds_read_b128 v[172:175], v228 offset:52224
	ds_read_b128 v[198:201], v228 offset:53248
	ds_read_b128 v[202:205], v228 offset:54272
	ds_read_b128 v[206:209], v228 offset:55296
	ds_read_b128 v[210:213], v228 offset:56320
	global_load_lds_dwordx4 v[214:215], off
	v_lshl_add_u64 v[214:215], v[216:217], 0, s[14:15]
	s_add_i32 m0, s4, 0x2000
	s_add_i32 s4, s5, s58
	global_load_lds_dwordx4 v[214:215], off
	v_lshl_add_u64 v[214:215], v[230:231], 0, s[14:15]
	s_mov_b32 m0, s4
	s_nop 0
	global_load_lds_dwordx4 v[214:215], off
	v_lshl_add_u64 v[214:215], v[232:233], 0, s[14:15]
	s_add_i32 m0, s4, 0x2000
	s_nop 0
	global_load_lds_dwordx4 v[214:215], off
	v_lshl_add_u64 v[214:215], v[234:235], 0, s[14:15]
	s_mov_b32 m0, s63
	s_nop 0
	global_load_lds_dwordx4 v[214:215], off
	v_lshl_add_u64 v[214:215], v[236:237], 0, s[14:15]
	s_mov_b32 m0, s66
	s_nop 0
	global_load_lds_dwordx4 v[214:215], off
	s_waitcnt vmcnt(8)
	s_waitcnt lgkmcnt(0)
	s_barrier
	s_waitcnt lgkmcnt(0)
	v_mfma_f32_16x16x32_bf16 v[60:63], v[128:131], v[160:163], v[60:63]
	v_mfma_f32_16x16x32_bf16 v[52:55], v[136:139], v[160:163], v[52:55]
	v_mfma_f32_16x16x32_bf16 v[44:47], v[128:131], v[168:171], v[44:47]
	v_mfma_f32_16x16x32_bf16 v[36:39], v[136:139], v[168:171], v[36:39]
	v_mfma_f32_16x16x32_bf16 v[28:31], v[128:131], v[198:201], v[28:31]
	v_mfma_f32_16x16x32_bf16 v[20:23], v[136:139], v[198:201], v[20:23]
	v_mfma_f32_16x16x32_bf16 v[12:15], v[128:131], v[206:209], v[12:15]
	v_mfma_f32_16x16x32_bf16 v[4:7], v[136:139], v[206:209], v[4:7]
	v_mfma_f32_16x16x32_bf16 v[60:63], v[132:135], v[164:167], v[60:63]
	v_mfma_f32_16x16x32_bf16 v[52:55], v[140:143], v[164:167], v[52:55]
	v_mfma_f32_16x16x32_bf16 v[44:47], v[132:135], v[172:175], v[44:47]
	v_mfma_f32_16x16x32_bf16 v[36:39], v[140:143], v[172:175], v[36:39]
	v_mfma_f32_16x16x32_bf16 v[28:31], v[132:135], v[202:205], v[28:31]
	v_mfma_f32_16x16x32_bf16 v[20:23], v[140:143], v[202:205], v[20:23]
	v_mfma_f32_16x16x32_bf16 v[12:15], v[132:135], v[210:213], v[12:15]
	v_mfma_f32_16x16x32_bf16 v[4:7], v[140:143], v[210:213], v[4:7]
	v_mfma_f32_16x16x32_bf16 v[56:59], v[144:147], v[160:163], v[56:59]
	v_mfma_f32_16x16x32_bf16 v[48:51], v[152:155], v[160:163], v[48:51]
	v_mfma_f32_16x16x32_bf16 v[40:43], v[144:147], v[168:171], v[40:43]
	v_mfma_f32_16x16x32_bf16 v[32:35], v[152:155], v[168:171], v[32:35]
	v_mfma_f32_16x16x32_bf16 v[24:27], v[144:147], v[198:201], v[24:27]
	v_mfma_f32_16x16x32_bf16 v[16:19], v[152:155], v[198:201], v[16:19]
	v_mfma_f32_16x16x32_bf16 v[8:11], v[144:147], v[206:209], v[8:11]
	v_mfma_f32_16x16x32_bf16 v[0:3], v[152:155], v[206:209], v[0:3]
	v_mfma_f32_16x16x32_bf16 v[56:59], v[148:151], v[164:167], v[56:59]
	v_mfma_f32_16x16x32_bf16 v[48:51], v[156:159], v[164:167], v[48:51]
	v_mfma_f32_16x16x32_bf16 v[40:43], v[148:151], v[172:175], v[40:43]
	v_mfma_f32_16x16x32_bf16 v[32:35], v[156:159], v[172:175], v[32:35]
	v_mfma_f32_16x16x32_bf16 v[24:27], v[148:151], v[202:205], v[24:27]
	v_mfma_f32_16x16x32_bf16 v[16:19], v[156:159], v[202:205], v[16:19]
	v_mfma_f32_16x16x32_bf16 v[8:11], v[148:151], v[210:213], v[8:11]
	v_mfma_f32_16x16x32_bf16 v[0:3], v[156:159], v[210:213], v[0:3]
	s_barrier
	s_add_u32 s42, s42, 0x100
	s_addc_u32 s43, s43, 0
	s_add_u32 s10, s10, 0x100
	s_addc_u32 s11, s11, 0
	s_cmp_ge_i32 s47, s67
	s_mov_b32 s44, s47
	s_cbranch_scc0 .LBB0_155

.LBB0_175:
	s_andn2_b64 vcc, exec, s[28:29]
	s_cbranch_vccnz .LBB0_145
	s_mov_b32 s100, 1
	s_branch .LBB0_145

.LBB0_260:
	v_mov_b32_e32 v123, 0
	s_andn2_b64 vcc, exec, s[22:23]
	v_mov_b32_e32 v122, v123
	v_mov_b32_e32 v121, v123
	v_mov_b32_e32 v120, v123
	v_mov_b32_e32 v127, v123
	v_mov_b32_e32 v126, v123
	v_mov_b32_e32 v125, v123
	v_mov_b32_e32 v124, v123
	v_mov_b32_e32 v111, v123
	v_mov_b32_e32 v110, v123
	v_mov_b32_e32 v109, v123
	v_mov_b32_e32 v108, v123
	v_mov_b32_e32 v107, v123
	v_mov_b32_e32 v106, v123
	v_mov_b32_e32 v105, v123
	v_mov_b32_e32 v104, v123
	v_mov_b32_e32 v95, v123
	v_mov_b32_e32 v94, v123
	v_mov_b32_e32 v93, v123
	v_mov_b32_e32 v92, v123
	v_mov_b32_e32 v91, v123
	v_mov_b32_e32 v90, v123
	v_mov_b32_e32 v89, v123
	v_mov_b32_e32 v88, v123
	v_mov_b32_e32 v79, v123
	v_mov_b32_e32 v78, v123
	v_mov_b32_e32 v77, v123
	v_mov_b32_e32 v76, v123
	v_mov_b32_e32 v75, v123
	v_mov_b32_e32 v74, v123
	v_mov_b32_e32 v73, v123
	v_mov_b32_e32 v72, v123
	v_mov_b32_e32 v119, v123
	v_mov_b32_e32 v118, v123
	v_mov_b32_e32 v117, v123
	v_mov_b32_e32 v116, v123
	v_mov_b32_e32 v115, v123
	v_mov_b32_e32 v114, v123
	v_mov_b32_e32 v113, v123
	v_mov_b32_e32 v112, v123
	v_mov_b32_e32 v103, v123
	v_mov_b32_e32 v102, v123
	v_mov_b32_e32 v101, v123
	v_mov_b32_e32 v100, v123
	v_mov_b32_e32 v99, v123
	v_mov_b32_e32 v98, v123
	v_mov_b32_e32 v97, v123
	v_mov_b32_e32 v96, v123
	v_mov_b32_e32 v87, v123
	v_mov_b32_e32 v86, v123
	v_mov_b32_e32 v85, v123
	v_mov_b32_e32 v84, v123
	v_mov_b32_e32 v83, v123
	v_mov_b32_e32 v82, v123
	v_mov_b32_e32 v81, v123
	v_mov_b32_e32 v80, v123
	v_mov_b32_e32 v71, v123
	v_mov_b32_e32 v70, v123
	v_mov_b32_e32 v69, v123
	v_mov_b32_e32 v68, v123
	v_mov_b32_e32 v67, v123
	v_mov_b32_e32 v66, v123
	v_mov_b32_e32 v65, v123
	v_mov_b32_e32 v64, v123
	v_mov_b32_e32 v63, v123
	v_mov_b32_e32 v62, v123
	v_mov_b32_e32 v61, v123
	v_mov_b32_e32 v60, v123
	v_mov_b32_e32 v59, v123
	v_mov_b32_e32 v58, v123
	v_mov_b32_e32 v57, v123
	v_mov_b32_e32 v56, v123
	v_mov_b32_e32 v47, v123
	v_mov_b32_e32 v46, v123
	v_mov_b32_e32 v45, v123
	v_mov_b32_e32 v44, v123
	v_mov_b32_e32 v43, v123
	v_mov_b32_e32 v42, v123
	v_mov_b32_e32 v41, v123
	v_mov_b32_e32 v40, v123
	v_mov_b32_e32 v31, v123
	v_mov_b32_e32 v30, v123
	v_mov_b32_e32 v29, v123
	v_mov_b32_e32 v28, v123
	v_mov_b32_e32 v27, v123
	v_mov_b32_e32 v26, v123
	v_mov_b32_e32 v25, v123
	v_mov_b32_e32 v24, v123
	v_mov_b32_e32 v15, v123
	v_mov_b32_e32 v14, v123
	v_mov_b32_e32 v13, v123
	v_mov_b32_e32 v12, v123
	v_mov_b32_e32 v11, v123
	v_mov_b32_e32 v10, v123
	v_mov_b32_e32 v9, v123
	v_mov_b32_e32 v8, v123
	v_mov_b32_e32 v55, v123
	v_mov_b32_e32 v54, v123
	v_mov_b32_e32 v53, v123
	v_mov_b32_e32 v52, v123
	v_mov_b32_e32 v51, v123
	v_mov_b32_e32 v50, v123
	v_mov_b32_e32 v49, v123
	v_mov_b32_e32 v48, v123
	v_mov_b32_e32 v39, v123
	v_mov_b32_e32 v38, v123
	v_mov_b32_e32 v37, v123
	v_mov_b32_e32 v36, v123
	v_mov_b32_e32 v35, v123
	v_mov_b32_e32 v34, v123
	v_mov_b32_e32 v33, v123
	v_mov_b32_e32 v32, v123
	v_mov_b32_e32 v23, v123
	v_mov_b32_e32 v22, v123
	v_mov_b32_e32 v21, v123
	v_mov_b32_e32 v20, v123
	v_mov_b32_e32 v19, v123
	v_mov_b32_e32 v18, v123
	v_mov_b32_e32 v17, v123
	v_mov_b32_e32 v16, v123
	v_mov_b32_e32 v7, v123
	v_mov_b32_e32 v6, v123
	v_mov_b32_e32 v5, v123
	v_mov_b32_e32 v4, v123
	v_mov_b32_e32 v3, v123
	v_mov_b32_e32 v2, v123
	s_waitcnt lgkmcnt(0)
	v_mov_b32_e32 v1, v123
	v_mov_b32_e32 v0, v123
	s_cbranch_vccnz .LBB0_263
	s_add_u32 s30, s30, 0x80
	s_addc_u32 s31, s31, 0
	s_add_u32 s10, s34, 0x100
	s_addc_u32 s11, s35, 0
	s_mov_b32 s34, 0
	s_cmp_lg_u32 s100, 0
	s_cbranch_scc0 .Llbb_1
	s_barrier
	s_mov_b32 s100, 0
.Llbb_1:
.LBB0_262:
	s_add_i32 s44, s34, 2
	s_add_u32 s4, s30, 0x80
	s_addc_u32 s5, s31, 0
	s_add_i32 s45, 0, 0x10000
	s_cmp_eq_u32 s62, s34
	s_cselect_b32 s35, s27, s5
	s_cselect_b32 s34, s26, s4
	s_cselect_b32 s5, s29, s11
	s_cselect_b32 s4, s28, s10
	s_add_i32 s54, 0, 0x14000
	v_add_u32_e32 v140, s45, v195
	v_add_u32_e32 v166, s54, v195
	ds_read_b128 v[128:131], v140
	ds_read_b128 v[132:135], v140 offset:1024
	ds_read_b128 v[136:139], v140 offset:2048
	ds_read_b128 v[140:143], v140 offset:3072
	ds_read_b128 v[144:147], v166
	ds_read_b128 v[148:151], v166 offset:1024
	ds_read_b128 v[152:155], v166 offset:2048
	ds_read_b128 v[166:169], v166 offset:3072
	v_lshl_add_u64 v[174:175], s[30:31], 0, v[162:163]
	s_add_i32 m0, s38, 0xc000
	ds_read_b128 v[170:173], v197
	ds_read_b128 v[186:189], v197 offset:1024
	ds_read_b128 v[190:193], v197 offset:2048
	ds_read_b128 v[198:201], v197 offset:3072
	ds_read_b128 v[202:205], v197 offset:4096
	ds_read_b128 v[206:209], v197 offset:5120
	ds_read_b128 v[210:213], v197 offset:6144
	ds_read_b128 v[214:217], v197 offset:7168
	global_load_lds_dwordx4 v[174:175], off
	v_lshl_add_u64 v[174:175], s[30:31], 0, v[164:165]
	s_add_i32 m0, s38, 0xe000
	s_nop 0
	global_load_lds_dwordx4 v[174:175], off
	s_waitcnt vmcnt(8)
	s_waitcnt lgkmcnt(0)
	s_barrier
	s_waitcnt lgkmcnt(0)
	v_mfma_f32_16x16x32_bf16 v[120:123], v[128:131], v[170:173], v[120:123]
	v_mfma_f32_16x16x32_bf16 v[124:127], v[136:139], v[170:173], v[124:127]
	v_mfma_f32_16x16x32_bf16 v[108:111], v[128:131], v[190:193], v[108:111]
	v_mfma_f32_16x16x32_bf16 v[104:107], v[136:139], v[190:193], v[104:107]
	v_mfma_f32_16x16x32_bf16 v[92:95], v[128:131], v[202:205], v[92:95]
	v_mfma_f32_16x16x32_bf16 v[88:91], v[136:139], v[202:205], v[88:91]
	v_mfma_f32_16x16x32_bf16 v[76:79], v[128:131], v[210:213], v[76:79]
	v_mfma_f32_16x16x32_bf16 v[72:75], v[136:139], v[210:213], v[72:75]
	v_mfma_f32_16x16x32_bf16 v[120:123], v[132:135], v[186:189], v[120:123]
	v_mfma_f32_16x16x32_bf16 v[124:127], v[140:143], v[186:189], v[124:127]
	v_mfma_f32_16x16x32_bf16 v[108:111], v[132:135], v[198:201], v[108:111]
	v_mfma_f32_16x16x32_bf16 v[104:107], v[140:143], v[198:201], v[104:107]
	v_mfma_f32_16x16x32_bf16 v[92:95], v[132:135], v[206:209], v[92:95]
	v_mfma_f32_16x16x32_bf16 v[88:91], v[140:143], v[206:209], v[88:91]
	v_mfma_f32_16x16x32_bf16 v[76:79], v[132:135], v[214:217], v[76:79]
	v_mfma_f32_16x16x32_bf16 v[72:75], v[140:143], v[214:217], v[72:75]
	v_mfma_f32_16x16x32_bf16 v[116:119], v[144:147], v[170:173], v[116:119]
	v_mfma_f32_16x16x32_bf16 v[112:115], v[152:155], v[170:173], v[112:115]
	v_mfma_f32_16x16x32_bf16 v[100:103], v[144:147], v[190:193], v[100:103]
	v_mfma_f32_16x16x32_bf16 v[96:99], v[152:155], v[190:193], v[96:99]
	v_mfma_f32_16x16x32_bf16 v[84:87], v[144:147], v[202:205], v[84:87]
	v_mfma_f32_16x16x32_bf16 v[80:83], v[152:155], v[202:205], v[80:83]
	v_mfma_f32_16x16x32_bf16 v[68:71], v[144:147], v[210:213], v[68:71]
	v_mfma_f32_16x16x32_bf16 v[64:67], v[152:155], v[210:213], v[64:67]
	v_mfma_f32_16x16x32_bf16 v[116:119], v[148:151], v[186:189], v[116:119]
	v_mfma_f32_16x16x32_bf16 v[112:115], v[166:169], v[186:189], v[112:115]
	v_mfma_f32_16x16x32_bf16 v[100:103], v[148:151], v[198:201], v[100:103]
	v_mfma_f32_16x16x32_bf16 v[96:99], v[166:169], v[198:201], v[96:99]
	v_mfma_f32_16x16x32_bf16 v[84:87], v[148:151], v[206:209], v[84:87]
	v_mfma_f32_16x16x32_bf16 v[80:83], v[166:169], v[206:209], v[80:83]
	v_mfma_f32_16x16x32_bf16 v[68:71], v[148:151], v[214:217], v[68:71]
	v_mfma_f32_16x16x32_bf16 v[64:67], v[166:169], v[214:217], v[64:67]
	s_barrier
	s_add_i32 s45, s45, s37
	v_lshl_add_u64 v[174:175], s[4:5], 0, v[176:177]
	s_mov_b32 m0, s45
	ds_read_b128 v[170:173], v197 offset:16384
	ds_read_b128 v[186:189], v197 offset:17408
	ds_read_b128 v[190:193], v197 offset:18432
	ds_read_b128 v[198:201], v197 offset:19456
	ds_read_b128 v[202:205], v197 offset:20480
	ds_read_b128 v[206:209], v197 offset:21504
	ds_read_b128 v[210:213], v197 offset:22528
	ds_read_b128 v[214:217], v197 offset:23552
	global_load_lds_dwordx4 v[174:175], off
	s_add_i32 m0, s45, 0x2000
	v_lshl_add_u64 v[222:223], s[4:5], 0, v[156:157]
	s_add_u32 s4, s4, s0
	s_addc_u32 s5, s5, s1
	s_add_i32 s45, s54, s37
	global_load_lds_dwordx4 v[222:223], off
	v_lshl_add_u64 v[224:225], s[4:5], 0, v[176:177]
	s_mov_b32 m0, s45
	v_lshl_add_u64 v[226:227], s[4:5], 0, v[156:157]
	global_load_lds_dwordx4 v[224:225], off
	s_add_i32 m0, s45, 0x2000
	v_lshl_add_u64 v[228:229], s[34:35], 0, v[160:161]
	global_load_lds_dwordx4 v[226:227], off
	s_mov_b32 m0, s38
	v_lshl_add_u64 v[230:231], s[34:35], 0, v[158:159]
	global_load_lds_dwordx4 v[228:229], off
	s_mov_b32 m0, s39
	s_nop 0
	global_load_lds_dwordx4 v[230:231], off
	s_waitcnt vmcnt(8)
	s_waitcnt lgkmcnt(0)
	s_barrier
	s_waitcnt lgkmcnt(0)
	v_mfma_f32_16x16x32_bf16 v[60:63], v[128:131], v[170:173], v[60:63]
	v_mfma_f32_16x16x32_bf16 v[56:59], v[136:139], v[170:173], v[56:59]
	v_mfma_f32_16x16x32_bf16 v[44:47], v[128:131], v[190:193], v[44:47]
	v_mfma_f32_16x16x32_bf16 v[40:43], v[136:139], v[190:193], v[40:43]
	v_mfma_f32_16x16x32_bf16 v[28:31], v[128:131], v[202:205], v[28:31]
	v_mfma_f32_16x16x32_bf16 v[24:27], v[136:139], v[202:205], v[24:27]
	v_mfma_f32_16x16x32_bf16 v[12:15], v[128:131], v[210:213], v[12:15]
	v_mfma_f32_16x16x32_bf16 v[8:11], v[136:139], v[210:213], v[8:11]
	v_mfma_f32_16x16x32_bf16 v[60:63], v[132:135], v[186:189], v[60:63]
	v_mfma_f32_16x16x32_bf16 v[56:59], v[140:143], v[186:189], v[56:59]
	v_mfma_f32_16x16x32_bf16 v[44:47], v[132:135], v[198:201], v[44:47]
	v_mfma_f32_16x16x32_bf16 v[40:43], v[140:143], v[198:201], v[40:43]
	v_mfma_f32_16x16x32_bf16 v[28:31], v[132:135], v[206:209], v[28:31]
	v_mfma_f32_16x16x32_bf16 v[24:27], v[140:143], v[206:209], v[24:27]
	v_mfma_f32_16x16x32_bf16 v[12:15], v[132:135], v[214:217], v[12:15]
	v_mfma_f32_16x16x32_bf16 v[8:11], v[140:143], v[214:217], v[8:11]
	v_mfma_f32_16x16x32_bf16 v[52:55], v[144:147], v[170:173], v[52:55]
	v_mfma_f32_16x16x32_bf16 v[48:51], v[152:155], v[170:173], v[48:51]
	v_mfma_f32_16x16x32_bf16 v[36:39], v[144:147], v[190:193], v[36:39]
	v_mfma_f32_16x16x32_bf16 v[32:35], v[152:155], v[190:193], v[32:35]
	v_mfma_f32_16x16x32_bf16 v[20:23], v[144:147], v[202:205], v[20:23]
	v_mfma_f32_16x16x32_bf16 v[16:19], v[152:155], v[202:205], v[16:19]
	v_mfma_f32_16x16x32_bf16 v[4:7], v[144:147], v[210:213], v[4:7]
	v_mfma_f32_16x16x32_bf16 v[0:3], v[152:155], v[210:213], v[0:3]
	v_mfma_f32_16x16x32_bf16 v[52:55], v[148:151], v[186:189], v[52:55]
	v_mfma_f32_16x16x32_bf16 v[48:51], v[166:169], v[186:189], v[48:51]
	v_mfma_f32_16x16x32_bf16 v[36:39], v[148:151], v[198:201], v[36:39]
	v_mfma_f32_16x16x32_bf16 v[32:35], v[166:169], v[198:201], v[32:35]
	v_mfma_f32_16x16x32_bf16 v[20:23], v[148:151], v[206:209], v[20:23]
	v_mfma_f32_16x16x32_bf16 v[16:19], v[166:169], v[206:209], v[16:19]
	v_mfma_f32_16x16x32_bf16 v[4:7], v[148:151], v[214:217], v[4:7]
	v_mfma_f32_16x16x32_bf16 v[0:3], v[166:169], v[214:217], v[0:3]
	s_barrier
	s_add_i32 s45, 0, 0x18000
	s_add_i32 s54, 0, 0x1c000
	v_add_u32_e32 v140, s45, v195
	v_add_u32_e32 v166, s54, v195
	ds_read_b128 v[128:131], v140
	ds_read_b128 v[132:135], v140 offset:1024
	ds_read_b128 v[136:139], v140 offset:2048
	ds_read_b128 v[140:143], v140 offset:3072
	ds_read_b128 v[144:147], v166
	ds_read_b128 v[148:151], v166 offset:1024
	ds_read_b128 v[152:155], v166 offset:2048
	ds_read_b128 v[166:169], v166 offset:3072
	s_add_u32 s4, s34, s0
	s_addc_u32 s5, s35, s1
	s_mov_b32 m0, s48
	v_lshl_add_u64 v[232:233], s[4:5], 0, v[160:161]
	ds_read_b128 v[170:173], v197 offset:32768
	ds_read_b128 v[186:189], v197 offset:33792
	ds_read_b128 v[190:193], v197 offset:34816
	ds_read_b128 v[198:201], v197 offset:35840
	ds_read_b128 v[202:205], v197 offset:36864
	ds_read_b128 v[206:209], v197 offset:37888
	ds_read_b128 v[210:213], v197 offset:38912
	ds_read_b128 v[214:217], v197 offset:39936
	global_load_lds_dwordx4 v[232:233], off
	v_lshl_add_u64 v[232:233], s[4:5], 0, v[158:159]
	s_mov_b32 m0, s49
	s_nop 0
	global_load_lds_dwordx4 v[232:233], off
	s_waitcnt vmcnt(8)
	s_waitcnt lgkmcnt(0)
	s_barrier
	s_waitcnt lgkmcnt(0)
	v_mfma_f32_16x16x32_bf16 v[120:123], v[128:131], v[170:173], v[120:123]
	v_mfma_f32_16x16x32_bf16 v[124:127], v[136:139], v[170:173], v[124:127]
	v_mfma_f32_16x16x32_bf16 v[108:111], v[128:131], v[190:193], v[108:111]
	v_mfma_f32_16x16x32_bf16 v[104:107], v[136:139], v[190:193], v[104:107]
	v_mfma_f32_16x16x32_bf16 v[92:95], v[128:131], v[202:205], v[92:95]
	v_mfma_f32_16x16x32_bf16 v[88:91], v[136:139], v[202:205], v[88:91]
	v_mfma_f32_16x16x32_bf16 v[76:79], v[128:131], v[210:213], v[76:79]
	v_mfma_f32_16x16x32_bf16 v[72:75], v[136:139], v[210:213], v[72:75]
	v_mfma_f32_16x16x32_bf16 v[120:123], v[132:135], v[186:189], v[120:123]
	v_mfma_f32_16x16x32_bf16 v[124:127], v[140:143], v[186:189], v[124:127]
	v_mfma_f32_16x16x32_bf16 v[108:111], v[132:135], v[198:201], v[108:111]
	v_mfma_f32_16x16x32_bf16 v[104:107], v[140:143], v[198:201], v[104:107]
	v_mfma_f32_16x16x32_bf16 v[92:95], v[132:135], v[206:209], v[92:95]
	v_mfma_f32_16x16x32_bf16 v[88:91], v[140:143], v[206:209], v[88:91]
	v_mfma_f32_16x16x32_bf16 v[76:79], v[132:135], v[214:217], v[76:79]
	v_mfma_f32_16x16x32_bf16 v[72:75], v[140:143], v[214:217], v[72:75]
	v_mfma_f32_16x16x32_bf16 v[116:119], v[144:147], v[170:173], v[116:119]
	v_mfma_f32_16x16x32_bf16 v[112:115], v[152:155], v[170:173], v[112:115]
	v_mfma_f32_16x16x32_bf16 v[100:103], v[144:147], v[190:193], v[100:103]
	v_mfma_f32_16x16x32_bf16 v[96:99], v[152:155], v[190:193], v[96:99]
	v_mfma_f32_16x16x32_bf16 v[84:87], v[144:147], v[202:205], v[84:87]
	v_mfma_f32_16x16x32_bf16 v[80:83], v[152:155], v[202:205], v[80:83]
	v_mfma_f32_16x16x32_bf16 v[68:71], v[144:147], v[210:213], v[68:71]
	v_mfma_f32_16x16x32_bf16 v[64:67], v[152:155], v[210:213], v[64:67]
	v_mfma_f32_16x16x32_bf16 v[116:119], v[148:151], v[186:189], v[116:119]
	v_mfma_f32_16x16x32_bf16 v[112:115], v[166:169], v[186:189], v[112:115]
	v_mfma_f32_16x16x32_bf16 v[100:103], v[148:151], v[198:201], v[100:103]
	v_mfma_f32_16x16x32_bf16 v[96:99], v[166:169], v[198:201], v[96:99]
	v_mfma_f32_16x16x32_bf16 v[84:87], v[148:151], v[206:209], v[84:87]
	v_mfma_f32_16x16x32_bf16 v[80:83], v[166:169], v[206:209], v[80:83]
	v_mfma_f32_16x16x32_bf16 v[68:71], v[148:151], v[214:217], v[68:71]
	v_mfma_f32_16x16x32_bf16 v[64:67], v[166:169], v[214:217], v[64:67]
	s_barrier
	s_add_i32 s4, s45, s37
	v_lshl_add_u64 v[174:175], v[174:175], 0, s[14:15]
	s_mov_b32 m0, s4
	ds_read_b128 v[170:173], v197 offset:49152
	ds_read_b128 v[186:189], v197 offset:50176
	ds_read_b128 v[190:193], v197 offset:51200
	ds_read_b128 v[198:201], v197 offset:52224
	ds_read_b128 v[202:205], v197 offset:53248
	ds_read_b128 v[206:209], v197 offset:54272
	ds_read_b128 v[210:213], v197 offset:55296
	ds_read_b128 v[214:217], v197 offset:56320
	global_load_lds_dwordx4 v[174:175], off
	v_lshl_add_u64 v[174:175], v[222:223], 0, s[14:15]
	s_add_i32 m0, s4, 0x2000
	s_add_i32 s4, s54, s37
	global_load_lds_dwordx4 v[174:175], off
	v_lshl_add_u64 v[174:175], v[224:225], 0, s[14:15]
	s_mov_b32 m0, s4
	s_nop 0
	global_load_lds_dwordx4 v[174:175], off
	v_lshl_add_u64 v[174:175], v[226:227], 0, s[14:15]
	s_add_i32 m0, s4, 0x2000
	s_nop 0
	global_load_lds_dwordx4 v[174:175], off
	v_lshl_add_u64 v[174:175], v[228:229], 0, s[14:15]
	s_mov_b32 m0, s60
	s_nop 0
	global_load_lds_dwordx4 v[174:175], off
	v_lshl_add_u64 v[174:175], v[230:231], 0, s[14:15]
	s_mov_b32 m0, s61
	s_nop 0
	global_load_lds_dwordx4 v[174:175], off
	s_waitcnt vmcnt(8)
	s_waitcnt lgkmcnt(0)
	s_barrier
	s_waitcnt lgkmcnt(0)
	v_mfma_f32_16x16x32_bf16 v[60:63], v[128:131], v[170:173], v[60:63]
	v_mfma_f32_16x16x32_bf16 v[56:59], v[136:139], v[170:173], v[56:59]
	v_mfma_f32_16x16x32_bf16 v[44:47], v[128:131], v[190:193], v[44:47]
	v_mfma_f32_16x16x32_bf16 v[40:43], v[136:139], v[190:193], v[40:43]
	v_mfma_f32_16x16x32_bf16 v[28:31], v[128:131], v[202:205], v[28:31]
	v_mfma_f32_16x16x32_bf16 v[24:27], v[136:139], v[202:205], v[24:27]
	v_mfma_f32_16x16x32_bf16 v[12:15], v[128:131], v[210:213], v[12:15]
	v_mfma_f32_16x16x32_bf16 v[8:11], v[136:139], v[210:213], v[8:11]
	v_mfma_f32_16x16x32_bf16 v[60:63], v[132:135], v[186:189], v[60:63]
	v_mfma_f32_16x16x32_bf16 v[56:59], v[140:143], v[186:189], v[56:59]
	v_mfma_f32_16x16x32_bf16 v[44:47], v[132:135], v[198:201], v[44:47]
	v_mfma_f32_16x16x32_bf16 v[40:43], v[140:143], v[198:201], v[40:43]
	v_mfma_f32_16x16x32_bf16 v[28:31], v[132:135], v[206:209], v[28:31]
	v_mfma_f32_16x16x32_bf16 v[24:27], v[140:143], v[206:209], v[24:27]
	v_mfma_f32_16x16x32_bf16 v[12:15], v[132:135], v[214:217], v[12:15]
	v_mfma_f32_16x16x32_bf16 v[8:11], v[140:143], v[214:217], v[8:11]
	v_mfma_f32_16x16x32_bf16 v[52:55], v[144:147], v[170:173], v[52:55]
	v_mfma_f32_16x16x32_bf16 v[48:51], v[152:155], v[170:173], v[48:51]
	v_mfma_f32_16x16x32_bf16 v[36:39], v[144:147], v[190:193], v[36:39]
	v_mfma_f32_16x16x32_bf16 v[32:35], v[152:155], v[190:193], v[32:35]
	v_mfma_f32_16x16x32_bf16 v[20:23], v[144:147], v[202:205], v[20:23]
	v_mfma_f32_16x16x32_bf16 v[16:19], v[152:155], v[202:205], v[16:19]
	v_mfma_f32_16x16x32_bf16 v[4:7], v[144:147], v[210:213], v[4:7]
	v_mfma_f32_16x16x32_bf16 v[0:3], v[152:155], v[210:213], v[0:3]
	v_mfma_f32_16x16x32_bf16 v[52:55], v[148:151], v[186:189], v[52:55]
	v_mfma_f32_16x16x32_bf16 v[48:51], v[166:169], v[186:189], v[48:51]
	v_mfma_f32_16x16x32_bf16 v[36:39], v[148:151], v[198:201], v[36:39]
	v_mfma_f32_16x16x32_bf16 v[32:35], v[166:169], v[198:201], v[32:35]
	v_mfma_f32_16x16x32_bf16 v[20:23], v[148:151], v[206:209], v[20:23]
	v_mfma_f32_16x16x32_bf16 v[16:19], v[166:169], v[206:209], v[16:19]
	v_mfma_f32_16x16x32_bf16 v[4:7], v[148:151], v[214:217], v[4:7]
	v_mfma_f32_16x16x32_bf16 v[0:3], v[166:169], v[214:217], v[0:3]
	s_barrier
	s_add_u32 s30, s30, 0x100
	s_addc_u32 s31, s31, 0
	s_add_u32 s10, s10, 0x100
	s_addc_u32 s11, s11, 0
	s_cmp_ge_i32 s44, s59
	s_mov_b32 s34, s44
	s_cbranch_scc0 .LBB0_262

.LBB0_281:
	s_or_b64 exec, exec, s[10:11]
	s_and_b64 vcc, exec, s[42:43]
	s_mov_b64 s[10:11], -1
	s_cbranch_vccnz .LBB0_249
	s_andn2_b64 vcc, exec, s[20:21]
	s_cbranch_vccnz .LBB0_248
	s_mov_b32 s100, 1
	s_branch .LBB0_248

.LBB0_303:
	v_mov_b32_e32 v127, 0
	s_andn2_b64 vcc, exec, s[22:23]
	v_mov_b32_e32 v126, v127
	v_mov_b32_e32 v125, v127
	v_mov_b32_e32 v124, v127
	v_mov_b32_e32 v123, v127
	v_mov_b32_e32 v122, v127
	v_mov_b32_e32 v121, v127
	v_mov_b32_e32 v120, v127
	v_mov_b32_e32 v111, v127
	v_mov_b32_e32 v110, v127
	v_mov_b32_e32 v109, v127
	v_mov_b32_e32 v108, v127
	v_mov_b32_e32 v107, v127
	v_mov_b32_e32 v106, v127
	v_mov_b32_e32 v105, v127
	v_mov_b32_e32 v104, v127
	v_mov_b32_e32 v95, v127
	v_mov_b32_e32 v94, v127
	v_mov_b32_e32 v93, v127
	v_mov_b32_e32 v92, v127
	v_mov_b32_e32 v91, v127
	v_mov_b32_e32 v90, v127
	v_mov_b32_e32 v89, v127
	v_mov_b32_e32 v88, v127
	v_mov_b32_e32 v79, v127
	v_mov_b32_e32 v78, v127
	v_mov_b32_e32 v77, v127
	v_mov_b32_e32 v76, v127
	v_mov_b32_e32 v75, v127
	v_mov_b32_e32 v74, v127
	v_mov_b32_e32 v73, v127
	v_mov_b32_e32 v72, v127
	v_mov_b32_e32 v119, v127
	v_mov_b32_e32 v118, v127
	v_mov_b32_e32 v117, v127
	v_mov_b32_e32 v116, v127
	v_mov_b32_e32 v115, v127
	v_mov_b32_e32 v114, v127
	v_mov_b32_e32 v113, v127
	v_mov_b32_e32 v112, v127
	v_mov_b32_e32 v103, v127
	v_mov_b32_e32 v102, v127
	v_mov_b32_e32 v101, v127
	v_mov_b32_e32 v100, v127
	v_mov_b32_e32 v99, v127
	v_mov_b32_e32 v98, v127
	v_mov_b32_e32 v97, v127
	v_mov_b32_e32 v96, v127
	v_mov_b32_e32 v87, v127
	v_mov_b32_e32 v86, v127
	v_mov_b32_e32 v85, v127
	v_mov_b32_e32 v84, v127
	v_mov_b32_e32 v83, v127
	v_mov_b32_e32 v82, v127
	v_mov_b32_e32 v81, v127
	v_mov_b32_e32 v80, v127
	v_mov_b32_e32 v71, v127
	v_mov_b32_e32 v70, v127
	v_mov_b32_e32 v69, v127
	v_mov_b32_e32 v68, v127
	v_mov_b32_e32 v67, v127
	v_mov_b32_e32 v66, v127
	v_mov_b32_e32 v65, v127
	v_mov_b32_e32 v64, v127
	v_mov_b32_e32 v63, v127
	v_mov_b32_e32 v62, v127
	v_mov_b32_e32 v61, v127
	v_mov_b32_e32 v60, v127
	v_mov_b32_e32 v59, v127
	v_mov_b32_e32 v58, v127
	v_mov_b32_e32 v57, v127
	v_mov_b32_e32 v56, v127
	v_mov_b32_e32 v47, v127
	v_mov_b32_e32 v46, v127
	v_mov_b32_e32 v45, v127
	v_mov_b32_e32 v44, v127
	v_mov_b32_e32 v43, v127
	v_mov_b32_e32 v42, v127
	v_mov_b32_e32 v41, v127
	v_mov_b32_e32 v40, v127
	v_mov_b32_e32 v31, v127
	v_mov_b32_e32 v30, v127
	v_mov_b32_e32 v29, v127
	v_mov_b32_e32 v28, v127
	v_mov_b32_e32 v27, v127
	v_mov_b32_e32 v26, v127
	v_mov_b32_e32 v25, v127
	v_mov_b32_e32 v24, v127
	v_mov_b32_e32 v15, v127
	v_mov_b32_e32 v14, v127
	v_mov_b32_e32 v13, v127
	v_mov_b32_e32 v12, v127
	v_mov_b32_e32 v11, v127
	v_mov_b32_e32 v10, v127
	v_mov_b32_e32 v9, v127
	v_mov_b32_e32 v8, v127
	v_mov_b32_e32 v55, v127
	v_mov_b32_e32 v54, v127
	v_mov_b32_e32 v53, v127
	v_mov_b32_e32 v52, v127
	v_mov_b32_e32 v51, v127
	v_mov_b32_e32 v50, v127
	v_mov_b32_e32 v49, v127
	v_mov_b32_e32 v48, v127
	v_mov_b32_e32 v39, v127
	v_mov_b32_e32 v38, v127
	v_mov_b32_e32 v37, v127
	v_mov_b32_e32 v36, v127
	v_mov_b32_e32 v35, v127
	v_mov_b32_e32 v34, v127
	v_mov_b32_e32 v33, v127
	v_mov_b32_e32 v32, v127
	v_mov_b32_e32 v23, v127
	v_mov_b32_e32 v22, v127
	v_mov_b32_e32 v21, v127
	v_mov_b32_e32 v20, v127
	v_mov_b32_e32 v19, v127
	v_mov_b32_e32 v18, v127
	v_mov_b32_e32 v17, v127
	v_mov_b32_e32 v16, v127
	v_mov_b32_e32 v7, v127
	v_mov_b32_e32 v6, v127
	v_mov_b32_e32 v5, v127
	v_mov_b32_e32 v4, v127
	v_mov_b32_e32 v3, v127
	v_mov_b32_e32 v2, v127
	s_waitcnt lgkmcnt(0)
	v_mov_b32_e32 v1, v127
	v_mov_b32_e32 v0, v127
	s_cbranch_vccnz .LBB0_306
	s_add_u32 s30, s30, 0x80
	s_addc_u32 s31, s31, 0
	s_add_u32 s10, s34, 0x100
	s_addc_u32 s11, s35, 0
	s_mov_b32 s34, 0
	s_cmp_lg_u32 s100, 0
	s_cbranch_scc0 .Llbb_2
	s_barrier
	s_mov_b32 s100, 0
.Llbb_2:
.LBB0_305:
	s_add_i32 s44, s34, 2
	s_add_u32 s4, s30, 0x80
	s_addc_u32 s5, s31, 0
	s_add_i32 s45, 0, 0x10000
	s_cmp_eq_u32 s62, s34
	s_cselect_b32 s35, s27, s5
	s_cselect_b32 s34, s26, s4
	s_cselect_b32 s5, s29, s11
	s_cselect_b32 s4, s28, s10
	s_add_i32 s54, 0, 0x14000
	v_add_u32_e32 v140, s45, v163
	v_add_u32_e32 v170, s54, v163
	ds_read_b128 v[128:131], v140
	ds_read_b128 v[132:135], v140 offset:1024
	ds_read_b128 v[136:139], v140 offset:2048
	ds_read_b128 v[140:143], v140 offset:3072
	ds_read_b128 v[154:157], v170
	ds_read_b128 v[158:161], v170 offset:1024
	ds_read_b128 v[166:169], v170 offset:2048
	ds_read_b128 v[170:173], v170 offset:3072
	v_lshl_add_u64 v[174:175], s[30:31], 0, v[150:151]
	s_add_i32 m0, s38, 0xc000
	ds_read_b128 v[186:189], v165
	ds_read_b128 v[190:193], v165 offset:1024
	ds_read_b128 v[194:197], v165 offset:2048
	ds_read_b128 v[198:201], v165 offset:3072
	ds_read_b128 v[202:205], v165 offset:4096
	ds_read_b128 v[206:209], v165 offset:5120
	ds_read_b128 v[210:213], v165 offset:6144
	ds_read_b128 v[214:217], v165 offset:7168
	global_load_lds_dwordx4 v[174:175], off
	v_lshl_add_u64 v[174:175], s[30:31], 0, v[152:153]
	s_add_i32 m0, s38, 0xe000
	s_nop 0
	global_load_lds_dwordx4 v[174:175], off
	s_waitcnt vmcnt(8)
	s_waitcnt lgkmcnt(0)
	s_barrier
	s_waitcnt lgkmcnt(0)
	v_mfma_f32_16x16x32_bf16 v[124:127], v[128:131], v[186:189], v[124:127]
	v_mfma_f32_16x16x32_bf16 v[120:123], v[136:139], v[186:189], v[120:123]
	v_mfma_f32_16x16x32_bf16 v[108:111], v[128:131], v[194:197], v[108:111]
	v_mfma_f32_16x16x32_bf16 v[104:107], v[136:139], v[194:197], v[104:107]
	v_mfma_f32_16x16x32_bf16 v[92:95], v[128:131], v[202:205], v[92:95]
	v_mfma_f32_16x16x32_bf16 v[88:91], v[136:139], v[202:205], v[88:91]
	v_mfma_f32_16x16x32_bf16 v[76:79], v[128:131], v[210:213], v[76:79]
	v_mfma_f32_16x16x32_bf16 v[72:75], v[136:139], v[210:213], v[72:75]
	v_mfma_f32_16x16x32_bf16 v[124:127], v[132:135], v[190:193], v[124:127]
	v_mfma_f32_16x16x32_bf16 v[120:123], v[140:143], v[190:193], v[120:123]
	v_mfma_f32_16x16x32_bf16 v[108:111], v[132:135], v[198:201], v[108:111]
	v_mfma_f32_16x16x32_bf16 v[104:107], v[140:143], v[198:201], v[104:107]
	v_mfma_f32_16x16x32_bf16 v[92:95], v[132:135], v[206:209], v[92:95]
	v_mfma_f32_16x16x32_bf16 v[88:91], v[140:143], v[206:209], v[88:91]
	v_mfma_f32_16x16x32_bf16 v[76:79], v[132:135], v[214:217], v[76:79]
	v_mfma_f32_16x16x32_bf16 v[72:75], v[140:143], v[214:217], v[72:75]
	v_mfma_f32_16x16x32_bf16 v[116:119], v[154:157], v[186:189], v[116:119]
	v_mfma_f32_16x16x32_bf16 v[112:115], v[166:169], v[186:189], v[112:115]
	v_mfma_f32_16x16x32_bf16 v[100:103], v[154:157], v[194:197], v[100:103]
	v_mfma_f32_16x16x32_bf16 v[96:99], v[166:169], v[194:197], v[96:99]
	v_mfma_f32_16x16x32_bf16 v[84:87], v[154:157], v[202:205], v[84:87]
	v_mfma_f32_16x16x32_bf16 v[80:83], v[166:169], v[202:205], v[80:83]
	v_mfma_f32_16x16x32_bf16 v[68:71], v[154:157], v[210:213], v[68:71]
	v_mfma_f32_16x16x32_bf16 v[64:67], v[166:169], v[210:213], v[64:67]
	v_mfma_f32_16x16x32_bf16 v[116:119], v[158:161], v[190:193], v[116:119]
	v_mfma_f32_16x16x32_bf16 v[112:115], v[170:173], v[190:193], v[112:115]
	v_mfma_f32_16x16x32_bf16 v[100:103], v[158:161], v[198:201], v[100:103]
	v_mfma_f32_16x16x32_bf16 v[96:99], v[170:173], v[198:201], v[96:99]
	v_mfma_f32_16x16x32_bf16 v[84:87], v[158:161], v[206:209], v[84:87]
	v_mfma_f32_16x16x32_bf16 v[80:83], v[170:173], v[206:209], v[80:83]
	v_mfma_f32_16x16x32_bf16 v[68:71], v[158:161], v[214:217], v[68:71]
	v_mfma_f32_16x16x32_bf16 v[64:67], v[170:173], v[214:217], v[64:67]
	s_barrier
	s_add_i32 s45, s45, s37
	v_lshl_add_u64 v[174:175], s[4:5], 0, v[176:177]
	s_mov_b32 m0, s45
	ds_read_b128 v[186:189], v165 offset:16384
	ds_read_b128 v[190:193], v165 offset:17408
	ds_read_b128 v[194:197], v165 offset:18432
	ds_read_b128 v[198:201], v165 offset:19456
	ds_read_b128 v[202:205], v165 offset:20480
	ds_read_b128 v[206:209], v165 offset:21504
	ds_read_b128 v[210:213], v165 offset:22528
	ds_read_b128 v[214:217], v165 offset:23552
	global_load_lds_dwordx4 v[174:175], off
	s_add_i32 m0, s45, 0x2000
	v_lshl_add_u64 v[222:223], s[4:5], 0, v[144:145]
	s_add_u32 s4, s4, s0
	s_addc_u32 s5, s5, s1
	s_add_i32 s45, s54, s37
	global_load_lds_dwordx4 v[222:223], off
	v_lshl_add_u64 v[224:225], s[4:5], 0, v[176:177]
	s_mov_b32 m0, s45
	v_lshl_add_u64 v[226:227], s[4:5], 0, v[144:145]
	global_load_lds_dwordx4 v[224:225], off
	s_add_i32 m0, s45, 0x2000
	v_lshl_add_u64 v[228:229], s[34:35], 0, v[148:149]
	global_load_lds_dwordx4 v[226:227], off
	s_mov_b32 m0, s38
	v_lshl_add_u64 v[230:231], s[34:35], 0, v[146:147]
	global_load_lds_dwordx4 v[228:229], off
	s_mov_b32 m0, s39
	s_nop 0
	global_load_lds_dwordx4 v[230:231], off
	s_waitcnt vmcnt(8)
	s_waitcnt lgkmcnt(0)
	s_barrier
	s_waitcnt lgkmcnt(0)
	v_mfma_f32_16x16x32_bf16 v[60:63], v[128:131], v[186:189], v[60:63]
	v_mfma_f32_16x16x32_bf16 v[56:59], v[136:139], v[186:189], v[56:59]
	v_mfma_f32_16x16x32_bf16 v[44:47], v[128:131], v[194:197], v[44:47]
	v_mfma_f32_16x16x32_bf16 v[40:43], v[136:139], v[194:197], v[40:43]
	v_mfma_f32_16x16x32_bf16 v[28:31], v[128:131], v[202:205], v[28:31]
	v_mfma_f32_16x16x32_bf16 v[24:27], v[136:139], v[202:205], v[24:27]
	v_mfma_f32_16x16x32_bf16 v[12:15], v[128:131], v[210:213], v[12:15]
	v_mfma_f32_16x16x32_bf16 v[8:11], v[136:139], v[210:213], v[8:11]
	v_mfma_f32_16x16x32_bf16 v[60:63], v[132:135], v[190:193], v[60:63]
	v_mfma_f32_16x16x32_bf16 v[56:59], v[140:143], v[190:193], v[56:59]
	v_mfma_f32_16x16x32_bf16 v[44:47], v[132:135], v[198:201], v[44:47]
	v_mfma_f32_16x16x32_bf16 v[40:43], v[140:143], v[198:201], v[40:43]
	v_mfma_f32_16x16x32_bf16 v[28:31], v[132:135], v[206:209], v[28:31]
	v_mfma_f32_16x16x32_bf16 v[24:27], v[140:143], v[206:209], v[24:27]
	v_mfma_f32_16x16x32_bf16 v[12:15], v[132:135], v[214:217], v[12:15]
	v_mfma_f32_16x16x32_bf16 v[8:11], v[140:143], v[214:217], v[8:11]
	v_mfma_f32_16x16x32_bf16 v[52:55], v[154:157], v[186:189], v[52:55]
	v_mfma_f32_16x16x32_bf16 v[48:51], v[166:169], v[186:189], v[48:51]
	v_mfma_f32_16x16x32_bf16 v[36:39], v[154:157], v[194:197], v[36:39]
	v_mfma_f32_16x16x32_bf16 v[32:35], v[166:169], v[194:197], v[32:35]
	v_mfma_f32_16x16x32_bf16 v[20:23], v[154:157], v[202:205], v[20:23]
	v_mfma_f32_16x16x32_bf16 v[16:19], v[166:169], v[202:205], v[16:19]
	v_mfma_f32_16x16x32_bf16 v[4:7], v[154:157], v[210:213], v[4:7]
	v_mfma_f32_16x16x32_bf16 v[0:3], v[166:169], v[210:213], v[0:3]
	v_mfma_f32_16x16x32_bf16 v[52:55], v[158:161], v[190:193], v[52:55]
	v_mfma_f32_16x16x32_bf16 v[48:51], v[170:173], v[190:193], v[48:51]
	v_mfma_f32_16x16x32_bf16 v[36:39], v[158:161], v[198:201], v[36:39]
	v_mfma_f32_16x16x32_bf16 v[32:35], v[170:173], v[198:201], v[32:35]
	v_mfma_f32_16x16x32_bf16 v[20:23], v[158:161], v[206:209], v[20:23]
	v_mfma_f32_16x16x32_bf16 v[16:19], v[170:173], v[206:209], v[16:19]
	v_mfma_f32_16x16x32_bf16 v[4:7], v[158:161], v[214:217], v[4:7]
	v_mfma_f32_16x16x32_bf16 v[0:3], v[170:173], v[214:217], v[0:3]
	s_barrier
	s_add_i32 s45, 0, 0x18000
	s_add_i32 s54, 0, 0x1c000
	v_add_u32_e32 v140, s45, v163
	v_add_u32_e32 v170, s54, v163
	ds_read_b128 v[128:131], v140
	ds_read_b128 v[132:135], v140 offset:1024
	ds_read_b128 v[136:139], v140 offset:2048
	ds_read_b128 v[140:143], v140 offset:3072
	ds_read_b128 v[154:157], v170
	ds_read_b128 v[158:161], v170 offset:1024
	ds_read_b128 v[166:169], v170 offset:2048
	ds_read_b128 v[170:173], v170 offset:3072
	s_add_u32 s4, s34, s0
	s_addc_u32 s5, s35, s1
	s_mov_b32 m0, s48
	v_lshl_add_u64 v[232:233], s[4:5], 0, v[148:149]
	ds_read_b128 v[186:189], v165 offset:32768
	ds_read_b128 v[190:193], v165 offset:33792
	ds_read_b128 v[194:197], v165 offset:34816
	ds_read_b128 v[198:201], v165 offset:35840
	ds_read_b128 v[202:205], v165 offset:36864
	ds_read_b128 v[206:209], v165 offset:37888
	ds_read_b128 v[210:213], v165 offset:38912
	ds_read_b128 v[214:217], v165 offset:39936
	global_load_lds_dwordx4 v[232:233], off
	v_lshl_add_u64 v[232:233], s[4:5], 0, v[146:147]
	s_mov_b32 m0, s49
	s_nop 0
	global_load_lds_dwordx4 v[232:233], off
	s_waitcnt vmcnt(8)
	s_waitcnt lgkmcnt(0)
	s_barrier
	s_waitcnt lgkmcnt(0)
	v_mfma_f32_16x16x32_bf16 v[124:127], v[128:131], v[186:189], v[124:127]
	v_mfma_f32_16x16x32_bf16 v[120:123], v[136:139], v[186:189], v[120:123]
	v_mfma_f32_16x16x32_bf16 v[108:111], v[128:131], v[194:197], v[108:111]
	v_mfma_f32_16x16x32_bf16 v[104:107], v[136:139], v[194:197], v[104:107]
	v_mfma_f32_16x16x32_bf16 v[92:95], v[128:131], v[202:205], v[92:95]
	v_mfma_f32_16x16x32_bf16 v[88:91], v[136:139], v[202:205], v[88:91]
	v_mfma_f32_16x16x32_bf16 v[76:79], v[128:131], v[210:213], v[76:79]
	v_mfma_f32_16x16x32_bf16 v[72:75], v[136:139], v[210:213], v[72:75]
	v_mfma_f32_16x16x32_bf16 v[124:127], v[132:135], v[190:193], v[124:127]
	v_mfma_f32_16x16x32_bf16 v[120:123], v[140:143], v[190:193], v[120:123]
	v_mfma_f32_16x16x32_bf16 v[108:111], v[132:135], v[198:201], v[108:111]
	v_mfma_f32_16x16x32_bf16 v[104:107], v[140:143], v[198:201], v[104:107]
	v_mfma_f32_16x16x32_bf16 v[92:95], v[132:135], v[206:209], v[92:95]
	v_mfma_f32_16x16x32_bf16 v[88:91], v[140:143], v[206:209], v[88:91]
	v_mfma_f32_16x16x32_bf16 v[76:79], v[132:135], v[214:217], v[76:79]
	v_mfma_f32_16x16x32_bf16 v[72:75], v[140:143], v[214:217], v[72:75]
	v_mfma_f32_16x16x32_bf16 v[116:119], v[154:157], v[186:189], v[116:119]
	v_mfma_f32_16x16x32_bf16 v[112:115], v[166:169], v[186:189], v[112:115]
	v_mfma_f32_16x16x32_bf16 v[100:103], v[154:157], v[194:197], v[100:103]
	v_mfma_f32_16x16x32_bf16 v[96:99], v[166:169], v[194:197], v[96:99]
	v_mfma_f32_16x16x32_bf16 v[84:87], v[154:157], v[202:205], v[84:87]
	v_mfma_f32_16x16x32_bf16 v[80:83], v[166:169], v[202:205], v[80:83]
	v_mfma_f32_16x16x32_bf16 v[68:71], v[154:157], v[210:213], v[68:71]
	v_mfma_f32_16x16x32_bf16 v[64:67], v[166:169], v[210:213], v[64:67]
	v_mfma_f32_16x16x32_bf16 v[116:119], v[158:161], v[190:193], v[116:119]
	v_mfma_f32_16x16x32_bf16 v[112:115], v[170:173], v[190:193], v[112:115]
	v_mfma_f32_16x16x32_bf16 v[100:103], v[158:161], v[198:201], v[100:103]
	v_mfma_f32_16x16x32_bf16 v[96:99], v[170:173], v[198:201], v[96:99]
	v_mfma_f32_16x16x32_bf16 v[84:87], v[158:161], v[206:209], v[84:87]
	v_mfma_f32_16x16x32_bf16 v[80:83], v[170:173], v[206:209], v[80:83]
	v_mfma_f32_16x16x32_bf16 v[68:71], v[158:161], v[214:217], v[68:71]
	v_mfma_f32_16x16x32_bf16 v[64:67], v[170:173], v[214:217], v[64:67]
	s_barrier
	s_add_i32 s4, s45, s37
	v_lshl_add_u64 v[174:175], v[174:175], 0, s[14:15]
	s_mov_b32 m0, s4
	ds_read_b128 v[186:189], v165 offset:49152
	ds_read_b128 v[190:193], v165 offset:50176
	ds_read_b128 v[194:197], v165 offset:51200
	ds_read_b128 v[198:201], v165 offset:52224
	ds_read_b128 v[202:205], v165 offset:53248
	ds_read_b128 v[206:209], v165 offset:54272
	ds_read_b128 v[210:213], v165 offset:55296
	ds_read_b128 v[214:217], v165 offset:56320
	global_load_lds_dwordx4 v[174:175], off
	v_lshl_add_u64 v[174:175], v[222:223], 0, s[14:15]
	s_add_i32 m0, s4, 0x2000
	s_add_i32 s4, s54, s37
	global_load_lds_dwordx4 v[174:175], off
	v_lshl_add_u64 v[174:175], v[224:225], 0, s[14:15]
	s_mov_b32 m0, s4
	s_nop 0
	global_load_lds_dwordx4 v[174:175], off
	v_lshl_add_u64 v[174:175], v[226:227], 0, s[14:15]
	s_add_i32 m0, s4, 0x2000
	s_nop 0
	global_load_lds_dwordx4 v[174:175], off
	v_lshl_add_u64 v[174:175], v[228:229], 0, s[14:15]
	s_mov_b32 m0, s60
	s_nop 0
	global_load_lds_dwordx4 v[174:175], off
	v_lshl_add_u64 v[174:175], v[230:231], 0, s[14:15]
	s_mov_b32 m0, s61
	s_nop 0
	global_load_lds_dwordx4 v[174:175], off
	s_waitcnt vmcnt(8)
	s_waitcnt lgkmcnt(0)
	s_barrier
	s_waitcnt lgkmcnt(0)
	v_mfma_f32_16x16x32_bf16 v[60:63], v[128:131], v[186:189], v[60:63]
	v_mfma_f32_16x16x32_bf16 v[56:59], v[136:139], v[186:189], v[56:59]
	v_mfma_f32_16x16x32_bf16 v[44:47], v[128:131], v[194:197], v[44:47]
	v_mfma_f32_16x16x32_bf16 v[40:43], v[136:139], v[194:197], v[40:43]
	v_mfma_f32_16x16x32_bf16 v[28:31], v[128:131], v[202:205], v[28:31]
	v_mfma_f32_16x16x32_bf16 v[24:27], v[136:139], v[202:205], v[24:27]
	v_mfma_f32_16x16x32_bf16 v[12:15], v[128:131], v[210:213], v[12:15]
	v_mfma_f32_16x16x32_bf16 v[8:11], v[136:139], v[210:213], v[8:11]
	v_mfma_f32_16x16x32_bf16 v[60:63], v[132:135], v[190:193], v[60:63]
	v_mfma_f32_16x16x32_bf16 v[56:59], v[140:143], v[190:193], v[56:59]
	v_mfma_f32_16x16x32_bf16 v[44:47], v[132:135], v[198:201], v[44:47]
	v_mfma_f32_16x16x32_bf16 v[40:43], v[140:143], v[198:201], v[40:43]
	v_mfma_f32_16x16x32_bf16 v[28:31], v[132:135], v[206:209], v[28:31]
	v_mfma_f32_16x16x32_bf16 v[24:27], v[140:143], v[206:209], v[24:27]
	v_mfma_f32_16x16x32_bf16 v[12:15], v[132:135], v[214:217], v[12:15]
	v_mfma_f32_16x16x32_bf16 v[8:11], v[140:143], v[214:217], v[8:11]
	v_mfma_f32_16x16x32_bf16 v[52:55], v[154:157], v[186:189], v[52:55]
	v_mfma_f32_16x16x32_bf16 v[48:51], v[166:169], v[186:189], v[48:51]
	v_mfma_f32_16x16x32_bf16 v[36:39], v[154:157], v[194:197], v[36:39]
	v_mfma_f32_16x16x32_bf16 v[32:35], v[166:169], v[194:197], v[32:35]
	v_mfma_f32_16x16x32_bf16 v[20:23], v[154:157], v[202:205], v[20:23]
	v_mfma_f32_16x16x32_bf16 v[16:19], v[166:169], v[202:205], v[16:19]
	v_mfma_f32_16x16x32_bf16 v[4:7], v[154:157], v[210:213], v[4:7]
	v_mfma_f32_16x16x32_bf16 v[0:3], v[166:169], v[210:213], v[0:3]
	v_mfma_f32_16x16x32_bf16 v[52:55], v[158:161], v[190:193], v[52:55]
	v_mfma_f32_16x16x32_bf16 v[48:51], v[170:173], v[190:193], v[48:51]
	v_mfma_f32_16x16x32_bf16 v[36:39], v[158:161], v[198:201], v[36:39]
	v_mfma_f32_16x16x32_bf16 v[32:35], v[170:173], v[198:201], v[32:35]
	v_mfma_f32_16x16x32_bf16 v[20:23], v[158:161], v[206:209], v[20:23]
	v_mfma_f32_16x16x32_bf16 v[16:19], v[170:173], v[206:209], v[16:19]
	v_mfma_f32_16x16x32_bf16 v[4:7], v[158:161], v[214:217], v[4:7]
	v_mfma_f32_16x16x32_bf16 v[0:3], v[170:173], v[214:217], v[0:3]
	s_barrier
	s_add_u32 s30, s30, 0x100
	s_addc_u32 s31, s31, 0
	s_add_u32 s10, s10, 0x100
	s_addc_u32 s11, s11, 0
	s_cmp_ge_i32 s44, s59
	s_mov_b32 s34, s44
	s_cbranch_scc0 .LBB0_305

.LBB0_392:
	v_mov_b32_e32 v123, 0
	s_andn2_b64 vcc, exec, s[20:21]
	v_mov_b32_e32 v122, v123
	v_mov_b32_e32 v121, v123
	v_mov_b32_e32 v120, v123
	v_mov_b32_e32 v119, v123
	v_mov_b32_e32 v118, v123
	v_mov_b32_e32 v117, v123
	v_mov_b32_e32 v116, v123
	v_mov_b32_e32 v111, v123
	v_mov_b32_e32 v110, v123
	v_mov_b32_e32 v109, v123
	v_mov_b32_e32 v108, v123
	v_mov_b32_e32 v103, v123
	v_mov_b32_e32 v102, v123
	v_mov_b32_e32 v101, v123
	v_mov_b32_e32 v100, v123
	v_mov_b32_e32 v95, v123
	v_mov_b32_e32 v94, v123
	v_mov_b32_e32 v93, v123
	v_mov_b32_e32 v92, v123
	v_mov_b32_e32 v87, v123
	v_mov_b32_e32 v86, v123
	v_mov_b32_e32 v85, v123
	v_mov_b32_e32 v84, v123
	v_mov_b32_e32 v79, v123
	v_mov_b32_e32 v78, v123
	v_mov_b32_e32 v77, v123
	v_mov_b32_e32 v76, v123
	v_mov_b32_e32 v71, v123
	v_mov_b32_e32 v70, v123
	v_mov_b32_e32 v69, v123
	v_mov_b32_e32 v68, v123
	v_mov_b32_e32 v127, v123
	v_mov_b32_e32 v126, v123
	v_mov_b32_e32 v125, v123
	v_mov_b32_e32 v124, v123
	v_mov_b32_e32 v115, v123
	v_mov_b32_e32 v114, v123
	v_mov_b32_e32 v113, v123
	v_mov_b32_e32 v112, v123
	v_mov_b32_e32 v107, v123
	v_mov_b32_e32 v106, v123
	v_mov_b32_e32 v105, v123
	v_mov_b32_e32 v104, v123
	v_mov_b32_e32 v99, v123
	v_mov_b32_e32 v98, v123
	v_mov_b32_e32 v97, v123
	v_mov_b32_e32 v96, v123
	v_mov_b32_e32 v91, v123
	v_mov_b32_e32 v90, v123
	v_mov_b32_e32 v89, v123
	v_mov_b32_e32 v88, v123
	v_mov_b32_e32 v83, v123
	v_mov_b32_e32 v82, v123
	v_mov_b32_e32 v81, v123
	v_mov_b32_e32 v80, v123
	v_mov_b32_e32 v75, v123
	v_mov_b32_e32 v74, v123
	v_mov_b32_e32 v73, v123
	v_mov_b32_e32 v72, v123
	v_mov_b32_e32 v67, v123
	v_mov_b32_e32 v66, v123
	v_mov_b32_e32 v65, v123
	v_mov_b32_e32 v64, v123
	v_mov_b32_e32 v63, v123
	v_mov_b32_e32 v62, v123
	v_mov_b32_e32 v61, v123
	v_mov_b32_e32 v60, v123
	v_mov_b32_e32 v55, v123
	v_mov_b32_e32 v54, v123
	v_mov_b32_e32 v53, v123
	v_mov_b32_e32 v52, v123
	v_mov_b32_e32 v47, v123
	v_mov_b32_e32 v46, v123
	v_mov_b32_e32 v45, v123
	v_mov_b32_e32 v44, v123
	v_mov_b32_e32 v39, v123
	v_mov_b32_e32 v38, v123
	v_mov_b32_e32 v37, v123
	v_mov_b32_e32 v36, v123
	v_mov_b32_e32 v31, v123
	v_mov_b32_e32 v30, v123
	v_mov_b32_e32 v29, v123
	v_mov_b32_e32 v28, v123
	v_mov_b32_e32 v23, v123
	v_mov_b32_e32 v22, v123
	v_mov_b32_e32 v21, v123
	v_mov_b32_e32 v20, v123
	v_mov_b32_e32 v15, v123
	v_mov_b32_e32 v14, v123
	v_mov_b32_e32 v13, v123
	v_mov_b32_e32 v12, v123
	v_mov_b32_e32 v7, v123
	v_mov_b32_e32 v6, v123
	v_mov_b32_e32 v5, v123
	v_mov_b32_e32 v4, v123
	v_mov_b32_e32 v59, v123
	v_mov_b32_e32 v58, v123
	v_mov_b32_e32 v57, v123
	v_mov_b32_e32 v56, v123
	v_mov_b32_e32 v51, v123
	v_mov_b32_e32 v50, v123
	v_mov_b32_e32 v49, v123
	v_mov_b32_e32 v48, v123
	v_mov_b32_e32 v43, v123
	v_mov_b32_e32 v42, v123
	v_mov_b32_e32 v41, v123
	v_mov_b32_e32 v40, v123
	v_mov_b32_e32 v35, v123
	v_mov_b32_e32 v34, v123
	v_mov_b32_e32 v33, v123
	v_mov_b32_e32 v32, v123
	v_mov_b32_e32 v27, v123
	v_mov_b32_e32 v26, v123
	v_mov_b32_e32 v25, v123
	v_mov_b32_e32 v24, v123
	v_mov_b32_e32 v19, v123
	v_mov_b32_e32 v18, v123
	v_mov_b32_e32 v17, v123
	v_mov_b32_e32 v16, v123
	v_mov_b32_e32 v11, v123
	v_mov_b32_e32 v10, v123
	v_mov_b32_e32 v9, v123
	v_mov_b32_e32 v8, v123
	v_mov_b32_e32 v3, v123
	v_mov_b32_e32 v2, v123
	v_mov_b32_e32 v1, v123
	v_mov_b32_e32 v0, v123
	s_cbranch_vccnz .LBB0_395
	s_add_u32 s28, s28, 0x80
	s_addc_u32 s29, s29, 0
	s_add_u32 s10, s30, 0x100
	s_addc_u32 s11, s31, 0
	s_mov_b32 s30, 0
	s_cmp_lg_u32 s100, 0
	s_cbranch_scc0 .Llbb_3
	s_barrier
	s_mov_b32 s100, 0
.Llbb_3:
.LBB0_394:
	s_add_i32 s44, s30, 2
	s_add_u32 s4, s28, 0x80
	s_addc_u32 s5, s29, 0
	s_add_i32 s45, 0, 0x10000
	s_cmp_eq_u32 s61, s30
	s_cselect_b32 s31, s25, s5
	s_cselect_b32 s30, s24, s4
	s_cselect_b32 s5, s27, s11
	s_cselect_b32 s4, s26, s10
	s_add_i32 s54, 0, 0x14000
	v_add_u32_e32 v156, s45, v151
	v_add_u32_e32 v172, s54, v151
	ds_read_b128 v[128:131], v156
	ds_read_b128 v[142:145], v156 offset:1024
	ds_read_b128 v[146:149], v156 offset:2048
	ds_read_b128 v[156:159], v156 offset:3072
	ds_read_b128 v[160:163], v172
	ds_read_b128 v[164:167], v172 offset:1024
	ds_read_b128 v[168:171], v172 offset:2048
	ds_read_b128 v[172:175], v172 offset:3072
	v_lshl_add_u64 v[222:223], s[28:29], 0, v[138:139]
	s_add_i32 m0, s37, 0xc000
	ds_read_b128 v[186:189], v155
	ds_read_b128 v[190:193], v155 offset:1024
	ds_read_b128 v[194:197], v155 offset:2048
	ds_read_b128 v[198:201], v155 offset:3072
	ds_read_b128 v[202:205], v155 offset:4096
	ds_read_b128 v[206:209], v155 offset:5120
	ds_read_b128 v[210:213], v155 offset:6144
	ds_read_b128 v[214:217], v155 offset:7168
	global_load_lds_dwordx4 v[222:223], off
	v_lshl_add_u64 v[222:223], s[28:29], 0, v[140:141]
	s_add_i32 m0, s37, 0xe000
	s_nop 0
	global_load_lds_dwordx4 v[222:223], off
	s_waitcnt vmcnt(8)
	s_waitcnt lgkmcnt(0)
	s_barrier
	s_waitcnt lgkmcnt(0)
	v_mfma_f32_16x16x32_bf16 v[120:123], v[128:131], v[186:189], v[120:123]
	v_mfma_f32_16x16x32_bf16 v[116:119], v[146:149], v[186:189], v[116:119]
	v_mfma_f32_16x16x32_bf16 v[108:111], v[128:131], v[194:197], v[108:111]
	v_mfma_f32_16x16x32_bf16 v[100:103], v[146:149], v[194:197], v[100:103]
	v_mfma_f32_16x16x32_bf16 v[92:95], v[128:131], v[202:205], v[92:95]
	v_mfma_f32_16x16x32_bf16 v[84:87], v[146:149], v[202:205], v[84:87]
	v_mfma_f32_16x16x32_bf16 v[76:79], v[128:131], v[210:213], v[76:79]
	v_mfma_f32_16x16x32_bf16 v[68:71], v[146:149], v[210:213], v[68:71]
	v_mfma_f32_16x16x32_bf16 v[120:123], v[142:145], v[190:193], v[120:123]
	v_mfma_f32_16x16x32_bf16 v[116:119], v[156:159], v[190:193], v[116:119]
	v_mfma_f32_16x16x32_bf16 v[108:111], v[142:145], v[198:201], v[108:111]
	v_mfma_f32_16x16x32_bf16 v[100:103], v[156:159], v[198:201], v[100:103]
	v_mfma_f32_16x16x32_bf16 v[92:95], v[142:145], v[206:209], v[92:95]
	v_mfma_f32_16x16x32_bf16 v[84:87], v[156:159], v[206:209], v[84:87]
	v_mfma_f32_16x16x32_bf16 v[76:79], v[142:145], v[214:217], v[76:79]
	v_mfma_f32_16x16x32_bf16 v[68:71], v[156:159], v[214:217], v[68:71]
	v_mfma_f32_16x16x32_bf16 v[124:127], v[160:163], v[186:189], v[124:127]
	v_mfma_f32_16x16x32_bf16 v[112:115], v[168:171], v[186:189], v[112:115]
	v_mfma_f32_16x16x32_bf16 v[104:107], v[160:163], v[194:197], v[104:107]
	v_mfma_f32_16x16x32_bf16 v[96:99], v[168:171], v[194:197], v[96:99]
	v_mfma_f32_16x16x32_bf16 v[88:91], v[160:163], v[202:205], v[88:91]
	v_mfma_f32_16x16x32_bf16 v[80:83], v[168:171], v[202:205], v[80:83]
	v_mfma_f32_16x16x32_bf16 v[72:75], v[160:163], v[210:213], v[72:75]
	v_mfma_f32_16x16x32_bf16 v[64:67], v[168:171], v[210:213], v[64:67]
	v_mfma_f32_16x16x32_bf16 v[124:127], v[164:167], v[190:193], v[124:127]
	v_mfma_f32_16x16x32_bf16 v[112:115], v[172:175], v[190:193], v[112:115]
	v_mfma_f32_16x16x32_bf16 v[104:107], v[164:167], v[198:201], v[104:107]
	v_mfma_f32_16x16x32_bf16 v[96:99], v[172:175], v[198:201], v[96:99]
	v_mfma_f32_16x16x32_bf16 v[88:91], v[164:167], v[206:209], v[88:91]
	v_mfma_f32_16x16x32_bf16 v[80:83], v[172:175], v[206:209], v[80:83]
	v_mfma_f32_16x16x32_bf16 v[72:75], v[164:167], v[214:217], v[72:75]
	v_mfma_f32_16x16x32_bf16 v[64:67], v[172:175], v[214:217], v[64:67]
	s_barrier
	s_add_i32 s45, s45, s36
	v_lshl_add_u64 v[222:223], s[4:5], 0, v[176:177]
	s_mov_b32 m0, s45
	ds_read_b128 v[186:189], v155 offset:16384
	ds_read_b128 v[190:193], v155 offset:17408
	ds_read_b128 v[194:197], v155 offset:18432
	ds_read_b128 v[198:201], v155 offset:19456
	ds_read_b128 v[202:205], v155 offset:20480
	ds_read_b128 v[206:209], v155 offset:21504
	ds_read_b128 v[210:213], v155 offset:22528
	ds_read_b128 v[214:217], v155 offset:23552
	global_load_lds_dwordx4 v[222:223], off
	s_add_i32 m0, s45, 0x2000
	v_lshl_add_u64 v[224:225], s[4:5], 0, v[132:133]
	s_add_u32 s4, s4, s6
	s_addc_u32 s5, s5, s7
	s_add_i32 s45, s54, s36
	global_load_lds_dwordx4 v[224:225], off
	v_lshl_add_u64 v[226:227], s[4:5], 0, v[176:177]
	s_mov_b32 m0, s45
	v_lshl_add_u64 v[228:229], s[4:5], 0, v[132:133]
	global_load_lds_dwordx4 v[226:227], off
	s_add_i32 m0, s45, 0x2000
	v_lshl_add_u64 v[230:231], s[30:31], 0, v[136:137]
	global_load_lds_dwordx4 v[228:229], off
	s_mov_b32 m0, s37
	v_lshl_add_u64 v[232:233], s[30:31], 0, v[134:135]
	global_load_lds_dwordx4 v[230:231], off
	s_mov_b32 m0, s38
	s_nop 0
	global_load_lds_dwordx4 v[232:233], off
	s_waitcnt vmcnt(8)
	s_waitcnt lgkmcnt(0)
	s_barrier
	s_waitcnt lgkmcnt(0)
	v_mfma_f32_16x16x32_bf16 v[60:63], v[128:131], v[186:189], v[60:63]
	v_mfma_f32_16x16x32_bf16 v[52:55], v[146:149], v[186:189], v[52:55]
	v_mfma_f32_16x16x32_bf16 v[44:47], v[128:131], v[194:197], v[44:47]
	v_mfma_f32_16x16x32_bf16 v[36:39], v[146:149], v[194:197], v[36:39]
	v_mfma_f32_16x16x32_bf16 v[28:31], v[128:131], v[202:205], v[28:31]
	v_mfma_f32_16x16x32_bf16 v[20:23], v[146:149], v[202:205], v[20:23]
	v_mfma_f32_16x16x32_bf16 v[12:15], v[128:131], v[210:213], v[12:15]
	v_mfma_f32_16x16x32_bf16 v[4:7], v[146:149], v[210:213], v[4:7]
	v_mfma_f32_16x16x32_bf16 v[60:63], v[142:145], v[190:193], v[60:63]
	v_mfma_f32_16x16x32_bf16 v[52:55], v[156:159], v[190:193], v[52:55]
	v_mfma_f32_16x16x32_bf16 v[44:47], v[142:145], v[198:201], v[44:47]
	v_mfma_f32_16x16x32_bf16 v[36:39], v[156:159], v[198:201], v[36:39]
	v_mfma_f32_16x16x32_bf16 v[28:31], v[142:145], v[206:209], v[28:31]
	v_mfma_f32_16x16x32_bf16 v[20:23], v[156:159], v[206:209], v[20:23]
	v_mfma_f32_16x16x32_bf16 v[12:15], v[142:145], v[214:217], v[12:15]
	v_mfma_f32_16x16x32_bf16 v[4:7], v[156:159], v[214:217], v[4:7]
	v_mfma_f32_16x16x32_bf16 v[56:59], v[160:163], v[186:189], v[56:59]
	v_mfma_f32_16x16x32_bf16 v[48:51], v[168:171], v[186:189], v[48:51]
	v_mfma_f32_16x16x32_bf16 v[40:43], v[160:163], v[194:197], v[40:43]
	v_mfma_f32_16x16x32_bf16 v[32:35], v[168:171], v[194:197], v[32:35]
	v_mfma_f32_16x16x32_bf16 v[24:27], v[160:163], v[202:205], v[24:27]
	v_mfma_f32_16x16x32_bf16 v[16:19], v[168:171], v[202:205], v[16:19]
	v_mfma_f32_16x16x32_bf16 v[8:11], v[160:163], v[210:213], v[8:11]
	v_mfma_f32_16x16x32_bf16 v[0:3], v[168:171], v[210:213], v[0:3]
	v_mfma_f32_16x16x32_bf16 v[56:59], v[164:167], v[190:193], v[56:59]
	v_mfma_f32_16x16x32_bf16 v[48:51], v[172:175], v[190:193], v[48:51]
	v_mfma_f32_16x16x32_bf16 v[40:43], v[164:167], v[198:201], v[40:43]
	v_mfma_f32_16x16x32_bf16 v[32:35], v[172:175], v[198:201], v[32:35]
	v_mfma_f32_16x16x32_bf16 v[24:27], v[164:167], v[206:209], v[24:27]
	v_mfma_f32_16x16x32_bf16 v[16:19], v[172:175], v[206:209], v[16:19]
	v_mfma_f32_16x16x32_bf16 v[8:11], v[164:167], v[214:217], v[8:11]
	v_mfma_f32_16x16x32_bf16 v[0:3], v[172:175], v[214:217], v[0:3]
	s_barrier
	s_add_i32 s45, 0, 0x18000
	s_add_i32 s54, 0, 0x1c000
	v_add_u32_e32 v156, s45, v151
	v_add_u32_e32 v172, s54, v151
	ds_read_b128 v[128:131], v156
	ds_read_b128 v[142:145], v156 offset:1024
	ds_read_b128 v[146:149], v156 offset:2048
	ds_read_b128 v[156:159], v156 offset:3072
	ds_read_b128 v[160:163], v172
	ds_read_b128 v[164:167], v172 offset:1024
	ds_read_b128 v[168:171], v172 offset:2048
	ds_read_b128 v[172:175], v172 offset:3072
	s_add_u32 s4, s30, s6
	s_addc_u32 s5, s31, s7
	s_mov_b32 m0, s39
	v_lshl_add_u64 v[234:235], s[4:5], 0, v[136:137]
	ds_read_b128 v[186:189], v155 offset:32768
	ds_read_b128 v[190:193], v155 offset:33792
	ds_read_b128 v[194:197], v155 offset:34816
	ds_read_b128 v[198:201], v155 offset:35840
	ds_read_b128 v[202:205], v155 offset:36864
	ds_read_b128 v[206:209], v155 offset:37888
	ds_read_b128 v[210:213], v155 offset:38912
	ds_read_b128 v[214:217], v155 offset:39936
	global_load_lds_dwordx4 v[234:235], off
	v_lshl_add_u64 v[234:235], s[4:5], 0, v[134:135]
	s_mov_b32 m0, s48
	s_nop 0
	global_load_lds_dwordx4 v[234:235], off
	s_waitcnt vmcnt(8)
	s_waitcnt lgkmcnt(0)
	s_barrier
	s_waitcnt lgkmcnt(0)
	v_mfma_f32_16x16x32_bf16 v[120:123], v[128:131], v[186:189], v[120:123]
	v_mfma_f32_16x16x32_bf16 v[116:119], v[146:149], v[186:189], v[116:119]
	v_mfma_f32_16x16x32_bf16 v[108:111], v[128:131], v[194:197], v[108:111]
	v_mfma_f32_16x16x32_bf16 v[100:103], v[146:149], v[194:197], v[100:103]
	v_mfma_f32_16x16x32_bf16 v[92:95], v[128:131], v[202:205], v[92:95]
	v_mfma_f32_16x16x32_bf16 v[84:87], v[146:149], v[202:205], v[84:87]
	v_mfma_f32_16x16x32_bf16 v[76:79], v[128:131], v[210:213], v[76:79]
	v_mfma_f32_16x16x32_bf16 v[68:71], v[146:149], v[210:213], v[68:71]
	v_mfma_f32_16x16x32_bf16 v[120:123], v[142:145], v[190:193], v[120:123]
	v_mfma_f32_16x16x32_bf16 v[116:119], v[156:159], v[190:193], v[116:119]
	v_mfma_f32_16x16x32_bf16 v[108:111], v[142:145], v[198:201], v[108:111]
	v_mfma_f32_16x16x32_bf16 v[100:103], v[156:159], v[198:201], v[100:103]
	v_mfma_f32_16x16x32_bf16 v[92:95], v[142:145], v[206:209], v[92:95]
	v_mfma_f32_16x16x32_bf16 v[84:87], v[156:159], v[206:209], v[84:87]
	v_mfma_f32_16x16x32_bf16 v[76:79], v[142:145], v[214:217], v[76:79]
	v_mfma_f32_16x16x32_bf16 v[68:71], v[156:159], v[214:217], v[68:71]
	v_mfma_f32_16x16x32_bf16 v[124:127], v[160:163], v[186:189], v[124:127]
	v_mfma_f32_16x16x32_bf16 v[112:115], v[168:171], v[186:189], v[112:115]
	v_mfma_f32_16x16x32_bf16 v[104:107], v[160:163], v[194:197], v[104:107]
	v_mfma_f32_16x16x32_bf16 v[96:99], v[168:171], v[194:197], v[96:99]
	v_mfma_f32_16x16x32_bf16 v[88:91], v[160:163], v[202:205], v[88:91]
	v_mfma_f32_16x16x32_bf16 v[80:83], v[168:171], v[202:205], v[80:83]
	v_mfma_f32_16x16x32_bf16 v[72:75], v[160:163], v[210:213], v[72:75]
	v_mfma_f32_16x16x32_bf16 v[64:67], v[168:171], v[210:213], v[64:67]
	v_mfma_f32_16x16x32_bf16 v[124:127], v[164:167], v[190:193], v[124:127]
	v_mfma_f32_16x16x32_bf16 v[112:115], v[172:175], v[190:193], v[112:115]
	v_mfma_f32_16x16x32_bf16 v[104:107], v[164:167], v[198:201], v[104:107]
	v_mfma_f32_16x16x32_bf16 v[96:99], v[172:175], v[198:201], v[96:99]
	v_mfma_f32_16x16x32_bf16 v[88:91], v[164:167], v[206:209], v[88:91]
	v_mfma_f32_16x16x32_bf16 v[80:83], v[172:175], v[206:209], v[80:83]
	v_mfma_f32_16x16x32_bf16 v[72:75], v[164:167], v[214:217], v[72:75]
	v_mfma_f32_16x16x32_bf16 v[64:67], v[172:175], v[214:217], v[64:67]
	s_barrier
	s_add_i32 s4, s45, s36
	v_lshl_add_u64 v[222:223], v[222:223], 0, s[14:15]
	s_mov_b32 m0, s4
	ds_read_b128 v[186:189], v155 offset:49152
	ds_read_b128 v[190:193], v155 offset:50176
	ds_read_b128 v[194:197], v155 offset:51200
	ds_read_b128 v[198:201], v155 offset:52224
	ds_read_b128 v[202:205], v155 offset:53248
	ds_read_b128 v[206:209], v155 offset:54272
	ds_read_b128 v[210:213], v155 offset:55296
	ds_read_b128 v[214:217], v155 offset:56320
	global_load_lds_dwordx4 v[222:223], off
	v_lshl_add_u64 v[222:223], v[224:225], 0, s[14:15]
	s_add_i32 m0, s4, 0x2000
	s_add_i32 s4, s54, s36
	global_load_lds_dwordx4 v[222:223], off
	v_lshl_add_u64 v[222:223], v[226:227], 0, s[14:15]
	s_mov_b32 m0, s4
	s_nop 0
	global_load_lds_dwordx4 v[222:223], off
	v_lshl_add_u64 v[222:223], v[228:229], 0, s[14:15]
	s_add_i32 m0, s4, 0x2000
	s_nop 0
	global_load_lds_dwordx4 v[222:223], off
	v_lshl_add_u64 v[222:223], v[230:231], 0, s[14:15]
	s_mov_b32 m0, s59
	s_nop 0
	global_load_lds_dwordx4 v[222:223], off
	v_lshl_add_u64 v[222:223], v[232:233], 0, s[14:15]
	s_mov_b32 m0, s60
	s_nop 0
	global_load_lds_dwordx4 v[222:223], off
	s_waitcnt vmcnt(8)
	s_waitcnt lgkmcnt(0)
	s_barrier
	s_waitcnt lgkmcnt(0)
	v_mfma_f32_16x16x32_bf16 v[60:63], v[128:131], v[186:189], v[60:63]
	v_mfma_f32_16x16x32_bf16 v[52:55], v[146:149], v[186:189], v[52:55]
	v_mfma_f32_16x16x32_bf16 v[44:47], v[128:131], v[194:197], v[44:47]
	v_mfma_f32_16x16x32_bf16 v[36:39], v[146:149], v[194:197], v[36:39]
	v_mfma_f32_16x16x32_bf16 v[28:31], v[128:131], v[202:205], v[28:31]
	v_mfma_f32_16x16x32_bf16 v[20:23], v[146:149], v[202:205], v[20:23]
	v_mfma_f32_16x16x32_bf16 v[12:15], v[128:131], v[210:213], v[12:15]
	v_mfma_f32_16x16x32_bf16 v[4:7], v[146:149], v[210:213], v[4:7]
	v_mfma_f32_16x16x32_bf16 v[60:63], v[142:145], v[190:193], v[60:63]
	v_mfma_f32_16x16x32_bf16 v[52:55], v[156:159], v[190:193], v[52:55]
	v_mfma_f32_16x16x32_bf16 v[44:47], v[142:145], v[198:201], v[44:47]
	v_mfma_f32_16x16x32_bf16 v[36:39], v[156:159], v[198:201], v[36:39]
	v_mfma_f32_16x16x32_bf16 v[28:31], v[142:145], v[206:209], v[28:31]
	v_mfma_f32_16x16x32_bf16 v[20:23], v[156:159], v[206:209], v[20:23]
	v_mfma_f32_16x16x32_bf16 v[12:15], v[142:145], v[214:217], v[12:15]
	v_mfma_f32_16x16x32_bf16 v[4:7], v[156:159], v[214:217], v[4:7]
	v_mfma_f32_16x16x32_bf16 v[56:59], v[160:163], v[186:189], v[56:59]
	v_mfma_f32_16x16x32_bf16 v[48:51], v[168:171], v[186:189], v[48:51]
	v_mfma_f32_16x16x32_bf16 v[40:43], v[160:163], v[194:197], v[40:43]
	v_mfma_f32_16x16x32_bf16 v[32:35], v[168:171], v[194:197], v[32:35]
	v_mfma_f32_16x16x32_bf16 v[24:27], v[160:163], v[202:205], v[24:27]
	v_mfma_f32_16x16x32_bf16 v[16:19], v[168:171], v[202:205], v[16:19]
	v_mfma_f32_16x16x32_bf16 v[8:11], v[160:163], v[210:213], v[8:11]
	v_mfma_f32_16x16x32_bf16 v[0:3], v[168:171], v[210:213], v[0:3]
	v_mfma_f32_16x16x32_bf16 v[56:59], v[164:167], v[190:193], v[56:59]
	v_mfma_f32_16x16x32_bf16 v[48:51], v[172:175], v[190:193], v[48:51]
	v_mfma_f32_16x16x32_bf16 v[40:43], v[164:167], v[198:201], v[40:43]
	v_mfma_f32_16x16x32_bf16 v[32:35], v[172:175], v[198:201], v[32:35]
	v_mfma_f32_16x16x32_bf16 v[24:27], v[164:167], v[206:209], v[24:27]
	v_mfma_f32_16x16x32_bf16 v[16:19], v[172:175], v[206:209], v[16:19]
	v_mfma_f32_16x16x32_bf16 v[8:11], v[164:167], v[214:217], v[8:11]
	v_mfma_f32_16x16x32_bf16 v[0:3], v[172:175], v[214:217], v[0:3]
	s_barrier
	s_add_u32 s28, s28, 0x100
	s_addc_u32 s29, s29, 0
	s_add_u32 s10, s10, 0x100
	s_addc_u32 s11, s11, 0
	s_cmp_ge_i32 s44, s49
	s_mov_b32 s30, s44
	s_cbranch_scc0 .LBB0_394

.LBB0_401:
	ds_read2_b32 v[156:157], v153 offset1:16
	s_waitcnt lgkmcnt(0)
	v_add_u32_e32 v128, 0x1000, v153
	ds_read2_b32 v[158:159], v128 offset1:16
	ds_read2_b32 v[148:149], v153 offset0:32 offset1:48
	ds_read2_b32 v[146:147], v128 offset0:32 offset1:48
	ds_read2_b32 v[144:145], v153 offset0:64 offset1:80
	ds_read2_b32 v[142:143], v128 offset0:64 offset1:80
	ds_read2_b32 v[130:131], v153 offset0:96 offset1:112
	ds_read2_b32 v[128:129], v128 offset0:96 offset1:112
	v_pk_mul_f32 v[114:115], v[114:115], v[118:119]
	v_pk_mul_f32 v[112:113], v[112:113], v[116:117]
	v_pk_mul_f32 v[160:161], v[120:121], v[156:157] op_sel_hi:[1,0]
	v_pk_mul_f32 v[162:163], v[122:123], v[156:157] op_sel_hi:[1,0]
	v_exp_f32_e32 v161, v161
	v_pk_mul_f32 v[122:123], v[126:127], v[122:123]
	v_exp_f32_e32 v126, v163
	v_pk_mul_f32 v[120:121], v[124:125], v[120:121]
	s_waitcnt lgkmcnt(0)
	v_fma_f32 v161, v161, v158, v158
	v_rcp_f32_e32 v165, v161
	v_exp_f32_e32 v161, v162
	v_fma_f32 v125, v126, v158, v158
	v_rcp_f32_e32 v125, v125
	v_pk_mul_f32 v[126:127], v[116:117], v[156:157] op_sel_hi:[1,0]
	v_fma_f32 v124, v161, v158, v158
	v_rcp_f32_e32 v124, v124
	v_exp_f32_e32 v164, v160
	v_exp_f32_e32 v126, v126
	v_exp_f32_e32 v127, v127
	v_pk_mul_f32 v[122:123], v[122:123], v[124:125]
	v_pk_mul_f32 v[124:125], v[118:119], v[156:157] op_sel_hi:[1,0]
	v_fma_f32 v164, v164, v158, v158
	v_exp_f32_e32 v124, v124
	v_exp_f32_e32 v125, v125
	v_fma_f32 v126, v126, v158, v158
	v_fma_f32 v127, v127, v158, v158
	v_fma_f32 v124, v124, v158, v158
	v_fma_f32 v125, v125, v158, v158
	v_rcp_f32_e32 v124, v124
	v_rcp_f32_e32 v125, v125
	v_rcp_f32_e32 v164, v164
	v_rcp_f32_e32 v126, v126
	v_rcp_f32_e32 v127, v127
	v_pk_mul_f32 v[118:119], v[114:115], v[124:125]
	v_or_b32_e32 v166, s10, v150
	v_lshl_or_b32 v160, s67, 8, v154
	v_pk_mul_f32 v[120:121], v[120:121], v[164:165]
	v_pk_mul_f32 v[112:113], v[112:113], v[126:127]
	v_cvt_pk_bf16_f32 v117, v118, v119
	s_movk_i32 s4, 0x1600
	v_mov_b32_e32 v118, v157
	v_cvt_pk_bf16_f32 v114, v120, v121
	v_cvt_pk_bf16_f32 v116, v112, v113
	v_mad_u64_u32 v[112:113], s[4:5], v166, s4, v[160:161]
	v_pk_mul_f32 v[120:121], v[108:109], v[118:119] op_sel_hi:[1,0]
	v_cvt_pk_bf16_f32 v115, v122, v123
	v_exp_f32_e32 v113, v120
	global_store_dwordx4 v112, v[114:117], s[18:19] nt
	v_pk_mul_f32 v[106:107], v[106:107], v[110:111]
	v_pk_mul_f32 v[104:105], v[104:105], v[108:109]
	v_exp_f32_e32 v117, v121
	v_fma_f32 v113, v113, v159, v159
	v_pk_mul_f32 v[114:115], v[110:111], v[118:119] op_sel_hi:[1,0]
	v_rcp_f32_e32 v116, v113
	v_fma_f32 v113, v117, v159, v159
	v_rcp_f32_e32 v117, v113
	v_exp_f32_e32 v113, v114
	v_exp_f32_e32 v110, v115
	v_pk_mul_f32 v[98:99], v[98:99], v[102:103]
	v_pk_mul_f32 v[96:97], v[96:97], v[100:101]
	v_fma_f32 v108, v113, v159, v159
	v_fma_f32 v109, v110, v159, v159
	v_rcp_f32_e32 v108, v108
	v_rcp_f32_e32 v109, v109
	v_pk_mul_f32 v[110:111], v[100:101], v[118:119] op_sel_hi:[1,0]
	v_pk_mul_f32 v[104:105], v[104:105], v[116:117]
	v_exp_f32_e32 v110, v110
	v_pk_mul_f32 v[106:107], v[106:107], v[108:109]
	v_pk_mul_f32 v[108:109], v[102:103], v[118:119] op_sel_hi:[1,0]
	v_exp_f32_e32 v111, v111
	v_exp_f32_e32 v108, v108
	v_exp_f32_e32 v109, v109
	v_fma_f32 v110, v110, v159, v159
	v_fma_f32 v111, v111, v159, v159
	v_fma_f32 v108, v108, v159, v159
	v_fmac_f32_e32 v159, v109, v159
	v_rcp_f32_e32 v110, v110
	v_rcp_f32_e32 v111, v111
	v_rcp_f32_e32 v108, v108
	v_rcp_f32_e32 v109, v159
	v_pk_mul_f32 v[90:91], v[90:91], v[94:95]
	v_pk_mul_f32 v[100:101], v[96:97], v[110:111]
	v_cvt_pk_bf16_f32 v96, v104, v105
	v_pk_mul_f32 v[102:103], v[98:99], v[108:109]
	v_cvt_pk_bf16_f32 v97, v106, v107
	v_cvt_pk_bf16_f32 v98, v100, v101
	v_cvt_pk_bf16_f32 v99, v102, v103
	v_add_u32_e32 v102, 0x16000, v112
	global_store_dwordx4 v102, v[96:99], s[18:19] nt
	v_pk_mul_f32 v[100:101], v[92:93], v[148:149] op_sel_hi:[1,0]
	v_pk_mul_f32 v[88:89], v[88:89], v[92:93]
	v_pk_mul_f32 v[96:97], v[94:95], v[148:149] op_sel_hi:[1,0]
	v_exp_f32_e32 v100, v100
	v_exp_f32_e32 v96, v96
	v_exp_f32_e32 v94, v97
	v_exp_f32_e32 v99, v101
	v_fma_f32 v98, v100, v146, v146
	v_fma_f32 v92, v96, v146, v146
	v_fma_f32 v93, v94, v146, v146
	v_rcp_f32_e32 v92, v92
	v_rcp_f32_e32 v93, v93
	v_pk_mul_f32 v[94:95], v[84:85], v[148:149] op_sel_hi:[1,0]
	v_fma_f32 v99, v99, v146, v146
	v_exp_f32_e32 v94, v94
	v_pk_mul_f32 v[90:91], v[90:91], v[92:93]
	v_pk_mul_f32 v[92:93], v[86:87], v[148:149] op_sel_hi:[1,0]
	v_exp_f32_e32 v95, v95
	v_exp_f32_e32 v92, v92
	v_exp_f32_e32 v93, v93
	v_fma_f32 v94, v94, v146, v146
	v_fma_f32 v95, v95, v146, v146
	v_fma_f32 v92, v92, v146, v146
	v_fma_f32 v93, v93, v146, v146
	v_rcp_f32_e32 v98, v98
	v_rcp_f32_e32 v99, v99
	v_rcp_f32_e32 v94, v94
	v_rcp_f32_e32 v95, v95
	v_rcp_f32_e32 v92, v92
	v_rcp_f32_e32 v93, v93
	v_pk_mul_f32 v[82:83], v[82:83], v[86:87]
	v_pk_mul_f32 v[80:81], v[80:81], v[84:85]
	v_pk_mul_f32 v[88:89], v[88:89], v[98:99]
	v_pk_mul_f32 v[84:85], v[80:81], v[94:95]
	v_pk_mul_f32 v[86:87], v[82:83], v[92:93]
	v_cvt_pk_bf16_f32 v80, v88, v89
	v_cvt_pk_bf16_f32 v81, v90, v91
	v_cvt_pk_bf16_f32 v82, v84, v85
	v_cvt_pk_bf16_f32 v83, v86, v87
	v_add_u32_e32 v85, 0x2c000, v112
	v_mov_b32_e32 v84, v149
	global_store_dwordx4 v85, v[80:83], s[18:19] nt
	v_pk_mul_f32 v[74:75], v[74:75], v[78:79]
	v_pk_mul_f32 v[86:87], v[76:77], v[84:85] op_sel_hi:[1,0]
	v_pk_mul_f32 v[80:81], v[78:79], v[84:85] op_sel_hi:[1,0]
	v_pk_mul_f32 v[72:73], v[72:73], v[76:77]
	v_exp_f32_e32 v80, v80
	v_exp_f32_e32 v78, v81
	v_exp_f32_e32 v86, v86
	v_exp_f32_e32 v83, v87
	v_fma_f32 v76, v80, v147, v147
	v_fma_f32 v77, v78, v147, v147
	v_rcp_f32_e32 v76, v76
	v_rcp_f32_e32 v77, v77
	v_pk_mul_f32 v[78:79], v[68:69], v[84:85] op_sel_hi:[1,0]
	v_fma_f32 v82, v86, v147, v147
	v_exp_f32_e32 v78, v78
	v_pk_mul_f32 v[74:75], v[74:75], v[76:77]
	v_pk_mul_f32 v[76:77], v[70:71], v[84:85] op_sel_hi:[1,0]
	v_exp_f32_e32 v79, v79
	v_exp_f32_e32 v76, v76
	v_exp_f32_e32 v77, v77
	v_fma_f32 v83, v83, v147, v147
	v_fma_f32 v78, v78, v147, v147
	v_fma_f32 v79, v79, v147, v147
	v_fma_f32 v76, v76, v147, v147
	v_fmac_f32_e32 v147, v77, v147
	v_rcp_f32_e32 v82, v82
	v_rcp_f32_e32 v83, v83
	v_rcp_f32_e32 v78, v78
	v_rcp_f32_e32 v79, v79
	v_rcp_f32_e32 v76, v76
	v_rcp_f32_e32 v77, v147
	v_pk_mul_f32 v[66:67], v[66:67], v[70:71]
	v_pk_mul_f32 v[64:65], v[64:65], v[68:69]
	v_pk_mul_f32 v[72:73], v[72:73], v[82:83]
	v_pk_mul_f32 v[68:69], v[64:65], v[78:79]
	v_pk_mul_f32 v[70:71], v[66:67], v[76:77]
	v_cvt_pk_bf16_f32 v64, v72, v73
	v_cvt_pk_bf16_f32 v65, v74, v75
	v_cvt_pk_bf16_f32 v66, v68, v69
	v_cvt_pk_bf16_f32 v67, v70, v71
	v_add_u32_e32 v70, 0x42000, v112
	global_store_dwordx4 v70, v[64:67], s[18:19] nt
	v_pk_mul_f32 v[58:59], v[58:59], v[62:63]
	v_pk_mul_f32 v[68:69], v[60:61], v[144:145] op_sel_hi:[1,0]
	v_pk_mul_f32 v[64:65], v[62:63], v[144:145] op_sel_hi:[1,0]
	v_pk_mul_f32 v[56:57], v[56:57], v[60:61]
	v_exp_f32_e32 v64, v64
	v_exp_f32_e32 v62, v65
	v_exp_f32_e32 v68, v68
	v_exp_f32_e32 v67, v69
	v_fma_f32 v60, v64, v142, v142
	v_fma_f32 v61, v62, v142, v142
	v_rcp_f32_e32 v60, v60
	v_rcp_f32_e32 v61, v61
	v_pk_mul_f32 v[62:63], v[52:53], v[144:145] op_sel_hi:[1,0]
	v_fma_f32 v66, v68, v142, v142
	v_exp_f32_e32 v62, v62
	v_pk_mul_f32 v[58:59], v[58:59], v[60:61]
	v_pk_mul_f32 v[60:61], v[54:55], v[144:145] op_sel_hi:[1,0]
	v_exp_f32_e32 v63, v63
	v_exp_f32_e32 v60, v60
	v_exp_f32_e32 v61, v61
	v_fma_f32 v67, v67, v142, v142
	v_fma_f32 v62, v62, v142, v142
	v_fma_f32 v63, v63, v142, v142
	v_fma_f32 v60, v60, v142, v142
	v_fma_f32 v61, v61, v142, v142
	v_rcp_f32_e32 v66, v66
	v_rcp_f32_e32 v67, v67
	v_rcp_f32_e32 v62, v62
	v_rcp_f32_e32 v63, v63
	v_rcp_f32_e32 v60, v60
	v_rcp_f32_e32 v61, v61
	v_pk_mul_f32 v[50:51], v[50:51], v[54:55]
	v_pk_mul_f32 v[48:49], v[48:49], v[52:53]
	v_pk_mul_f32 v[56:57], v[56:57], v[66:67]
	v_pk_mul_f32 v[52:53], v[48:49], v[62:63]
	v_pk_mul_f32 v[54:55], v[50:51], v[60:61]
	v_cvt_pk_bf16_f32 v48, v56, v57
	v_cvt_pk_bf16_f32 v49, v58, v59
	v_cvt_pk_bf16_f32 v50, v52, v53
	v_cvt_pk_bf16_f32 v51, v54, v55
	v_add_u32_e32 v53, 0xb0000, v112
	v_mov_b32_e32 v52, v145
	global_store_dwordx4 v53, v[48:51], s[18:19] nt
	v_pk_mul_f32 v[42:43], v[42:43], v[46:47]
	v_pk_mul_f32 v[54:55], v[44:45], v[52:53] op_sel_hi:[1,0]
	v_pk_mul_f32 v[48:49], v[46:47], v[52:53] op_sel_hi:[1,0]
	v_pk_mul_f32 v[40:41], v[40:41], v[44:45]
	v_exp_f32_e32 v48, v48
	v_exp_f32_e32 v46, v49
	v_exp_f32_e32 v54, v54
	v_exp_f32_e32 v51, v55
	v_fma_f32 v44, v48, v143, v143
	v_fma_f32 v45, v46, v143, v143
	v_rcp_f32_e32 v44, v44
	v_rcp_f32_e32 v45, v45
	v_pk_mul_f32 v[46:47], v[36:37], v[52:53] op_sel_hi:[1,0]
	v_fma_f32 v50, v54, v143, v143
	v_exp_f32_e32 v46, v46
	v_pk_mul_f32 v[42:43], v[42:43], v[44:45]
	v_pk_mul_f32 v[44:45], v[38:39], v[52:53] op_sel_hi:[1,0]
	v_exp_f32_e32 v47, v47
	v_exp_f32_e32 v44, v44
	v_exp_f32_e32 v45, v45
	v_fma_f32 v51, v51, v143, v143
	v_fma_f32 v46, v46, v143, v143
	v_fma_f32 v47, v47, v143, v143
	v_fma_f32 v44, v44, v143, v143
	v_fmac_f32_e32 v143, v45, v143
	v_rcp_f32_e32 v50, v50
	v_rcp_f32_e32 v51, v51
	v_rcp_f32_e32 v46, v46
	v_rcp_f32_e32 v47, v47
	v_rcp_f32_e32 v44, v44
	v_rcp_f32_e32 v45, v143
	v_pk_mul_f32 v[34:35], v[34:35], v[38:39]
	v_pk_mul_f32 v[32:33], v[32:33], v[36:37]
	v_pk_mul_f32 v[40:41], v[40:41], v[50:51]
	v_pk_mul_f32 v[36:37], v[32:33], v[46:47]
	v_pk_mul_f32 v[38:39], v[34:35], v[44:45]
	v_cvt_pk_bf16_f32 v32, v40, v41
	v_cvt_pk_bf16_f32 v33, v42, v43
	v_cvt_pk_bf16_f32 v34, v36, v37
	v_cvt_pk_bf16_f32 v35, v38, v39
	v_add_u32_e32 v38, 0xc6000, v112
	global_store_dwordx4 v38, v[32:35], s[18:19] nt
	v_pk_mul_f32 v[26:27], v[26:27], v[30:31]
	v_pk_mul_f32 v[36:37], v[28:29], v[130:131] op_sel_hi:[1,0]
	v_pk_mul_f32 v[32:33], v[30:31], v[130:131] op_sel_hi:[1,0]
	v_pk_mul_f32 v[24:25], v[24:25], v[28:29]
	v_exp_f32_e32 v32, v32
	v_exp_f32_e32 v30, v33
	v_exp_f32_e32 v36, v36
	v_exp_f32_e32 v35, v37
	v_fma_f32 v28, v32, v128, v128
	v_fma_f32 v29, v30, v128, v128
	v_rcp_f32_e32 v28, v28
	v_rcp_f32_e32 v29, v29
	v_pk_mul_f32 v[30:31], v[20:21], v[130:131] op_sel_hi:[1,0]
	v_fma_f32 v34, v36, v128, v128
	v_exp_f32_e32 v30, v30
	v_pk_mul_f32 v[26:27], v[26:27], v[28:29]
	v_pk_mul_f32 v[28:29], v[22:23], v[130:131] op_sel_hi:[1,0]
	v_exp_f32_e32 v31, v31
	v_exp_f32_e32 v28, v28
	v_exp_f32_e32 v29, v29
	v_fma_f32 v35, v35, v128, v128
	v_fma_f32 v30, v30, v128, v128
	v_fma_f32 v31, v31, v128, v128
	v_fma_f32 v28, v28, v128, v128
	v_fma_f32 v29, v29, v128, v128
	v_rcp_f32_e32 v34, v34
	v_rcp_f32_e32 v35, v35
	v_rcp_f32_e32 v30, v30
	v_rcp_f32_e32 v31, v31
	v_rcp_f32_e32 v28, v28
	v_rcp_f32_e32 v29, v29
	v_pk_mul_f32 v[18:19], v[18:19], v[22:23]
	v_pk_mul_f32 v[16:17], v[16:17], v[20:21]
	v_pk_mul_f32 v[24:25], v[24:25], v[34:35]
	v_pk_mul_f32 v[20:21], v[16:17], v[30:31]
	v_pk_mul_f32 v[22:23], v[18:19], v[28:29]
	v_cvt_pk_bf16_f32 v16, v24, v25
	v_cvt_pk_bf16_f32 v17, v26, v27
	v_cvt_pk_bf16_f32 v18, v20, v21
	v_cvt_pk_bf16_f32 v19, v22, v23
	v_add_u32_e32 v21, 0xdc000, v112
	v_mov_b32_e32 v20, v131
	global_store_dwordx4 v21, v[16:19], s[18:19] nt
	v_pk_mul_f32 v[10:11], v[10:11], v[14:15]
	v_pk_mul_f32 v[22:23], v[12:13], v[20:21] op_sel_hi:[1,0]
	v_pk_mul_f32 v[16:17], v[14:15], v[20:21] op_sel_hi:[1,0]
	v_pk_mul_f32 v[8:9], v[8:9], v[12:13]
	v_exp_f32_e32 v16, v16
	v_exp_f32_e32 v14, v17
	v_exp_f32_e32 v22, v22
	v_exp_f32_e32 v19, v23
	v_fma_f32 v12, v16, v129, v129
	v_fma_f32 v13, v14, v129, v129
	v_rcp_f32_e32 v12, v12
	v_rcp_f32_e32 v13, v13
	v_pk_mul_f32 v[14:15], v[4:5], v[20:21] op_sel_hi:[1,0]
	v_fma_f32 v18, v22, v129, v129
	v_exp_f32_e32 v14, v14
	v_pk_mul_f32 v[10:11], v[10:11], v[12:13]
	v_pk_mul_f32 v[12:13], v[6:7], v[20:21] op_sel_hi:[1,0]
	v_exp_f32_e32 v15, v15
	v_exp_f32_e32 v12, v12
	v_exp_f32_e32 v13, v13
	v_fma_f32 v19, v19, v129, v129
	v_fma_f32 v14, v14, v129, v129
	v_fma_f32 v15, v15, v129, v129
	v_fma_f32 v12, v12, v129, v129
	v_fmac_f32_e32 v129, v13, v129
	v_rcp_f32_e32 v18, v18
	v_rcp_f32_e32 v19, v19
	v_rcp_f32_e32 v14, v14
	v_rcp_f32_e32 v15, v15
	v_rcp_f32_e32 v12, v12
	v_rcp_f32_e32 v13, v129
	v_pk_mul_f32 v[2:3], v[2:3], v[6:7]
	v_pk_mul_f32 v[0:1], v[0:1], v[4:5]
	v_pk_mul_f32 v[8:9], v[8:9], v[18:19]
	v_pk_mul_f32 v[4:5], v[0:1], v[14:15]
	v_pk_mul_f32 v[6:7], v[2:3], v[12:13]
	v_cvt_pk_bf16_f32 v0, v8, v9
	v_cvt_pk_bf16_f32 v1, v10, v11
	v_cvt_pk_bf16_f32 v2, v4, v5
	v_cvt_pk_bf16_f32 v3, v6, v7
	v_add_u32_e32 v4, 0xf2000, v112
	s_and_b64 vcc, exec, s[42:43]
	s_mov_b64 s[10:11], -1
	global_store_dwordx4 v4, v[0:3], s[18:19] nt
	s_cbranch_vccnz .LBB0_385
	s_andn2_b64 vcc, exec, s[12:13]
	s_cbranch_vccnz .LBB0_384
	s_mov_b32 s100, 1
	s_branch .LBB0_384

.LBB0_473:
	v_mov_b32_e32 v123, 0
	s_andn2_b64 vcc, exec, s[20:21]
	v_mov_b32_e32 v122, v123
	v_mov_b32_e32 v121, v123
	v_mov_b32_e32 v120, v123
	v_mov_b32_e32 v127, v123
	v_mov_b32_e32 v126, v123
	v_mov_b32_e32 v125, v123
	v_mov_b32_e32 v124, v123
	v_mov_b32_e32 v111, v123
	v_mov_b32_e32 v110, v123
	v_mov_b32_e32 v109, v123
	v_mov_b32_e32 v108, v123
	v_mov_b32_e32 v107, v123
	v_mov_b32_e32 v106, v123
	v_mov_b32_e32 v105, v123
	v_mov_b32_e32 v104, v123
	v_mov_b32_e32 v95, v123
	v_mov_b32_e32 v94, v123
	v_mov_b32_e32 v93, v123
	v_mov_b32_e32 v92, v123
	v_mov_b32_e32 v91, v123
	v_mov_b32_e32 v90, v123
	v_mov_b32_e32 v89, v123
	v_mov_b32_e32 v88, v123
	v_mov_b32_e32 v79, v123
	v_mov_b32_e32 v78, v123
	v_mov_b32_e32 v77, v123
	v_mov_b32_e32 v76, v123
	v_mov_b32_e32 v75, v123
	v_mov_b32_e32 v74, v123
	v_mov_b32_e32 v73, v123
	v_mov_b32_e32 v72, v123
	v_mov_b32_e32 v119, v123
	v_mov_b32_e32 v118, v123
	v_mov_b32_e32 v117, v123
	v_mov_b32_e32 v116, v123
	v_mov_b32_e32 v115, v123
	v_mov_b32_e32 v114, v123
	v_mov_b32_e32 v113, v123
	v_mov_b32_e32 v112, v123
	v_mov_b32_e32 v103, v123
	v_mov_b32_e32 v102, v123
	v_mov_b32_e32 v101, v123
	v_mov_b32_e32 v100, v123
	v_mov_b32_e32 v99, v123
	v_mov_b32_e32 v98, v123
	v_mov_b32_e32 v97, v123
	v_mov_b32_e32 v96, v123
	v_mov_b32_e32 v87, v123
	v_mov_b32_e32 v86, v123
	v_mov_b32_e32 v85, v123
	v_mov_b32_e32 v84, v123
	v_mov_b32_e32 v83, v123
	v_mov_b32_e32 v82, v123
	v_mov_b32_e32 v81, v123
	v_mov_b32_e32 v80, v123
	v_mov_b32_e32 v71, v123
	v_mov_b32_e32 v70, v123
	v_mov_b32_e32 v69, v123
	v_mov_b32_e32 v68, v123
	v_mov_b32_e32 v67, v123
	v_mov_b32_e32 v66, v123
	v_mov_b32_e32 v65, v123
	v_mov_b32_e32 v64, v123
	v_mov_b32_e32 v63, v123
	v_mov_b32_e32 v62, v123
	v_mov_b32_e32 v61, v123
	v_mov_b32_e32 v60, v123
	v_mov_b32_e32 v59, v123
	v_mov_b32_e32 v58, v123
	v_mov_b32_e32 v57, v123
	v_mov_b32_e32 v56, v123
	v_mov_b32_e32 v47, v123
	v_mov_b32_e32 v46, v123
	v_mov_b32_e32 v45, v123
	v_mov_b32_e32 v44, v123
	v_mov_b32_e32 v43, v123
	v_mov_b32_e32 v42, v123
	v_mov_b32_e32 v41, v123
	v_mov_b32_e32 v40, v123
	v_mov_b32_e32 v31, v123
	v_mov_b32_e32 v30, v123
	v_mov_b32_e32 v29, v123
	v_mov_b32_e32 v28, v123
	v_mov_b32_e32 v27, v123
	v_mov_b32_e32 v26, v123
	v_mov_b32_e32 v25, v123
	v_mov_b32_e32 v24, v123
	v_mov_b32_e32 v15, v123
	v_mov_b32_e32 v14, v123
	v_mov_b32_e32 v13, v123
	v_mov_b32_e32 v12, v123
	v_mov_b32_e32 v11, v123
	v_mov_b32_e32 v10, v123
	v_mov_b32_e32 v9, v123
	v_mov_b32_e32 v8, v123
	v_mov_b32_e32 v55, v123
	v_mov_b32_e32 v54, v123
	v_mov_b32_e32 v53, v123
	v_mov_b32_e32 v52, v123
	v_mov_b32_e32 v51, v123
	v_mov_b32_e32 v50, v123
	v_mov_b32_e32 v49, v123
	v_mov_b32_e32 v48, v123
	v_mov_b32_e32 v39, v123
	v_mov_b32_e32 v38, v123
	v_mov_b32_e32 v37, v123
	v_mov_b32_e32 v36, v123
	v_mov_b32_e32 v35, v123
	v_mov_b32_e32 v34, v123
	v_mov_b32_e32 v33, v123
	v_mov_b32_e32 v32, v123
	v_mov_b32_e32 v23, v123
	v_mov_b32_e32 v22, v123
	v_mov_b32_e32 v21, v123
	v_mov_b32_e32 v20, v123
	v_mov_b32_e32 v19, v123
	v_mov_b32_e32 v18, v123
	v_mov_b32_e32 v17, v123
	v_mov_b32_e32 v16, v123
	v_mov_b32_e32 v7, v123
	v_mov_b32_e32 v6, v123
	v_mov_b32_e32 v5, v123
	v_mov_b32_e32 v4, v123
	v_mov_b32_e32 v3, v123
	v_mov_b32_e32 v2, v123
	s_waitcnt lgkmcnt(0)
	v_mov_b32_e32 v1, v123
	v_mov_b32_e32 v0, v123
	s_cbranch_vccnz .LBB0_476
	s_add_u32 s28, s28, 0x80
	s_addc_u32 s29, s29, 0
	s_add_u32 s10, s30, 0x100
	s_addc_u32 s11, s31, 0
	s_mov_b32 s30, 0
	s_cmp_lg_u32 s100, 0
	s_cbranch_scc0 .Llbb_4
	s_barrier
	s_mov_b32 s100, 0
.Llbb_4:
.LBB0_475:
	s_add_i32 s44, s30, 2
	s_add_u32 s4, s28, 0x80
	s_addc_u32 s5, s29, 0
	s_add_i32 s45, 0, 0x10000
	s_cmp_eq_u32 s61, s30
	s_cselect_b32 s31, s25, s5
	s_cselect_b32 s30, s24, s4
	s_cselect_b32 s5, s27, s11
	s_cselect_b32 s4, s26, s10
	s_add_i32 s54, 0, 0x14000
	v_add_u32_e32 v140, s45, v195
	v_add_u32_e32 v166, s54, v195
	ds_read_b128 v[128:131], v140
	ds_read_b128 v[132:135], v140 offset:1024
	ds_read_b128 v[136:139], v140 offset:2048
	ds_read_b128 v[140:143], v140 offset:3072
	ds_read_b128 v[144:147], v166
	ds_read_b128 v[148:151], v166 offset:1024
	ds_read_b128 v[152:155], v166 offset:2048
	ds_read_b128 v[166:169], v166 offset:3072
	v_lshl_add_u64 v[174:175], s[28:29], 0, v[162:163]
	s_add_i32 m0, s38, 0xc000
	ds_read_b128 v[170:173], v197
	ds_read_b128 v[186:189], v197 offset:1024
	ds_read_b128 v[190:193], v197 offset:2048
	ds_read_b128 v[198:201], v197 offset:3072
	ds_read_b128 v[202:205], v197 offset:4096
	ds_read_b128 v[206:209], v197 offset:5120
	ds_read_b128 v[210:213], v197 offset:6144
	ds_read_b128 v[214:217], v197 offset:7168
	global_load_lds_dwordx4 v[174:175], off
	v_lshl_add_u64 v[174:175], s[28:29], 0, v[164:165]
	s_add_i32 m0, s38, 0xe000
	s_nop 0
	global_load_lds_dwordx4 v[174:175], off
	s_waitcnt vmcnt(8)
	s_waitcnt lgkmcnt(0)
	s_barrier
	s_waitcnt lgkmcnt(0)
	v_mfma_f32_16x16x32_bf16 v[120:123], v[128:131], v[170:173], v[120:123]
	v_mfma_f32_16x16x32_bf16 v[124:127], v[136:139], v[170:173], v[124:127]
	v_mfma_f32_16x16x32_bf16 v[108:111], v[128:131], v[190:193], v[108:111]
	v_mfma_f32_16x16x32_bf16 v[104:107], v[136:139], v[190:193], v[104:107]
	v_mfma_f32_16x16x32_bf16 v[92:95], v[128:131], v[202:205], v[92:95]
	v_mfma_f32_16x16x32_bf16 v[88:91], v[136:139], v[202:205], v[88:91]
	v_mfma_f32_16x16x32_bf16 v[76:79], v[128:131], v[210:213], v[76:79]
	v_mfma_f32_16x16x32_bf16 v[72:75], v[136:139], v[210:213], v[72:75]
	v_mfma_f32_16x16x32_bf16 v[120:123], v[132:135], v[186:189], v[120:123]
	v_mfma_f32_16x16x32_bf16 v[124:127], v[140:143], v[186:189], v[124:127]
	v_mfma_f32_16x16x32_bf16 v[108:111], v[132:135], v[198:201], v[108:111]
	v_mfma_f32_16x16x32_bf16 v[104:107], v[140:143], v[198:201], v[104:107]
	v_mfma_f32_16x16x32_bf16 v[92:95], v[132:135], v[206:209], v[92:95]
	v_mfma_f32_16x16x32_bf16 v[88:91], v[140:143], v[206:209], v[88:91]
	v_mfma_f32_16x16x32_bf16 v[76:79], v[132:135], v[214:217], v[76:79]
	v_mfma_f32_16x16x32_bf16 v[72:75], v[140:143], v[214:217], v[72:75]
	v_mfma_f32_16x16x32_bf16 v[116:119], v[144:147], v[170:173], v[116:119]
	v_mfma_f32_16x16x32_bf16 v[112:115], v[152:155], v[170:173], v[112:115]
	v_mfma_f32_16x16x32_bf16 v[100:103], v[144:147], v[190:193], v[100:103]
	v_mfma_f32_16x16x32_bf16 v[96:99], v[152:155], v[190:193], v[96:99]
	v_mfma_f32_16x16x32_bf16 v[84:87], v[144:147], v[202:205], v[84:87]
	v_mfma_f32_16x16x32_bf16 v[80:83], v[152:155], v[202:205], v[80:83]
	v_mfma_f32_16x16x32_bf16 v[68:71], v[144:147], v[210:213], v[68:71]
	v_mfma_f32_16x16x32_bf16 v[64:67], v[152:155], v[210:213], v[64:67]
	v_mfma_f32_16x16x32_bf16 v[116:119], v[148:151], v[186:189], v[116:119]
	v_mfma_f32_16x16x32_bf16 v[112:115], v[166:169], v[186:189], v[112:115]
	v_mfma_f32_16x16x32_bf16 v[100:103], v[148:151], v[198:201], v[100:103]
	v_mfma_f32_16x16x32_bf16 v[96:99], v[166:169], v[198:201], v[96:99]
	v_mfma_f32_16x16x32_bf16 v[84:87], v[148:151], v[206:209], v[84:87]
	v_mfma_f32_16x16x32_bf16 v[80:83], v[166:169], v[206:209], v[80:83]
	v_mfma_f32_16x16x32_bf16 v[68:71], v[148:151], v[214:217], v[68:71]
	v_mfma_f32_16x16x32_bf16 v[64:67], v[166:169], v[214:217], v[64:67]
	s_barrier
	s_add_i32 s45, s45, s37
	v_lshl_add_u64 v[174:175], s[4:5], 0, v[176:177]
	s_mov_b32 m0, s45
	ds_read_b128 v[170:173], v197 offset:16384
	ds_read_b128 v[186:189], v197 offset:17408
	ds_read_b128 v[190:193], v197 offset:18432
	ds_read_b128 v[198:201], v197 offset:19456
	ds_read_b128 v[202:205], v197 offset:20480
	ds_read_b128 v[206:209], v197 offset:21504
	ds_read_b128 v[210:213], v197 offset:22528
	ds_read_b128 v[214:217], v197 offset:23552
	global_load_lds_dwordx4 v[174:175], off
	s_add_i32 m0, s45, 0x2000
	v_lshl_add_u64 v[222:223], s[4:5], 0, v[156:157]
	s_add_u32 s4, s4, s6
	s_addc_u32 s5, s5, s7
	s_add_i32 s45, s54, s37
	global_load_lds_dwordx4 v[222:223], off
	v_lshl_add_u64 v[224:225], s[4:5], 0, v[176:177]
	s_mov_b32 m0, s45
	v_lshl_add_u64 v[226:227], s[4:5], 0, v[156:157]
	global_load_lds_dwordx4 v[224:225], off
	s_add_i32 m0, s45, 0x2000
	v_lshl_add_u64 v[228:229], s[30:31], 0, v[160:161]
	global_load_lds_dwordx4 v[226:227], off
	s_mov_b32 m0, s38
	v_lshl_add_u64 v[230:231], s[30:31], 0, v[158:159]
	global_load_lds_dwordx4 v[228:229], off
	s_mov_b32 m0, s39
	s_nop 0
	global_load_lds_dwordx4 v[230:231], off
	s_waitcnt vmcnt(8)
	s_waitcnt lgkmcnt(0)
	s_barrier
	s_waitcnt lgkmcnt(0)
	v_mfma_f32_16x16x32_bf16 v[60:63], v[128:131], v[170:173], v[60:63]
	v_mfma_f32_16x16x32_bf16 v[56:59], v[136:139], v[170:173], v[56:59]
	v_mfma_f32_16x16x32_bf16 v[44:47], v[128:131], v[190:193], v[44:47]
	v_mfma_f32_16x16x32_bf16 v[40:43], v[136:139], v[190:193], v[40:43]
	v_mfma_f32_16x16x32_bf16 v[28:31], v[128:131], v[202:205], v[28:31]
	v_mfma_f32_16x16x32_bf16 v[24:27], v[136:139], v[202:205], v[24:27]
	v_mfma_f32_16x16x32_bf16 v[12:15], v[128:131], v[210:213], v[12:15]
	v_mfma_f32_16x16x32_bf16 v[8:11], v[136:139], v[210:213], v[8:11]
	v_mfma_f32_16x16x32_bf16 v[60:63], v[132:135], v[186:189], v[60:63]
	v_mfma_f32_16x16x32_bf16 v[56:59], v[140:143], v[186:189], v[56:59]
	v_mfma_f32_16x16x32_bf16 v[44:47], v[132:135], v[198:201], v[44:47]
	v_mfma_f32_16x16x32_bf16 v[40:43], v[140:143], v[198:201], v[40:43]
	v_mfma_f32_16x16x32_bf16 v[28:31], v[132:135], v[206:209], v[28:31]
	v_mfma_f32_16x16x32_bf16 v[24:27], v[140:143], v[206:209], v[24:27]
	v_mfma_f32_16x16x32_bf16 v[12:15], v[132:135], v[214:217], v[12:15]
	v_mfma_f32_16x16x32_bf16 v[8:11], v[140:143], v[214:217], v[8:11]
	v_mfma_f32_16x16x32_bf16 v[52:55], v[144:147], v[170:173], v[52:55]
	v_mfma_f32_16x16x32_bf16 v[48:51], v[152:155], v[170:173], v[48:51]
	v_mfma_f32_16x16x32_bf16 v[36:39], v[144:147], v[190:193], v[36:39]
	v_mfma_f32_16x16x32_bf16 v[32:35], v[152:155], v[190:193], v[32:35]
	v_mfma_f32_16x16x32_bf16 v[20:23], v[144:147], v[202:205], v[20:23]
	v_mfma_f32_16x16x32_bf16 v[16:19], v[152:155], v[202:205], v[16:19]
	v_mfma_f32_16x16x32_bf16 v[4:7], v[144:147], v[210:213], v[4:7]
	v_mfma_f32_16x16x32_bf16 v[0:3], v[152:155], v[210:213], v[0:3]
	v_mfma_f32_16x16x32_bf16 v[52:55], v[148:151], v[186:189], v[52:55]
	v_mfma_f32_16x16x32_bf16 v[48:51], v[166:169], v[186:189], v[48:51]
	v_mfma_f32_16x16x32_bf16 v[36:39], v[148:151], v[198:201], v[36:39]
	v_mfma_f32_16x16x32_bf16 v[32:35], v[166:169], v[198:201], v[32:35]
	v_mfma_f32_16x16x32_bf16 v[20:23], v[148:151], v[206:209], v[20:23]
	v_mfma_f32_16x16x32_bf16 v[16:19], v[166:169], v[206:209], v[16:19]
	v_mfma_f32_16x16x32_bf16 v[4:7], v[148:151], v[214:217], v[4:7]
	v_mfma_f32_16x16x32_bf16 v[0:3], v[166:169], v[214:217], v[0:3]
	s_barrier
	s_add_i32 s45, 0, 0x18000
	s_add_i32 s54, 0, 0x1c000
	v_add_u32_e32 v140, s45, v195
	v_add_u32_e32 v166, s54, v195
	ds_read_b128 v[128:131], v140
	ds_read_b128 v[132:135], v140 offset:1024
	ds_read_b128 v[136:139], v140 offset:2048
	ds_read_b128 v[140:143], v140 offset:3072
	ds_read_b128 v[144:147], v166
	ds_read_b128 v[148:151], v166 offset:1024
	ds_read_b128 v[152:155], v166 offset:2048
	ds_read_b128 v[166:169], v166 offset:3072
	s_add_u32 s4, s30, s6
	s_addc_u32 s5, s31, s7
	s_mov_b32 m0, s48
	v_lshl_add_u64 v[232:233], s[4:5], 0, v[160:161]
	ds_read_b128 v[170:173], v197 offset:32768
	ds_read_b128 v[186:189], v197 offset:33792
	ds_read_b128 v[190:193], v197 offset:34816
	ds_read_b128 v[198:201], v197 offset:35840
	ds_read_b128 v[202:205], v197 offset:36864
	ds_read_b128 v[206:209], v197 offset:37888
	ds_read_b128 v[210:213], v197 offset:38912
	ds_read_b128 v[214:217], v197 offset:39936
	global_load_lds_dwordx4 v[232:233], off
	v_lshl_add_u64 v[232:233], s[4:5], 0, v[158:159]
	s_mov_b32 m0, s49
	s_nop 0
	global_load_lds_dwordx4 v[232:233], off
	s_waitcnt vmcnt(8)
	s_waitcnt lgkmcnt(0)
	s_barrier
	s_waitcnt lgkmcnt(0)
	v_mfma_f32_16x16x32_bf16 v[120:123], v[128:131], v[170:173], v[120:123]
	v_mfma_f32_16x16x32_bf16 v[124:127], v[136:139], v[170:173], v[124:127]
	v_mfma_f32_16x16x32_bf16 v[108:111], v[128:131], v[190:193], v[108:111]
	v_mfma_f32_16x16x32_bf16 v[104:107], v[136:139], v[190:193], v[104:107]
	v_mfma_f32_16x16x32_bf16 v[92:95], v[128:131], v[202:205], v[92:95]
	v_mfma_f32_16x16x32_bf16 v[88:91], v[136:139], v[202:205], v[88:91]
	v_mfma_f32_16x16x32_bf16 v[76:79], v[128:131], v[210:213], v[76:79]
	v_mfma_f32_16x16x32_bf16 v[72:75], v[136:139], v[210:213], v[72:75]
	v_mfma_f32_16x16x32_bf16 v[120:123], v[132:135], v[186:189], v[120:123]
	v_mfma_f32_16x16x32_bf16 v[124:127], v[140:143], v[186:189], v[124:127]
	v_mfma_f32_16x16x32_bf16 v[108:111], v[132:135], v[198:201], v[108:111]
	v_mfma_f32_16x16x32_bf16 v[104:107], v[140:143], v[198:201], v[104:107]
	v_mfma_f32_16x16x32_bf16 v[92:95], v[132:135], v[206:209], v[92:95]
	v_mfma_f32_16x16x32_bf16 v[88:91], v[140:143], v[206:209], v[88:91]
	v_mfma_f32_16x16x32_bf16 v[76:79], v[132:135], v[214:217], v[76:79]
	v_mfma_f32_16x16x32_bf16 v[72:75], v[140:143], v[214:217], v[72:75]
	v_mfma_f32_16x16x32_bf16 v[116:119], v[144:147], v[170:173], v[116:119]
	v_mfma_f32_16x16x32_bf16 v[112:115], v[152:155], v[170:173], v[112:115]
	v_mfma_f32_16x16x32_bf16 v[100:103], v[144:147], v[190:193], v[100:103]
	v_mfma_f32_16x16x32_bf16 v[96:99], v[152:155], v[190:193], v[96:99]
	v_mfma_f32_16x16x32_bf16 v[84:87], v[144:147], v[202:205], v[84:87]
	v_mfma_f32_16x16x32_bf16 v[80:83], v[152:155], v[202:205], v[80:83]
	v_mfma_f32_16x16x32_bf16 v[68:71], v[144:147], v[210:213], v[68:71]
	v_mfma_f32_16x16x32_bf16 v[64:67], v[152:155], v[210:213], v[64:67]
	v_mfma_f32_16x16x32_bf16 v[116:119], v[148:151], v[186:189], v[116:119]
	v_mfma_f32_16x16x32_bf16 v[112:115], v[166:169], v[186:189], v[112:115]
	v_mfma_f32_16x16x32_bf16 v[100:103], v[148:151], v[198:201], v[100:103]
	v_mfma_f32_16x16x32_bf16 v[96:99], v[166:169], v[198:201], v[96:99]
	v_mfma_f32_16x16x32_bf16 v[84:87], v[148:151], v[206:209], v[84:87]
	v_mfma_f32_16x16x32_bf16 v[80:83], v[166:169], v[206:209], v[80:83]
	v_mfma_f32_16x16x32_bf16 v[68:71], v[148:151], v[214:217], v[68:71]
	v_mfma_f32_16x16x32_bf16 v[64:67], v[166:169], v[214:217], v[64:67]
	s_barrier
	s_add_i32 s4, s45, s37
	v_lshl_add_u64 v[174:175], v[174:175], 0, s[14:15]
	s_mov_b32 m0, s4
	ds_read_b128 v[170:173], v197 offset:49152
	ds_read_b128 v[186:189], v197 offset:50176
	ds_read_b128 v[190:193], v197 offset:51200
	ds_read_b128 v[198:201], v197 offset:52224
	ds_read_b128 v[202:205], v197 offset:53248
	ds_read_b128 v[206:209], v197 offset:54272
	ds_read_b128 v[210:213], v197 offset:55296
	ds_read_b128 v[214:217], v197 offset:56320
	global_load_lds_dwordx4 v[174:175], off
	v_lshl_add_u64 v[174:175], v[222:223], 0, s[14:15]
	s_add_i32 m0, s4, 0x2000
	s_add_i32 s4, s54, s37
	global_load_lds_dwordx4 v[174:175], off
	v_lshl_add_u64 v[174:175], v[224:225], 0, s[14:15]
	s_mov_b32 m0, s4
	s_nop 0
	global_load_lds_dwordx4 v[174:175], off
	v_lshl_add_u64 v[174:175], v[226:227], 0, s[14:15]
	s_add_i32 m0, s4, 0x2000
	s_nop 0
	global_load_lds_dwordx4 v[174:175], off
	v_lshl_add_u64 v[174:175], v[228:229], 0, s[14:15]
	s_mov_b32 m0, s59
	s_nop 0
	global_load_lds_dwordx4 v[174:175], off
	v_lshl_add_u64 v[174:175], v[230:231], 0, s[14:15]
	s_mov_b32 m0, s60
	s_nop 0
	global_load_lds_dwordx4 v[174:175], off
	s_waitcnt vmcnt(8)
	s_waitcnt lgkmcnt(0)
	s_barrier
	s_waitcnt lgkmcnt(0)
	v_mfma_f32_16x16x32_bf16 v[60:63], v[128:131], v[170:173], v[60:63]
	v_mfma_f32_16x16x32_bf16 v[56:59], v[136:139], v[170:173], v[56:59]
	v_mfma_f32_16x16x32_bf16 v[44:47], v[128:131], v[190:193], v[44:47]
	v_mfma_f32_16x16x32_bf16 v[40:43], v[136:139], v[190:193], v[40:43]
	v_mfma_f32_16x16x32_bf16 v[28:31], v[128:131], v[202:205], v[28:31]
	v_mfma_f32_16x16x32_bf16 v[24:27], v[136:139], v[202:205], v[24:27]
	v_mfma_f32_16x16x32_bf16 v[12:15], v[128:131], v[210:213], v[12:15]
	v_mfma_f32_16x16x32_bf16 v[8:11], v[136:139], v[210:213], v[8:11]
	v_mfma_f32_16x16x32_bf16 v[60:63], v[132:135], v[186:189], v[60:63]
	v_mfma_f32_16x16x32_bf16 v[56:59], v[140:143], v[186:189], v[56:59]
	v_mfma_f32_16x16x32_bf16 v[44:47], v[132:135], v[198:201], v[44:47]
	v_mfma_f32_16x16x32_bf16 v[40:43], v[140:143], v[198:201], v[40:43]
	v_mfma_f32_16x16x32_bf16 v[28:31], v[132:135], v[206:209], v[28:31]
	v_mfma_f32_16x16x32_bf16 v[24:27], v[140:143], v[206:209], v[24:27]
	v_mfma_f32_16x16x32_bf16 v[12:15], v[132:135], v[214:217], v[12:15]
	v_mfma_f32_16x16x32_bf16 v[8:11], v[140:143], v[214:217], v[8:11]
	v_mfma_f32_16x16x32_bf16 v[52:55], v[144:147], v[170:173], v[52:55]
	v_mfma_f32_16x16x32_bf16 v[48:51], v[152:155], v[170:173], v[48:51]
	v_mfma_f32_16x16x32_bf16 v[36:39], v[144:147], v[190:193], v[36:39]
	v_mfma_f32_16x16x32_bf16 v[32:35], v[152:155], v[190:193], v[32:35]
	v_mfma_f32_16x16x32_bf16 v[20:23], v[144:147], v[202:205], v[20:23]
	v_mfma_f32_16x16x32_bf16 v[16:19], v[152:155], v[202:205], v[16:19]
	v_mfma_f32_16x16x32_bf16 v[4:7], v[144:147], v[210:213], v[4:7]
	v_mfma_f32_16x16x32_bf16 v[0:3], v[152:155], v[210:213], v[0:3]
	v_mfma_f32_16x16x32_bf16 v[52:55], v[148:151], v[186:189], v[52:55]
	v_mfma_f32_16x16x32_bf16 v[48:51], v[166:169], v[186:189], v[48:51]
	v_mfma_f32_16x16x32_bf16 v[36:39], v[148:151], v[198:201], v[36:39]
	v_mfma_f32_16x16x32_bf16 v[32:35], v[166:169], v[198:201], v[32:35]
	v_mfma_f32_16x16x32_bf16 v[20:23], v[148:151], v[206:209], v[20:23]
	v_mfma_f32_16x16x32_bf16 v[16:19], v[166:169], v[206:209], v[16:19]
	v_mfma_f32_16x16x32_bf16 v[4:7], v[148:151], v[214:217], v[4:7]
	v_mfma_f32_16x16x32_bf16 v[0:3], v[166:169], v[214:217], v[0:3]
	s_barrier
	s_add_u32 s28, s28, 0x100
	s_addc_u32 s29, s29, 0
	s_add_u32 s10, s10, 0x100
	s_addc_u32 s11, s11, 0
	s_cmp_ge_i32 s44, s58
	s_mov_b32 s30, s44
	s_cbranch_scc0 .LBB0_475

.LBB0_494:
	s_or_b64 exec, exec, s[10:11]
	s_and_b64 vcc, exec, s[42:43]
	s_mov_b64 s[10:11], -1
	s_cbranch_vccnz .LBB0_462
	s_andn2_b64 vcc, exec, s[12:13]
	s_cbranch_vccnz .LBB0_461
	s_mov_b32 s100, 1
	s_branch .LBB0_461

.LBB0_574:
	v_mov_b32_e32 v127, 0
	s_andn2_b64 vcc, exec, s[36:37]
	v_mov_b32_e32 v126, v127
	v_mov_b32_e32 v125, v127
	v_mov_b32_e32 v124, v127
	v_mov_b32_e32 v123, v127
	v_mov_b32_e32 v122, v127
	v_mov_b32_e32 v121, v127
	v_mov_b32_e32 v120, v127
	v_mov_b32_e32 v111, v127
	v_mov_b32_e32 v110, v127
	v_mov_b32_e32 v109, v127
	v_mov_b32_e32 v108, v127
	v_mov_b32_e32 v107, v127
	v_mov_b32_e32 v106, v127
	v_mov_b32_e32 v105, v127
	v_mov_b32_e32 v104, v127
	v_mov_b32_e32 v95, v127
	v_mov_b32_e32 v94, v127
	v_mov_b32_e32 v93, v127
	v_mov_b32_e32 v92, v127
	v_mov_b32_e32 v91, v127
	v_mov_b32_e32 v90, v127
	v_mov_b32_e32 v89, v127
	v_mov_b32_e32 v88, v127
	v_mov_b32_e32 v79, v127
	v_mov_b32_e32 v78, v127
	v_mov_b32_e32 v77, v127
	v_mov_b32_e32 v76, v127
	v_mov_b32_e32 v75, v127
	v_mov_b32_e32 v74, v127
	v_mov_b32_e32 v73, v127
	v_mov_b32_e32 v72, v127
	v_mov_b32_e32 v119, v127
	v_mov_b32_e32 v118, v127
	v_mov_b32_e32 v117, v127
	v_mov_b32_e32 v116, v127
	v_mov_b32_e32 v115, v127
	v_mov_b32_e32 v114, v127
	v_mov_b32_e32 v113, v127
	v_mov_b32_e32 v112, v127
	v_mov_b32_e32 v103, v127
	v_mov_b32_e32 v102, v127
	v_mov_b32_e32 v101, v127
	v_mov_b32_e32 v100, v127
	v_mov_b32_e32 v99, v127
	v_mov_b32_e32 v98, v127
	v_mov_b32_e32 v97, v127
	v_mov_b32_e32 v96, v127
	v_mov_b32_e32 v87, v127
	v_mov_b32_e32 v86, v127
	v_mov_b32_e32 v85, v127
	v_mov_b32_e32 v84, v127
	v_mov_b32_e32 v83, v127
	v_mov_b32_e32 v82, v127
	v_mov_b32_e32 v81, v127
	v_mov_b32_e32 v80, v127
	v_mov_b32_e32 v71, v127
	v_mov_b32_e32 v70, v127
	v_mov_b32_e32 v69, v127
	v_mov_b32_e32 v68, v127
	v_mov_b32_e32 v67, v127
	v_mov_b32_e32 v66, v127
	v_mov_b32_e32 v65, v127
	v_mov_b32_e32 v64, v127
	v_mov_b32_e32 v63, v127
	v_mov_b32_e32 v62, v127
	v_mov_b32_e32 v61, v127
	v_mov_b32_e32 v60, v127
	v_mov_b32_e32 v59, v127
	v_mov_b32_e32 v58, v127
	v_mov_b32_e32 v57, v127
	v_mov_b32_e32 v56, v127
	v_mov_b32_e32 v47, v127
	v_mov_b32_e32 v46, v127
	v_mov_b32_e32 v45, v127
	v_mov_b32_e32 v44, v127
	v_mov_b32_e32 v43, v127
	v_mov_b32_e32 v42, v127
	v_mov_b32_e32 v41, v127
	v_mov_b32_e32 v40, v127
	v_mov_b32_e32 v31, v127
	v_mov_b32_e32 v30, v127
	v_mov_b32_e32 v29, v127
	v_mov_b32_e32 v28, v127
	v_mov_b32_e32 v27, v127
	v_mov_b32_e32 v26, v127
	v_mov_b32_e32 v25, v127
	v_mov_b32_e32 v24, v127
	v_mov_b32_e32 v15, v127
	v_mov_b32_e32 v14, v127
	v_mov_b32_e32 v13, v127
	v_mov_b32_e32 v12, v127
	v_mov_b32_e32 v11, v127
	v_mov_b32_e32 v10, v127
	v_mov_b32_e32 v9, v127
	v_mov_b32_e32 v8, v127
	v_mov_b32_e32 v55, v127
	v_mov_b32_e32 v54, v127
	v_mov_b32_e32 v53, v127
	v_mov_b32_e32 v52, v127
	v_mov_b32_e32 v51, v127
	v_mov_b32_e32 v50, v127
	v_mov_b32_e32 v49, v127
	v_mov_b32_e32 v48, v127
	v_mov_b32_e32 v39, v127
	v_mov_b32_e32 v38, v127
	v_mov_b32_e32 v37, v127
	v_mov_b32_e32 v36, v127
	v_mov_b32_e32 v35, v127
	v_mov_b32_e32 v34, v127
	v_mov_b32_e32 v33, v127
	v_mov_b32_e32 v32, v127
	v_mov_b32_e32 v23, v127
	v_mov_b32_e32 v22, v127
	v_mov_b32_e32 v21, v127
	v_mov_b32_e32 v20, v127
	v_mov_b32_e32 v19, v127
	v_mov_b32_e32 v18, v127
	v_mov_b32_e32 v17, v127
	v_mov_b32_e32 v16, v127
	v_mov_b32_e32 v7, v127
	v_mov_b32_e32 v6, v127
	v_mov_b32_e32 v5, v127
	v_mov_b32_e32 v4, v127
	v_mov_b32_e32 v3, v127
	v_mov_b32_e32 v2, v127
	v_mov_b32_e32 v1, v127
	v_mov_b32_e32 v0, v127
	s_cbranch_vccnz .LBB0_577
	s_add_u32 s0, s0, 0x80
	s_addc_u32 s1, s1, 0
	s_add_u32 s38, s38, 0x100
	s_addc_u32 s39, s39, 0
	s_mov_b32 s16, 0
	s_cmp_lg_u32 s100, 0
	s_cbranch_scc0 .Llbb_5
	s_barrier
	s_mov_b32 s100, 0
.Llbb_5:
.LBB0_576:
	s_add_i32 s44, s16, 2
	s_add_u32 s45, s0, 0x80
	s_addc_u32 s17, s1, 0
	s_add_i32 s64, 0, 0x10000
	s_cmp_eq_u32 s63, s16
	s_cselect_b32 s17, s57, s17
	s_cselect_b32 s16, s56, s45
	v_add_u32_e32 v152, s64, v153
	s_cselect_b32 s47, s9, s39
	s_cselect_b32 s46, s8, s38
	s_add_i32 s45, 0, 0x14000
	ds_read_b128 v[128:131], v152
	s_waitcnt vmcnt(0)
	ds_read_b128 v[158:161], v152 offset:1024
	ds_read_b128 v[162:165], v152 offset:2048
	ds_read_b128 v[166:169], v152 offset:3072
	v_add_u32_e32 v152, s45, v153
	ds_read_b128 v[170:173], v152
	ds_read_b128 v[174:177], v152 offset:1024
	ds_read_b128 v[194:197], v152 offset:2048
	ds_read_b128 v[206:209], v152 offset:3072
	v_lshl_add_u64 v[178:179], s[0:1], 0, v[148:149]
	s_add_i32 m0, s52, 0xc000
	ds_read_b128 v[210:213], v157
	ds_read_b128 v[214:217], v157 offset:1024
	ds_read_b128 v[220:223], v157 offset:2048
	ds_read_b128 v[224:227], v157 offset:3072
	ds_read_b128 v[228:231], v157 offset:4096
	ds_read_b128 v[232:235], v157 offset:5120
	ds_read_b128 v[236:239], v157 offset:6144
	ds_read_b128 v[240:243], v157 offset:7168
	global_load_lds_dwordx4 v[178:179], off
	v_lshl_add_u64 v[178:179], s[0:1], 0, v[150:151]
	s_add_i32 m0, s52, 0xe000
	s_nop 0
	global_load_lds_dwordx4 v[178:179], off
	s_waitcnt vmcnt(8)
	s_waitcnt lgkmcnt(0)
	s_barrier
	s_waitcnt lgkmcnt(0)
	v_mfma_f32_16x16x32_bf16 v[124:127], v[128:131], v[210:213], v[124:127]
	v_mfma_f32_16x16x32_bf16 v[120:123], v[162:165], v[210:213], v[120:123]
	v_mfma_f32_16x16x32_bf16 v[108:111], v[128:131], v[220:223], v[108:111]
	v_mfma_f32_16x16x32_bf16 v[104:107], v[162:165], v[220:223], v[104:107]
	v_mfma_f32_16x16x32_bf16 v[92:95], v[128:131], v[228:231], v[92:95]
	v_mfma_f32_16x16x32_bf16 v[88:91], v[162:165], v[228:231], v[88:91]
	v_mfma_f32_16x16x32_bf16 v[76:79], v[128:131], v[236:239], v[76:79]
	v_mfma_f32_16x16x32_bf16 v[72:75], v[162:165], v[236:239], v[72:75]
	v_mfma_f32_16x16x32_bf16 v[124:127], v[158:161], v[214:217], v[124:127]
	v_mfma_f32_16x16x32_bf16 v[120:123], v[166:169], v[214:217], v[120:123]
	v_mfma_f32_16x16x32_bf16 v[108:111], v[158:161], v[224:227], v[108:111]
	v_mfma_f32_16x16x32_bf16 v[104:107], v[166:169], v[224:227], v[104:107]
	v_mfma_f32_16x16x32_bf16 v[92:95], v[158:161], v[232:235], v[92:95]
	v_mfma_f32_16x16x32_bf16 v[88:91], v[166:169], v[232:235], v[88:91]
	v_mfma_f32_16x16x32_bf16 v[76:79], v[158:161], v[240:243], v[76:79]
	v_mfma_f32_16x16x32_bf16 v[72:75], v[166:169], v[240:243], v[72:75]
	v_mfma_f32_16x16x32_bf16 v[116:119], v[170:173], v[210:213], v[116:119]
	v_mfma_f32_16x16x32_bf16 v[112:115], v[194:197], v[210:213], v[112:115]
	v_mfma_f32_16x16x32_bf16 v[100:103], v[170:173], v[220:223], v[100:103]
	v_mfma_f32_16x16x32_bf16 v[96:99], v[194:197], v[220:223], v[96:99]
	v_mfma_f32_16x16x32_bf16 v[84:87], v[170:173], v[228:231], v[84:87]
	v_mfma_f32_16x16x32_bf16 v[80:83], v[194:197], v[228:231], v[80:83]
	v_mfma_f32_16x16x32_bf16 v[68:71], v[170:173], v[236:239], v[68:71]
	v_mfma_f32_16x16x32_bf16 v[64:67], v[194:197], v[236:239], v[64:67]
	v_mfma_f32_16x16x32_bf16 v[116:119], v[174:177], v[214:217], v[116:119]
	v_mfma_f32_16x16x32_bf16 v[112:115], v[206:209], v[214:217], v[112:115]
	v_mfma_f32_16x16x32_bf16 v[100:103], v[174:177], v[224:227], v[100:103]
	v_mfma_f32_16x16x32_bf16 v[96:99], v[206:209], v[224:227], v[96:99]
	v_mfma_f32_16x16x32_bf16 v[84:87], v[174:177], v[232:235], v[84:87]
	v_mfma_f32_16x16x32_bf16 v[80:83], v[206:209], v[232:235], v[80:83]
	v_mfma_f32_16x16x32_bf16 v[68:71], v[174:177], v[240:243], v[68:71]
	v_mfma_f32_16x16x32_bf16 v[64:67], v[206:209], v[240:243], v[64:67]
	s_barrier
	s_add_i32 s64, s64, s4
	v_lshl_add_u64 v[178:179], s[46:47], 0, v[134:135]
	s_mov_b32 m0, s64
	ds_read_b128 v[210:213], v157 offset:16384
	ds_read_b128 v[214:217], v157 offset:17408
	ds_read_b128 v[220:223], v157 offset:18432
	ds_read_b128 v[224:227], v157 offset:19456
	ds_read_b128 v[228:231], v157 offset:20480
	ds_read_b128 v[232:235], v157 offset:21504
	ds_read_b128 v[236:239], v157 offset:22528
	ds_read_b128 v[240:243], v157 offset:23552
	global_load_lds_dwordx4 v[178:179], off
	s_add_i32 m0, s64, 0x2000
	v_lshl_add_u64 v[198:199], s[46:47], 0, v[138:139]
	s_add_u32 s46, s46, s24
	s_addc_u32 s47, s47, s25
	s_add_i32 s45, s45, s4
	global_load_lds_dwordx4 v[198:199], off
	v_lshl_add_u64 v[244:245], s[46:47], 0, v[134:135]
	s_mov_b32 m0, s45
	v_lshl_add_u64 v[246:247], s[46:47], 0, v[138:139]
	global_load_lds_dwordx4 v[244:245], off
	s_add_i32 m0, s45, 0x2000
	v_lshl_add_u64 v[248:249], s[16:17], 0, v[132:133]
	global_load_lds_dwordx4 v[246:247], off
	s_mov_b32 m0, s52
	v_lshl_add_u64 v[250:251], s[16:17], 0, v[136:137]
	global_load_lds_dwordx4 v[248:249], off
	s_mov_b32 m0, s18
	s_nop 0
	global_load_lds_dwordx4 v[250:251], off
	s_waitcnt vmcnt(8)
	s_waitcnt lgkmcnt(0)
	s_barrier
	s_waitcnt lgkmcnt(0)
	v_mfma_f32_16x16x32_bf16 v[60:63], v[128:131], v[210:213], v[60:63]
	v_mfma_f32_16x16x32_bf16 v[56:59], v[162:165], v[210:213], v[56:59]
	v_mfma_f32_16x16x32_bf16 v[44:47], v[128:131], v[220:223], v[44:47]
	v_mfma_f32_16x16x32_bf16 v[40:43], v[162:165], v[220:223], v[40:43]
	v_mfma_f32_16x16x32_bf16 v[28:31], v[128:131], v[228:231], v[28:31]
	v_mfma_f32_16x16x32_bf16 v[24:27], v[162:165], v[228:231], v[24:27]
	v_mfma_f32_16x16x32_bf16 v[12:15], v[128:131], v[236:239], v[12:15]
	v_mfma_f32_16x16x32_bf16 v[8:11], v[162:165], v[236:239], v[8:11]
	v_mfma_f32_16x16x32_bf16 v[60:63], v[158:161], v[214:217], v[60:63]
	v_mfma_f32_16x16x32_bf16 v[56:59], v[166:169], v[214:217], v[56:59]
	v_mfma_f32_16x16x32_bf16 v[44:47], v[158:161], v[224:227], v[44:47]
	v_mfma_f32_16x16x32_bf16 v[40:43], v[166:169], v[224:227], v[40:43]
	v_mfma_f32_16x16x32_bf16 v[28:31], v[158:161], v[232:235], v[28:31]
	v_mfma_f32_16x16x32_bf16 v[24:27], v[166:169], v[232:235], v[24:27]
	v_mfma_f32_16x16x32_bf16 v[12:15], v[158:161], v[240:243], v[12:15]
	v_mfma_f32_16x16x32_bf16 v[8:11], v[166:169], v[240:243], v[8:11]
	v_mfma_f32_16x16x32_bf16 v[52:55], v[170:173], v[210:213], v[52:55]
	v_mfma_f32_16x16x32_bf16 v[48:51], v[194:197], v[210:213], v[48:51]
	v_mfma_f32_16x16x32_bf16 v[36:39], v[170:173], v[220:223], v[36:39]
	v_mfma_f32_16x16x32_bf16 v[32:35], v[194:197], v[220:223], v[32:35]
	v_mfma_f32_16x16x32_bf16 v[20:23], v[170:173], v[228:231], v[20:23]
	v_mfma_f32_16x16x32_bf16 v[16:19], v[194:197], v[228:231], v[16:19]
	v_mfma_f32_16x16x32_bf16 v[4:7], v[170:173], v[236:239], v[4:7]
	v_mfma_f32_16x16x32_bf16 v[0:3], v[194:197], v[236:239], v[0:3]
	v_mfma_f32_16x16x32_bf16 v[52:55], v[174:177], v[214:217], v[52:55]
	v_mfma_f32_16x16x32_bf16 v[48:51], v[206:209], v[214:217], v[48:51]
	v_mfma_f32_16x16x32_bf16 v[36:39], v[174:177], v[224:227], v[36:39]
	v_mfma_f32_16x16x32_bf16 v[32:35], v[206:209], v[224:227], v[32:35]
	v_mfma_f32_16x16x32_bf16 v[20:23], v[174:177], v[232:235], v[20:23]
	v_mfma_f32_16x16x32_bf16 v[16:19], v[206:209], v[232:235], v[16:19]
	v_mfma_f32_16x16x32_bf16 v[4:7], v[174:177], v[240:243], v[4:7]
	v_mfma_f32_16x16x32_bf16 v[0:3], v[206:209], v[240:243], v[0:3]
	s_barrier
	s_add_i32 s45, 0, 0x18000
	v_add_u32_e32 v152, s45, v153
	s_add_i32 s46, 0, 0x1c000
	ds_read_b128 v[128:131], v152
	ds_read_b128 v[158:161], v152 offset:1024
	ds_read_b128 v[162:165], v152 offset:2048
	ds_read_b128 v[166:169], v152 offset:3072
	v_add_u32_e32 v152, s46, v153
	ds_read_b128 v[170:173], v152
	ds_read_b128 v[174:177], v152 offset:1024
	ds_read_b128 v[194:197], v152 offset:2048
	ds_read_b128 v[206:209], v152 offset:3072
	s_add_u32 s16, s16, s24
	s_addc_u32 s17, s17, s25
	s_mov_b32 m0, s19
	v_lshl_add_u64 v[202:203], s[16:17], 0, v[132:133]
	ds_read_b128 v[210:213], v157 offset:32768
	ds_read_b128 v[214:217], v157 offset:33792
	ds_read_b128 v[220:223], v157 offset:34816
	ds_read_b128 v[224:227], v157 offset:35840
	ds_read_b128 v[228:231], v157 offset:36864
	ds_read_b128 v[232:235], v157 offset:37888
	ds_read_b128 v[236:239], v157 offset:38912
	ds_read_b128 v[240:243], v157 offset:39936
	global_load_lds_dwordx4 v[202:203], off
	v_lshl_add_u64 v[202:203], s[16:17], 0, v[136:137]
	s_mov_b32 m0, s33
	s_nop 0
	global_load_lds_dwordx4 v[202:203], off
	s_waitcnt vmcnt(8)
	s_waitcnt lgkmcnt(0)
	s_barrier
	s_waitcnt lgkmcnt(0)
	v_mfma_f32_16x16x32_bf16 v[124:127], v[128:131], v[210:213], v[124:127]
	v_mfma_f32_16x16x32_bf16 v[120:123], v[162:165], v[210:213], v[120:123]
	v_mfma_f32_16x16x32_bf16 v[108:111], v[128:131], v[220:223], v[108:111]
	v_mfma_f32_16x16x32_bf16 v[104:107], v[162:165], v[220:223], v[104:107]
	v_mfma_f32_16x16x32_bf16 v[92:95], v[128:131], v[228:231], v[92:95]
	v_mfma_f32_16x16x32_bf16 v[88:91], v[162:165], v[228:231], v[88:91]
	v_mfma_f32_16x16x32_bf16 v[76:79], v[128:131], v[236:239], v[76:79]
	v_mfma_f32_16x16x32_bf16 v[72:75], v[162:165], v[236:239], v[72:75]
	v_mfma_f32_16x16x32_bf16 v[124:127], v[158:161], v[214:217], v[124:127]
	v_mfma_f32_16x16x32_bf16 v[120:123], v[166:169], v[214:217], v[120:123]
	v_mfma_f32_16x16x32_bf16 v[108:111], v[158:161], v[224:227], v[108:111]
	v_mfma_f32_16x16x32_bf16 v[104:107], v[166:169], v[224:227], v[104:107]
	v_mfma_f32_16x16x32_bf16 v[92:95], v[158:161], v[232:235], v[92:95]
	v_mfma_f32_16x16x32_bf16 v[88:91], v[166:169], v[232:235], v[88:91]
	v_mfma_f32_16x16x32_bf16 v[76:79], v[158:161], v[240:243], v[76:79]
	v_mfma_f32_16x16x32_bf16 v[72:75], v[166:169], v[240:243], v[72:75]
	v_mfma_f32_16x16x32_bf16 v[116:119], v[170:173], v[210:213], v[116:119]
	v_mfma_f32_16x16x32_bf16 v[112:115], v[194:197], v[210:213], v[112:115]
	v_mfma_f32_16x16x32_bf16 v[100:103], v[170:173], v[220:223], v[100:103]
	v_mfma_f32_16x16x32_bf16 v[96:99], v[194:197], v[220:223], v[96:99]
	v_mfma_f32_16x16x32_bf16 v[84:87], v[170:173], v[228:231], v[84:87]
	v_mfma_f32_16x16x32_bf16 v[80:83], v[194:197], v[228:231], v[80:83]
	v_mfma_f32_16x16x32_bf16 v[68:71], v[170:173], v[236:239], v[68:71]
	v_mfma_f32_16x16x32_bf16 v[64:67], v[194:197], v[236:239], v[64:67]
	v_mfma_f32_16x16x32_bf16 v[116:119], v[174:177], v[214:217], v[116:119]
	v_mfma_f32_16x16x32_bf16 v[112:115], v[206:209], v[214:217], v[112:115]
	v_mfma_f32_16x16x32_bf16 v[100:103], v[174:177], v[224:227], v[100:103]
	v_mfma_f32_16x16x32_bf16 v[96:99], v[206:209], v[224:227], v[96:99]
	v_mfma_f32_16x16x32_bf16 v[84:87], v[174:177], v[232:235], v[84:87]
	v_mfma_f32_16x16x32_bf16 v[80:83], v[206:209], v[232:235], v[80:83]
	v_mfma_f32_16x16x32_bf16 v[68:71], v[174:177], v[240:243], v[68:71]
	v_mfma_f32_16x16x32_bf16 v[64:67], v[206:209], v[240:243], v[64:67]
	s_barrier
	s_add_i32 s16, s45, s4
	v_lshl_add_u64 v[178:179], v[178:179], 0, s[12:13]
	s_mov_b32 m0, s16
	ds_read_b128 v[210:213], v157 offset:49152
	ds_read_b128 v[214:217], v157 offset:50176
	ds_read_b128 v[220:223], v157 offset:51200
	ds_read_b128 v[224:227], v157 offset:52224
	ds_read_b128 v[228:231], v157 offset:53248
	ds_read_b128 v[232:235], v157 offset:54272
	ds_read_b128 v[236:239], v157 offset:55296
	ds_read_b128 v[240:243], v157 offset:56320
	global_load_lds_dwordx4 v[178:179], off
	v_lshl_add_u64 v[178:179], v[198:199], 0, s[12:13]
	s_add_i32 m0, s16, 0x2000
	s_add_i32 s16, s46, s4
	global_load_lds_dwordx4 v[178:179], off
	v_lshl_add_u64 v[178:179], v[244:245], 0, s[12:13]
	s_mov_b32 m0, s16
	s_nop 0
	global_load_lds_dwordx4 v[178:179], off
	v_lshl_add_u64 v[178:179], v[246:247], 0, s[12:13]
	s_add_i32 m0, s16, 0x2000
	s_nop 0
	global_load_lds_dwordx4 v[178:179], off
	v_lshl_add_u64 v[178:179], v[248:249], 0, s[12:13]
	s_mov_b32 m0, s59
	s_nop 0
	global_load_lds_dwordx4 v[178:179], off
	v_lshl_add_u64 v[178:179], v[250:251], 0, s[12:13]
	s_mov_b32 m0, s60
	s_nop 0
	global_load_lds_dwordx4 v[178:179], off
	s_waitcnt vmcnt(8)
	s_waitcnt lgkmcnt(0)
	s_barrier
	s_waitcnt lgkmcnt(0)
	v_mfma_f32_16x16x32_bf16 v[60:63], v[128:131], v[210:213], v[60:63]
	v_mfma_f32_16x16x32_bf16 v[56:59], v[162:165], v[210:213], v[56:59]
	v_mfma_f32_16x16x32_bf16 v[44:47], v[128:131], v[220:223], v[44:47]
	v_mfma_f32_16x16x32_bf16 v[40:43], v[162:165], v[220:223], v[40:43]
	v_mfma_f32_16x16x32_bf16 v[28:31], v[128:131], v[228:231], v[28:31]
	v_mfma_f32_16x16x32_bf16 v[24:27], v[162:165], v[228:231], v[24:27]
	v_mfma_f32_16x16x32_bf16 v[12:15], v[128:131], v[236:239], v[12:15]
	v_mfma_f32_16x16x32_bf16 v[8:11], v[162:165], v[236:239], v[8:11]
	v_mfma_f32_16x16x32_bf16 v[60:63], v[158:161], v[214:217], v[60:63]
	v_mfma_f32_16x16x32_bf16 v[56:59], v[166:169], v[214:217], v[56:59]
	v_mfma_f32_16x16x32_bf16 v[44:47], v[158:161], v[224:227], v[44:47]
	v_mfma_f32_16x16x32_bf16 v[40:43], v[166:169], v[224:227], v[40:43]
	v_mfma_f32_16x16x32_bf16 v[28:31], v[158:161], v[232:235], v[28:31]
	v_mfma_f32_16x16x32_bf16 v[24:27], v[166:169], v[232:235], v[24:27]
	v_mfma_f32_16x16x32_bf16 v[12:15], v[158:161], v[240:243], v[12:15]
	v_mfma_f32_16x16x32_bf16 v[8:11], v[166:169], v[240:243], v[8:11]
	v_mfma_f32_16x16x32_bf16 v[52:55], v[170:173], v[210:213], v[52:55]
	v_mfma_f32_16x16x32_bf16 v[48:51], v[194:197], v[210:213], v[48:51]
	v_mfma_f32_16x16x32_bf16 v[36:39], v[170:173], v[220:223], v[36:39]
	v_mfma_f32_16x16x32_bf16 v[32:35], v[194:197], v[220:223], v[32:35]
	v_mfma_f32_16x16x32_bf16 v[20:23], v[170:173], v[228:231], v[20:23]
	v_mfma_f32_16x16x32_bf16 v[16:19], v[194:197], v[228:231], v[16:19]
	v_mfma_f32_16x16x32_bf16 v[4:7], v[170:173], v[236:239], v[4:7]
	v_mfma_f32_16x16x32_bf16 v[0:3], v[194:197], v[236:239], v[0:3]
	v_mfma_f32_16x16x32_bf16 v[52:55], v[174:177], v[214:217], v[52:55]
	v_mfma_f32_16x16x32_bf16 v[48:51], v[206:209], v[214:217], v[48:51]
	v_mfma_f32_16x16x32_bf16 v[36:39], v[174:177], v[224:227], v[36:39]
	v_mfma_f32_16x16x32_bf16 v[32:35], v[206:209], v[224:227], v[32:35]
	v_mfma_f32_16x16x32_bf16 v[20:23], v[174:177], v[232:235], v[20:23]
	v_mfma_f32_16x16x32_bf16 v[16:19], v[206:209], v[232:235], v[16:19]
	v_mfma_f32_16x16x32_bf16 v[4:7], v[174:177], v[240:243], v[4:7]
	v_mfma_f32_16x16x32_bf16 v[0:3], v[206:209], v[240:243], v[0:3]
	s_barrier
	s_add_u32 s0, s0, 0x100
	s_addc_u32 s1, s1, 0
	s_add_u32 s38, s38, 0x100
	s_addc_u32 s39, s39, 0
	s_cmp_ge_i32 s44, s68
	s_mov_b32 s16, s44
	s_cbranch_scc0 .LBB0_576

.LBB0_796:
	v_mov_b32_e32 v127, 0
	s_andn2_b64 vcc, exec, s[20:21]
	v_mov_b32_e32 v126, v127
	v_mov_b32_e32 v125, v127
	v_mov_b32_e32 v124, v127
	v_mov_b32_e32 v123, v127
	v_mov_b32_e32 v122, v127
	v_mov_b32_e32 v121, v127
	v_mov_b32_e32 v120, v127
	v_mov_b32_e32 v111, v127
	v_mov_b32_e32 v110, v127
	v_mov_b32_e32 v109, v127
	v_mov_b32_e32 v108, v127
	v_mov_b32_e32 v107, v127
	v_mov_b32_e32 v106, v127
	v_mov_b32_e32 v105, v127
	v_mov_b32_e32 v104, v127
	v_mov_b32_e32 v95, v127
	v_mov_b32_e32 v94, v127
	v_mov_b32_e32 v93, v127
	v_mov_b32_e32 v92, v127
	v_mov_b32_e32 v91, v127
	v_mov_b32_e32 v90, v127
	v_mov_b32_e32 v89, v127
	v_mov_b32_e32 v88, v127
	v_mov_b32_e32 v79, v127
	v_mov_b32_e32 v78, v127
	v_mov_b32_e32 v77, v127
	v_mov_b32_e32 v76, v127
	v_mov_b32_e32 v75, v127
	v_mov_b32_e32 v74, v127
	v_mov_b32_e32 v73, v127
	v_mov_b32_e32 v72, v127
	v_mov_b32_e32 v119, v127
	v_mov_b32_e32 v118, v127
	v_mov_b32_e32 v117, v127
	v_mov_b32_e32 v116, v127
	v_mov_b32_e32 v115, v127
	v_mov_b32_e32 v114, v127
	v_mov_b32_e32 v113, v127
	v_mov_b32_e32 v112, v127
	v_mov_b32_e32 v103, v127
	v_mov_b32_e32 v102, v127
	v_mov_b32_e32 v101, v127
	v_mov_b32_e32 v100, v127
	v_mov_b32_e32 v99, v127
	v_mov_b32_e32 v98, v127
	v_mov_b32_e32 v97, v127
	v_mov_b32_e32 v96, v127
	v_mov_b32_e32 v87, v127
	v_mov_b32_e32 v86, v127
	v_mov_b32_e32 v85, v127
	v_mov_b32_e32 v84, v127
	v_mov_b32_e32 v83, v127
	v_mov_b32_e32 v82, v127
	v_mov_b32_e32 v81, v127
	v_mov_b32_e32 v80, v127
	v_mov_b32_e32 v71, v127
	v_mov_b32_e32 v70, v127
	v_mov_b32_e32 v69, v127
	v_mov_b32_e32 v68, v127
	v_mov_b32_e32 v67, v127
	v_mov_b32_e32 v66, v127
	v_mov_b32_e32 v65, v127
	v_mov_b32_e32 v64, v127
	v_mov_b32_e32 v63, v127
	v_mov_b32_e32 v62, v127
	v_mov_b32_e32 v61, v127
	v_mov_b32_e32 v60, v127
	v_mov_b32_e32 v59, v127
	v_mov_b32_e32 v58, v127
	v_mov_b32_e32 v57, v127
	v_mov_b32_e32 v56, v127
	v_mov_b32_e32 v47, v127
	v_mov_b32_e32 v46, v127
	v_mov_b32_e32 v45, v127
	v_mov_b32_e32 v44, v127
	v_mov_b32_e32 v43, v127
	v_mov_b32_e32 v42, v127
	v_mov_b32_e32 v41, v127
	v_mov_b32_e32 v40, v127
	v_mov_b32_e32 v31, v127
	v_mov_b32_e32 v30, v127
	v_mov_b32_e32 v29, v127
	v_mov_b32_e32 v28, v127
	v_mov_b32_e32 v27, v127
	v_mov_b32_e32 v26, v127
	v_mov_b32_e32 v25, v127
	v_mov_b32_e32 v24, v127
	v_mov_b32_e32 v15, v127
	v_mov_b32_e32 v14, v127
	v_mov_b32_e32 v13, v127
	v_mov_b32_e32 v12, v127
	v_mov_b32_e32 v11, v127
	v_mov_b32_e32 v10, v127
	v_mov_b32_e32 v9, v127
	v_mov_b32_e32 v8, v127
	v_mov_b32_e32 v55, v127
	v_mov_b32_e32 v54, v127
	v_mov_b32_e32 v53, v127
	v_mov_b32_e32 v52, v127
	v_mov_b32_e32 v51, v127
	v_mov_b32_e32 v50, v127
	v_mov_b32_e32 v49, v127
	v_mov_b32_e32 v48, v127
	v_mov_b32_e32 v39, v127
	v_mov_b32_e32 v38, v127
	v_mov_b32_e32 v37, v127
	v_mov_b32_e32 v36, v127
	v_mov_b32_e32 v35, v127
	v_mov_b32_e32 v34, v127
	v_mov_b32_e32 v33, v127
	v_mov_b32_e32 v32, v127
	v_mov_b32_e32 v23, v127
	v_mov_b32_e32 v22, v127
	v_mov_b32_e32 v21, v127
	v_mov_b32_e32 v20, v127
	v_mov_b32_e32 v19, v127
	v_mov_b32_e32 v18, v127
	v_mov_b32_e32 v17, v127
	v_mov_b32_e32 v16, v127
	v_mov_b32_e32 v7, v127
	v_mov_b32_e32 v6, v127
	v_mov_b32_e32 v5, v127
	v_mov_b32_e32 v4, v127
	v_mov_b32_e32 v3, v127
	v_mov_b32_e32 v2, v127
	v_mov_b32_e32 v1, v127
	v_mov_b32_e32 v0, v127
	s_cbranch_vccnz .LBB0_799
	s_add_u32 s28, s16, 0x80
	s_addc_u32 s29, s17, 0
	s_add_u32 s10, s30, 0x100
	s_addc_u32 s11, s31, 0
	s_mov_b32 s16, 0
	s_cmp_lg_u32 s100, 0
	s_cbranch_scc0 .Llbb_6
	s_barrier
	s_mov_b32 s100, 0
.Llbb_6:
.LBB0_798:
	s_add_i32 s30, s16, 2
	s_add_u32 s31, s28, 0x80
	s_addc_u32 s17, s29, 0
	s_add_i32 s59, 0, 0x10000
	s_cmp_eq_u32 s48, s16
	s_cselect_b32 s17, s25, s17
	s_cselect_b32 s16, s24, s31
	v_add_u32_e32 v140, s59, v143
	s_cselect_b32 s43, s27, s11
	s_cselect_b32 s42, s26, s10
	s_add_i32 s31, 0, 0x14000
	ds_read_b128 v[146:149], v140
	ds_read_b128 v[150:153], v140 offset:1024
	ds_read_b128 v[154:157], v140 offset:2048
	s_waitcnt vmcnt(0)
	ds_read_b128 v[158:161], v140 offset:3072
	v_add_u32_e32 v140, s31, v143
	ds_read_b128 v[162:165], v140
	ds_read_b128 v[166:169], v140 offset:1024
	ds_read_b128 v[170:173], v140 offset:2048
	ds_read_b128 v[174:177], v140 offset:3072
	v_lshl_add_u64 v[178:179], s[28:29], 0, v[136:137]
	s_add_i32 m0, s37, 0xc000
	ds_read_b128 v[194:197], v145
	ds_read_b128 v[206:209], v145 offset:1024
	ds_read_b128 v[210:213], v145 offset:2048
	ds_read_b128 v[214:217], v145 offset:3072
	ds_read_b128 v[220:223], v145 offset:4096
	ds_read_b128 v[224:227], v145 offset:5120
	ds_read_b128 v[228:231], v145 offset:6144
	ds_read_b128 v[232:235], v145 offset:7168
	global_load_lds_dwordx4 v[178:179], off
	v_lshl_add_u64 v[178:179], s[28:29], 0, v[138:139]
	s_add_i32 m0, s37, 0xe000
	s_nop 0
	global_load_lds_dwordx4 v[178:179], off
	s_waitcnt vmcnt(8)
	s_waitcnt lgkmcnt(0)
	s_barrier
	s_waitcnt lgkmcnt(0)
	v_mfma_f32_16x16x32_bf16 v[124:127], v[146:149], v[194:197], v[124:127]
	v_mfma_f32_16x16x32_bf16 v[120:123], v[154:157], v[194:197], v[120:123]
	v_mfma_f32_16x16x32_bf16 v[108:111], v[146:149], v[210:213], v[108:111]
	v_mfma_f32_16x16x32_bf16 v[104:107], v[154:157], v[210:213], v[104:107]
	v_mfma_f32_16x16x32_bf16 v[92:95], v[146:149], v[220:223], v[92:95]
	v_mfma_f32_16x16x32_bf16 v[88:91], v[154:157], v[220:223], v[88:91]
	v_mfma_f32_16x16x32_bf16 v[76:79], v[146:149], v[228:231], v[76:79]
	v_mfma_f32_16x16x32_bf16 v[72:75], v[154:157], v[228:231], v[72:75]
	v_mfma_f32_16x16x32_bf16 v[124:127], v[150:153], v[206:209], v[124:127]
	v_mfma_f32_16x16x32_bf16 v[120:123], v[158:161], v[206:209], v[120:123]
	v_mfma_f32_16x16x32_bf16 v[108:111], v[150:153], v[214:217], v[108:111]
	v_mfma_f32_16x16x32_bf16 v[104:107], v[158:161], v[214:217], v[104:107]
	v_mfma_f32_16x16x32_bf16 v[92:95], v[150:153], v[224:227], v[92:95]
	v_mfma_f32_16x16x32_bf16 v[88:91], v[158:161], v[224:227], v[88:91]
	v_mfma_f32_16x16x32_bf16 v[76:79], v[150:153], v[232:235], v[76:79]
	v_mfma_f32_16x16x32_bf16 v[72:75], v[158:161], v[232:235], v[72:75]
	v_mfma_f32_16x16x32_bf16 v[116:119], v[162:165], v[194:197], v[116:119]
	v_mfma_f32_16x16x32_bf16 v[112:115], v[170:173], v[194:197], v[112:115]
	v_mfma_f32_16x16x32_bf16 v[100:103], v[162:165], v[210:213], v[100:103]
	v_mfma_f32_16x16x32_bf16 v[96:99], v[170:173], v[210:213], v[96:99]
	v_mfma_f32_16x16x32_bf16 v[84:87], v[162:165], v[220:223], v[84:87]
	v_mfma_f32_16x16x32_bf16 v[80:83], v[170:173], v[220:223], v[80:83]
	v_mfma_f32_16x16x32_bf16 v[68:71], v[162:165], v[228:231], v[68:71]
	v_mfma_f32_16x16x32_bf16 v[64:67], v[170:173], v[228:231], v[64:67]
	v_mfma_f32_16x16x32_bf16 v[116:119], v[166:169], v[206:209], v[116:119]
	v_mfma_f32_16x16x32_bf16 v[112:115], v[174:177], v[206:209], v[112:115]
	v_mfma_f32_16x16x32_bf16 v[100:103], v[166:169], v[214:217], v[100:103]
	v_mfma_f32_16x16x32_bf16 v[96:99], v[174:177], v[214:217], v[96:99]
	v_mfma_f32_16x16x32_bf16 v[84:87], v[166:169], v[224:227], v[84:87]
	v_mfma_f32_16x16x32_bf16 v[80:83], v[174:177], v[224:227], v[80:83]
	v_mfma_f32_16x16x32_bf16 v[68:71], v[166:169], v[232:235], v[68:71]
	v_mfma_f32_16x16x32_bf16 v[64:67], v[174:177], v[232:235], v[64:67]
	s_barrier
	s_add_i32 s59, s59, s36
	v_lshl_add_u64 v[178:179], s[42:43], 0, v[132:133]
	s_mov_b32 m0, s59
	ds_read_b128 v[194:197], v145 offset:16384
	ds_read_b128 v[206:209], v145 offset:17408
	ds_read_b128 v[210:213], v145 offset:18432
	ds_read_b128 v[214:217], v145 offset:19456
	ds_read_b128 v[220:223], v145 offset:20480
	ds_read_b128 v[224:227], v145 offset:21504
	ds_read_b128 v[228:231], v145 offset:22528
	ds_read_b128 v[232:235], v145 offset:23552
	global_load_lds_dwordx4 v[178:179], off
	s_add_i32 m0, s59, 0x2000
	v_lshl_add_u64 v[198:199], s[42:43], 0, v[128:129]
	s_add_u32 s42, s42, s0
	s_addc_u32 s43, s43, s1
	s_add_i32 s31, s31, s36
	global_load_lds_dwordx4 v[198:199], off
	v_lshl_add_u64 v[202:203], s[42:43], 0, v[132:133]
	s_mov_b32 m0, s31
	v_lshl_add_u64 v[236:237], s[42:43], 0, v[128:129]
	global_load_lds_dwordx4 v[202:203], off
	s_add_i32 m0, s31, 0x2000
	v_lshl_add_u64 v[238:239], s[16:17], 0, v[134:135]
	global_load_lds_dwordx4 v[236:237], off
	s_mov_b32 m0, s37
	v_lshl_add_u64 v[240:241], s[16:17], 0, v[130:131]
	global_load_lds_dwordx4 v[238:239], off
	s_mov_b32 m0, s38
	s_nop 0
	global_load_lds_dwordx4 v[240:241], off
	s_waitcnt vmcnt(8)
	s_waitcnt lgkmcnt(0)
	s_barrier
	s_waitcnt lgkmcnt(0)
	v_mfma_f32_16x16x32_bf16 v[60:63], v[146:149], v[194:197], v[60:63]
	v_mfma_f32_16x16x32_bf16 v[56:59], v[154:157], v[194:197], v[56:59]
	v_mfma_f32_16x16x32_bf16 v[44:47], v[146:149], v[210:213], v[44:47]
	v_mfma_f32_16x16x32_bf16 v[40:43], v[154:157], v[210:213], v[40:43]
	v_mfma_f32_16x16x32_bf16 v[28:31], v[146:149], v[220:223], v[28:31]
	v_mfma_f32_16x16x32_bf16 v[24:27], v[154:157], v[220:223], v[24:27]
	v_mfma_f32_16x16x32_bf16 v[12:15], v[146:149], v[228:231], v[12:15]
	v_mfma_f32_16x16x32_bf16 v[8:11], v[154:157], v[228:231], v[8:11]
	v_mfma_f32_16x16x32_bf16 v[60:63], v[150:153], v[206:209], v[60:63]
	v_mfma_f32_16x16x32_bf16 v[56:59], v[158:161], v[206:209], v[56:59]
	v_mfma_f32_16x16x32_bf16 v[44:47], v[150:153], v[214:217], v[44:47]
	v_mfma_f32_16x16x32_bf16 v[40:43], v[158:161], v[214:217], v[40:43]
	v_mfma_f32_16x16x32_bf16 v[28:31], v[150:153], v[224:227], v[28:31]
	v_mfma_f32_16x16x32_bf16 v[24:27], v[158:161], v[224:227], v[24:27]
	v_mfma_f32_16x16x32_bf16 v[12:15], v[150:153], v[232:235], v[12:15]
	v_mfma_f32_16x16x32_bf16 v[8:11], v[158:161], v[232:235], v[8:11]
	v_mfma_f32_16x16x32_bf16 v[52:55], v[162:165], v[194:197], v[52:55]
	v_mfma_f32_16x16x32_bf16 v[48:51], v[170:173], v[194:197], v[48:51]
	v_mfma_f32_16x16x32_bf16 v[36:39], v[162:165], v[210:213], v[36:39]
	v_mfma_f32_16x16x32_bf16 v[32:35], v[170:173], v[210:213], v[32:35]
	v_mfma_f32_16x16x32_bf16 v[20:23], v[162:165], v[220:223], v[20:23]
	v_mfma_f32_16x16x32_bf16 v[16:19], v[170:173], v[220:223], v[16:19]
	v_mfma_f32_16x16x32_bf16 v[4:7], v[162:165], v[228:231], v[4:7]
	v_mfma_f32_16x16x32_bf16 v[0:3], v[170:173], v[228:231], v[0:3]
	v_mfma_f32_16x16x32_bf16 v[52:55], v[166:169], v[206:209], v[52:55]
	v_mfma_f32_16x16x32_bf16 v[48:51], v[174:177], v[206:209], v[48:51]
	v_mfma_f32_16x16x32_bf16 v[36:39], v[166:169], v[214:217], v[36:39]
	v_mfma_f32_16x16x32_bf16 v[32:35], v[174:177], v[214:217], v[32:35]
	v_mfma_f32_16x16x32_bf16 v[20:23], v[166:169], v[224:227], v[20:23]
	v_mfma_f32_16x16x32_bf16 v[16:19], v[174:177], v[224:227], v[16:19]
	v_mfma_f32_16x16x32_bf16 v[4:7], v[166:169], v[232:235], v[4:7]
	v_mfma_f32_16x16x32_bf16 v[0:3], v[174:177], v[232:235], v[0:3]
	s_barrier
	s_add_i32 s31, 0, 0x18000
	v_add_u32_e32 v140, s31, v143
	s_add_i32 s42, 0, 0x1c000
	ds_read_b128 v[146:149], v140
	ds_read_b128 v[150:153], v140 offset:1024
	ds_read_b128 v[154:157], v140 offset:2048
	ds_read_b128 v[158:161], v140 offset:3072
	v_add_u32_e32 v140, s42, v143
	ds_read_b128 v[162:165], v140
	ds_read_b128 v[166:169], v140 offset:1024
	ds_read_b128 v[170:173], v140 offset:2048
	ds_read_b128 v[174:177], v140 offset:3072
	s_add_u32 s16, s16, s0
	s_addc_u32 s17, s17, s1
	s_mov_b32 m0, s39
	v_lshl_add_u64 v[242:243], s[16:17], 0, v[134:135]
	ds_read_b128 v[194:197], v145 offset:32768
	ds_read_b128 v[206:209], v145 offset:33792
	ds_read_b128 v[210:213], v145 offset:34816
	ds_read_b128 v[214:217], v145 offset:35840
	ds_read_b128 v[220:223], v145 offset:36864
	ds_read_b128 v[224:227], v145 offset:37888
	ds_read_b128 v[228:231], v145 offset:38912
	ds_read_b128 v[232:235], v145 offset:39936
	global_load_lds_dwordx4 v[242:243], off
	v_lshl_add_u64 v[242:243], s[16:17], 0, v[130:131]
	s_mov_b32 m0, s44
	s_nop 0
	global_load_lds_dwordx4 v[242:243], off
	s_waitcnt vmcnt(8)
	s_waitcnt lgkmcnt(0)
	s_barrier
	s_waitcnt lgkmcnt(0)
	v_mfma_f32_16x16x32_bf16 v[124:127], v[146:149], v[194:197], v[124:127]
	v_mfma_f32_16x16x32_bf16 v[120:123], v[154:157], v[194:197], v[120:123]
	v_mfma_f32_16x16x32_bf16 v[108:111], v[146:149], v[210:213], v[108:111]
	v_mfma_f32_16x16x32_bf16 v[104:107], v[154:157], v[210:213], v[104:107]
	v_mfma_f32_16x16x32_bf16 v[92:95], v[146:149], v[220:223], v[92:95]
	v_mfma_f32_16x16x32_bf16 v[88:91], v[154:157], v[220:223], v[88:91]
	v_mfma_f32_16x16x32_bf16 v[76:79], v[146:149], v[228:231], v[76:79]
	v_mfma_f32_16x16x32_bf16 v[72:75], v[154:157], v[228:231], v[72:75]
	v_mfma_f32_16x16x32_bf16 v[124:127], v[150:153], v[206:209], v[124:127]
	v_mfma_f32_16x16x32_bf16 v[120:123], v[158:161], v[206:209], v[120:123]
	v_mfma_f32_16x16x32_bf16 v[108:111], v[150:153], v[214:217], v[108:111]
	v_mfma_f32_16x16x32_bf16 v[104:107], v[158:161], v[214:217], v[104:107]
	v_mfma_f32_16x16x32_bf16 v[92:95], v[150:153], v[224:227], v[92:95]
	v_mfma_f32_16x16x32_bf16 v[88:91], v[158:161], v[224:227], v[88:91]
	v_mfma_f32_16x16x32_bf16 v[76:79], v[150:153], v[232:235], v[76:79]
	v_mfma_f32_16x16x32_bf16 v[72:75], v[158:161], v[232:235], v[72:75]
	v_mfma_f32_16x16x32_bf16 v[116:119], v[162:165], v[194:197], v[116:119]
	v_mfma_f32_16x16x32_bf16 v[112:115], v[170:173], v[194:197], v[112:115]
	v_mfma_f32_16x16x32_bf16 v[100:103], v[162:165], v[210:213], v[100:103]
	v_mfma_f32_16x16x32_bf16 v[96:99], v[170:173], v[210:213], v[96:99]
	v_mfma_f32_16x16x32_bf16 v[84:87], v[162:165], v[220:223], v[84:87]
	v_mfma_f32_16x16x32_bf16 v[80:83], v[170:173], v[220:223], v[80:83]
	v_mfma_f32_16x16x32_bf16 v[68:71], v[162:165], v[228:231], v[68:71]
	v_mfma_f32_16x16x32_bf16 v[64:67], v[170:173], v[228:231], v[64:67]
	v_mfma_f32_16x16x32_bf16 v[116:119], v[166:169], v[206:209], v[116:119]
	v_mfma_f32_16x16x32_bf16 v[112:115], v[174:177], v[206:209], v[112:115]
	v_mfma_f32_16x16x32_bf16 v[100:103], v[166:169], v[214:217], v[100:103]
	v_mfma_f32_16x16x32_bf16 v[96:99], v[174:177], v[214:217], v[96:99]
	v_mfma_f32_16x16x32_bf16 v[84:87], v[166:169], v[224:227], v[84:87]
	v_mfma_f32_16x16x32_bf16 v[80:83], v[174:177], v[224:227], v[80:83]
	v_mfma_f32_16x16x32_bf16 v[68:71], v[166:169], v[232:235], v[68:71]
	v_mfma_f32_16x16x32_bf16 v[64:67], v[174:177], v[232:235], v[64:67]
	s_barrier
	s_add_i32 s16, s31, s36
	v_lshl_add_u64 v[178:179], v[178:179], 0, s[12:13]
	s_mov_b32 m0, s16
	ds_read_b128 v[194:197], v145 offset:49152
	ds_read_b128 v[206:209], v145 offset:50176
	ds_read_b128 v[210:213], v145 offset:51200
	ds_read_b128 v[214:217], v145 offset:52224
	ds_read_b128 v[220:223], v145 offset:53248
	ds_read_b128 v[224:227], v145 offset:54272
	ds_read_b128 v[228:231], v145 offset:55296
	ds_read_b128 v[232:235], v145 offset:56320
	global_load_lds_dwordx4 v[178:179], off
	v_lshl_add_u64 v[178:179], v[198:199], 0, s[12:13]
	s_add_i32 m0, s16, 0x2000
	s_add_i32 s16, s42, s36
	global_load_lds_dwordx4 v[178:179], off
	v_lshl_add_u64 v[178:179], v[202:203], 0, s[12:13]
	s_mov_b32 m0, s16
	s_nop 0
	global_load_lds_dwordx4 v[178:179], off
	v_lshl_add_u64 v[178:179], v[236:237], 0, s[12:13]
	s_add_i32 m0, s16, 0x2000
	s_nop 0
	global_load_lds_dwordx4 v[178:179], off
	v_lshl_add_u64 v[178:179], v[238:239], 0, s[12:13]
	s_mov_b32 m0, s45
	s_nop 0
	global_load_lds_dwordx4 v[178:179], off
	v_lshl_add_u64 v[178:179], v[240:241], 0, s[12:13]
	s_mov_b32 m0, s46
	s_nop 0
	global_load_lds_dwordx4 v[178:179], off
	s_waitcnt vmcnt(8)
	s_waitcnt lgkmcnt(0)
	s_barrier
	s_waitcnt lgkmcnt(0)
	v_mfma_f32_16x16x32_bf16 v[60:63], v[146:149], v[194:197], v[60:63]
	v_mfma_f32_16x16x32_bf16 v[56:59], v[154:157], v[194:197], v[56:59]
	v_mfma_f32_16x16x32_bf16 v[44:47], v[146:149], v[210:213], v[44:47]
	v_mfma_f32_16x16x32_bf16 v[40:43], v[154:157], v[210:213], v[40:43]
	v_mfma_f32_16x16x32_bf16 v[28:31], v[146:149], v[220:223], v[28:31]
	v_mfma_f32_16x16x32_bf16 v[24:27], v[154:157], v[220:223], v[24:27]
	v_mfma_f32_16x16x32_bf16 v[12:15], v[146:149], v[228:231], v[12:15]
	v_mfma_f32_16x16x32_bf16 v[8:11], v[154:157], v[228:231], v[8:11]
	v_mfma_f32_16x16x32_bf16 v[60:63], v[150:153], v[206:209], v[60:63]
	v_mfma_f32_16x16x32_bf16 v[56:59], v[158:161], v[206:209], v[56:59]
	v_mfma_f32_16x16x32_bf16 v[44:47], v[150:153], v[214:217], v[44:47]
	v_mfma_f32_16x16x32_bf16 v[40:43], v[158:161], v[214:217], v[40:43]
	v_mfma_f32_16x16x32_bf16 v[28:31], v[150:153], v[224:227], v[28:31]
	v_mfma_f32_16x16x32_bf16 v[24:27], v[158:161], v[224:227], v[24:27]
	v_mfma_f32_16x16x32_bf16 v[12:15], v[150:153], v[232:235], v[12:15]
	v_mfma_f32_16x16x32_bf16 v[8:11], v[158:161], v[232:235], v[8:11]
	v_mfma_f32_16x16x32_bf16 v[52:55], v[162:165], v[194:197], v[52:55]
	v_mfma_f32_16x16x32_bf16 v[48:51], v[170:173], v[194:197], v[48:51]
	v_mfma_f32_16x16x32_bf16 v[36:39], v[162:165], v[210:213], v[36:39]
	v_mfma_f32_16x16x32_bf16 v[32:35], v[170:173], v[210:213], v[32:35]
	v_mfma_f32_16x16x32_bf16 v[20:23], v[162:165], v[220:223], v[20:23]
	v_mfma_f32_16x16x32_bf16 v[16:19], v[170:173], v[220:223], v[16:19]
	v_mfma_f32_16x16x32_bf16 v[4:7], v[162:165], v[228:231], v[4:7]
	v_mfma_f32_16x16x32_bf16 v[0:3], v[170:173], v[228:231], v[0:3]
	v_mfma_f32_16x16x32_bf16 v[52:55], v[166:169], v[206:209], v[52:55]
	v_mfma_f32_16x16x32_bf16 v[48:51], v[174:177], v[206:209], v[48:51]
	v_mfma_f32_16x16x32_bf16 v[36:39], v[166:169], v[214:217], v[36:39]
	v_mfma_f32_16x16x32_bf16 v[32:35], v[174:177], v[214:217], v[32:35]
	v_mfma_f32_16x16x32_bf16 v[20:23], v[166:169], v[224:227], v[20:23]
	v_mfma_f32_16x16x32_bf16 v[16:19], v[174:177], v[224:227], v[16:19]
	v_mfma_f32_16x16x32_bf16 v[4:7], v[166:169], v[232:235], v[4:7]
	v_mfma_f32_16x16x32_bf16 v[0:3], v[174:177], v[232:235], v[0:3]
	s_barrier
	s_add_u32 s28, s28, 0x100
	s_addc_u32 s29, s29, 0
	s_add_u32 s10, s10, 0x100
	s_addc_u32 s11, s11, 0
	s_cmp_ge_i32 s30, s47
	s_mov_b32 s16, s30
	s_cbranch_scc0 .LBB0_798

.LBB0_801:
	v_lshl_add_u32 v156, s58, 8, v141
	v_ashrrev_i32_e32 v157, 31, v156
	v_lshl_add_u64 v[146:147], v[156:157], 4, s[14:15]
	global_load_dwordx4 v[146:149], v[146:147], off
	v_or_b32_e32 v154, 16, v156
	v_ashrrev_i32_e32 v155, 31, v154
	v_or_b32_e32 v158, 32, v156
	v_ashrrev_i32_e32 v159, 31, v158
	s_waitcnt vmcnt(0)
	v_or_b32_e32 v160, 48, v156
	v_ashrrev_i32_e32 v161, 31, v160
	v_add_u32_e32 v162, 0x80, v156
	v_ashrrev_i32_e32 v163, 31, v162
	v_add_u32_e32 v164, 0x90, v156
	v_ashrrev_i32_e32 v165, 31, v164
	s_lshl_b32 s10, s57, 8
	s_ashr_i32 s11, s10, 31
	s_lshl_b64 s[16:17], s[10:11], 1
	s_mov_b64 s[10:11], -1
	s_and_b64 vcc, exec, s[40:41]
	s_waitcnt vmcnt(0)
	v_mov_b32_e32 v150, v147
	v_mov_b32_e32 v151, v148
	v_mov_b32_e32 v147, v149
	v_pk_add_f32 v[146:147], v[150:151], v[146:147]
	s_nop 0
	v_add_f32_e32 v140, v146, v147
	v_lshl_add_u64 v[146:147], v[154:155], 4, s[14:15]
	global_load_dwordx4 v[146:149], v[146:147], off
	v_add_f32_e32 v140, 0, v140
	v_fmamk_f32 v140, v140, 0x3b800000, v200
	v_rsq_f32_e32 v140, v140
	s_waitcnt vmcnt(0)
	v_mov_b32_e32 v150, v147
	v_mov_b32_e32 v151, v148
	v_mov_b32_e32 v147, v149
	v_pk_add_f32 v[146:147], v[150:151], v[146:147]
	v_pk_mul_f32 v[124:125], v[124:125], v[140:141] op_sel_hi:[1,0]
	v_add_f32_e32 v142, v146, v147
	v_lshl_add_u64 v[146:147], v[158:159], 4, s[14:15]
	global_load_dwordx4 v[146:149], v[146:147], off
	v_add_f32_e32 v142, 0, v142
	v_fmamk_f32 v142, v142, 0x3b800000, v200
	v_rsq_f32_e32 v142, v142
	v_pk_mul_f32 v[126:127], v[126:127], v[140:141] op_sel_hi:[1,0]
	v_pk_mul_f32 v[118:119], v[118:119], v[140:141] op_sel_hi:[1,0]
	v_pk_mul_f32 v[116:117], v[116:117], v[140:141] op_sel_hi:[1,0]
	v_pk_mul_f32 v[108:109], v[108:109], v[142:143] op_sel_hi:[1,0]
	v_pk_mul_f32 v[110:111], v[110:111], v[142:143] op_sel_hi:[1,0]
	v_pk_mul_f32 v[102:103], v[102:103], v[142:143] op_sel_hi:[1,0]
	v_pk_mul_f32 v[100:101], v[100:101], v[142:143] op_sel_hi:[1,0]
	s_waitcnt vmcnt(0)
	v_mov_b32_e32 v150, v147
	v_mov_b32_e32 v151, v148
	v_mov_b32_e32 v147, v149
	v_pk_add_f32 v[146:147], v[150:151], v[146:147]
	s_nop 0
	v_add_f32_e32 v144, v146, v147
	v_lshl_add_u64 v[146:147], v[160:161], 4, s[14:15]
	global_load_dwordx4 v[146:149], v[146:147], off
	v_add_f32_e32 v144, 0, v144
	v_fmamk_f32 v144, v144, 0x3b800000, v200
	v_rsq_f32_e32 v144, v144
	s_waitcnt vmcnt(0)
	v_mov_b32_e32 v150, v147
	v_mov_b32_e32 v151, v148
	v_mov_b32_e32 v147, v149
	v_lshl_add_u64 v[148:149], v[162:163], 4, s[14:15]
	v_pk_add_f32 v[146:147], v[150:151], v[146:147]
	global_load_dwordx4 v[148:151], v[148:149], off
	v_add_f32_e32 v146, v146, v147
	v_pk_mul_f32 v[92:93], v[92:93], v[144:145] op_sel_hi:[1,0]
	v_add_f32_e32 v146, 0, v146
	v_fmamk_f32 v146, v146, 0x3b800000, v200
	v_rsq_f32_e32 v146, v146
	v_pk_mul_f32 v[94:95], v[94:95], v[144:145] op_sel_hi:[1,0]
	v_pk_mul_f32 v[86:87], v[86:87], v[144:145] op_sel_hi:[1,0]
	v_pk_mul_f32 v[84:85], v[84:85], v[144:145] op_sel_hi:[1,0]
	s_waitcnt vmcnt(0)
	v_mov_b32_e32 v152, v149
	v_mov_b32_e32 v153, v150
	v_mov_b32_e32 v149, v151
	v_lshl_add_u64 v[150:151], v[164:165], 4, s[14:15]
	v_pk_add_f32 v[148:149], v[152:153], v[148:149]
	global_load_dwordx4 v[150:153], v[150:151], off
	v_add_f32_e32 v147, v148, v149
	v_add_f32_e32 v147, 0, v147
	v_fmamk_f32 v147, v147, 0x3b800000, v200
	v_rsq_f32_e32 v148, v147
	s_waitcnt vmcnt(0)
	v_mov_b32_e32 v166, v151
	v_mov_b32_e32 v167, v152
	v_mov_b32_e32 v151, v153
	v_pk_add_f32 v[150:151], v[166:167], v[150:151]
	v_add_u32_e32 v166, 0xa0, v156
	v_ashrrev_i32_e32 v167, 31, v166
	v_lshl_add_u64 v[152:153], v[166:167], 4, s[14:15]
	global_load_dwordx4 v[168:171], v[152:153], off
	v_add_f32_e32 v147, v150, v151
	v_add_f32_e32 v147, 0, v147
	v_fmamk_f32 v147, v147, 0x3b800000, v200
	v_rsq_f32_e32 v150, v147
	v_pk_mul_f32 v[60:61], v[60:61], v[148:149] op_sel_hi:[1,0]
	v_pk_mul_f32 v[62:63], v[62:63], v[148:149] op_sel_hi:[1,0]
	v_pk_mul_f32 v[54:55], v[54:55], v[148:149] op_sel_hi:[1,0]
	v_pk_mul_f32 v[52:53], v[52:53], v[148:149] op_sel_hi:[1,0]
	v_pk_mul_f32 v[44:45], v[44:45], v[150:151] op_sel_hi:[1,0]
	v_pk_mul_f32 v[46:47], v[46:47], v[150:151] op_sel_hi:[1,0]
	v_pk_mul_f32 v[38:39], v[38:39], v[150:151] op_sel_hi:[1,0]
	v_pk_mul_f32 v[36:37], v[36:37], v[150:151] op_sel_hi:[1,0]
	s_waitcnt vmcnt(0)
	v_mov_b32_e32 v152, v169
	v_mov_b32_e32 v153, v170
	v_mov_b32_e32 v169, v171
	v_pk_add_f32 v[152:153], v[152:153], v[168:169]
	v_add_u32_e32 v168, 0xb0, v156
	v_ashrrev_i32_e32 v169, 31, v168
	v_lshl_add_u64 v[170:171], v[168:169], 4, s[14:15]
	global_load_dwordx4 v[170:173], v[170:171], off
	v_lshlrev_b64 v[156:157], 11, v[156:157]
	v_add_f32_e32 v147, v152, v153
	v_add_f32_e32 v147, 0, v147
	v_fmamk_f32 v147, v147, 0x3b800000, v200
	v_rsq_f32_e32 v152, v147
	s_waitcnt vmcnt(0)
	v_mov_b32_e32 v174, v171
	v_mov_b32_e32 v175, v172
	v_mov_b32_e32 v171, v173
	v_pk_mul_f32 v[172:173], v[122:123], v[140:141] op_sel_hi:[1,0]
	v_pk_mul_f32 v[122:123], v[120:121], v[140:141] op_sel_hi:[1,0]
	v_cvt_pk_bf16_f32 v120, v124, v125
	v_lshl_add_u64 v[124:125], s[18:19], 0, v[156:157]
	v_lshl_add_u64 v[124:125], v[124:125], 0, s[16:17]
	v_lshl_add_u64 v[124:125], v[124:125], 0, s[64:65]
	v_cvt_pk_bf16_f32 v121, v126, v127
	v_cvt_pk_bf16_f32 v122, v122, v123
	v_cvt_pk_bf16_f32 v123, v172, v173
	v_lshl_add_u64 v[124:125], v[124:125], 0, v[180:181]
	global_store_dwordx4 v[124:125], v[120:123], off
	v_pk_add_f32 v[170:171], v[174:175], v[170:171]
	v_pk_mul_f32 v[28:29], v[28:29], v[152:153] op_sel_hi:[1,0]
	v_pk_mul_f32 v[120:121], v[114:115], v[140:141] op_sel_hi:[1,0]
	v_pk_mul_f32 v[114:115], v[112:113], v[140:141] op_sel_hi:[1,0]
	v_cvt_pk_bf16_f32 v112, v116, v117
	v_cvt_pk_bf16_f32 v113, v118, v119
	v_cvt_pk_bf16_f32 v114, v114, v115
	v_cvt_pk_bf16_f32 v115, v120, v121
	global_store_dwordx4 v[124:125], v[112:115], off offset:256
	v_add_f32_e32 v147, v170, v171
	v_add_f32_e32 v147, 0, v147
	v_lshlrev_b64 v[112:113], 11, v[154:155]
	v_pk_mul_f32 v[114:115], v[106:107], v[142:143] op_sel_hi:[1,0]
	v_pk_mul_f32 v[106:107], v[104:105], v[142:143] op_sel_hi:[1,0]
	v_cvt_pk_bf16_f32 v104, v108, v109
	v_lshl_add_u64 v[108:109], s[18:19], 0, v[112:113]
	v_lshl_add_u64 v[108:109], v[108:109], 0, s[16:17]
	v_lshl_add_u64 v[108:109], v[108:109], 0, s[64:65]
	v_cvt_pk_bf16_f32 v105, v110, v111
	v_cvt_pk_bf16_f32 v106, v106, v107
	v_cvt_pk_bf16_f32 v107, v114, v115
	v_lshl_add_u64 v[108:109], v[108:109], 0, v[180:181]
	global_store_dwordx4 v[108:109], v[104:107], off
	v_fmamk_f32 v147, v147, 0x3b800000, v200
	v_pk_mul_f32 v[76:77], v[76:77], v[146:147] op_sel_hi:[1,0]
	v_pk_mul_f32 v[104:105], v[98:99], v[142:143] op_sel_hi:[1,0]
	v_pk_mul_f32 v[98:99], v[96:97], v[142:143] op_sel_hi:[1,0]
	v_cvt_pk_bf16_f32 v96, v100, v101
	v_cvt_pk_bf16_f32 v97, v102, v103
	v_cvt_pk_bf16_f32 v98, v98, v99
	v_cvt_pk_bf16_f32 v99, v104, v105
	global_store_dwordx4 v[108:109], v[96:99], off offset:256
	v_pk_mul_f32 v[78:79], v[78:79], v[146:147] op_sel_hi:[1,0]
	v_pk_mul_f32 v[70:71], v[70:71], v[146:147] op_sel_hi:[1,0]
	v_lshlrev_b64 v[96:97], 11, v[158:159]
	v_pk_mul_f32 v[98:99], v[90:91], v[144:145] op_sel_hi:[1,0]
	v_pk_mul_f32 v[90:91], v[88:89], v[144:145] op_sel_hi:[1,0]
	v_cvt_pk_bf16_f32 v88, v92, v93
	v_lshl_add_u64 v[92:93], s[18:19], 0, v[96:97]
	v_lshl_add_u64 v[92:93], v[92:93], 0, s[16:17]
	v_lshl_add_u64 v[92:93], v[92:93], 0, s[64:65]
	v_cvt_pk_bf16_f32 v89, v94, v95
	v_cvt_pk_bf16_f32 v90, v90, v91
	v_cvt_pk_bf16_f32 v91, v98, v99
	v_lshl_add_u64 v[92:93], v[92:93], 0, v[180:181]
	global_store_dwordx4 v[92:93], v[88:91], off
	v_pk_mul_f32 v[68:69], v[68:69], v[146:147] op_sel_hi:[1,0]
	v_rsq_f32_e32 v170, v147
	v_pk_mul_f32 v[88:89], v[82:83], v[144:145] op_sel_hi:[1,0]
	v_pk_mul_f32 v[82:83], v[80:81], v[144:145] op_sel_hi:[1,0]
	v_cvt_pk_bf16_f32 v80, v84, v85
	v_cvt_pk_bf16_f32 v81, v86, v87
	v_cvt_pk_bf16_f32 v82, v82, v83
	v_cvt_pk_bf16_f32 v83, v88, v89
	global_store_dwordx4 v[92:93], v[80:83], off offset:256
	v_pk_mul_f32 v[30:31], v[30:31], v[152:153] op_sel_hi:[1,0]
	v_pk_mul_f32 v[22:23], v[22:23], v[152:153] op_sel_hi:[1,0]
	v_lshlrev_b64 v[80:81], 11, v[160:161]
	v_pk_mul_f32 v[82:83], v[74:75], v[146:147] op_sel_hi:[1,0]
	v_pk_mul_f32 v[74:75], v[72:73], v[146:147] op_sel_hi:[1,0]
	v_cvt_pk_bf16_f32 v72, v76, v77
	v_lshl_add_u64 v[76:77], s[18:19], 0, v[80:81]
	v_lshl_add_u64 v[76:77], v[76:77], 0, s[16:17]
	v_lshl_add_u64 v[76:77], v[76:77], 0, s[64:65]
	v_cvt_pk_bf16_f32 v73, v78, v79
	v_cvt_pk_bf16_f32 v74, v74, v75
	v_cvt_pk_bf16_f32 v75, v82, v83
	v_lshl_add_u64 v[76:77], v[76:77], 0, v[180:181]
	global_store_dwordx4 v[76:77], v[72:75], off
	v_pk_mul_f32 v[20:21], v[20:21], v[152:153] op_sel_hi:[1,0]
	v_pk_mul_f32 v[12:13], v[12:13], v[170:171] op_sel_hi:[1,0]
	v_pk_mul_f32 v[72:73], v[66:67], v[146:147] op_sel_hi:[1,0]
	v_pk_mul_f32 v[66:67], v[64:65], v[146:147] op_sel_hi:[1,0]
	v_cvt_pk_bf16_f32 v64, v68, v69
	v_cvt_pk_bf16_f32 v65, v70, v71
	v_cvt_pk_bf16_f32 v66, v66, v67
	v_cvt_pk_bf16_f32 v67, v72, v73
	global_store_dwordx4 v[76:77], v[64:67], off offset:256
	v_pk_mul_f32 v[14:15], v[14:15], v[170:171] op_sel_hi:[1,0]
	v_pk_mul_f32 v[6:7], v[6:7], v[170:171] op_sel_hi:[1,0]
	v_lshlrev_b64 v[64:65], 11, v[162:163]
	v_pk_mul_f32 v[66:67], v[58:59], v[148:149] op_sel_hi:[1,0]
	v_pk_mul_f32 v[58:59], v[56:57], v[148:149] op_sel_hi:[1,0]
	v_cvt_pk_bf16_f32 v56, v60, v61
	v_lshl_add_u64 v[60:61], s[18:19], 0, v[64:65]
	v_lshl_add_u64 v[60:61], v[60:61], 0, s[16:17]
	v_lshl_add_u64 v[60:61], v[60:61], 0, s[64:65]
	v_cvt_pk_bf16_f32 v57, v62, v63
	v_cvt_pk_bf16_f32 v58, v58, v59
	v_cvt_pk_bf16_f32 v59, v66, v67
	v_lshl_add_u64 v[60:61], v[60:61], 0, v[180:181]
	global_store_dwordx4 v[60:61], v[56:59], off
	v_pk_mul_f32 v[4:5], v[4:5], v[170:171] op_sel_hi:[1,0]
	s_nop 0
	v_pk_mul_f32 v[56:57], v[50:51], v[148:149] op_sel_hi:[1,0]
	v_pk_mul_f32 v[50:51], v[48:49], v[148:149] op_sel_hi:[1,0]
	v_cvt_pk_bf16_f32 v48, v52, v53
	v_cvt_pk_bf16_f32 v49, v54, v55
	v_cvt_pk_bf16_f32 v50, v50, v51
	v_cvt_pk_bf16_f32 v51, v56, v57
	global_store_dwordx4 v[60:61], v[48:51], off offset:256
	s_nop 1
	v_lshlrev_b64 v[48:49], 11, v[164:165]
	v_pk_mul_f32 v[50:51], v[42:43], v[150:151] op_sel_hi:[1,0]
	v_pk_mul_f32 v[42:43], v[40:41], v[150:151] op_sel_hi:[1,0]
	v_cvt_pk_bf16_f32 v40, v44, v45
	v_lshl_add_u64 v[44:45], s[18:19], 0, v[48:49]
	v_lshl_add_u64 v[44:45], v[44:45], 0, s[16:17]
	v_lshl_add_u64 v[44:45], v[44:45], 0, s[64:65]
	v_cvt_pk_bf16_f32 v41, v46, v47
	v_cvt_pk_bf16_f32 v42, v42, v43
	v_cvt_pk_bf16_f32 v43, v50, v51
	v_lshl_add_u64 v[44:45], v[44:45], 0, v[180:181]
	global_store_dwordx4 v[44:45], v[40:43], off
	s_nop 1
	v_pk_mul_f32 v[40:41], v[34:35], v[150:151] op_sel_hi:[1,0]
	v_pk_mul_f32 v[34:35], v[32:33], v[150:151] op_sel_hi:[1,0]
	v_cvt_pk_bf16_f32 v32, v36, v37
	v_cvt_pk_bf16_f32 v33, v38, v39
	v_cvt_pk_bf16_f32 v34, v34, v35
	v_cvt_pk_bf16_f32 v35, v40, v41
	global_store_dwordx4 v[44:45], v[32:35], off offset:256
	s_nop 1
	v_lshlrev_b64 v[32:33], 11, v[166:167]
	v_pk_mul_f32 v[34:35], v[26:27], v[152:153] op_sel_hi:[1,0]
	v_pk_mul_f32 v[26:27], v[24:25], v[152:153] op_sel_hi:[1,0]
	v_cvt_pk_bf16_f32 v24, v28, v29
	v_lshl_add_u64 v[28:29], s[18:19], 0, v[32:33]
	v_lshl_add_u64 v[28:29], v[28:29], 0, s[16:17]
	v_lshl_add_u64 v[28:29], v[28:29], 0, s[64:65]
	v_cvt_pk_bf16_f32 v25, v30, v31
	v_cvt_pk_bf16_f32 v26, v26, v27
	v_cvt_pk_bf16_f32 v27, v34, v35
	v_lshl_add_u64 v[28:29], v[28:29], 0, v[180:181]
	global_store_dwordx4 v[28:29], v[24:27], off
	s_nop 1
	v_pk_mul_f32 v[24:25], v[18:19], v[152:153] op_sel_hi:[1,0]
	v_pk_mul_f32 v[18:19], v[16:17], v[152:153] op_sel_hi:[1,0]
	v_cvt_pk_bf16_f32 v16, v20, v21
	v_cvt_pk_bf16_f32 v17, v22, v23
	v_cvt_pk_bf16_f32 v18, v18, v19
	v_cvt_pk_bf16_f32 v19, v24, v25
	global_store_dwordx4 v[28:29], v[16:19], off offset:256
	s_nop 1
	v_lshlrev_b64 v[16:17], 11, v[168:169]
	v_pk_mul_f32 v[18:19], v[10:11], v[170:171] op_sel_hi:[1,0]
	v_pk_mul_f32 v[10:11], v[8:9], v[170:171] op_sel_hi:[1,0]
	v_cvt_pk_bf16_f32 v8, v12, v13
	v_lshl_add_u64 v[12:13], s[18:19], 0, v[16:17]
	v_lshl_add_u64 v[12:13], v[12:13], 0, s[16:17]
	v_lshl_add_u64 v[12:13], v[12:13], 0, s[64:65]
	v_cvt_pk_bf16_f32 v9, v14, v15
	v_cvt_pk_bf16_f32 v10, v10, v11
	v_cvt_pk_bf16_f32 v11, v18, v19
	v_lshl_add_u64 v[12:13], v[12:13], 0, v[180:181]
	global_store_dwordx4 v[12:13], v[8:11], off
	s_nop 1
	v_pk_mul_f32 v[8:9], v[2:3], v[170:171] op_sel_hi:[1,0]
	v_pk_mul_f32 v[2:3], v[0:1], v[170:171] op_sel_hi:[1,0]
	v_cvt_pk_bf16_f32 v0, v4, v5
	v_cvt_pk_bf16_f32 v1, v6, v7
	v_cvt_pk_bf16_f32 v2, v2, v3
	v_cvt_pk_bf16_f32 v3, v8, v9
	global_store_dwordx4 v[12:13], v[0:3], off offset:256
	s_cbranch_vccnz .LBB0_785
	s_andn2_b64 vcc, exec, s[8:9]
	s_cbranch_vccnz .LBB0_784
	s_mov_b32 s100, 1
	s_branch .LBB0_784

.LBB0_821:
	v_mov_b32_e32 v123, 0
	s_andn2_b64 vcc, exec, s[18:19]
	v_mov_b32_e32 v122, v123
	v_mov_b32_e32 v121, v123
	v_mov_b32_e32 v120, v123
	v_mov_b32_e32 v127, v123
	v_mov_b32_e32 v126, v123
	v_mov_b32_e32 v125, v123
	v_mov_b32_e32 v124, v123
	v_mov_b32_e32 v119, v123
	v_mov_b32_e32 v118, v123
	v_mov_b32_e32 v117, v123
	v_mov_b32_e32 v116, v123
	v_mov_b32_e32 v115, v123
	v_mov_b32_e32 v114, v123
	v_mov_b32_e32 v113, v123
	v_mov_b32_e32 v112, v123
	v_mov_b32_e32 v111, v123
	v_mov_b32_e32 v110, v123
	v_mov_b32_e32 v109, v123
	v_mov_b32_e32 v108, v123
	v_mov_b32_e32 v107, v123
	v_mov_b32_e32 v106, v123
	v_mov_b32_e32 v105, v123
	v_mov_b32_e32 v104, v123
	v_mov_b32_e32 v103, v123
	v_mov_b32_e32 v102, v123
	v_mov_b32_e32 v101, v123
	v_mov_b32_e32 v100, v123
	v_mov_b32_e32 v99, v123
	v_mov_b32_e32 v98, v123
	v_mov_b32_e32 v97, v123
	v_mov_b32_e32 v96, v123
	v_mov_b32_e32 v63, v123
	v_mov_b32_e32 v62, v123
	v_mov_b32_e32 v61, v123
	v_mov_b32_e32 v60, v123
	v_mov_b32_e32 v59, v123
	v_mov_b32_e32 v58, v123
	v_mov_b32_e32 v57, v123
	v_mov_b32_e32 v56, v123
	v_mov_b32_e32 v55, v123
	v_mov_b32_e32 v54, v123
	v_mov_b32_e32 v53, v123
	v_mov_b32_e32 v52, v123
	v_mov_b32_e32 v51, v123
	v_mov_b32_e32 v50, v123
	v_mov_b32_e32 v49, v123
	v_mov_b32_e32 v48, v123
	v_mov_b32_e32 v47, v123
	v_mov_b32_e32 v46, v123
	v_mov_b32_e32 v45, v123
	v_mov_b32_e32 v44, v123
	v_mov_b32_e32 v43, v123
	v_mov_b32_e32 v42, v123
	v_mov_b32_e32 v41, v123
	v_mov_b32_e32 v40, v123
	v_mov_b32_e32 v39, v123
	v_mov_b32_e32 v38, v123
	v_mov_b32_e32 v37, v123
	v_mov_b32_e32 v36, v123
	v_mov_b32_e32 v35, v123
	v_mov_b32_e32 v34, v123
	v_mov_b32_e32 v33, v123
	v_mov_b32_e32 v32, v123
	v_mov_b32_e32 v95, v123
	v_mov_b32_e32 v94, v123
	v_mov_b32_e32 v93, v123
	v_mov_b32_e32 v92, v123
	v_mov_b32_e32 v91, v123
	v_mov_b32_e32 v90, v123
	v_mov_b32_e32 v89, v123
	v_mov_b32_e32 v88, v123
	v_mov_b32_e32 v87, v123
	v_mov_b32_e32 v86, v123
	v_mov_b32_e32 v85, v123
	v_mov_b32_e32 v84, v123
	v_mov_b32_e32 v83, v123
	v_mov_b32_e32 v82, v123
	v_mov_b32_e32 v81, v123
	v_mov_b32_e32 v80, v123
	v_mov_b32_e32 v79, v123
	v_mov_b32_e32 v78, v123
	v_mov_b32_e32 v77, v123
	v_mov_b32_e32 v76, v123
	v_mov_b32_e32 v75, v123
	v_mov_b32_e32 v74, v123
	v_mov_b32_e32 v73, v123
	v_mov_b32_e32 v72, v123
	v_mov_b32_e32 v71, v123
	v_mov_b32_e32 v70, v123
	v_mov_b32_e32 v69, v123
	v_mov_b32_e32 v68, v123
	v_mov_b32_e32 v67, v123
	v_mov_b32_e32 v66, v123
	v_mov_b32_e32 v65, v123
	v_mov_b32_e32 v64, v123
	v_mov_b32_e32 v31, v123
	v_mov_b32_e32 v30, v123
	v_mov_b32_e32 v29, v123
	v_mov_b32_e32 v28, v123
	v_mov_b32_e32 v27, v123
	v_mov_b32_e32 v26, v123
	v_mov_b32_e32 v25, v123
	v_mov_b32_e32 v24, v123
	v_mov_b32_e32 v23, v123
	v_mov_b32_e32 v22, v123
	v_mov_b32_e32 v21, v123
	v_mov_b32_e32 v20, v123
	v_mov_b32_e32 v19, v123
	v_mov_b32_e32 v18, v123
	v_mov_b32_e32 v17, v123
	v_mov_b32_e32 v16, v123
	v_mov_b32_e32 v15, v123
	v_mov_b32_e32 v14, v123
	v_mov_b32_e32 v13, v123
	v_mov_b32_e32 v12, v123
	v_mov_b32_e32 v11, v123
	v_mov_b32_e32 v10, v123
	v_mov_b32_e32 v9, v123
	v_mov_b32_e32 v8, v123
	v_mov_b32_e32 v7, v123
	v_mov_b32_e32 v6, v123
	v_mov_b32_e32 v5, v123
	v_mov_b32_e32 v4, v123
	v_mov_b32_e32 v3, v123
	v_mov_b32_e32 v2, v123
	v_mov_b32_e32 v1, v123
	v_mov_b32_e32 v0, v123
	s_cbranch_vccnz .LBB0_824
	s_add_u32 s26, s26, 0x80
	s_addc_u32 s27, s27, 0
	s_add_u32 s10, s28, 0x100
	s_addc_u32 s11, s29, 0
	s_mov_b32 s16, 0
	s_cmp_lg_u32 s100, 0
	s_cbranch_scc0 .Llbb_7
	s_barrier
	s_mov_b32 s100, 0
.Llbb_7:
.LBB0_823:
	s_add_i32 s28, s16, 2
	s_add_u32 s29, s26, 0x80
	s_addc_u32 s17, s27, 0
	s_add_i32 s59, 0, 0x10000
	s_cmp_eq_u32 s48, s16
	s_cselect_b32 s17, s23, s17
	s_cselect_b32 s16, s22, s29
	v_add_u32_e32 v140, s59, v143
	s_cselect_b32 s43, s25, s11
	s_cselect_b32 s42, s24, s10
	s_add_i32 s29, 0, 0x14000
	ds_read_b128 v[146:149], v140
	ds_read_b128 v[150:153], v140 offset:1024
	ds_read_b128 v[154:157], v140 offset:2048
	s_waitcnt vmcnt(0)
	ds_read_b128 v[158:161], v140 offset:3072
	v_add_u32_e32 v140, s29, v143
	ds_read_b128 v[162:165], v140
	ds_read_b128 v[166:169], v140 offset:1024
	ds_read_b128 v[170:173], v140 offset:2048
	ds_read_b128 v[174:177], v140 offset:3072
	v_lshl_add_u64 v[140:141], s[26:27], 0, v[136:137]
	s_add_i32 m0, s35, 0xc000
	ds_read_b128 v[194:197], v145
	ds_read_b128 v[206:209], v145 offset:1024
	ds_read_b128 v[210:213], v145 offset:2048
	ds_read_b128 v[214:217], v145 offset:3072
	ds_read_b128 v[220:223], v145 offset:4096
	ds_read_b128 v[224:227], v145 offset:5120
	ds_read_b128 v[228:231], v145 offset:6144
	ds_read_b128 v[232:235], v145 offset:7168
	global_load_lds_dwordx4 v[140:141], off
	v_lshl_add_u64 v[140:141], s[26:27], 0, v[138:139]
	s_add_i32 m0, s35, 0xe000
	s_nop 0
	global_load_lds_dwordx4 v[140:141], off
	s_waitcnt vmcnt(8)
	s_waitcnt lgkmcnt(0)
	s_barrier
	s_waitcnt lgkmcnt(0)
	v_mfma_f32_16x16x32_bf16 v[120:123], v[146:149], v[194:197], v[120:123]
	v_mfma_f32_16x16x32_bf16 v[124:127], v[154:157], v[194:197], v[124:127]
	v_mfma_f32_16x16x32_bf16 v[116:119], v[146:149], v[210:213], v[116:119]
	v_mfma_f32_16x16x32_bf16 v[112:115], v[154:157], v[210:213], v[112:115]
	v_mfma_f32_16x16x32_bf16 v[108:111], v[146:149], v[220:223], v[108:111]
	v_mfma_f32_16x16x32_bf16 v[104:107], v[154:157], v[220:223], v[104:107]
	v_mfma_f32_16x16x32_bf16 v[100:103], v[146:149], v[228:231], v[100:103]
	v_mfma_f32_16x16x32_bf16 v[96:99], v[154:157], v[228:231], v[96:99]
	v_mfma_f32_16x16x32_bf16 v[120:123], v[150:153], v[206:209], v[120:123]
	v_mfma_f32_16x16x32_bf16 v[124:127], v[158:161], v[206:209], v[124:127]
	v_mfma_f32_16x16x32_bf16 v[116:119], v[150:153], v[214:217], v[116:119]
	v_mfma_f32_16x16x32_bf16 v[112:115], v[158:161], v[214:217], v[112:115]
	v_mfma_f32_16x16x32_bf16 v[108:111], v[150:153], v[224:227], v[108:111]
	v_mfma_f32_16x16x32_bf16 v[104:107], v[158:161], v[224:227], v[104:107]
	v_mfma_f32_16x16x32_bf16 v[100:103], v[150:153], v[232:235], v[100:103]
	v_mfma_f32_16x16x32_bf16 v[96:99], v[158:161], v[232:235], v[96:99]
	v_mfma_f32_16x16x32_bf16 v[60:63], v[162:165], v[194:197], v[60:63]
	v_mfma_f32_16x16x32_bf16 v[56:59], v[170:173], v[194:197], v[56:59]
	v_mfma_f32_16x16x32_bf16 v[52:55], v[162:165], v[210:213], v[52:55]
	v_mfma_f32_16x16x32_bf16 v[48:51], v[170:173], v[210:213], v[48:51]
	v_mfma_f32_16x16x32_bf16 v[44:47], v[162:165], v[220:223], v[44:47]
	v_mfma_f32_16x16x32_bf16 v[40:43], v[170:173], v[220:223], v[40:43]
	v_mfma_f32_16x16x32_bf16 v[36:39], v[162:165], v[228:231], v[36:39]
	v_mfma_f32_16x16x32_bf16 v[32:35], v[170:173], v[228:231], v[32:35]
	v_mfma_f32_16x16x32_bf16 v[60:63], v[166:169], v[206:209], v[60:63]
	v_mfma_f32_16x16x32_bf16 v[56:59], v[174:177], v[206:209], v[56:59]
	v_mfma_f32_16x16x32_bf16 v[52:55], v[166:169], v[214:217], v[52:55]
	v_mfma_f32_16x16x32_bf16 v[48:51], v[174:177], v[214:217], v[48:51]
	v_mfma_f32_16x16x32_bf16 v[44:47], v[166:169], v[224:227], v[44:47]
	v_mfma_f32_16x16x32_bf16 v[40:43], v[174:177], v[224:227], v[40:43]
	v_mfma_f32_16x16x32_bf16 v[36:39], v[166:169], v[232:235], v[36:39]
	v_mfma_f32_16x16x32_bf16 v[32:35], v[174:177], v[232:235], v[32:35]
	s_barrier
	s_add_i32 s59, s59, s34
	v_lshl_add_u64 v[140:141], s[42:43], 0, v[132:133]
	s_mov_b32 m0, s59
	ds_read_b128 v[194:197], v145 offset:16384
	ds_read_b128 v[206:209], v145 offset:17408
	ds_read_b128 v[210:213], v145 offset:18432
	ds_read_b128 v[214:217], v145 offset:19456
	ds_read_b128 v[220:223], v145 offset:20480
	ds_read_b128 v[224:227], v145 offset:21504
	ds_read_b128 v[228:231], v145 offset:22528
	ds_read_b128 v[232:235], v145 offset:23552
	global_load_lds_dwordx4 v[140:141], off
	s_add_i32 m0, s59, 0x2000
	v_lshl_add_u64 v[178:179], s[42:43], 0, v[128:129]
	s_add_u32 s42, s42, s0
	s_addc_u32 s43, s43, s1
	s_add_i32 s29, s29, s34
	global_load_lds_dwordx4 v[178:179], off
	v_lshl_add_u64 v[198:199], s[42:43], 0, v[132:133]
	s_mov_b32 m0, s29
	v_lshl_add_u64 v[202:203], s[42:43], 0, v[128:129]
	global_load_lds_dwordx4 v[198:199], off
	s_add_i32 m0, s29, 0x2000
	v_lshl_add_u64 v[236:237], s[16:17], 0, v[134:135]
	global_load_lds_dwordx4 v[202:203], off
	s_mov_b32 m0, s35
	v_lshl_add_u64 v[238:239], s[16:17], 0, v[130:131]
	global_load_lds_dwordx4 v[236:237], off
	s_mov_b32 m0, s36
	s_nop 0
	global_load_lds_dwordx4 v[238:239], off
	s_waitcnt vmcnt(8)
	s_waitcnt lgkmcnt(0)
	s_barrier
	s_waitcnt lgkmcnt(0)
	v_mfma_f32_16x16x32_bf16 v[92:95], v[146:149], v[194:197], v[92:95]
	v_mfma_f32_16x16x32_bf16 v[88:91], v[154:157], v[194:197], v[88:91]
	v_mfma_f32_16x16x32_bf16 v[84:87], v[146:149], v[210:213], v[84:87]
	v_mfma_f32_16x16x32_bf16 v[80:83], v[154:157], v[210:213], v[80:83]
	v_mfma_f32_16x16x32_bf16 v[76:79], v[146:149], v[220:223], v[76:79]
	v_mfma_f32_16x16x32_bf16 v[72:75], v[154:157], v[220:223], v[72:75]
	v_mfma_f32_16x16x32_bf16 v[68:71], v[146:149], v[228:231], v[68:71]
	v_mfma_f32_16x16x32_bf16 v[64:67], v[154:157], v[228:231], v[64:67]
	v_mfma_f32_16x16x32_bf16 v[92:95], v[150:153], v[206:209], v[92:95]
	v_mfma_f32_16x16x32_bf16 v[88:91], v[158:161], v[206:209], v[88:91]
	v_mfma_f32_16x16x32_bf16 v[84:87], v[150:153], v[214:217], v[84:87]
	v_mfma_f32_16x16x32_bf16 v[80:83], v[158:161], v[214:217], v[80:83]
	v_mfma_f32_16x16x32_bf16 v[76:79], v[150:153], v[224:227], v[76:79]
	v_mfma_f32_16x16x32_bf16 v[72:75], v[158:161], v[224:227], v[72:75]
	v_mfma_f32_16x16x32_bf16 v[68:71], v[150:153], v[232:235], v[68:71]
	v_mfma_f32_16x16x32_bf16 v[64:67], v[158:161], v[232:235], v[64:67]
	v_mfma_f32_16x16x32_bf16 v[28:31], v[162:165], v[194:197], v[28:31]
	v_mfma_f32_16x16x32_bf16 v[24:27], v[170:173], v[194:197], v[24:27]
	v_mfma_f32_16x16x32_bf16 v[20:23], v[162:165], v[210:213], v[20:23]
	v_mfma_f32_16x16x32_bf16 v[16:19], v[170:173], v[210:213], v[16:19]
	v_mfma_f32_16x16x32_bf16 v[12:15], v[162:165], v[220:223], v[12:15]
	v_mfma_f32_16x16x32_bf16 v[8:11], v[170:173], v[220:223], v[8:11]
	v_mfma_f32_16x16x32_bf16 v[4:7], v[162:165], v[228:231], v[4:7]
	v_mfma_f32_16x16x32_bf16 v[0:3], v[170:173], v[228:231], v[0:3]
	v_mfma_f32_16x16x32_bf16 v[28:31], v[166:169], v[206:209], v[28:31]
	v_mfma_f32_16x16x32_bf16 v[24:27], v[174:177], v[206:209], v[24:27]
	v_mfma_f32_16x16x32_bf16 v[20:23], v[166:169], v[214:217], v[20:23]
	v_mfma_f32_16x16x32_bf16 v[16:19], v[174:177], v[214:217], v[16:19]
	v_mfma_f32_16x16x32_bf16 v[12:15], v[166:169], v[224:227], v[12:15]
	v_mfma_f32_16x16x32_bf16 v[8:11], v[174:177], v[224:227], v[8:11]
	v_mfma_f32_16x16x32_bf16 v[4:7], v[166:169], v[232:235], v[4:7]
	v_mfma_f32_16x16x32_bf16 v[0:3], v[174:177], v[232:235], v[0:3]
	s_barrier
	s_add_i32 s29, 0, 0x18000
	s_add_i32 s42, 0, 0x1c000
	v_add_u32_e32 v158, s29, v143
	v_add_u32_e32 v174, s42, v143
	ds_read_b128 v[146:149], v158
	ds_read_b128 v[150:153], v158 offset:1024
	ds_read_b128 v[154:157], v158 offset:2048
	ds_read_b128 v[158:161], v158 offset:3072
	ds_read_b128 v[162:165], v174
	ds_read_b128 v[166:169], v174 offset:1024
	ds_read_b128 v[170:173], v174 offset:2048
	ds_read_b128 v[174:177], v174 offset:3072
	s_add_u32 s16, s16, s0
	s_addc_u32 s17, s17, s1
	s_mov_b32 m0, s37
	v_lshl_add_u64 v[240:241], s[16:17], 0, v[134:135]
	ds_read_b128 v[194:197], v145 offset:32768
	ds_read_b128 v[206:209], v145 offset:33792
	ds_read_b128 v[210:213], v145 offset:34816
	ds_read_b128 v[214:217], v145 offset:35840
	ds_read_b128 v[220:223], v145 offset:36864
	ds_read_b128 v[224:227], v145 offset:37888
	ds_read_b128 v[228:231], v145 offset:38912
	ds_read_b128 v[232:235], v145 offset:39936
	global_load_lds_dwordx4 v[240:241], off
	v_lshl_add_u64 v[240:241], s[16:17], 0, v[130:131]
	s_mov_b32 m0, s38
	s_nop 0
	global_load_lds_dwordx4 v[240:241], off
	s_waitcnt vmcnt(8)
	s_waitcnt lgkmcnt(0)
	s_barrier
	s_waitcnt lgkmcnt(0)
	v_mfma_f32_16x16x32_bf16 v[120:123], v[146:149], v[194:197], v[120:123]
	v_mfma_f32_16x16x32_bf16 v[124:127], v[154:157], v[194:197], v[124:127]
	v_mfma_f32_16x16x32_bf16 v[116:119], v[146:149], v[210:213], v[116:119]
	v_mfma_f32_16x16x32_bf16 v[112:115], v[154:157], v[210:213], v[112:115]
	v_mfma_f32_16x16x32_bf16 v[108:111], v[146:149], v[220:223], v[108:111]
	v_mfma_f32_16x16x32_bf16 v[104:107], v[154:157], v[220:223], v[104:107]
	v_mfma_f32_16x16x32_bf16 v[100:103], v[146:149], v[228:231], v[100:103]
	v_mfma_f32_16x16x32_bf16 v[96:99], v[154:157], v[228:231], v[96:99]
	v_mfma_f32_16x16x32_bf16 v[120:123], v[150:153], v[206:209], v[120:123]
	v_mfma_f32_16x16x32_bf16 v[124:127], v[158:161], v[206:209], v[124:127]
	v_mfma_f32_16x16x32_bf16 v[116:119], v[150:153], v[214:217], v[116:119]
	v_mfma_f32_16x16x32_bf16 v[112:115], v[158:161], v[214:217], v[112:115]
	v_mfma_f32_16x16x32_bf16 v[108:111], v[150:153], v[224:227], v[108:111]
	v_mfma_f32_16x16x32_bf16 v[104:107], v[158:161], v[224:227], v[104:107]
	v_mfma_f32_16x16x32_bf16 v[100:103], v[150:153], v[232:235], v[100:103]
	v_mfma_f32_16x16x32_bf16 v[96:99], v[158:161], v[232:235], v[96:99]
	v_mfma_f32_16x16x32_bf16 v[60:63], v[162:165], v[194:197], v[60:63]
	v_mfma_f32_16x16x32_bf16 v[56:59], v[170:173], v[194:197], v[56:59]
	v_mfma_f32_16x16x32_bf16 v[52:55], v[162:165], v[210:213], v[52:55]
	v_mfma_f32_16x16x32_bf16 v[48:51], v[170:173], v[210:213], v[48:51]
	v_mfma_f32_16x16x32_bf16 v[44:47], v[162:165], v[220:223], v[44:47]
	v_mfma_f32_16x16x32_bf16 v[40:43], v[170:173], v[220:223], v[40:43]
	v_mfma_f32_16x16x32_bf16 v[36:39], v[162:165], v[228:231], v[36:39]
	v_mfma_f32_16x16x32_bf16 v[32:35], v[170:173], v[228:231], v[32:35]
	v_mfma_f32_16x16x32_bf16 v[60:63], v[166:169], v[206:209], v[60:63]
	v_mfma_f32_16x16x32_bf16 v[56:59], v[174:177], v[206:209], v[56:59]
	v_mfma_f32_16x16x32_bf16 v[52:55], v[166:169], v[214:217], v[52:55]
	v_mfma_f32_16x16x32_bf16 v[48:51], v[174:177], v[214:217], v[48:51]
	v_mfma_f32_16x16x32_bf16 v[44:47], v[166:169], v[224:227], v[44:47]
	v_mfma_f32_16x16x32_bf16 v[40:43], v[174:177], v[224:227], v[40:43]
	v_mfma_f32_16x16x32_bf16 v[36:39], v[166:169], v[232:235], v[36:39]
	v_mfma_f32_16x16x32_bf16 v[32:35], v[174:177], v[232:235], v[32:35]
	s_barrier
	s_add_i32 s16, s29, s34
	v_lshl_add_u64 v[140:141], v[140:141], 0, s[12:13]
	s_mov_b32 m0, s16
	ds_read_b128 v[194:197], v145 offset:49152
	ds_read_b128 v[206:209], v145 offset:50176
	ds_read_b128 v[210:213], v145 offset:51200
	ds_read_b128 v[214:217], v145 offset:52224
	ds_read_b128 v[220:223], v145 offset:53248
	ds_read_b128 v[224:227], v145 offset:54272
	ds_read_b128 v[228:231], v145 offset:55296
	ds_read_b128 v[232:235], v145 offset:56320
	global_load_lds_dwordx4 v[140:141], off
	v_lshl_add_u64 v[140:141], v[178:179], 0, s[12:13]
	s_add_i32 m0, s16, 0x2000
	s_add_i32 s16, s42, s34
	global_load_lds_dwordx4 v[140:141], off
	v_lshl_add_u64 v[140:141], v[198:199], 0, s[12:13]
	s_mov_b32 m0, s16
	s_nop 0
	global_load_lds_dwordx4 v[140:141], off
	v_lshl_add_u64 v[140:141], v[202:203], 0, s[12:13]
	s_add_i32 m0, s16, 0x2000
	s_nop 0
	global_load_lds_dwordx4 v[140:141], off
	v_lshl_add_u64 v[140:141], v[236:237], 0, s[12:13]
	s_mov_b32 m0, s46
	s_nop 0
	global_load_lds_dwordx4 v[140:141], off
	v_lshl_add_u64 v[140:141], v[238:239], 0, s[12:13]
	s_mov_b32 m0, s47
	s_nop 0
	global_load_lds_dwordx4 v[140:141], off
	s_waitcnt vmcnt(8)
	s_waitcnt lgkmcnt(0)
	s_barrier
	s_waitcnt lgkmcnt(0)
	v_mfma_f32_16x16x32_bf16 v[92:95], v[146:149], v[194:197], v[92:95]
	v_mfma_f32_16x16x32_bf16 v[88:91], v[154:157], v[194:197], v[88:91]
	v_mfma_f32_16x16x32_bf16 v[84:87], v[146:149], v[210:213], v[84:87]
	v_mfma_f32_16x16x32_bf16 v[80:83], v[154:157], v[210:213], v[80:83]
	v_mfma_f32_16x16x32_bf16 v[76:79], v[146:149], v[220:223], v[76:79]
	v_mfma_f32_16x16x32_bf16 v[72:75], v[154:157], v[220:223], v[72:75]
	v_mfma_f32_16x16x32_bf16 v[68:71], v[146:149], v[228:231], v[68:71]
	v_mfma_f32_16x16x32_bf16 v[64:67], v[154:157], v[228:231], v[64:67]
	v_mfma_f32_16x16x32_bf16 v[92:95], v[150:153], v[206:209], v[92:95]
	v_mfma_f32_16x16x32_bf16 v[88:91], v[158:161], v[206:209], v[88:91]
	v_mfma_f32_16x16x32_bf16 v[84:87], v[150:153], v[214:217], v[84:87]
	v_mfma_f32_16x16x32_bf16 v[80:83], v[158:161], v[214:217], v[80:83]
	v_mfma_f32_16x16x32_bf16 v[76:79], v[150:153], v[224:227], v[76:79]
	v_mfma_f32_16x16x32_bf16 v[72:75], v[158:161], v[224:227], v[72:75]
	v_mfma_f32_16x16x32_bf16 v[68:71], v[150:153], v[232:235], v[68:71]
	v_mfma_f32_16x16x32_bf16 v[64:67], v[158:161], v[232:235], v[64:67]
	v_mfma_f32_16x16x32_bf16 v[28:31], v[162:165], v[194:197], v[28:31]
	v_mfma_f32_16x16x32_bf16 v[24:27], v[170:173], v[194:197], v[24:27]
	v_mfma_f32_16x16x32_bf16 v[20:23], v[162:165], v[210:213], v[20:23]
	v_mfma_f32_16x16x32_bf16 v[16:19], v[170:173], v[210:213], v[16:19]
	v_mfma_f32_16x16x32_bf16 v[12:15], v[162:165], v[220:223], v[12:15]
	v_mfma_f32_16x16x32_bf16 v[8:11], v[170:173], v[220:223], v[8:11]
	v_mfma_f32_16x16x32_bf16 v[4:7], v[162:165], v[228:231], v[4:7]
	v_mfma_f32_16x16x32_bf16 v[0:3], v[170:173], v[228:231], v[0:3]
	v_mfma_f32_16x16x32_bf16 v[28:31], v[166:169], v[206:209], v[28:31]
	v_mfma_f32_16x16x32_bf16 v[24:27], v[174:177], v[206:209], v[24:27]
	v_mfma_f32_16x16x32_bf16 v[20:23], v[166:169], v[214:217], v[20:23]
	v_mfma_f32_16x16x32_bf16 v[16:19], v[174:177], v[214:217], v[16:19]
	v_mfma_f32_16x16x32_bf16 v[12:15], v[166:169], v[224:227], v[12:15]
	v_mfma_f32_16x16x32_bf16 v[8:11], v[174:177], v[224:227], v[8:11]
	v_mfma_f32_16x16x32_bf16 v[4:7], v[166:169], v[232:235], v[4:7]
	v_mfma_f32_16x16x32_bf16 v[0:3], v[174:177], v[232:235], v[0:3]
	s_barrier
	s_add_u32 s26, s26, 0x100
	s_addc_u32 s27, s27, 0
	s_add_u32 s10, s10, 0x100
	s_addc_u32 s11, s11, 0
	s_cmp_ge_i32 s28, s45
	s_mov_b32 s16, s28
	s_cbranch_scc0 .LBB0_823

.LBB0_826:
	s_lshl_b32 s16, s57, 8
	v_or_b32_e32 v140, s16, v144
	v_ashrrev_i32_e32 v141, 31, v140
	s_waitcnt vmcnt(0)
	v_or_b32_e32 v162, 4, v140
	v_lshl_add_u64 v[158:159], v[140:141], 4, s[14:15]
	v_ashrrev_i32_e32 v163, 31, v162
	global_load_dwordx4 v[146:149], v[158:159], off
	global_load_dwordx4 v[150:153], v[158:159], off offset:16
	global_load_dwordx4 v[154:157], v[158:159], off offset:32
	s_nop 0
	global_load_dwordx4 v[158:161], v[158:159], off offset:48
	v_lshl_add_u64 v[174:175], v[162:163], 4, s[14:15]
	global_load_dwordx4 v[162:165], v[174:175], off
	global_load_dwordx4 v[166:169], v[174:175], off offset:16
	global_load_dwordx4 v[170:173], v[174:175], off offset:32
	s_nop 0
	global_load_dwordx4 v[174:177], v[174:175], off offset:48
	s_ashr_i32 s10, s57, 3
	s_ashr_i32 s11, s10, 31
	v_lshl_add_u32 v178, s58, 8, v142
	s_lshl_b64 s[10:11], s[10:11], 22
	v_bitop3_b32 v141, s16, v252, v144 bitop3:0xc8
	v_ashrrev_i32_e32 v179, 31, v178
	s_add_u32 s16, s39, s10
	v_lshlrev_b64 v[194:195], 12, v[178:179]
	s_addc_u32 s17, s44, s11
	v_lshlrev_b32_e32 v180, 1, v141
	s_mov_b64 s[10:11], 0x80000
	s_and_b64 vcc, exec, s[40:41]
	s_waitcnt vmcnt(0)
	v_mov_b32_e32 v196, v147
	v_mov_b32_e32 v197, v148
	v_mov_b32_e32 v147, v149
	v_mov_b32_e32 v148, v151
	v_mov_b32_e32 v149, v152
	v_mov_b32_e32 v151, v153
	v_mov_b32_e32 v152, v155
	v_mov_b32_e32 v153, v156
	v_mov_b32_e32 v155, v157
	v_mov_b32_e32 v156, v159
	v_mov_b32_e32 v157, v160
	v_mov_b32_e32 v159, v161
	v_pk_add_f32 v[146:147], v[196:197], v[146:147]
	v_mov_b32_e32 v160, v163
	v_mov_b32_e32 v161, v164
	v_mov_b32_e32 v163, v165
	v_pk_add_f32 v[148:149], v[148:149], v[150:151]
	v_mov_b32_e32 v150, v167
	v_mov_b32_e32 v151, v168
	v_mov_b32_e32 v167, v169
	v_pk_add_f32 v[152:153], v[152:153], v[154:155]
	v_mov_b32_e32 v154, v171
	v_mov_b32_e32 v155, v172
	v_mov_b32_e32 v171, v173
	v_pk_add_f32 v[156:157], v[156:157], v[158:159]
	v_mov_b32_e32 v158, v175
	v_mov_b32_e32 v159, v176
	v_mov_b32_e32 v175, v177
	v_add_f32_e32 v164, v146, v147
	v_pk_add_f32 v[146:147], v[160:161], v[162:163]
	v_add_f32_e32 v160, v148, v149
	v_pk_add_f32 v[148:149], v[150:151], v[166:167]
	v_add_f32_e32 v161, v152, v153
	v_pk_add_f32 v[150:151], v[154:155], v[170:171]
	v_add_f32_e32 v154, v156, v157
	v_pk_add_f32 v[152:153], v[158:159], v[174:175]
	v_add_f32_e32 v155, 0, v164
	v_add_f32_e32 v146, v146, v147
	v_add_f32_e32 v147, 0, v160
	v_add_f32_e32 v148, v148, v149
	v_add_f32_e32 v149, 0, v161
	v_add_f32_e32 v150, v150, v151
	v_add_f32_e32 v151, 0, v154
	v_add_f32_e32 v152, v152, v153
	v_fmamk_f32 v153, v155, 0x3b800000, v200
	v_add_f32_e32 v154, 0, v146
	v_fmamk_f32 v147, v147, 0x3b800000, v200
	v_add_f32_e32 v148, 0, v148
	v_fmamk_f32 v149, v149, 0x3b800000, v200
	v_add_f32_e32 v150, 0, v150
	v_fmamk_f32 v151, v151, 0x3b800000, v200
	v_add_f32_e32 v152, 0, v152
	v_rsq_f32_e32 v146, v153
	v_fmamk_f32 v153, v154, 0x3b800000, v200
	v_rsq_f32_e32 v147, v147
	v_fmamk_f32 v154, v148, 0x3b800000, v200
	v_rsq_f32_e32 v148, v149
	v_fmamk_f32 v155, v150, 0x3b800000, v200
	v_rsq_f32_e32 v149, v151
	v_fmamk_f32 v151, v152, 0x3b800000, v200
	v_rsq_f32_e32 v150, v153
	v_rsq_f32_e32 v152, v155
	v_rsq_f32_e32 v153, v151
	v_rsq_f32_e32 v151, v154
	v_pk_mul_f32 v[120:121], v[120:121], v[146:147]
	v_pk_mul_f32 v[154:155], v[122:123], v[148:149]
	v_pk_mul_f32 v[126:127], v[126:127], v[152:153]
	v_pk_mul_f32 v[124:125], v[124:125], v[150:151]
	v_cvt_pk_bf16_f32 v122, v120, v121
	v_lshl_add_u64 v[120:121], s[16:17], 0, v[194:195]
	v_cvt_pk_bf16_f32 v123, v154, v155
	v_cvt_pk_bf16_f32 v124, v124, v125
	v_cvt_pk_bf16_f32 v125, v126, v127
	v_lshl_add_u64 v[126:127], v[120:121], 0, v[180:181]
	global_store_dwordx4 v[126:127], v[122:125], off
	v_pk_mul_f32 v[116:117], v[116:117], v[146:147]
	v_pk_mul_f32 v[112:113], v[112:113], v[150:151]
	v_or_b32_e32 v122, 16, v178
	v_ashrrev_i32_e32 v123, 31, v122
	v_pk_mul_f32 v[124:125], v[114:115], v[152:153]
	v_cvt_pk_bf16_f32 v114, v116, v117
	v_cvt_pk_bf16_f32 v116, v112, v113
	v_lshlrev_b64 v[112:113], 12, v[122:123]
	v_pk_mul_f32 v[118:119], v[118:119], v[148:149]
	v_lshl_add_u64 v[112:113], s[16:17], 0, v[112:113]
	v_cvt_pk_bf16_f32 v115, v118, v119
	v_cvt_pk_bf16_f32 v117, v124, v125
	v_lshl_add_u64 v[118:119], v[112:113], 0, v[180:181]
	global_store_dwordx4 v[118:119], v[114:117], off
	v_pk_mul_f32 v[108:109], v[108:109], v[146:147]
	v_pk_mul_f32 v[104:105], v[104:105], v[150:151]
	v_or_b32_e32 v114, 32, v178
	v_ashrrev_i32_e32 v115, 31, v114
	v_pk_mul_f32 v[116:117], v[106:107], v[152:153]
	v_cvt_pk_bf16_f32 v106, v108, v109
	v_cvt_pk_bf16_f32 v108, v104, v105
	v_lshlrev_b64 v[104:105], 12, v[114:115]
	v_pk_mul_f32 v[110:111], v[110:111], v[148:149]
	v_lshl_add_u64 v[104:105], s[16:17], 0, v[104:105]
	v_cvt_pk_bf16_f32 v107, v110, v111
	v_cvt_pk_bf16_f32 v109, v116, v117
	v_lshl_add_u64 v[110:111], v[104:105], 0, v[180:181]
	global_store_dwordx4 v[110:111], v[106:109], off
	v_pk_mul_f32 v[100:101], v[100:101], v[146:147]
	v_pk_mul_f32 v[96:97], v[96:97], v[150:151]
	v_or_b32_e32 v106, 48, v178
	v_ashrrev_i32_e32 v107, 31, v106
	v_pk_mul_f32 v[108:109], v[98:99], v[152:153]
	v_cvt_pk_bf16_f32 v98, v100, v101
	v_cvt_pk_bf16_f32 v100, v96, v97
	v_lshlrev_b64 v[96:97], 12, v[106:107]
	v_pk_mul_f32 v[102:103], v[102:103], v[148:149]
	v_lshl_add_u64 v[96:97], s[16:17], 0, v[96:97]
	v_cvt_pk_bf16_f32 v99, v102, v103
	v_cvt_pk_bf16_f32 v101, v108, v109
	v_lshl_add_u64 v[102:103], v[96:97], 0, v[180:181]
	v_pk_mul_f32 v[92:93], v[92:93], v[146:147]
	v_pk_mul_f32 v[88:89], v[88:89], v[150:151]
	global_store_dwordx4 v[102:103], v[98:101], off
	v_pk_mul_f32 v[94:95], v[94:95], v[148:149]
	v_pk_mul_f32 v[84:85], v[84:85], v[146:147]
	v_pk_mul_f32 v[98:99], v[90:91], v[152:153]
	v_cvt_pk_bf16_f32 v90, v92, v93
	v_cvt_pk_bf16_f32 v92, v88, v89
	v_lshl_add_u64 v[88:89], v[120:121], 0, s[10:11]
	v_cvt_pk_bf16_f32 v91, v94, v95
	v_cvt_pk_bf16_f32 v93, v98, v99
	v_lshl_add_u64 v[94:95], v[88:89], 0, v[180:181]
	v_pk_mul_f32 v[80:81], v[80:81], v[150:151]
	s_mov_b64 s[10:11], 0x90000
	global_store_dwordx4 v[94:95], v[90:93], off
	v_pk_mul_f32 v[86:87], v[86:87], v[148:149]
	v_pk_mul_f32 v[76:77], v[76:77], v[146:147]
	v_pk_mul_f32 v[90:91], v[82:83], v[152:153]
	v_cvt_pk_bf16_f32 v82, v84, v85
	v_cvt_pk_bf16_f32 v84, v80, v81
	v_lshl_add_u64 v[80:81], v[120:121], 0, s[10:11]
	v_cvt_pk_bf16_f32 v83, v86, v87
	v_cvt_pk_bf16_f32 v85, v90, v91
	v_lshl_add_u64 v[86:87], v[80:81], 0, v[180:181]
	v_pk_mul_f32 v[72:73], v[72:73], v[150:151]
	s_mov_b64 s[10:11], 0xa0000
	global_store_dwordx4 v[86:87], v[82:85], off
	v_pk_mul_f32 v[78:79], v[78:79], v[148:149]
	v_pk_mul_f32 v[68:69], v[68:69], v[146:147]
	v_pk_mul_f32 v[82:83], v[74:75], v[152:153]
	v_cvt_pk_bf16_f32 v74, v76, v77
	v_cvt_pk_bf16_f32 v76, v72, v73
	v_lshl_add_u64 v[72:73], v[120:121], 0, s[10:11]
	v_cvt_pk_bf16_f32 v75, v78, v79
	v_cvt_pk_bf16_f32 v77, v82, v83
	v_lshl_add_u64 v[78:79], v[72:73], 0, v[180:181]
	v_pk_mul_f32 v[64:65], v[64:65], v[150:151]
	s_mov_b64 s[10:11], 0xb0000
	global_store_dwordx4 v[78:79], v[74:77], off
	v_pk_mul_f32 v[70:71], v[70:71], v[148:149]
	s_nop 0
	v_pk_mul_f32 v[74:75], v[66:67], v[152:153]
	v_cvt_pk_bf16_f32 v66, v68, v69
	v_cvt_pk_bf16_f32 v68, v64, v65
	v_lshl_add_u64 v[64:65], v[120:121], 0, s[10:11]
	v_cvt_pk_bf16_f32 v67, v70, v71
	v_cvt_pk_bf16_f32 v69, v74, v75
	v_lshl_add_u64 v[70:71], v[64:65], 0, v[180:181]
	global_store_dwordx4 v[70:71], v[66:69], off
	v_or_b32_e32 v74, 0x84, v140
	v_ashrrev_i32_e32 v75, 31, v74
	v_or_b32_e32 v66, 0x80, v140
	v_ashrrev_i32_e32 v67, 31, v66
	v_lshl_add_u64 v[70:71], v[66:67], 4, s[14:15]
	global_load_dwordx4 v[66:69], v[70:71], off
	v_lshl_add_u64 v[78:79], v[74:75], 4, s[14:15]
	global_load_dwordx4 v[74:77], v[78:79], off
	global_load_dwordx4 v[82:85], v[70:71], off offset:16
	global_load_dwordx4 v[90:93], v[78:79], off offset:16
	global_load_dwordx4 v[98:101], v[70:71], off offset:32
	global_load_dwordx4 v[106:109], v[78:79], off offset:32
	global_load_dwordx4 v[114:117], v[70:71], off offset:48
	global_load_dwordx4 v[122:125], v[78:79], off offset:48
	s_movk_i32 s10, 0x7f8
	v_bitop3_b32 v78, v140, s10, v201 bitop3:0xc8
	v_lshlrev_b32_e32 v180, 1, v78
	s_mov_b64 s[10:11], -1
	s_waitcnt vmcnt(0)
	v_mov_b32_e32 v70, v67
	v_mov_b32_e32 v71, v68
	v_mov_b32_e32 v67, v69
	v_mov_b32_e32 v68, v75
	v_mov_b32_e32 v69, v76
	v_mov_b32_e32 v75, v77
	v_pk_add_f32 v[66:67], v[70:71], v[66:67]
	v_pk_add_f32 v[68:69], v[68:69], v[74:75]
	v_add_f32_e32 v66, v66, v67
	v_add_f32_e32 v67, v68, v69
	v_add_f32_e32 v67, 0, v67
	v_mov_b32_e32 v70, v83
	v_mov_b32_e32 v71, v84
	v_mov_b32_e32 v83, v85
	v_fmamk_f32 v67, v67, 0x3b800000, v200
	v_pk_add_f32 v[70:71], v[70:71], v[82:83]
	v_rsq_f32_e32 v68, v67
	v_add_f32_e32 v67, v70, v71
	v_mov_b32_e32 v70, v91
	v_mov_b32_e32 v71, v92
	v_mov_b32_e32 v91, v93
	v_pk_add_f32 v[70:71], v[70:71], v[90:91]
	v_mov_b32_e32 v74, v107
	v_add_f32_e32 v69, v70, v71
	v_mov_b32_e32 v70, v99
	v_mov_b32_e32 v71, v100
	v_mov_b32_e32 v99, v101
	v_mov_b32_e32 v75, v108
	v_mov_b32_e32 v107, v109
	v_pk_add_f32 v[70:71], v[70:71], v[98:99]
	v_pk_add_f32 v[74:75], v[74:75], v[106:107]
	v_add_f32_e32 v70, v70, v71
	v_add_f32_e32 v71, v74, v75
	v_add_f32_e32 v71, 0, v71
	v_mov_b32_e32 v76, v115
	v_mov_b32_e32 v77, v116
	v_mov_b32_e32 v115, v117
	v_fmamk_f32 v71, v71, 0x3b800000, v200
	v_pk_add_f32 v[76:77], v[76:77], v[114:115]
	v_rsq_f32_e32 v74, v71
	v_add_f32_e32 v71, v76, v77
	v_mov_b32_e32 v76, v123
	v_mov_b32_e32 v77, v124
	v_mov_b32_e32 v123, v125
	v_pk_add_f32 v[76:77], v[76:77], v[122:123]
	v_add_f32_e32 v66, 0, v66
	v_add_f32_e32 v75, v76, v77
	v_add_f32_e32 v67, 0, v67
	v_add_f32_e32 v69, 0, v69
	v_add_f32_e32 v70, 0, v70
	v_add_f32_e32 v71, 0, v71
	v_add_f32_e32 v75, 0, v75
	v_fmamk_f32 v66, v66, 0x3b800000, v200
	v_fmamk_f32 v67, v67, 0x3b800000, v200
	v_fmamk_f32 v69, v69, 0x3b800000, v200
	v_fmamk_f32 v70, v70, 0x3b800000, v200
	v_fmamk_f32 v71, v71, 0x3b800000, v200
	v_fmamk_f32 v75, v75, 0x3b800000, v200
	v_rsq_f32_e32 v66, v66
	v_rsq_f32_e32 v67, v67
	v_rsq_f32_e32 v69, v69
	v_rsq_f32_e32 v70, v70
	v_rsq_f32_e32 v71, v71
	v_rsq_f32_e32 v75, v75
	v_pk_mul_f32 v[60:61], v[60:61], v[66:67]
	v_pk_mul_f32 v[52:53], v[52:53], v[66:67]
	v_pk_mul_f32 v[62:63], v[62:63], v[70:71]
	v_pk_mul_f32 v[76:77], v[58:59], v[74:75]
	v_pk_mul_f32 v[58:59], v[56:57], v[68:69]
	v_cvt_pk_bf16_f32 v56, v60, v61
	v_cvt_pk_bf16_f32 v57, v62, v63
	v_cvt_pk_bf16_f32 v58, v58, v59
	v_cvt_pk_bf16_f32 v59, v76, v77
	v_lshl_add_u64 v[60:61], v[120:121], 0, v[180:181]
	global_store_dwordx4 v[60:61], v[56:59], off
	v_pk_mul_f32 v[54:55], v[54:55], v[70:71]
	v_pk_mul_f32 v[46:47], v[46:47], v[70:71]
	v_pk_mul_f32 v[56:57], v[50:51], v[74:75]
	v_pk_mul_f32 v[50:51], v[48:49], v[68:69]
	v_cvt_pk_bf16_f32 v48, v52, v53
	v_cvt_pk_bf16_f32 v49, v54, v55
	v_cvt_pk_bf16_f32 v50, v50, v51
	v_cvt_pk_bf16_f32 v51, v56, v57
	v_lshl_add_u64 v[52:53], v[112:113], 0, v[180:181]
	global_store_dwordx4 v[52:53], v[48:51], off
	v_pk_mul_f32 v[44:45], v[44:45], v[66:67]
	v_pk_mul_f32 v[38:39], v[38:39], v[70:71]
	v_pk_mul_f32 v[48:49], v[42:43], v[74:75]
	v_pk_mul_f32 v[42:43], v[40:41], v[68:69]
	v_cvt_pk_bf16_f32 v40, v44, v45
	v_cvt_pk_bf16_f32 v41, v46, v47
	v_cvt_pk_bf16_f32 v42, v42, v43
	v_cvt_pk_bf16_f32 v43, v48, v49
	v_lshl_add_u64 v[44:45], v[104:105], 0, v[180:181]
	global_store_dwordx4 v[44:45], v[40:43], off
	v_pk_mul_f32 v[36:37], v[36:37], v[66:67]
	v_pk_mul_f32 v[30:31], v[30:31], v[70:71]
	v_pk_mul_f32 v[40:41], v[34:35], v[74:75]
	v_pk_mul_f32 v[34:35], v[32:33], v[68:69]
	v_cvt_pk_bf16_f32 v32, v36, v37
	v_cvt_pk_bf16_f32 v33, v38, v39
	v_cvt_pk_bf16_f32 v34, v34, v35
	v_cvt_pk_bf16_f32 v35, v40, v41
	v_lshl_add_u64 v[36:37], v[96:97], 0, v[180:181]
	global_store_dwordx4 v[36:37], v[32:35], off
	v_pk_mul_f32 v[28:29], v[28:29], v[66:67]
	v_pk_mul_f32 v[22:23], v[22:23], v[70:71]
	v_pk_mul_f32 v[32:33], v[26:27], v[74:75]
	v_pk_mul_f32 v[26:27], v[24:25], v[68:69]
	v_cvt_pk_bf16_f32 v24, v28, v29
	v_cvt_pk_bf16_f32 v25, v30, v31
	v_cvt_pk_bf16_f32 v26, v26, v27
	v_cvt_pk_bf16_f32 v27, v32, v33
	v_lshl_add_u64 v[28:29], v[88:89], 0, v[180:181]
	global_store_dwordx4 v[28:29], v[24:27], off
	v_pk_mul_f32 v[20:21], v[20:21], v[66:67]
	v_pk_mul_f32 v[14:15], v[14:15], v[70:71]
	v_pk_mul_f32 v[24:25], v[18:19], v[74:75]
	v_pk_mul_f32 v[18:19], v[16:17], v[68:69]
	v_cvt_pk_bf16_f32 v16, v20, v21
	v_cvt_pk_bf16_f32 v17, v22, v23
	v_cvt_pk_bf16_f32 v18, v18, v19
	v_cvt_pk_bf16_f32 v19, v24, v25
	v_lshl_add_u64 v[20:21], v[80:81], 0, v[180:181]
	global_store_dwordx4 v[20:21], v[16:19], off
	v_pk_mul_f32 v[12:13], v[12:13], v[66:67]
	v_pk_mul_f32 v[6:7], v[6:7], v[70:71]
	v_pk_mul_f32 v[16:17], v[10:11], v[74:75]
	v_pk_mul_f32 v[10:11], v[8:9], v[68:69]
	v_cvt_pk_bf16_f32 v8, v12, v13
	v_cvt_pk_bf16_f32 v9, v14, v15
	v_cvt_pk_bf16_f32 v10, v10, v11
	v_cvt_pk_bf16_f32 v11, v16, v17
	v_lshl_add_u64 v[12:13], v[72:73], 0, v[180:181]
	global_store_dwordx4 v[12:13], v[8:11], off
	v_pk_mul_f32 v[4:5], v[4:5], v[66:67]
	s_nop 0
	v_pk_mul_f32 v[8:9], v[2:3], v[74:75]
	v_pk_mul_f32 v[2:3], v[0:1], v[68:69]
	v_cvt_pk_bf16_f32 v0, v4, v5
	v_cvt_pk_bf16_f32 v1, v6, v7
	v_cvt_pk_bf16_f32 v2, v2, v3
	v_cvt_pk_bf16_f32 v3, v8, v9
	v_lshl_add_u64 v[4:5], v[64:65], 0, v[180:181]
	global_store_dwordx4 v[4:5], v[0:3], off
	s_cbranch_vccnz .LBB0_810
	s_andn2_b64 vcc, exec, s[8:9]
	s_cbranch_vccnz .LBB0_809
	s_mov_b32 s100, 1
	s_branch .LBB0_809

.LBB0_842:
	v_mov_b32_e32 v127, 0
	s_andn2_b64 vcc, exec, s[22:23]
	v_mov_b32_e32 v126, v127
	v_mov_b32_e32 v125, v127
	v_mov_b32_e32 v124, v127
	v_mov_b32_e32 v123, v127
	v_mov_b32_e32 v122, v127
	v_mov_b32_e32 v121, v127
	v_mov_b32_e32 v120, v127
	v_mov_b32_e32 v111, v127
	v_mov_b32_e32 v110, v127
	v_mov_b32_e32 v109, v127
	v_mov_b32_e32 v108, v127
	v_mov_b32_e32 v107, v127
	v_mov_b32_e32 v106, v127
	v_mov_b32_e32 v105, v127
	v_mov_b32_e32 v104, v127
	v_mov_b32_e32 v95, v127
	v_mov_b32_e32 v94, v127
	v_mov_b32_e32 v93, v127
	v_mov_b32_e32 v92, v127
	v_mov_b32_e32 v91, v127
	v_mov_b32_e32 v90, v127
	v_mov_b32_e32 v89, v127
	v_mov_b32_e32 v88, v127
	v_mov_b32_e32 v79, v127
	v_mov_b32_e32 v78, v127
	v_mov_b32_e32 v77, v127
	v_mov_b32_e32 v76, v127
	v_mov_b32_e32 v75, v127
	v_mov_b32_e32 v74, v127
	v_mov_b32_e32 v73, v127
	v_mov_b32_e32 v72, v127
	v_mov_b32_e32 v119, v127
	v_mov_b32_e32 v118, v127
	v_mov_b32_e32 v117, v127
	v_mov_b32_e32 v116, v127
	v_mov_b32_e32 v115, v127
	v_mov_b32_e32 v114, v127
	v_mov_b32_e32 v113, v127
	v_mov_b32_e32 v112, v127
	v_mov_b32_e32 v103, v127
	v_mov_b32_e32 v102, v127
	v_mov_b32_e32 v101, v127
	v_mov_b32_e32 v100, v127
	v_mov_b32_e32 v99, v127
	v_mov_b32_e32 v98, v127
	v_mov_b32_e32 v97, v127
	v_mov_b32_e32 v96, v127
	v_mov_b32_e32 v87, v127
	v_mov_b32_e32 v86, v127
	v_mov_b32_e32 v85, v127
	v_mov_b32_e32 v84, v127
	v_mov_b32_e32 v83, v127
	v_mov_b32_e32 v82, v127
	v_mov_b32_e32 v81, v127
	v_mov_b32_e32 v80, v127
	v_mov_b32_e32 v71, v127
	v_mov_b32_e32 v70, v127
	v_mov_b32_e32 v69, v127
	v_mov_b32_e32 v68, v127
	v_mov_b32_e32 v67, v127
	v_mov_b32_e32 v66, v127
	v_mov_b32_e32 v65, v127
	v_mov_b32_e32 v64, v127
	v_mov_b32_e32 v63, v127
	v_mov_b32_e32 v62, v127
	v_mov_b32_e32 v61, v127
	v_mov_b32_e32 v60, v127
	v_mov_b32_e32 v59, v127
	v_mov_b32_e32 v58, v127
	v_mov_b32_e32 v57, v127
	v_mov_b32_e32 v56, v127
	v_mov_b32_e32 v47, v127
	v_mov_b32_e32 v46, v127
	v_mov_b32_e32 v45, v127
	v_mov_b32_e32 v44, v127
	v_mov_b32_e32 v43, v127
	v_mov_b32_e32 v42, v127
	v_mov_b32_e32 v41, v127
	v_mov_b32_e32 v40, v127
	v_mov_b32_e32 v31, v127
	v_mov_b32_e32 v30, v127
	v_mov_b32_e32 v29, v127
	v_mov_b32_e32 v28, v127
	v_mov_b32_e32 v27, v127
	v_mov_b32_e32 v26, v127
	v_mov_b32_e32 v25, v127
	v_mov_b32_e32 v24, v127
	v_mov_b32_e32 v15, v127
	v_mov_b32_e32 v14, v127
	v_mov_b32_e32 v13, v127
	v_mov_b32_e32 v12, v127
	v_mov_b32_e32 v11, v127
	v_mov_b32_e32 v10, v127
	v_mov_b32_e32 v9, v127
	v_mov_b32_e32 v8, v127
	v_mov_b32_e32 v55, v127
	v_mov_b32_e32 v54, v127
	v_mov_b32_e32 v53, v127
	v_mov_b32_e32 v52, v127
	v_mov_b32_e32 v51, v127
	v_mov_b32_e32 v50, v127
	v_mov_b32_e32 v49, v127
	v_mov_b32_e32 v48, v127
	v_mov_b32_e32 v39, v127
	v_mov_b32_e32 v38, v127
	v_mov_b32_e32 v37, v127
	v_mov_b32_e32 v36, v127
	v_mov_b32_e32 v35, v127
	v_mov_b32_e32 v34, v127
	v_mov_b32_e32 v33, v127
	v_mov_b32_e32 v32, v127
	v_mov_b32_e32 v23, v127
	v_mov_b32_e32 v22, v127
	v_mov_b32_e32 v21, v127
	v_mov_b32_e32 v20, v127
	v_mov_b32_e32 v19, v127
	v_mov_b32_e32 v18, v127
	v_mov_b32_e32 v17, v127
	v_mov_b32_e32 v16, v127
	v_mov_b32_e32 v7, v127
	v_mov_b32_e32 v6, v127
	v_mov_b32_e32 v5, v127
	v_mov_b32_e32 v4, v127
	v_mov_b32_e32 v3, v127
	v_mov_b32_e32 v2, v127
	v_mov_b32_e32 v1, v127
	v_mov_b32_e32 v0, v127
	s_cbranch_vccnz .LBB0_845
	s_add_u32 s0, s0, 0x80
	s_addc_u32 s1, s1, 0
	s_add_u32 s10, s30, 0x100
	s_addc_u32 s11, s31, 0
	s_mov_b32 s16, 0
	s_cmp_lg_u32 s100, 0
	s_cbranch_scc0 .Llbb_8
	s_barrier
	s_mov_b32 s100, 0
.Llbb_8:
.LBB0_844:
	s_add_i32 s30, s16, 2
	s_add_u32 s31, s0, 0x80
	s_addc_u32 s17, s1, 0
	s_add_i32 s35, 0, 0x10000
	s_cmp_eq_u32 s57, s16
	s_cselect_b32 s17, s27, s17
	s_cselect_b32 s16, s26, s31
	s_cselect_b32 s43, s29, s11
	s_cselect_b32 s42, s28, s10
	s_add_i32 s31, 0, 0x14000
	v_add_u32_e32 v156, s35, v164
	v_add_u32_e32 v167, s31, v164
	ds_read_b128 v[144:147], v156
	ds_read_b128 v[148:151], v156 offset:1024
	ds_read_b128 v[152:155], v156 offset:2048
	ds_read_b128 v[156:159], v156 offset:3072
	ds_read_b128 v[160:163], v167
	ds_read_b128 v[168:171], v167 offset:1024
	ds_read_b128 v[172:175], v167 offset:2048
	ds_read_b128 v[176:179], v167 offset:3072
	v_lshl_add_u64 v[198:199], s[0:1], 0, v[140:141]
	s_add_i32 m0, s39, 0xc000
	ds_read_b128 v[194:197], v166
	ds_read_b128 v[206:209], v166 offset:1024
	ds_read_b128 v[210:213], v166 offset:2048
	ds_read_b128 v[214:217], v166 offset:3072
	ds_read_b128 v[220:223], v166 offset:4096
	ds_read_b128 v[224:227], v166 offset:5120
	ds_read_b128 v[228:231], v166 offset:6144
	ds_read_b128 v[232:235], v166 offset:7168
	global_load_lds_dwordx4 v[198:199], off
	v_lshl_add_u64 v[198:199], s[0:1], 0, v[142:143]
	s_add_i32 m0, s39, 0xe000
	s_nop 0
	global_load_lds_dwordx4 v[198:199], off
	s_waitcnt vmcnt(8)
	s_waitcnt lgkmcnt(0)
	s_barrier
	s_waitcnt lgkmcnt(0)
	v_mfma_f32_16x16x32_bf16 v[124:127], v[144:147], v[194:197], v[124:127]
	v_mfma_f32_16x16x32_bf16 v[120:123], v[152:155], v[194:197], v[120:123]
	v_mfma_f32_16x16x32_bf16 v[108:111], v[144:147], v[210:213], v[108:111]
	v_mfma_f32_16x16x32_bf16 v[104:107], v[152:155], v[210:213], v[104:107]
	v_mfma_f32_16x16x32_bf16 v[92:95], v[144:147], v[220:223], v[92:95]
	v_mfma_f32_16x16x32_bf16 v[88:91], v[152:155], v[220:223], v[88:91]
	v_mfma_f32_16x16x32_bf16 v[76:79], v[144:147], v[228:231], v[76:79]
	v_mfma_f32_16x16x32_bf16 v[72:75], v[152:155], v[228:231], v[72:75]
	v_mfma_f32_16x16x32_bf16 v[124:127], v[148:151], v[206:209], v[124:127]
	v_mfma_f32_16x16x32_bf16 v[120:123], v[156:159], v[206:209], v[120:123]
	v_mfma_f32_16x16x32_bf16 v[108:111], v[148:151], v[214:217], v[108:111]
	v_mfma_f32_16x16x32_bf16 v[104:107], v[156:159], v[214:217], v[104:107]
	v_mfma_f32_16x16x32_bf16 v[92:95], v[148:151], v[224:227], v[92:95]
	v_mfma_f32_16x16x32_bf16 v[88:91], v[156:159], v[224:227], v[88:91]
	v_mfma_f32_16x16x32_bf16 v[76:79], v[148:151], v[232:235], v[76:79]
	v_mfma_f32_16x16x32_bf16 v[72:75], v[156:159], v[232:235], v[72:75]
	v_mfma_f32_16x16x32_bf16 v[116:119], v[160:163], v[194:197], v[116:119]
	v_mfma_f32_16x16x32_bf16 v[112:115], v[172:175], v[194:197], v[112:115]
	v_mfma_f32_16x16x32_bf16 v[100:103], v[160:163], v[210:213], v[100:103]
	v_mfma_f32_16x16x32_bf16 v[96:99], v[172:175], v[210:213], v[96:99]
	v_mfma_f32_16x16x32_bf16 v[84:87], v[160:163], v[220:223], v[84:87]
	v_mfma_f32_16x16x32_bf16 v[80:83], v[172:175], v[220:223], v[80:83]
	v_mfma_f32_16x16x32_bf16 v[68:71], v[160:163], v[228:231], v[68:71]
	v_mfma_f32_16x16x32_bf16 v[64:67], v[172:175], v[228:231], v[64:67]
	v_mfma_f32_16x16x32_bf16 v[116:119], v[168:171], v[206:209], v[116:119]
	v_mfma_f32_16x16x32_bf16 v[112:115], v[176:179], v[206:209], v[112:115]
	v_mfma_f32_16x16x32_bf16 v[100:103], v[168:171], v[214:217], v[100:103]
	v_mfma_f32_16x16x32_bf16 v[96:99], v[176:179], v[214:217], v[96:99]
	v_mfma_f32_16x16x32_bf16 v[84:87], v[168:171], v[224:227], v[84:87]
	v_mfma_f32_16x16x32_bf16 v[80:83], v[176:179], v[224:227], v[80:83]
	v_mfma_f32_16x16x32_bf16 v[68:71], v[168:171], v[232:235], v[68:71]
	v_mfma_f32_16x16x32_bf16 v[64:67], v[176:179], v[232:235], v[64:67]
	s_barrier
	s_add_i32 s35, s35, s38
	v_lshl_add_u64 v[198:199], s[42:43], 0, v[132:133]
	s_mov_b32 m0, s35
	ds_read_b128 v[194:197], v166 offset:16384
	ds_read_b128 v[206:209], v166 offset:17408
	ds_read_b128 v[210:213], v166 offset:18432
	ds_read_b128 v[214:217], v166 offset:19456
	ds_read_b128 v[220:223], v166 offset:20480
	ds_read_b128 v[224:227], v166 offset:21504
	ds_read_b128 v[228:231], v166 offset:22528
	ds_read_b128 v[232:235], v166 offset:23552
	global_load_lds_dwordx4 v[198:199], off
	s_add_i32 m0, s35, 0x2000
	v_lshl_add_u64 v[202:203], s[42:43], 0, v[128:129]
	s_add_u32 s42, s42, s6
	s_addc_u32 s43, s43, s7
	s_add_i32 s31, s31, s38
	global_load_lds_dwordx4 v[202:203], off
	v_lshl_add_u64 v[236:237], s[42:43], 0, v[132:133]
	s_mov_b32 m0, s31
	v_lshl_add_u64 v[238:239], s[42:43], 0, v[128:129]
	global_load_lds_dwordx4 v[236:237], off
	s_add_i32 m0, s31, 0x2000
	v_lshl_add_u64 v[240:241], s[16:17], 0, v[134:135]
	global_load_lds_dwordx4 v[238:239], off
	s_mov_b32 m0, s39
	v_lshl_add_u64 v[242:243], s[16:17], 0, v[130:131]
	global_load_lds_dwordx4 v[240:241], off
	s_mov_b32 m0, s44
	s_nop 0
	global_load_lds_dwordx4 v[242:243], off
	s_waitcnt vmcnt(8)
	s_waitcnt lgkmcnt(0)
	s_barrier
	s_waitcnt lgkmcnt(0)
	v_mfma_f32_16x16x32_bf16 v[60:63], v[144:147], v[194:197], v[60:63]
	v_mfma_f32_16x16x32_bf16 v[56:59], v[152:155], v[194:197], v[56:59]
	v_mfma_f32_16x16x32_bf16 v[44:47], v[144:147], v[210:213], v[44:47]
	v_mfma_f32_16x16x32_bf16 v[40:43], v[152:155], v[210:213], v[40:43]
	v_mfma_f32_16x16x32_bf16 v[28:31], v[144:147], v[220:223], v[28:31]
	v_mfma_f32_16x16x32_bf16 v[24:27], v[152:155], v[220:223], v[24:27]
	v_mfma_f32_16x16x32_bf16 v[12:15], v[144:147], v[228:231], v[12:15]
	v_mfma_f32_16x16x32_bf16 v[8:11], v[152:155], v[228:231], v[8:11]
	v_mfma_f32_16x16x32_bf16 v[60:63], v[148:151], v[206:209], v[60:63]
	v_mfma_f32_16x16x32_bf16 v[56:59], v[156:159], v[206:209], v[56:59]
	v_mfma_f32_16x16x32_bf16 v[44:47], v[148:151], v[214:217], v[44:47]
	v_mfma_f32_16x16x32_bf16 v[40:43], v[156:159], v[214:217], v[40:43]
	v_mfma_f32_16x16x32_bf16 v[28:31], v[148:151], v[224:227], v[28:31]
	v_mfma_f32_16x16x32_bf16 v[24:27], v[156:159], v[224:227], v[24:27]
	v_mfma_f32_16x16x32_bf16 v[12:15], v[148:151], v[232:235], v[12:15]
	v_mfma_f32_16x16x32_bf16 v[8:11], v[156:159], v[232:235], v[8:11]
	v_mfma_f32_16x16x32_bf16 v[52:55], v[160:163], v[194:197], v[52:55]
	v_mfma_f32_16x16x32_bf16 v[48:51], v[172:175], v[194:197], v[48:51]
	v_mfma_f32_16x16x32_bf16 v[36:39], v[160:163], v[210:213], v[36:39]
	v_mfma_f32_16x16x32_bf16 v[32:35], v[172:175], v[210:213], v[32:35]
	v_mfma_f32_16x16x32_bf16 v[20:23], v[160:163], v[220:223], v[20:23]
	v_mfma_f32_16x16x32_bf16 v[16:19], v[172:175], v[220:223], v[16:19]
	v_mfma_f32_16x16x32_bf16 v[4:7], v[160:163], v[228:231], v[4:7]
	v_mfma_f32_16x16x32_bf16 v[0:3], v[172:175], v[228:231], v[0:3]
	v_mfma_f32_16x16x32_bf16 v[52:55], v[168:171], v[206:209], v[52:55]
	v_mfma_f32_16x16x32_bf16 v[48:51], v[176:179], v[206:209], v[48:51]
	v_mfma_f32_16x16x32_bf16 v[36:39], v[168:171], v[214:217], v[36:39]
	v_mfma_f32_16x16x32_bf16 v[32:35], v[176:179], v[214:217], v[32:35]
	v_mfma_f32_16x16x32_bf16 v[20:23], v[168:171], v[224:227], v[20:23]
	v_mfma_f32_16x16x32_bf16 v[16:19], v[176:179], v[224:227], v[16:19]
	v_mfma_f32_16x16x32_bf16 v[4:7], v[168:171], v[232:235], v[4:7]
	v_mfma_f32_16x16x32_bf16 v[0:3], v[176:179], v[232:235], v[0:3]
	s_barrier
	s_add_i32 s31, 0, 0x18000
	s_add_i32 s35, 0, 0x1c000
	v_add_u32_e32 v156, s31, v164
	v_add_u32_e32 v167, s35, v164
	ds_read_b128 v[144:147], v156
	ds_read_b128 v[148:151], v156 offset:1024
	ds_read_b128 v[152:155], v156 offset:2048
	ds_read_b128 v[156:159], v156 offset:3072
	ds_read_b128 v[160:163], v167
	ds_read_b128 v[168:171], v167 offset:1024
	ds_read_b128 v[172:175], v167 offset:2048
	ds_read_b128 v[176:179], v167 offset:3072
	s_add_u32 s16, s16, s6
	s_addc_u32 s17, s17, s7
	s_mov_b32 m0, s45
	v_lshl_add_u64 v[244:245], s[16:17], 0, v[134:135]
	ds_read_b128 v[194:197], v166 offset:32768
	ds_read_b128 v[206:209], v166 offset:33792
	ds_read_b128 v[210:213], v166 offset:34816
	ds_read_b128 v[214:217], v166 offset:35840
	ds_read_b128 v[220:223], v166 offset:36864
	ds_read_b128 v[224:227], v166 offset:37888
	ds_read_b128 v[228:231], v166 offset:38912
	ds_read_b128 v[232:235], v166 offset:39936
	global_load_lds_dwordx4 v[244:245], off
	v_lshl_add_u64 v[244:245], s[16:17], 0, v[130:131]
	s_mov_b32 m0, s46
	s_nop 0
	global_load_lds_dwordx4 v[244:245], off
	s_waitcnt vmcnt(8)
	s_waitcnt lgkmcnt(0)
	s_barrier
	s_waitcnt lgkmcnt(0)
	v_mfma_f32_16x16x32_bf16 v[124:127], v[144:147], v[194:197], v[124:127]
	v_mfma_f32_16x16x32_bf16 v[120:123], v[152:155], v[194:197], v[120:123]
	v_mfma_f32_16x16x32_bf16 v[108:111], v[144:147], v[210:213], v[108:111]
	v_mfma_f32_16x16x32_bf16 v[104:107], v[152:155], v[210:213], v[104:107]
	v_mfma_f32_16x16x32_bf16 v[92:95], v[144:147], v[220:223], v[92:95]
	v_mfma_f32_16x16x32_bf16 v[88:91], v[152:155], v[220:223], v[88:91]
	v_mfma_f32_16x16x32_bf16 v[76:79], v[144:147], v[228:231], v[76:79]
	v_mfma_f32_16x16x32_bf16 v[72:75], v[152:155], v[228:231], v[72:75]
	v_mfma_f32_16x16x32_bf16 v[124:127], v[148:151], v[206:209], v[124:127]
	v_mfma_f32_16x16x32_bf16 v[120:123], v[156:159], v[206:209], v[120:123]
	v_mfma_f32_16x16x32_bf16 v[108:111], v[148:151], v[214:217], v[108:111]
	v_mfma_f32_16x16x32_bf16 v[104:107], v[156:159], v[214:217], v[104:107]
	v_mfma_f32_16x16x32_bf16 v[92:95], v[148:151], v[224:227], v[92:95]
	v_mfma_f32_16x16x32_bf16 v[88:91], v[156:159], v[224:227], v[88:91]
	v_mfma_f32_16x16x32_bf16 v[76:79], v[148:151], v[232:235], v[76:79]
	v_mfma_f32_16x16x32_bf16 v[72:75], v[156:159], v[232:235], v[72:75]
	v_mfma_f32_16x16x32_bf16 v[116:119], v[160:163], v[194:197], v[116:119]
	v_mfma_f32_16x16x32_bf16 v[112:115], v[172:175], v[194:197], v[112:115]
	v_mfma_f32_16x16x32_bf16 v[100:103], v[160:163], v[210:213], v[100:103]
	v_mfma_f32_16x16x32_bf16 v[96:99], v[172:175], v[210:213], v[96:99]
	v_mfma_f32_16x16x32_bf16 v[84:87], v[160:163], v[220:223], v[84:87]
	v_mfma_f32_16x16x32_bf16 v[80:83], v[172:175], v[220:223], v[80:83]
	v_mfma_f32_16x16x32_bf16 v[68:71], v[160:163], v[228:231], v[68:71]
	v_mfma_f32_16x16x32_bf16 v[64:67], v[172:175], v[228:231], v[64:67]
	v_mfma_f32_16x16x32_bf16 v[116:119], v[168:171], v[206:209], v[116:119]
	v_mfma_f32_16x16x32_bf16 v[112:115], v[176:179], v[206:209], v[112:115]
	v_mfma_f32_16x16x32_bf16 v[100:103], v[168:171], v[214:217], v[100:103]
	v_mfma_f32_16x16x32_bf16 v[96:99], v[176:179], v[214:217], v[96:99]
	v_mfma_f32_16x16x32_bf16 v[84:87], v[168:171], v[224:227], v[84:87]
	v_mfma_f32_16x16x32_bf16 v[80:83], v[176:179], v[224:227], v[80:83]
	v_mfma_f32_16x16x32_bf16 v[68:71], v[168:171], v[232:235], v[68:71]
	v_mfma_f32_16x16x32_bf16 v[64:67], v[176:179], v[232:235], v[64:67]
	s_barrier
	s_add_i32 s16, s31, s38
	v_lshl_add_u64 v[198:199], v[198:199], 0, s[12:13]
	s_mov_b32 m0, s16
	ds_read_b128 v[194:197], v166 offset:49152
	ds_read_b128 v[206:209], v166 offset:50176
	ds_read_b128 v[210:213], v166 offset:51200
	ds_read_b128 v[214:217], v166 offset:52224
	ds_read_b128 v[220:223], v166 offset:53248
	ds_read_b128 v[224:227], v166 offset:54272
	ds_read_b128 v[228:231], v166 offset:55296
	ds_read_b128 v[232:235], v166 offset:56320
	global_load_lds_dwordx4 v[198:199], off
	v_lshl_add_u64 v[198:199], v[202:203], 0, s[12:13]
	s_add_i32 m0, s16, 0x2000
	s_add_i32 s16, s35, s38
	global_load_lds_dwordx4 v[198:199], off
	v_lshl_add_u64 v[198:199], v[236:237], 0, s[12:13]
	s_mov_b32 m0, s16
	s_nop 0
	global_load_lds_dwordx4 v[198:199], off
	v_lshl_add_u64 v[198:199], v[238:239], 0, s[12:13]
	s_add_i32 m0, s16, 0x2000
	s_nop 0
	global_load_lds_dwordx4 v[198:199], off
	v_lshl_add_u64 v[198:199], v[240:241], 0, s[12:13]
	s_mov_b32 m0, s47
	s_nop 0
	global_load_lds_dwordx4 v[198:199], off
	v_lshl_add_u64 v[198:199], v[242:243], 0, s[12:13]
	s_mov_b32 m0, s48
	s_nop 0
	global_load_lds_dwordx4 v[198:199], off
	s_waitcnt vmcnt(8)
	s_waitcnt lgkmcnt(0)
	s_barrier
	s_waitcnt lgkmcnt(0)
	v_mfma_f32_16x16x32_bf16 v[60:63], v[144:147], v[194:197], v[60:63]
	v_mfma_f32_16x16x32_bf16 v[56:59], v[152:155], v[194:197], v[56:59]
	v_mfma_f32_16x16x32_bf16 v[44:47], v[144:147], v[210:213], v[44:47]
	v_mfma_f32_16x16x32_bf16 v[40:43], v[152:155], v[210:213], v[40:43]
	v_mfma_f32_16x16x32_bf16 v[28:31], v[144:147], v[220:223], v[28:31]
	v_mfma_f32_16x16x32_bf16 v[24:27], v[152:155], v[220:223], v[24:27]
	v_mfma_f32_16x16x32_bf16 v[12:15], v[144:147], v[228:231], v[12:15]
	v_mfma_f32_16x16x32_bf16 v[8:11], v[152:155], v[228:231], v[8:11]
	v_mfma_f32_16x16x32_bf16 v[60:63], v[148:151], v[206:209], v[60:63]
	v_mfma_f32_16x16x32_bf16 v[56:59], v[156:159], v[206:209], v[56:59]
	v_mfma_f32_16x16x32_bf16 v[44:47], v[148:151], v[214:217], v[44:47]
	v_mfma_f32_16x16x32_bf16 v[40:43], v[156:159], v[214:217], v[40:43]
	v_mfma_f32_16x16x32_bf16 v[28:31], v[148:151], v[224:227], v[28:31]
	v_mfma_f32_16x16x32_bf16 v[24:27], v[156:159], v[224:227], v[24:27]
	v_mfma_f32_16x16x32_bf16 v[12:15], v[148:151], v[232:235], v[12:15]
	v_mfma_f32_16x16x32_bf16 v[8:11], v[156:159], v[232:235], v[8:11]
	v_mfma_f32_16x16x32_bf16 v[52:55], v[160:163], v[194:197], v[52:55]
	v_mfma_f32_16x16x32_bf16 v[48:51], v[172:175], v[194:197], v[48:51]
	v_mfma_f32_16x16x32_bf16 v[36:39], v[160:163], v[210:213], v[36:39]
	v_mfma_f32_16x16x32_bf16 v[32:35], v[172:175], v[210:213], v[32:35]
	v_mfma_f32_16x16x32_bf16 v[20:23], v[160:163], v[220:223], v[20:23]
	v_mfma_f32_16x16x32_bf16 v[16:19], v[172:175], v[220:223], v[16:19]
	v_mfma_f32_16x16x32_bf16 v[4:7], v[160:163], v[228:231], v[4:7]
	v_mfma_f32_16x16x32_bf16 v[0:3], v[172:175], v[228:231], v[0:3]
	v_mfma_f32_16x16x32_bf16 v[52:55], v[168:171], v[206:209], v[52:55]
	v_mfma_f32_16x16x32_bf16 v[48:51], v[176:179], v[206:209], v[48:51]
	v_mfma_f32_16x16x32_bf16 v[36:39], v[168:171], v[214:217], v[36:39]
	v_mfma_f32_16x16x32_bf16 v[32:35], v[176:179], v[214:217], v[32:35]
	v_mfma_f32_16x16x32_bf16 v[20:23], v[168:171], v[224:227], v[20:23]
	v_mfma_f32_16x16x32_bf16 v[16:19], v[176:179], v[224:227], v[16:19]
	v_mfma_f32_16x16x32_bf16 v[4:7], v[168:171], v[232:235], v[4:7]
	v_mfma_f32_16x16x32_bf16 v[0:3], v[176:179], v[232:235], v[0:3]
	s_barrier
	s_add_u32 s0, s0, 0x100
	s_addc_u32 s1, s1, 0
	s_add_u32 s10, s10, 0x100
	s_addc_u32 s11, s11, 0
	s_cmp_ge_i32 s30, s49
	s_mov_b32 s16, s30
	s_cbranch_scc0 .LBB0_844

.LBB0_880:
	s_andn2_b64 vcc, exec, s[14:15]
	s_cbranch_vccnz .LBB0_834
	s_mov_b32 s100, 1
	s_branch .LBB0_834

.LBB0_983:
	s_mov_b32 s100, 0
	s_waitcnt vmcnt(0)
	s_barrier
	s_and_saveexec_b64 s[0:1], s[74:75]
	s_cbranch_execz .LBB0_1035
	v_readlane_b32 s4, v254, 54
	s_waitcnt vmcnt(0) expcnt(0) lgkmcnt(0)
	s_nop 0
	v_mov_b32_e32 v0, s4
	ds_read_b32 v2, v0
	v_readlane_b32 s4, v254, 55
	s_waitcnt lgkmcnt(0)
	v_cmp_ne_u32_e32 vcc, 0, v2
	v_mov_b32_e32 v0, s4
	ds_read_b32 v0, v0
	s_cbranch_vccnz .LBB0_999
	s_mov_b32 s4, 1
	s_branch .LBB0_987

.LBB0_1051:
	v_mov_b32_e32 v123, 0
	s_andn2_b64 vcc, exec, s[20:21]
	v_mov_b32_e32 v122, v123
	v_mov_b32_e32 v121, v123
	v_mov_b32_e32 v120, v123
	v_mov_b32_e32 v127, v123
	v_mov_b32_e32 v126, v123
	v_mov_b32_e32 v125, v123
	v_mov_b32_e32 v124, v123
	v_mov_b32_e32 v111, v123
	v_mov_b32_e32 v110, v123
	v_mov_b32_e32 v109, v123
	v_mov_b32_e32 v108, v123
	v_mov_b32_e32 v107, v123
	v_mov_b32_e32 v106, v123
	v_mov_b32_e32 v105, v123
	v_mov_b32_e32 v104, v123
	v_mov_b32_e32 v95, v123
	v_mov_b32_e32 v94, v123
	v_mov_b32_e32 v93, v123
	v_mov_b32_e32 v92, v123
	v_mov_b32_e32 v91, v123
	v_mov_b32_e32 v90, v123
	v_mov_b32_e32 v89, v123
	v_mov_b32_e32 v88, v123
	v_mov_b32_e32 v79, v123
	v_mov_b32_e32 v78, v123
	v_mov_b32_e32 v77, v123
	v_mov_b32_e32 v76, v123
	v_mov_b32_e32 v75, v123
	v_mov_b32_e32 v74, v123
	v_mov_b32_e32 v73, v123
	v_mov_b32_e32 v72, v123
	v_mov_b32_e32 v119, v123
	v_mov_b32_e32 v118, v123
	v_mov_b32_e32 v117, v123
	v_mov_b32_e32 v116, v123
	v_mov_b32_e32 v115, v123
	v_mov_b32_e32 v114, v123
	v_mov_b32_e32 v113, v123
	v_mov_b32_e32 v112, v123
	v_mov_b32_e32 v103, v123
	v_mov_b32_e32 v102, v123
	v_mov_b32_e32 v101, v123
	v_mov_b32_e32 v100, v123
	v_mov_b32_e32 v99, v123
	v_mov_b32_e32 v98, v123
	v_mov_b32_e32 v97, v123
	v_mov_b32_e32 v96, v123
	v_mov_b32_e32 v87, v123
	v_mov_b32_e32 v86, v123
	v_mov_b32_e32 v85, v123
	v_mov_b32_e32 v84, v123
	v_mov_b32_e32 v83, v123
	v_mov_b32_e32 v82, v123
	v_mov_b32_e32 v81, v123
	v_mov_b32_e32 v80, v123
	v_mov_b32_e32 v71, v123
	v_mov_b32_e32 v70, v123
	v_mov_b32_e32 v69, v123
	v_mov_b32_e32 v68, v123
	v_mov_b32_e32 v67, v123
	v_mov_b32_e32 v66, v123
	v_mov_b32_e32 v65, v123
	v_mov_b32_e32 v64, v123
	v_mov_b32_e32 v63, v123
	v_mov_b32_e32 v62, v123
	v_mov_b32_e32 v61, v123
	v_mov_b32_e32 v60, v123
	v_mov_b32_e32 v59, v123
	v_mov_b32_e32 v58, v123
	v_mov_b32_e32 v57, v123
	v_mov_b32_e32 v56, v123
	v_mov_b32_e32 v47, v123
	v_mov_b32_e32 v46, v123
	v_mov_b32_e32 v45, v123
	v_mov_b32_e32 v44, v123
	v_mov_b32_e32 v43, v123
	v_mov_b32_e32 v42, v123
	v_mov_b32_e32 v41, v123
	v_mov_b32_e32 v40, v123
	v_mov_b32_e32 v31, v123
	v_mov_b32_e32 v30, v123
	v_mov_b32_e32 v29, v123
	v_mov_b32_e32 v28, v123
	v_mov_b32_e32 v27, v123
	v_mov_b32_e32 v26, v123
	v_mov_b32_e32 v25, v123
	v_mov_b32_e32 v24, v123
	v_mov_b32_e32 v15, v123
	v_mov_b32_e32 v14, v123
	v_mov_b32_e32 v13, v123
	v_mov_b32_e32 v12, v123
	v_mov_b32_e32 v11, v123
	v_mov_b32_e32 v10, v123
	v_mov_b32_e32 v9, v123
	v_mov_b32_e32 v8, v123
	v_mov_b32_e32 v55, v123
	v_mov_b32_e32 v54, v123
	v_mov_b32_e32 v53, v123
	v_mov_b32_e32 v52, v123
	v_mov_b32_e32 v51, v123
	v_mov_b32_e32 v50, v123
	v_mov_b32_e32 v49, v123
	v_mov_b32_e32 v48, v123
	v_mov_b32_e32 v39, v123
	v_mov_b32_e32 v38, v123
	v_mov_b32_e32 v37, v123
	v_mov_b32_e32 v36, v123
	v_mov_b32_e32 v35, v123
	v_mov_b32_e32 v34, v123
	v_mov_b32_e32 v33, v123
	v_mov_b32_e32 v32, v123
	v_mov_b32_e32 v23, v123
	v_mov_b32_e32 v22, v123
	v_mov_b32_e32 v21, v123
	v_mov_b32_e32 v20, v123
	v_mov_b32_e32 v19, v123
	v_mov_b32_e32 v18, v123
	v_mov_b32_e32 v17, v123
	v_mov_b32_e32 v16, v123
	v_mov_b32_e32 v7, v123
	v_mov_b32_e32 v6, v123
	v_mov_b32_e32 v5, v123
	v_mov_b32_e32 v4, v123
	v_mov_b32_e32 v3, v123
	v_mov_b32_e32 v2, v123
	s_waitcnt lgkmcnt(0)
	v_mov_b32_e32 v1, v123
	v_mov_b32_e32 v0, v123
	s_cbranch_vccnz .LBB0_1054
	s_add_u32 s28, s28, 0x80
	s_addc_u32 s29, s29, 0
	s_add_u32 s10, s30, 0x100
	s_addc_u32 s11, s31, 0
	s_mov_b32 s16, 0
	s_cmp_lg_u32 s100, 0
	s_cbranch_scc0 .Llbb_9
	s_barrier
	s_mov_b32 s100, 0
.Llbb_9:
.LBB0_1053:
	s_add_i32 s30, s16, 2
	s_add_u32 s31, s28, 0x80
	s_addc_u32 s17, s29, 0
	s_add_i32 s62, 0, 0x10000
	s_cmp_eq_u32 s56, s16
	s_cselect_b32 s17, s25, s17
	s_cselect_b32 s16, s24, s31
	s_cselect_b32 s45, s27, s11
	s_cselect_b32 s44, s26, s10
	s_add_i32 s31, 0, 0x14000
	v_add_u32_e32 v140, s62, v199
	v_add_u32_e32 v166, s31, v199
	ds_read_b128 v[128:131], v140
	ds_read_b128 v[132:135], v140 offset:1024
	ds_read_b128 v[136:139], v140 offset:2048
	ds_read_b128 v[140:143], v140 offset:3072
	ds_read_b128 v[144:147], v166
	ds_read_b128 v[148:151], v166 offset:1024
	ds_read_b128 v[152:155], v166 offset:2048
	ds_read_b128 v[166:169], v166 offset:3072
	v_lshl_add_u64 v[178:179], s[28:29], 0, v[162:163]
	s_add_i32 m0, s37, 0xc000
	ds_read_b128 v[170:173], v206
	ds_read_b128 v[174:177], v206 offset:1024
	ds_read_b128 v[194:197], v206 offset:2048
	ds_read_b128 v[208:211], v206 offset:3072
	ds_read_b128 v[212:215], v206 offset:4096
	ds_read_b128 v[220:223], v206 offset:5120
	ds_read_b128 v[224:227], v206 offset:6144
	ds_read_b128 v[228:231], v206 offset:7168
	global_load_lds_dwordx4 v[178:179], off
	v_lshl_add_u64 v[178:179], s[28:29], 0, v[164:165]
	s_add_i32 m0, s37, 0xe000
	s_nop 0
	global_load_lds_dwordx4 v[178:179], off
	s_waitcnt vmcnt(8)
	s_waitcnt lgkmcnt(0)
	s_barrier
	s_waitcnt lgkmcnt(0)
	v_mfma_f32_16x16x32_bf16 v[120:123], v[128:131], v[170:173], v[120:123]
	v_mfma_f32_16x16x32_bf16 v[124:127], v[136:139], v[170:173], v[124:127]
	v_mfma_f32_16x16x32_bf16 v[108:111], v[128:131], v[194:197], v[108:111]
	v_mfma_f32_16x16x32_bf16 v[104:107], v[136:139], v[194:197], v[104:107]
	v_mfma_f32_16x16x32_bf16 v[92:95], v[128:131], v[212:215], v[92:95]
	v_mfma_f32_16x16x32_bf16 v[88:91], v[136:139], v[212:215], v[88:91]
	v_mfma_f32_16x16x32_bf16 v[76:79], v[128:131], v[224:227], v[76:79]
	v_mfma_f32_16x16x32_bf16 v[72:75], v[136:139], v[224:227], v[72:75]
	v_mfma_f32_16x16x32_bf16 v[120:123], v[132:135], v[174:177], v[120:123]
	v_mfma_f32_16x16x32_bf16 v[124:127], v[140:143], v[174:177], v[124:127]
	v_mfma_f32_16x16x32_bf16 v[108:111], v[132:135], v[208:211], v[108:111]
	v_mfma_f32_16x16x32_bf16 v[104:107], v[140:143], v[208:211], v[104:107]
	v_mfma_f32_16x16x32_bf16 v[92:95], v[132:135], v[220:223], v[92:95]
	v_mfma_f32_16x16x32_bf16 v[88:91], v[140:143], v[220:223], v[88:91]
	v_mfma_f32_16x16x32_bf16 v[76:79], v[132:135], v[228:231], v[76:79]
	v_mfma_f32_16x16x32_bf16 v[72:75], v[140:143], v[228:231], v[72:75]
	v_mfma_f32_16x16x32_bf16 v[116:119], v[144:147], v[170:173], v[116:119]
	v_mfma_f32_16x16x32_bf16 v[112:115], v[152:155], v[170:173], v[112:115]
	v_mfma_f32_16x16x32_bf16 v[100:103], v[144:147], v[194:197], v[100:103]
	v_mfma_f32_16x16x32_bf16 v[96:99], v[152:155], v[194:197], v[96:99]
	v_mfma_f32_16x16x32_bf16 v[84:87], v[144:147], v[212:215], v[84:87]
	v_mfma_f32_16x16x32_bf16 v[80:83], v[152:155], v[212:215], v[80:83]
	v_mfma_f32_16x16x32_bf16 v[68:71], v[144:147], v[224:227], v[68:71]
	v_mfma_f32_16x16x32_bf16 v[64:67], v[152:155], v[224:227], v[64:67]
	v_mfma_f32_16x16x32_bf16 v[116:119], v[148:151], v[174:177], v[116:119]
	v_mfma_f32_16x16x32_bf16 v[112:115], v[166:169], v[174:177], v[112:115]
	v_mfma_f32_16x16x32_bf16 v[100:103], v[148:151], v[208:211], v[100:103]
	v_mfma_f32_16x16x32_bf16 v[96:99], v[166:169], v[208:211], v[96:99]
	v_mfma_f32_16x16x32_bf16 v[84:87], v[148:151], v[220:223], v[84:87]
	v_mfma_f32_16x16x32_bf16 v[80:83], v[166:169], v[220:223], v[80:83]
	v_mfma_f32_16x16x32_bf16 v[68:71], v[148:151], v[228:231], v[68:71]
	v_mfma_f32_16x16x32_bf16 v[64:67], v[166:169], v[228:231], v[64:67]
	s_barrier
	s_add_i32 s62, s62, s36
	v_lshl_add_u64 v[178:179], s[44:45], 0, v[180:181]
	s_mov_b32 m0, s62
	ds_read_b128 v[170:173], v206 offset:16384
	ds_read_b128 v[174:177], v206 offset:17408
	ds_read_b128 v[194:197], v206 offset:18432
	ds_read_b128 v[208:211], v206 offset:19456
	ds_read_b128 v[212:215], v206 offset:20480
	ds_read_b128 v[220:223], v206 offset:21504
	ds_read_b128 v[224:227], v206 offset:22528
	ds_read_b128 v[228:231], v206 offset:23552
	global_load_lds_dwordx4 v[178:179], off
	s_add_i32 m0, s62, 0x2000
	v_lshl_add_u64 v[202:203], s[44:45], 0, v[156:157]
	s_add_u32 s44, s44, s6
	s_addc_u32 s45, s45, s7
	s_add_i32 s31, s31, s36
	global_load_lds_dwordx4 v[202:203], off
	v_lshl_add_u64 v[216:217], s[44:45], 0, v[180:181]
	s_mov_b32 m0, s31
	v_lshl_add_u64 v[232:233], s[44:45], 0, v[156:157]
	global_load_lds_dwordx4 v[216:217], off
	s_add_i32 m0, s31, 0x2000
	v_lshl_add_u64 v[234:235], s[16:17], 0, v[160:161]
	global_load_lds_dwordx4 v[232:233], off
	s_mov_b32 m0, s37
	v_lshl_add_u64 v[236:237], s[16:17], 0, v[158:159]
	global_load_lds_dwordx4 v[234:235], off
	s_mov_b32 m0, s38
	s_nop 0
	global_load_lds_dwordx4 v[236:237], off
	s_waitcnt vmcnt(8)
	s_waitcnt lgkmcnt(0)
	s_barrier
	s_waitcnt lgkmcnt(0)
	v_mfma_f32_16x16x32_bf16 v[60:63], v[128:131], v[170:173], v[60:63]
	v_mfma_f32_16x16x32_bf16 v[56:59], v[136:139], v[170:173], v[56:59]
	v_mfma_f32_16x16x32_bf16 v[44:47], v[128:131], v[194:197], v[44:47]
	v_mfma_f32_16x16x32_bf16 v[40:43], v[136:139], v[194:197], v[40:43]
	v_mfma_f32_16x16x32_bf16 v[28:31], v[128:131], v[212:215], v[28:31]
	v_mfma_f32_16x16x32_bf16 v[24:27], v[136:139], v[212:215], v[24:27]
	v_mfma_f32_16x16x32_bf16 v[12:15], v[128:131], v[224:227], v[12:15]
	v_mfma_f32_16x16x32_bf16 v[8:11], v[136:139], v[224:227], v[8:11]
	v_mfma_f32_16x16x32_bf16 v[60:63], v[132:135], v[174:177], v[60:63]
	v_mfma_f32_16x16x32_bf16 v[56:59], v[140:143], v[174:177], v[56:59]
	v_mfma_f32_16x16x32_bf16 v[44:47], v[132:135], v[208:211], v[44:47]
	v_mfma_f32_16x16x32_bf16 v[40:43], v[140:143], v[208:211], v[40:43]
	v_mfma_f32_16x16x32_bf16 v[28:31], v[132:135], v[220:223], v[28:31]
	v_mfma_f32_16x16x32_bf16 v[24:27], v[140:143], v[220:223], v[24:27]
	v_mfma_f32_16x16x32_bf16 v[12:15], v[132:135], v[228:231], v[12:15]
	v_mfma_f32_16x16x32_bf16 v[8:11], v[140:143], v[228:231], v[8:11]
	v_mfma_f32_16x16x32_bf16 v[52:55], v[144:147], v[170:173], v[52:55]
	v_mfma_f32_16x16x32_bf16 v[48:51], v[152:155], v[170:173], v[48:51]
	v_mfma_f32_16x16x32_bf16 v[36:39], v[144:147], v[194:197], v[36:39]
	v_mfma_f32_16x16x32_bf16 v[32:35], v[152:155], v[194:197], v[32:35]
	v_mfma_f32_16x16x32_bf16 v[20:23], v[144:147], v[212:215], v[20:23]
	v_mfma_f32_16x16x32_bf16 v[16:19], v[152:155], v[212:215], v[16:19]
	v_mfma_f32_16x16x32_bf16 v[4:7], v[144:147], v[224:227], v[4:7]
	v_mfma_f32_16x16x32_bf16 v[0:3], v[152:155], v[224:227], v[0:3]
	v_mfma_f32_16x16x32_bf16 v[52:55], v[148:151], v[174:177], v[52:55]
	v_mfma_f32_16x16x32_bf16 v[48:51], v[166:169], v[174:177], v[48:51]
	v_mfma_f32_16x16x32_bf16 v[36:39], v[148:151], v[208:211], v[36:39]
	v_mfma_f32_16x16x32_bf16 v[32:35], v[166:169], v[208:211], v[32:35]
	v_mfma_f32_16x16x32_bf16 v[20:23], v[148:151], v[220:223], v[20:23]
	v_mfma_f32_16x16x32_bf16 v[16:19], v[166:169], v[220:223], v[16:19]
	v_mfma_f32_16x16x32_bf16 v[4:7], v[148:151], v[228:231], v[4:7]
	v_mfma_f32_16x16x32_bf16 v[0:3], v[166:169], v[228:231], v[0:3]
	s_barrier
	s_add_i32 s31, 0, 0x18000
	s_add_i32 s44, 0, 0x1c000
	v_add_u32_e32 v140, s31, v199
	v_add_u32_e32 v166, s44, v199
	ds_read_b128 v[128:131], v140
	ds_read_b128 v[132:135], v140 offset:1024
	ds_read_b128 v[136:139], v140 offset:2048
	ds_read_b128 v[140:143], v140 offset:3072
	ds_read_b128 v[144:147], v166
	ds_read_b128 v[148:151], v166 offset:1024
	ds_read_b128 v[152:155], v166 offset:2048
	ds_read_b128 v[166:169], v166 offset:3072
	s_add_u32 s16, s16, s6
	s_addc_u32 s17, s17, s7
	s_mov_b32 m0, s39
	v_lshl_add_u64 v[238:239], s[16:17], 0, v[160:161]
	ds_read_b128 v[170:173], v206 offset:32768
	ds_read_b128 v[174:177], v206 offset:33792
	ds_read_b128 v[194:197], v206 offset:34816
	ds_read_b128 v[208:211], v206 offset:35840
	ds_read_b128 v[212:215], v206 offset:36864
	ds_read_b128 v[220:223], v206 offset:37888
	ds_read_b128 v[224:227], v206 offset:38912
	ds_read_b128 v[228:231], v206 offset:39936
	global_load_lds_dwordx4 v[238:239], off
	v_lshl_add_u64 v[238:239], s[16:17], 0, v[158:159]
	s_mov_b32 m0, s46
	s_nop 0
	global_load_lds_dwordx4 v[238:239], off
	s_waitcnt vmcnt(8)
	s_waitcnt lgkmcnt(0)
	s_barrier
	s_waitcnt lgkmcnt(0)
	v_mfma_f32_16x16x32_bf16 v[120:123], v[128:131], v[170:173], v[120:123]
	v_mfma_f32_16x16x32_bf16 v[124:127], v[136:139], v[170:173], v[124:127]
	v_mfma_f32_16x16x32_bf16 v[108:111], v[128:131], v[194:197], v[108:111]
	v_mfma_f32_16x16x32_bf16 v[104:107], v[136:139], v[194:197], v[104:107]
	v_mfma_f32_16x16x32_bf16 v[92:95], v[128:131], v[212:215], v[92:95]
	v_mfma_f32_16x16x32_bf16 v[88:91], v[136:139], v[212:215], v[88:91]
	v_mfma_f32_16x16x32_bf16 v[76:79], v[128:131], v[224:227], v[76:79]
	v_mfma_f32_16x16x32_bf16 v[72:75], v[136:139], v[224:227], v[72:75]
	v_mfma_f32_16x16x32_bf16 v[120:123], v[132:135], v[174:177], v[120:123]
	v_mfma_f32_16x16x32_bf16 v[124:127], v[140:143], v[174:177], v[124:127]
	v_mfma_f32_16x16x32_bf16 v[108:111], v[132:135], v[208:211], v[108:111]
	v_mfma_f32_16x16x32_bf16 v[104:107], v[140:143], v[208:211], v[104:107]
	v_mfma_f32_16x16x32_bf16 v[92:95], v[132:135], v[220:223], v[92:95]
	v_mfma_f32_16x16x32_bf16 v[88:91], v[140:143], v[220:223], v[88:91]
	v_mfma_f32_16x16x32_bf16 v[76:79], v[132:135], v[228:231], v[76:79]
	v_mfma_f32_16x16x32_bf16 v[72:75], v[140:143], v[228:231], v[72:75]
	v_mfma_f32_16x16x32_bf16 v[116:119], v[144:147], v[170:173], v[116:119]
	v_mfma_f32_16x16x32_bf16 v[112:115], v[152:155], v[170:173], v[112:115]
	v_mfma_f32_16x16x32_bf16 v[100:103], v[144:147], v[194:197], v[100:103]
	v_mfma_f32_16x16x32_bf16 v[96:99], v[152:155], v[194:197], v[96:99]
	v_mfma_f32_16x16x32_bf16 v[84:87], v[144:147], v[212:215], v[84:87]
	v_mfma_f32_16x16x32_bf16 v[80:83], v[152:155], v[212:215], v[80:83]
	v_mfma_f32_16x16x32_bf16 v[68:71], v[144:147], v[224:227], v[68:71]
	v_mfma_f32_16x16x32_bf16 v[64:67], v[152:155], v[224:227], v[64:67]
	v_mfma_f32_16x16x32_bf16 v[116:119], v[148:151], v[174:177], v[116:119]
	v_mfma_f32_16x16x32_bf16 v[112:115], v[166:169], v[174:177], v[112:115]
	v_mfma_f32_16x16x32_bf16 v[100:103], v[148:151], v[208:211], v[100:103]
	v_mfma_f32_16x16x32_bf16 v[96:99], v[166:169], v[208:211], v[96:99]
	v_mfma_f32_16x16x32_bf16 v[84:87], v[148:151], v[220:223], v[84:87]
	v_mfma_f32_16x16x32_bf16 v[80:83], v[166:169], v[220:223], v[80:83]
	v_mfma_f32_16x16x32_bf16 v[68:71], v[148:151], v[228:231], v[68:71]
	v_mfma_f32_16x16x32_bf16 v[64:67], v[166:169], v[228:231], v[64:67]
	s_barrier
	s_add_i32 s16, s31, s36
	v_lshl_add_u64 v[178:179], v[178:179], 0, s[12:13]
	s_mov_b32 m0, s16
	ds_read_b128 v[170:173], v206 offset:49152
	ds_read_b128 v[174:177], v206 offset:50176
	ds_read_b128 v[194:197], v206 offset:51200
	ds_read_b128 v[208:211], v206 offset:52224
	ds_read_b128 v[212:215], v206 offset:53248
	ds_read_b128 v[220:223], v206 offset:54272
	ds_read_b128 v[224:227], v206 offset:55296
	ds_read_b128 v[228:231], v206 offset:56320
	global_load_lds_dwordx4 v[178:179], off
	v_lshl_add_u64 v[178:179], v[202:203], 0, s[12:13]
	s_add_i32 m0, s16, 0x2000
	s_add_i32 s16, s44, s36
	global_load_lds_dwordx4 v[178:179], off
	v_lshl_add_u64 v[178:179], v[216:217], 0, s[12:13]
	s_mov_b32 m0, s16
	s_nop 0
	global_load_lds_dwordx4 v[178:179], off
	v_lshl_add_u64 v[178:179], v[232:233], 0, s[12:13]
	s_add_i32 m0, s16, 0x2000
	s_nop 0
	global_load_lds_dwordx4 v[178:179], off
	v_lshl_add_u64 v[178:179], v[234:235], 0, s[12:13]
	s_mov_b32 m0, s49
	s_nop 0
	global_load_lds_dwordx4 v[178:179], off
	v_lshl_add_u64 v[178:179], v[236:237], 0, s[12:13]
	s_mov_b32 m0, s52
	s_nop 0
	global_load_lds_dwordx4 v[178:179], off
	s_waitcnt vmcnt(8)
	s_waitcnt lgkmcnt(0)
	s_barrier
	s_waitcnt lgkmcnt(0)
	v_mfma_f32_16x16x32_bf16 v[60:63], v[128:131], v[170:173], v[60:63]
	v_mfma_f32_16x16x32_bf16 v[56:59], v[136:139], v[170:173], v[56:59]
	v_mfma_f32_16x16x32_bf16 v[44:47], v[128:131], v[194:197], v[44:47]
	v_mfma_f32_16x16x32_bf16 v[40:43], v[136:139], v[194:197], v[40:43]
	v_mfma_f32_16x16x32_bf16 v[28:31], v[128:131], v[212:215], v[28:31]
	v_mfma_f32_16x16x32_bf16 v[24:27], v[136:139], v[212:215], v[24:27]
	v_mfma_f32_16x16x32_bf16 v[12:15], v[128:131], v[224:227], v[12:15]
	v_mfma_f32_16x16x32_bf16 v[8:11], v[136:139], v[224:227], v[8:11]
	v_mfma_f32_16x16x32_bf16 v[60:63], v[132:135], v[174:177], v[60:63]
	v_mfma_f32_16x16x32_bf16 v[56:59], v[140:143], v[174:177], v[56:59]
	v_mfma_f32_16x16x32_bf16 v[44:47], v[132:135], v[208:211], v[44:47]
	v_mfma_f32_16x16x32_bf16 v[40:43], v[140:143], v[208:211], v[40:43]
	v_mfma_f32_16x16x32_bf16 v[28:31], v[132:135], v[220:223], v[28:31]
	v_mfma_f32_16x16x32_bf16 v[24:27], v[140:143], v[220:223], v[24:27]
	v_mfma_f32_16x16x32_bf16 v[12:15], v[132:135], v[228:231], v[12:15]
	v_mfma_f32_16x16x32_bf16 v[8:11], v[140:143], v[228:231], v[8:11]
	v_mfma_f32_16x16x32_bf16 v[52:55], v[144:147], v[170:173], v[52:55]
	v_mfma_f32_16x16x32_bf16 v[48:51], v[152:155], v[170:173], v[48:51]
	v_mfma_f32_16x16x32_bf16 v[36:39], v[144:147], v[194:197], v[36:39]
	v_mfma_f32_16x16x32_bf16 v[32:35], v[152:155], v[194:197], v[32:35]
	v_mfma_f32_16x16x32_bf16 v[20:23], v[144:147], v[212:215], v[20:23]
	v_mfma_f32_16x16x32_bf16 v[16:19], v[152:155], v[212:215], v[16:19]
	v_mfma_f32_16x16x32_bf16 v[4:7], v[144:147], v[224:227], v[4:7]
	v_mfma_f32_16x16x32_bf16 v[0:3], v[152:155], v[224:227], v[0:3]
	v_mfma_f32_16x16x32_bf16 v[52:55], v[148:151], v[174:177], v[52:55]
	v_mfma_f32_16x16x32_bf16 v[48:51], v[166:169], v[174:177], v[48:51]
	v_mfma_f32_16x16x32_bf16 v[36:39], v[148:151], v[208:211], v[36:39]
	v_mfma_f32_16x16x32_bf16 v[32:35], v[166:169], v[208:211], v[32:35]
	v_mfma_f32_16x16x32_bf16 v[20:23], v[148:151], v[220:223], v[20:23]
	v_mfma_f32_16x16x32_bf16 v[16:19], v[166:169], v[220:223], v[16:19]
	v_mfma_f32_16x16x32_bf16 v[4:7], v[148:151], v[228:231], v[4:7]
	v_mfma_f32_16x16x32_bf16 v[0:3], v[166:169], v[228:231], v[0:3]
	s_barrier
	s_add_u32 s28, s28, 0x100
	s_addc_u32 s29, s29, 0
	s_add_u32 s10, s10, 0x100
	s_addc_u32 s11, s11, 0
	s_cmp_ge_i32 s30, s48
	s_mov_b32 s16, s30
	s_cbranch_scc0 .LBB0_1053

.LBB0_1072:
	s_or_b64 exec, exec, s[10:11]
	v_lshlrev_b32_e32 v250, 2, v218
	v_add_u32_e32 v250, 0x20400, v250
	ds_read_b32 v240, v250
	s_waitcnt lgkmcnt(0)
	s_and_b64 vcc, exec, s[42:43]
	s_mov_b64 s[10:11], -1
	s_cbranch_vccnz .LBB0_1040
	s_andn2_b64 vcc, exec, s[14:15]
	s_cbranch_vccnz .LBB0_1039
	s_mov_b32 s100, 1
	s_branch .LBB0_1039

.LBB0_1143:
	s_add_u32 s28, s28, 0x80
	s_addc_u32 s29, s29, 0
	s_add_u32 s10, s30, 0x100
	v_mov_b32_e32 v0, 0
	s_addc_u32 s11, s31, 0
	s_mov_b32 s16, 0
	v_mov_b32_e32 v1, v0
	v_mov_b32_e32 v2, v0
	v_mov_b32_e32 v3, v0
	v_mov_b32_e32 v8, v0
	v_mov_b32_e32 v9, v0
	v_mov_b32_e32 v10, v0
	v_mov_b32_e32 v11, v0
	v_mov_b32_e32 v16, v0
	v_mov_b32_e32 v17, v0
	v_mov_b32_e32 v18, v0
	v_mov_b32_e32 v19, v0
	v_mov_b32_e32 v24, v0
	v_mov_b32_e32 v25, v0
	v_mov_b32_e32 v26, v0
	v_mov_b32_e32 v27, v0
	v_mov_b32_e32 v32, v0
	v_mov_b32_e32 v33, v0
	v_mov_b32_e32 v34, v0
	v_mov_b32_e32 v35, v0
	v_mov_b32_e32 v40, v0
	v_mov_b32_e32 v41, v0
	v_mov_b32_e32 v42, v0
	v_mov_b32_e32 v43, v0
	v_mov_b32_e32 v48, v0
	v_mov_b32_e32 v49, v0
	v_mov_b32_e32 v50, v0
	v_mov_b32_e32 v51, v0
	v_mov_b32_e32 v56, v0
	v_mov_b32_e32 v57, v0
	v_mov_b32_e32 v58, v0
	v_mov_b32_e32 v59, v0
	v_mov_b32_e32 v4, v0
	v_mov_b32_e32 v5, v0
	v_mov_b32_e32 v6, v0
	v_mov_b32_e32 v7, v0
	v_mov_b32_e32 v12, v0
	v_mov_b32_e32 v13, v0
	v_mov_b32_e32 v14, v0
	v_mov_b32_e32 v15, v0
	v_mov_b32_e32 v20, v0
	v_mov_b32_e32 v21, v0
	v_mov_b32_e32 v22, v0
	v_mov_b32_e32 v23, v0
	v_mov_b32_e32 v28, v0
	v_mov_b32_e32 v29, v0
	v_mov_b32_e32 v30, v0
	v_mov_b32_e32 v31, v0
	v_mov_b32_e32 v36, v0
	v_mov_b32_e32 v37, v0
	v_mov_b32_e32 v38, v0
	v_mov_b32_e32 v39, v0
	v_mov_b32_e32 v44, v0
	v_mov_b32_e32 v45, v0
	v_mov_b32_e32 v46, v0
	v_mov_b32_e32 v47, v0
	v_mov_b32_e32 v52, v0
	v_mov_b32_e32 v53, v0
	v_mov_b32_e32 v54, v0
	v_mov_b32_e32 v55, v0
	v_mov_b32_e32 v60, v0
	v_mov_b32_e32 v61, v0
	v_mov_b32_e32 v62, v0
	v_mov_b32_e32 v63, v0
	v_mov_b32_e32 v64, v0
	v_mov_b32_e32 v65, v0
	v_mov_b32_e32 v66, v0
	v_mov_b32_e32 v67, v0
	v_mov_b32_e32 v72, v0
	v_mov_b32_e32 v73, v0
	v_mov_b32_e32 v74, v0
	v_mov_b32_e32 v75, v0
	v_mov_b32_e32 v80, v0
	v_mov_b32_e32 v81, v0
	v_mov_b32_e32 v82, v0
	v_mov_b32_e32 v83, v0
	v_mov_b32_e32 v88, v0
	v_mov_b32_e32 v89, v0
	v_mov_b32_e32 v90, v0
	v_mov_b32_e32 v91, v0
	v_mov_b32_e32 v96, v0
	v_mov_b32_e32 v97, v0
	v_mov_b32_e32 v98, v0
	v_mov_b32_e32 v99, v0
	v_mov_b32_e32 v104, v0
	v_mov_b32_e32 v105, v0
	v_mov_b32_e32 v106, v0
	v_mov_b32_e32 v107, v0
	v_mov_b32_e32 v112, v0
	v_mov_b32_e32 v113, v0
	v_mov_b32_e32 v114, v0
	v_mov_b32_e32 v115, v0
	v_mov_b32_e32 v124, v0
	v_mov_b32_e32 v125, v0
	v_mov_b32_e32 v126, v0
	v_mov_b32_e32 v127, v0
	v_mov_b32_e32 v68, v0
	v_mov_b32_e32 v69, v0
	v_mov_b32_e32 v70, v0
	v_mov_b32_e32 v71, v0
	v_mov_b32_e32 v76, v0
	v_mov_b32_e32 v77, v0
	v_mov_b32_e32 v78, v0
	v_mov_b32_e32 v79, v0
	v_mov_b32_e32 v84, v0
	v_mov_b32_e32 v85, v0
	v_mov_b32_e32 v86, v0
	v_mov_b32_e32 v87, v0
	v_mov_b32_e32 v92, v0
	v_mov_b32_e32 v93, v0
	v_mov_b32_e32 v94, v0
	v_mov_b32_e32 v95, v0
	v_mov_b32_e32 v100, v0
	v_mov_b32_e32 v101, v0
	v_mov_b32_e32 v102, v0
	v_mov_b32_e32 v103, v0
	v_mov_b32_e32 v108, v0
	v_mov_b32_e32 v109, v0
	v_mov_b32_e32 v110, v0
	v_mov_b32_e32 v111, v0
	v_mov_b32_e32 v116, v0
	v_mov_b32_e32 v117, v0
	v_mov_b32_e32 v118, v0
	v_mov_b32_e32 v119, v0
	v_mov_b32_e32 v120, v0
	v_mov_b32_e32 v121, v0
	v_mov_b32_e32 v122, v0
	v_mov_b32_e32 v123, v0
	s_waitcnt vmcnt(0)
	s_cmp_lg_u32 s100, 0
	s_cbranch_scc0 .Llbb_10
	s_barrier
	s_mov_b32 s100, 0
.Llbb_10:
.LBB0_1144:
	s_add_i32 s30, s16, 2
	s_add_u32 s31, s28, 0x80
	s_addc_u32 s17, s29, 0
	s_add_i32 s63, 0, 0x10000
	s_cmp_eq_u32 s56, s16
	s_cselect_b32 s17, s25, s17
	s_cselect_b32 s16, s24, s31
	s_cselect_b32 s45, s27, s11
	s_cselect_b32 s44, s26, s10
	s_add_i32 s31, 0, 0x14000
	v_add_u32_e32 v156, s63, v151
	v_add_u32_e32 v172, s31, v151
	ds_read_b128 v[128:131], v156
	ds_read_b128 v[142:145], v156 offset:1024
	ds_read_b128 v[146:149], v156 offset:2048
	ds_read_b128 v[156:159], v156 offset:3072
	ds_read_b128 v[160:163], v172
	ds_read_b128 v[164:167], v172 offset:1024
	ds_read_b128 v[168:171], v172 offset:2048
	ds_read_b128 v[172:175], v172 offset:3072
	v_lshl_add_u64 v[198:199], s[28:29], 0, v[138:139]
	s_add_i32 m0, s37, 0xc000
	ds_read_b128 v[176:179], v155
	ds_read_b128 v[194:197], v155 offset:1024
	ds_read_b128 v[206:209], v155 offset:2048
	ds_read_b128 v[210:213], v155 offset:3072
	ds_read_b128 v[214:217], v155 offset:4096
	ds_read_b128 v[220:223], v155 offset:5120
	ds_read_b128 v[224:227], v155 offset:6144
	ds_read_b128 v[228:231], v155 offset:7168
	global_load_lds_dwordx4 v[198:199], off
	v_lshl_add_u64 v[198:199], s[28:29], 0, v[140:141]
	s_add_i32 m0, s37, 0xe000
	s_nop 0
	global_load_lds_dwordx4 v[198:199], off
	s_waitcnt vmcnt(8)
	s_waitcnt lgkmcnt(0)
	s_barrier
	s_waitcnt lgkmcnt(0)
	v_mfma_f32_16x16x32_bf16 v[120:123], v[128:131], v[176:179], v[120:123]
	v_mfma_f32_16x16x32_bf16 v[116:119], v[146:149], v[176:179], v[116:119]
	v_mfma_f32_16x16x32_bf16 v[108:111], v[128:131], v[206:209], v[108:111]
	v_mfma_f32_16x16x32_bf16 v[100:103], v[146:149], v[206:209], v[100:103]
	v_mfma_f32_16x16x32_bf16 v[92:95], v[128:131], v[214:217], v[92:95]
	v_mfma_f32_16x16x32_bf16 v[84:87], v[146:149], v[214:217], v[84:87]
	v_mfma_f32_16x16x32_bf16 v[76:79], v[128:131], v[224:227], v[76:79]
	v_mfma_f32_16x16x32_bf16 v[68:71], v[146:149], v[224:227], v[68:71]
	v_mfma_f32_16x16x32_bf16 v[120:123], v[142:145], v[194:197], v[120:123]
	v_mfma_f32_16x16x32_bf16 v[116:119], v[156:159], v[194:197], v[116:119]
	v_mfma_f32_16x16x32_bf16 v[108:111], v[142:145], v[210:213], v[108:111]
	v_mfma_f32_16x16x32_bf16 v[100:103], v[156:159], v[210:213], v[100:103]
	v_mfma_f32_16x16x32_bf16 v[92:95], v[142:145], v[220:223], v[92:95]
	v_mfma_f32_16x16x32_bf16 v[84:87], v[156:159], v[220:223], v[84:87]
	v_mfma_f32_16x16x32_bf16 v[76:79], v[142:145], v[228:231], v[76:79]
	v_mfma_f32_16x16x32_bf16 v[68:71], v[156:159], v[228:231], v[68:71]
	v_mfma_f32_16x16x32_bf16 v[124:127], v[160:163], v[176:179], v[124:127]
	v_mfma_f32_16x16x32_bf16 v[112:115], v[168:171], v[176:179], v[112:115]
	v_mfma_f32_16x16x32_bf16 v[104:107], v[160:163], v[206:209], v[104:107]
	v_mfma_f32_16x16x32_bf16 v[96:99], v[168:171], v[206:209], v[96:99]
	v_mfma_f32_16x16x32_bf16 v[88:91], v[160:163], v[214:217], v[88:91]
	v_mfma_f32_16x16x32_bf16 v[80:83], v[168:171], v[214:217], v[80:83]
	v_mfma_f32_16x16x32_bf16 v[72:75], v[160:163], v[224:227], v[72:75]
	v_mfma_f32_16x16x32_bf16 v[64:67], v[168:171], v[224:227], v[64:67]
	v_mfma_f32_16x16x32_bf16 v[124:127], v[164:167], v[194:197], v[124:127]
	v_mfma_f32_16x16x32_bf16 v[112:115], v[172:175], v[194:197], v[112:115]
	v_mfma_f32_16x16x32_bf16 v[104:107], v[164:167], v[210:213], v[104:107]
	v_mfma_f32_16x16x32_bf16 v[96:99], v[172:175], v[210:213], v[96:99]
	v_mfma_f32_16x16x32_bf16 v[88:91], v[164:167], v[220:223], v[88:91]
	v_mfma_f32_16x16x32_bf16 v[80:83], v[172:175], v[220:223], v[80:83]
	v_mfma_f32_16x16x32_bf16 v[72:75], v[164:167], v[228:231], v[72:75]
	v_mfma_f32_16x16x32_bf16 v[64:67], v[172:175], v[228:231], v[64:67]
	s_barrier
	s_add_i32 s63, s63, s36
	v_lshl_add_u64 v[198:199], s[44:45], 0, v[180:181]
	s_mov_b32 m0, s63
	ds_read_b128 v[176:179], v155 offset:16384
	ds_read_b128 v[194:197], v155 offset:17408
	ds_read_b128 v[206:209], v155 offset:18432
	ds_read_b128 v[210:213], v155 offset:19456
	ds_read_b128 v[214:217], v155 offset:20480
	ds_read_b128 v[220:223], v155 offset:21504
	ds_read_b128 v[224:227], v155 offset:22528
	ds_read_b128 v[228:231], v155 offset:23552
	global_load_lds_dwordx4 v[198:199], off
	s_add_i32 m0, s63, 0x2000
	v_lshl_add_u64 v[202:203], s[44:45], 0, v[132:133]
	s_add_u32 s44, s44, s6
	s_addc_u32 s45, s45, s7
	s_add_i32 s31, s31, s36
	global_load_lds_dwordx4 v[202:203], off
	v_lshl_add_u64 v[232:233], s[44:45], 0, v[180:181]
	s_mov_b32 m0, s31
	v_lshl_add_u64 v[234:235], s[44:45], 0, v[132:133]
	global_load_lds_dwordx4 v[232:233], off
	s_add_i32 m0, s31, 0x2000
	v_lshl_add_u64 v[236:237], s[16:17], 0, v[136:137]
	global_load_lds_dwordx4 v[234:235], off
	s_mov_b32 m0, s37
	v_lshl_add_u64 v[238:239], s[16:17], 0, v[134:135]
	global_load_lds_dwordx4 v[236:237], off
	s_mov_b32 m0, s38
	s_nop 0
	global_load_lds_dwordx4 v[238:239], off
	s_waitcnt vmcnt(8)
	s_waitcnt lgkmcnt(0)
	s_barrier
	s_waitcnt lgkmcnt(0)
	v_mfma_f32_16x16x32_bf16 v[60:63], v[128:131], v[176:179], v[60:63]
	v_mfma_f32_16x16x32_bf16 v[52:55], v[146:149], v[176:179], v[52:55]
	v_mfma_f32_16x16x32_bf16 v[44:47], v[128:131], v[206:209], v[44:47]
	v_mfma_f32_16x16x32_bf16 v[36:39], v[146:149], v[206:209], v[36:39]
	v_mfma_f32_16x16x32_bf16 v[28:31], v[128:131], v[214:217], v[28:31]
	v_mfma_f32_16x16x32_bf16 v[20:23], v[146:149], v[214:217], v[20:23]
	v_mfma_f32_16x16x32_bf16 v[12:15], v[128:131], v[224:227], v[12:15]
	v_mfma_f32_16x16x32_bf16 v[4:7], v[146:149], v[224:227], v[4:7]
	v_mfma_f32_16x16x32_bf16 v[60:63], v[142:145], v[194:197], v[60:63]
	v_mfma_f32_16x16x32_bf16 v[52:55], v[156:159], v[194:197], v[52:55]
	v_mfma_f32_16x16x32_bf16 v[44:47], v[142:145], v[210:213], v[44:47]
	v_mfma_f32_16x16x32_bf16 v[36:39], v[156:159], v[210:213], v[36:39]
	v_mfma_f32_16x16x32_bf16 v[28:31], v[142:145], v[220:223], v[28:31]
	v_mfma_f32_16x16x32_bf16 v[20:23], v[156:159], v[220:223], v[20:23]
	v_mfma_f32_16x16x32_bf16 v[12:15], v[142:145], v[228:231], v[12:15]
	v_mfma_f32_16x16x32_bf16 v[4:7], v[156:159], v[228:231], v[4:7]
	v_mfma_f32_16x16x32_bf16 v[56:59], v[160:163], v[176:179], v[56:59]
	v_mfma_f32_16x16x32_bf16 v[48:51], v[168:171], v[176:179], v[48:51]
	v_mfma_f32_16x16x32_bf16 v[40:43], v[160:163], v[206:209], v[40:43]
	v_mfma_f32_16x16x32_bf16 v[32:35], v[168:171], v[206:209], v[32:35]
	v_mfma_f32_16x16x32_bf16 v[24:27], v[160:163], v[214:217], v[24:27]
	v_mfma_f32_16x16x32_bf16 v[16:19], v[168:171], v[214:217], v[16:19]
	v_mfma_f32_16x16x32_bf16 v[8:11], v[160:163], v[224:227], v[8:11]
	v_mfma_f32_16x16x32_bf16 v[0:3], v[168:171], v[224:227], v[0:3]
	v_mfma_f32_16x16x32_bf16 v[56:59], v[164:167], v[194:197], v[56:59]
	v_mfma_f32_16x16x32_bf16 v[48:51], v[172:175], v[194:197], v[48:51]
	v_mfma_f32_16x16x32_bf16 v[40:43], v[164:167], v[210:213], v[40:43]
	v_mfma_f32_16x16x32_bf16 v[32:35], v[172:175], v[210:213], v[32:35]
	v_mfma_f32_16x16x32_bf16 v[24:27], v[164:167], v[220:223], v[24:27]
	v_mfma_f32_16x16x32_bf16 v[16:19], v[172:175], v[220:223], v[16:19]
	v_mfma_f32_16x16x32_bf16 v[8:11], v[164:167], v[228:231], v[8:11]
	v_mfma_f32_16x16x32_bf16 v[0:3], v[172:175], v[228:231], v[0:3]
	s_barrier
	s_add_i32 s31, 0, 0x18000
	s_add_i32 s44, 0, 0x1c000
	v_add_u32_e32 v156, s31, v151
	v_add_u32_e32 v172, s44, v151
	ds_read_b128 v[128:131], v156
	ds_read_b128 v[142:145], v156 offset:1024
	ds_read_b128 v[146:149], v156 offset:2048
	ds_read_b128 v[156:159], v156 offset:3072
	ds_read_b128 v[160:163], v172
	ds_read_b128 v[164:167], v172 offset:1024
	ds_read_b128 v[168:171], v172 offset:2048
	ds_read_b128 v[172:175], v172 offset:3072
	s_add_u32 s16, s16, s6
	s_addc_u32 s17, s17, s7
	s_mov_b32 m0, s39
	v_lshl_add_u64 v[240:241], s[16:17], 0, v[136:137]
	ds_read_b128 v[176:179], v155 offset:32768
	ds_read_b128 v[194:197], v155 offset:33792
	ds_read_b128 v[206:209], v155 offset:34816
	ds_read_b128 v[210:213], v155 offset:35840
	ds_read_b128 v[214:217], v155 offset:36864
	ds_read_b128 v[220:223], v155 offset:37888
	ds_read_b128 v[224:227], v155 offset:38912
	ds_read_b128 v[228:231], v155 offset:39936
	global_load_lds_dwordx4 v[240:241], off
	v_lshl_add_u64 v[240:241], s[16:17], 0, v[134:135]
	s_mov_b32 m0, s46
	s_nop 0
	global_load_lds_dwordx4 v[240:241], off
	s_waitcnt vmcnt(8)
	s_waitcnt lgkmcnt(0)
	s_barrier
	s_waitcnt lgkmcnt(0)
	v_mfma_f32_16x16x32_bf16 v[120:123], v[128:131], v[176:179], v[120:123]
	v_mfma_f32_16x16x32_bf16 v[116:119], v[146:149], v[176:179], v[116:119]
	v_mfma_f32_16x16x32_bf16 v[108:111], v[128:131], v[206:209], v[108:111]
	v_mfma_f32_16x16x32_bf16 v[100:103], v[146:149], v[206:209], v[100:103]
	v_mfma_f32_16x16x32_bf16 v[92:95], v[128:131], v[214:217], v[92:95]
	v_mfma_f32_16x16x32_bf16 v[84:87], v[146:149], v[214:217], v[84:87]
	v_mfma_f32_16x16x32_bf16 v[76:79], v[128:131], v[224:227], v[76:79]
	v_mfma_f32_16x16x32_bf16 v[68:71], v[146:149], v[224:227], v[68:71]
	v_mfma_f32_16x16x32_bf16 v[120:123], v[142:145], v[194:197], v[120:123]
	v_mfma_f32_16x16x32_bf16 v[116:119], v[156:159], v[194:197], v[116:119]
	v_mfma_f32_16x16x32_bf16 v[108:111], v[142:145], v[210:213], v[108:111]
	v_mfma_f32_16x16x32_bf16 v[100:103], v[156:159], v[210:213], v[100:103]
	v_mfma_f32_16x16x32_bf16 v[92:95], v[142:145], v[220:223], v[92:95]
	v_mfma_f32_16x16x32_bf16 v[84:87], v[156:159], v[220:223], v[84:87]
	v_mfma_f32_16x16x32_bf16 v[76:79], v[142:145], v[228:231], v[76:79]
	v_mfma_f32_16x16x32_bf16 v[68:71], v[156:159], v[228:231], v[68:71]
	v_mfma_f32_16x16x32_bf16 v[124:127], v[160:163], v[176:179], v[124:127]
	v_mfma_f32_16x16x32_bf16 v[112:115], v[168:171], v[176:179], v[112:115]
	v_mfma_f32_16x16x32_bf16 v[104:107], v[160:163], v[206:209], v[104:107]
	v_mfma_f32_16x16x32_bf16 v[96:99], v[168:171], v[206:209], v[96:99]
	v_mfma_f32_16x16x32_bf16 v[88:91], v[160:163], v[214:217], v[88:91]
	v_mfma_f32_16x16x32_bf16 v[80:83], v[168:171], v[214:217], v[80:83]
	v_mfma_f32_16x16x32_bf16 v[72:75], v[160:163], v[224:227], v[72:75]
	v_mfma_f32_16x16x32_bf16 v[64:67], v[168:171], v[224:227], v[64:67]
	v_mfma_f32_16x16x32_bf16 v[124:127], v[164:167], v[194:197], v[124:127]
	v_mfma_f32_16x16x32_bf16 v[112:115], v[172:175], v[194:197], v[112:115]
	v_mfma_f32_16x16x32_bf16 v[104:107], v[164:167], v[210:213], v[104:107]
	v_mfma_f32_16x16x32_bf16 v[96:99], v[172:175], v[210:213], v[96:99]
	v_mfma_f32_16x16x32_bf16 v[88:91], v[164:167], v[220:223], v[88:91]
	v_mfma_f32_16x16x32_bf16 v[80:83], v[172:175], v[220:223], v[80:83]
	v_mfma_f32_16x16x32_bf16 v[72:75], v[164:167], v[228:231], v[72:75]
	v_mfma_f32_16x16x32_bf16 v[64:67], v[172:175], v[228:231], v[64:67]
	s_barrier
	s_add_i32 s16, s31, s36
	v_lshl_add_u64 v[198:199], v[198:199], 0, s[12:13]
	s_mov_b32 m0, s16
	ds_read_b128 v[176:179], v155 offset:49152
	ds_read_b128 v[194:197], v155 offset:50176
	ds_read_b128 v[206:209], v155 offset:51200
	ds_read_b128 v[210:213], v155 offset:52224
	ds_read_b128 v[214:217], v155 offset:53248
	ds_read_b128 v[220:223], v155 offset:54272
	ds_read_b128 v[224:227], v155 offset:55296
	ds_read_b128 v[228:231], v155 offset:56320
	global_load_lds_dwordx4 v[198:199], off
	v_lshl_add_u64 v[198:199], v[202:203], 0, s[12:13]
	s_add_i32 m0, s16, 0x2000
	s_add_i32 s16, s44, s36
	global_load_lds_dwordx4 v[198:199], off
	v_lshl_add_u64 v[198:199], v[232:233], 0, s[12:13]
	s_mov_b32 m0, s16
	s_nop 0
	global_load_lds_dwordx4 v[198:199], off
	v_lshl_add_u64 v[198:199], v[234:235], 0, s[12:13]
	s_add_i32 m0, s16, 0x2000
	s_nop 0
	global_load_lds_dwordx4 v[198:199], off
	v_lshl_add_u64 v[198:199], v[236:237], 0, s[12:13]
	s_mov_b32 m0, s49
	s_nop 0
	global_load_lds_dwordx4 v[198:199], off
	v_lshl_add_u64 v[198:199], v[238:239], 0, s[12:13]
	s_mov_b32 m0, s52
	s_nop 0
	global_load_lds_dwordx4 v[198:199], off
	s_waitcnt vmcnt(8)
	s_waitcnt lgkmcnt(0)
	s_barrier
	s_waitcnt lgkmcnt(0)
	v_mfma_f32_16x16x32_bf16 v[60:63], v[128:131], v[176:179], v[60:63]
	v_mfma_f32_16x16x32_bf16 v[52:55], v[146:149], v[176:179], v[52:55]
	v_mfma_f32_16x16x32_bf16 v[44:47], v[128:131], v[206:209], v[44:47]
	v_mfma_f32_16x16x32_bf16 v[36:39], v[146:149], v[206:209], v[36:39]
	v_mfma_f32_16x16x32_bf16 v[28:31], v[128:131], v[214:217], v[28:31]
	v_mfma_f32_16x16x32_bf16 v[20:23], v[146:149], v[214:217], v[20:23]
	v_mfma_f32_16x16x32_bf16 v[12:15], v[128:131], v[224:227], v[12:15]
	v_mfma_f32_16x16x32_bf16 v[4:7], v[146:149], v[224:227], v[4:7]
	v_mfma_f32_16x16x32_bf16 v[60:63], v[142:145], v[194:197], v[60:63]
	v_mfma_f32_16x16x32_bf16 v[52:55], v[156:159], v[194:197], v[52:55]
	v_mfma_f32_16x16x32_bf16 v[44:47], v[142:145], v[210:213], v[44:47]
	v_mfma_f32_16x16x32_bf16 v[36:39], v[156:159], v[210:213], v[36:39]
	v_mfma_f32_16x16x32_bf16 v[28:31], v[142:145], v[220:223], v[28:31]
	v_mfma_f32_16x16x32_bf16 v[20:23], v[156:159], v[220:223], v[20:23]
	v_mfma_f32_16x16x32_bf16 v[12:15], v[142:145], v[228:231], v[12:15]
	v_mfma_f32_16x16x32_bf16 v[4:7], v[156:159], v[228:231], v[4:7]
	v_mfma_f32_16x16x32_bf16 v[56:59], v[160:163], v[176:179], v[56:59]
	v_mfma_f32_16x16x32_bf16 v[48:51], v[168:171], v[176:179], v[48:51]
	v_mfma_f32_16x16x32_bf16 v[40:43], v[160:163], v[206:209], v[40:43]
	v_mfma_f32_16x16x32_bf16 v[32:35], v[168:171], v[206:209], v[32:35]
	v_mfma_f32_16x16x32_bf16 v[24:27], v[160:163], v[214:217], v[24:27]
	v_mfma_f32_16x16x32_bf16 v[16:19], v[168:171], v[214:217], v[16:19]
	v_mfma_f32_16x16x32_bf16 v[8:11], v[160:163], v[224:227], v[8:11]
	v_mfma_f32_16x16x32_bf16 v[0:3], v[168:171], v[224:227], v[0:3]
	v_mfma_f32_16x16x32_bf16 v[56:59], v[164:167], v[194:197], v[56:59]
	v_mfma_f32_16x16x32_bf16 v[48:51], v[172:175], v[194:197], v[48:51]
	v_mfma_f32_16x16x32_bf16 v[40:43], v[164:167], v[210:213], v[40:43]
	v_mfma_f32_16x16x32_bf16 v[32:35], v[172:175], v[210:213], v[32:35]
	v_mfma_f32_16x16x32_bf16 v[24:27], v[164:167], v[220:223], v[24:27]
	v_mfma_f32_16x16x32_bf16 v[16:19], v[172:175], v[220:223], v[16:19]
	v_mfma_f32_16x16x32_bf16 v[8:11], v[164:167], v[228:231], v[8:11]
	v_mfma_f32_16x16x32_bf16 v[0:3], v[172:175], v[228:231], v[0:3]
	s_barrier
	s_add_u32 s28, s28, 0x100
	s_addc_u32 s29, s29, 0
	s_add_u32 s10, s10, 0x100
	s_addc_u32 s11, s11, 0
	s_cmp_ge_i32 s30, s47
	s_mov_b32 s16, s30
	s_cbranch_scc0 .LBB0_1144
	v_readlane_b32 s63, v253, 0
	s_and_b64 vcc, exec, s[22:23]
	s_cbranch_vccz .LBB0_1142

.LBB0_1150:
	ds_read2_b32 v[156:157], v153 offset1:16
	s_waitcnt lgkmcnt(0)
	v_add_u32_e32 v128, 0x1000, v153
	ds_read2_b32 v[158:159], v128 offset1:16
	ds_read2_b32 v[148:149], v153 offset0:32 offset1:48
	ds_read2_b32 v[146:147], v128 offset0:32 offset1:48
	ds_read2_b32 v[144:145], v153 offset0:64 offset1:80
	ds_read2_b32 v[142:143], v128 offset0:64 offset1:80
	ds_read2_b32 v[130:131], v153 offset0:96 offset1:112
	ds_read2_b32 v[128:129], v128 offset0:96 offset1:112
	v_pk_mul_f32 v[114:115], v[114:115], v[118:119]
	v_pk_mul_f32 v[112:113], v[112:113], v[116:117]
	s_waitcnt vmcnt(0)
	v_pk_mul_f32 v[160:161], v[120:121], v[156:157] op_sel_hi:[1,0]
	v_pk_mul_f32 v[162:163], v[122:123], v[156:157] op_sel_hi:[1,0]
	v_exp_f32_e32 v161, v161
	v_pk_mul_f32 v[122:123], v[126:127], v[122:123]
	v_exp_f32_e32 v126, v163
	v_pk_mul_f32 v[120:121], v[124:125], v[120:121]
	s_waitcnt lgkmcnt(6)
	v_fma_f32 v161, v161, v158, v158
	v_rcp_f32_e32 v165, v161
	v_exp_f32_e32 v161, v162
	v_fma_f32 v125, v126, v158, v158
	v_rcp_f32_e32 v125, v125
	v_pk_mul_f32 v[126:127], v[116:117], v[156:157] op_sel_hi:[1,0]
	v_fma_f32 v124, v161, v158, v158
	v_rcp_f32_e32 v124, v124
	v_exp_f32_e32 v164, v160
	v_exp_f32_e32 v126, v126
	v_exp_f32_e32 v127, v127
	v_pk_mul_f32 v[122:123], v[122:123], v[124:125]
	v_pk_mul_f32 v[124:125], v[118:119], v[156:157] op_sel_hi:[1,0]
	v_fma_f32 v164, v164, v158, v158
	v_exp_f32_e32 v124, v124
	v_exp_f32_e32 v125, v125
	v_fma_f32 v126, v126, v158, v158
	v_fma_f32 v127, v127, v158, v158
	v_fma_f32 v124, v124, v158, v158
	v_fma_f32 v125, v125, v158, v158
	v_rcp_f32_e32 v124, v124
	v_rcp_f32_e32 v125, v125
	v_rcp_f32_e32 v164, v164
	v_rcp_f32_e32 v126, v126
	v_rcp_f32_e32 v127, v127
	v_pk_mul_f32 v[118:119], v[114:115], v[124:125]
	v_or_b32_e32 v166, s10, v150
	v_lshl_or_b32 v160, s60, 8, v154
	v_pk_mul_f32 v[120:121], v[120:121], v[164:165]
	v_pk_mul_f32 v[112:113], v[112:113], v[126:127]
	v_cvt_pk_bf16_f32 v117, v118, v119
	s_movk_i32 s10, 0x1600
	v_mov_b32_e32 v118, v157
	v_cvt_pk_bf16_f32 v114, v120, v121
	v_cvt_pk_bf16_f32 v116, v112, v113
	v_mad_u64_u32 v[112:113], s[10:11], v166, s10, v[160:161]
	v_pk_mul_f32 v[120:121], v[108:109], v[118:119] op_sel_hi:[1,0]
	v_cvt_pk_bf16_f32 v115, v122, v123
	v_exp_f32_e32 v113, v120
	global_store_dwordx4 v112, v[114:117], s[18:19] nt
	v_pk_mul_f32 v[106:107], v[106:107], v[110:111]
	v_pk_mul_f32 v[104:105], v[104:105], v[108:109]
	v_exp_f32_e32 v117, v121
	v_fma_f32 v113, v113, v159, v159
	v_pk_mul_f32 v[114:115], v[110:111], v[118:119] op_sel_hi:[1,0]
	v_rcp_f32_e32 v116, v113
	v_fma_f32 v113, v117, v159, v159
	v_rcp_f32_e32 v117, v113
	v_exp_f32_e32 v113, v114
	v_exp_f32_e32 v110, v115
	v_pk_mul_f32 v[98:99], v[98:99], v[102:103]
	v_pk_mul_f32 v[96:97], v[96:97], v[100:101]
	v_fma_f32 v108, v113, v159, v159
	v_fma_f32 v109, v110, v159, v159
	v_rcp_f32_e32 v108, v108
	v_rcp_f32_e32 v109, v109
	v_pk_mul_f32 v[110:111], v[100:101], v[118:119] op_sel_hi:[1,0]
	v_pk_mul_f32 v[104:105], v[104:105], v[116:117]
	v_exp_f32_e32 v110, v110
	v_pk_mul_f32 v[106:107], v[106:107], v[108:109]
	v_pk_mul_f32 v[108:109], v[102:103], v[118:119] op_sel_hi:[1,0]
	v_exp_f32_e32 v111, v111
	v_exp_f32_e32 v108, v108
	v_exp_f32_e32 v109, v109
	v_fma_f32 v110, v110, v159, v159
	v_fma_f32 v111, v111, v159, v159
	v_fma_f32 v108, v108, v159, v159
	v_fmac_f32_e32 v159, v109, v159
	v_rcp_f32_e32 v110, v110
	v_rcp_f32_e32 v111, v111
	v_rcp_f32_e32 v108, v108
	v_rcp_f32_e32 v109, v159
	v_pk_mul_f32 v[90:91], v[90:91], v[94:95]
	v_pk_mul_f32 v[100:101], v[96:97], v[110:111]
	v_cvt_pk_bf16_f32 v96, v104, v105
	v_pk_mul_f32 v[102:103], v[98:99], v[108:109]
	v_cvt_pk_bf16_f32 v97, v106, v107
	v_cvt_pk_bf16_f32 v98, v100, v101
	v_cvt_pk_bf16_f32 v99, v102, v103
	v_add_u32_e32 v102, 0x16000, v112
	global_store_dwordx4 v102, v[96:99], s[18:19] nt
	s_waitcnt lgkmcnt(5)
	v_pk_mul_f32 v[100:101], v[92:93], v[148:149] op_sel_hi:[1,0]
	v_pk_mul_f32 v[88:89], v[88:89], v[92:93]
	v_pk_mul_f32 v[96:97], v[94:95], v[148:149] op_sel_hi:[1,0]
	v_exp_f32_e32 v100, v100
	v_exp_f32_e32 v96, v96
	v_exp_f32_e32 v94, v97
	v_exp_f32_e32 v99, v101
	s_waitcnt lgkmcnt(4)
	v_fma_f32 v98, v100, v146, v146
	v_fma_f32 v92, v96, v146, v146
	v_fma_f32 v93, v94, v146, v146
	v_rcp_f32_e32 v92, v92
	v_rcp_f32_e32 v93, v93
	v_pk_mul_f32 v[94:95], v[84:85], v[148:149] op_sel_hi:[1,0]
	v_fma_f32 v99, v99, v146, v146
	v_exp_f32_e32 v94, v94
	v_pk_mul_f32 v[90:91], v[90:91], v[92:93]
	v_pk_mul_f32 v[92:93], v[86:87], v[148:149] op_sel_hi:[1,0]
	v_exp_f32_e32 v95, v95
	v_exp_f32_e32 v92, v92
	v_exp_f32_e32 v93, v93
	v_fma_f32 v94, v94, v146, v146
	v_fma_f32 v95, v95, v146, v146
	v_fma_f32 v92, v92, v146, v146
	v_fma_f32 v93, v93, v146, v146
	v_rcp_f32_e32 v98, v98
	v_rcp_f32_e32 v99, v99
	v_rcp_f32_e32 v94, v94
	v_rcp_f32_e32 v95, v95
	v_rcp_f32_e32 v92, v92
	v_rcp_f32_e32 v93, v93
	v_pk_mul_f32 v[82:83], v[82:83], v[86:87]
	v_pk_mul_f32 v[80:81], v[80:81], v[84:85]
	v_pk_mul_f32 v[88:89], v[88:89], v[98:99]
	v_pk_mul_f32 v[84:85], v[80:81], v[94:95]
	v_pk_mul_f32 v[86:87], v[82:83], v[92:93]
	v_cvt_pk_bf16_f32 v80, v88, v89
	v_cvt_pk_bf16_f32 v81, v90, v91
	v_cvt_pk_bf16_f32 v82, v84, v85
	v_cvt_pk_bf16_f32 v83, v86, v87
	v_add_u32_e32 v85, 0x2c000, v112
	v_mov_b32_e32 v84, v149
	global_store_dwordx4 v85, v[80:83], s[18:19] nt
	v_pk_mul_f32 v[74:75], v[74:75], v[78:79]
	v_pk_mul_f32 v[86:87], v[76:77], v[84:85] op_sel_hi:[1,0]
	v_pk_mul_f32 v[80:81], v[78:79], v[84:85] op_sel_hi:[1,0]
	v_pk_mul_f32 v[72:73], v[72:73], v[76:77]
	v_exp_f32_e32 v80, v80
	v_exp_f32_e32 v78, v81
	v_exp_f32_e32 v86, v86
	v_exp_f32_e32 v83, v87
	v_fma_f32 v76, v80, v147, v147
	v_fma_f32 v77, v78, v147, v147
	v_rcp_f32_e32 v76, v76
	v_rcp_f32_e32 v77, v77
	v_pk_mul_f32 v[78:79], v[68:69], v[84:85] op_sel_hi:[1,0]
	v_fma_f32 v82, v86, v147, v147
	v_exp_f32_e32 v78, v78
	v_pk_mul_f32 v[74:75], v[74:75], v[76:77]
	v_pk_mul_f32 v[76:77], v[70:71], v[84:85] op_sel_hi:[1,0]
	v_exp_f32_e32 v79, v79
	v_exp_f32_e32 v76, v76
	v_exp_f32_e32 v77, v77
	v_fma_f32 v83, v83, v147, v147
	v_fma_f32 v78, v78, v147, v147
	v_fma_f32 v79, v79, v147, v147
	v_fma_f32 v76, v76, v147, v147
	v_fmac_f32_e32 v147, v77, v147
	v_rcp_f32_e32 v82, v82
	v_rcp_f32_e32 v83, v83
	v_rcp_f32_e32 v78, v78
	v_rcp_f32_e32 v79, v79
	v_rcp_f32_e32 v76, v76
	v_rcp_f32_e32 v77, v147
	v_pk_mul_f32 v[66:67], v[66:67], v[70:71]
	v_pk_mul_f32 v[64:65], v[64:65], v[68:69]
	v_pk_mul_f32 v[72:73], v[72:73], v[82:83]
	v_pk_mul_f32 v[68:69], v[64:65], v[78:79]
	v_pk_mul_f32 v[70:71], v[66:67], v[76:77]
	v_cvt_pk_bf16_f32 v64, v72, v73
	v_cvt_pk_bf16_f32 v65, v74, v75
	v_cvt_pk_bf16_f32 v66, v68, v69
	v_cvt_pk_bf16_f32 v67, v70, v71
	v_add_u32_e32 v70, 0x42000, v112
	global_store_dwordx4 v70, v[64:67], s[18:19] nt
	v_pk_mul_f32 v[58:59], v[58:59], v[62:63]
	s_waitcnt lgkmcnt(3)
	v_pk_mul_f32 v[68:69], v[60:61], v[144:145] op_sel_hi:[1,0]
	v_pk_mul_f32 v[64:65], v[62:63], v[144:145] op_sel_hi:[1,0]
	v_pk_mul_f32 v[56:57], v[56:57], v[60:61]
	v_exp_f32_e32 v64, v64
	v_exp_f32_e32 v62, v65
	v_exp_f32_e32 v68, v68
	v_exp_f32_e32 v67, v69
	s_waitcnt lgkmcnt(2)
	v_fma_f32 v60, v64, v142, v142
	v_fma_f32 v61, v62, v142, v142
	v_rcp_f32_e32 v60, v60
	v_rcp_f32_e32 v61, v61
	v_pk_mul_f32 v[62:63], v[52:53], v[144:145] op_sel_hi:[1,0]
	v_fma_f32 v66, v68, v142, v142
	v_exp_f32_e32 v62, v62
	v_pk_mul_f32 v[58:59], v[58:59], v[60:61]
	v_pk_mul_f32 v[60:61], v[54:55], v[144:145] op_sel_hi:[1,0]
	v_exp_f32_e32 v63, v63
	v_exp_f32_e32 v60, v60
	v_exp_f32_e32 v61, v61
	v_fma_f32 v67, v67, v142, v142
	v_fma_f32 v62, v62, v142, v142
	v_fma_f32 v63, v63, v142, v142
	v_fma_f32 v60, v60, v142, v142
	v_fma_f32 v61, v61, v142, v142
	v_rcp_f32_e32 v66, v66
	v_rcp_f32_e32 v67, v67
	v_rcp_f32_e32 v62, v62
	v_rcp_f32_e32 v63, v63
	v_rcp_f32_e32 v60, v60
	v_rcp_f32_e32 v61, v61
	v_pk_mul_f32 v[50:51], v[50:51], v[54:55]
	v_pk_mul_f32 v[48:49], v[48:49], v[52:53]
	v_pk_mul_f32 v[56:57], v[56:57], v[66:67]
	v_pk_mul_f32 v[52:53], v[48:49], v[62:63]
	v_pk_mul_f32 v[54:55], v[50:51], v[60:61]
	v_cvt_pk_bf16_f32 v48, v56, v57
	v_cvt_pk_bf16_f32 v49, v58, v59
	v_cvt_pk_bf16_f32 v50, v52, v53
	v_cvt_pk_bf16_f32 v51, v54, v55
	v_add_u32_e32 v53, 0xb0000, v112
	v_mov_b32_e32 v52, v145
	global_store_dwordx4 v53, v[48:51], s[18:19] nt
	v_pk_mul_f32 v[42:43], v[42:43], v[46:47]
	v_pk_mul_f32 v[54:55], v[44:45], v[52:53] op_sel_hi:[1,0]
	v_pk_mul_f32 v[48:49], v[46:47], v[52:53] op_sel_hi:[1,0]
	v_pk_mul_f32 v[40:41], v[40:41], v[44:45]
	v_exp_f32_e32 v48, v48
	v_exp_f32_e32 v46, v49
	v_exp_f32_e32 v54, v54
	v_exp_f32_e32 v51, v55
	v_fma_f32 v44, v48, v143, v143
	v_fma_f32 v45, v46, v143, v143
	v_rcp_f32_e32 v44, v44
	v_rcp_f32_e32 v45, v45
	v_pk_mul_f32 v[46:47], v[36:37], v[52:53] op_sel_hi:[1,0]
	v_fma_f32 v50, v54, v143, v143
	v_exp_f32_e32 v46, v46
	v_pk_mul_f32 v[42:43], v[42:43], v[44:45]
	v_pk_mul_f32 v[44:45], v[38:39], v[52:53] op_sel_hi:[1,0]
	v_exp_f32_e32 v47, v47
	v_exp_f32_e32 v44, v44
	v_exp_f32_e32 v45, v45
	v_fma_f32 v51, v51, v143, v143
	v_fma_f32 v46, v46, v143, v143
	v_fma_f32 v47, v47, v143, v143
	v_fma_f32 v44, v44, v143, v143
	v_fmac_f32_e32 v143, v45, v143
	v_rcp_f32_e32 v50, v50
	v_rcp_f32_e32 v51, v51
	v_rcp_f32_e32 v46, v46
	v_rcp_f32_e32 v47, v47
	v_rcp_f32_e32 v44, v44
	v_rcp_f32_e32 v45, v143
	v_pk_mul_f32 v[34:35], v[34:35], v[38:39]
	v_pk_mul_f32 v[32:33], v[32:33], v[36:37]
	v_pk_mul_f32 v[40:41], v[40:41], v[50:51]
	v_pk_mul_f32 v[36:37], v[32:33], v[46:47]
	v_pk_mul_f32 v[38:39], v[34:35], v[44:45]
	v_cvt_pk_bf16_f32 v32, v40, v41
	v_cvt_pk_bf16_f32 v33, v42, v43
	v_cvt_pk_bf16_f32 v34, v36, v37
	v_cvt_pk_bf16_f32 v35, v38, v39
	v_add_u32_e32 v38, 0xc6000, v112
	global_store_dwordx4 v38, v[32:35], s[18:19] nt
	v_pk_mul_f32 v[26:27], v[26:27], v[30:31]
	s_waitcnt lgkmcnt(1)
	v_pk_mul_f32 v[36:37], v[28:29], v[130:131] op_sel_hi:[1,0]
	v_pk_mul_f32 v[32:33], v[30:31], v[130:131] op_sel_hi:[1,0]
	v_pk_mul_f32 v[24:25], v[24:25], v[28:29]
	v_exp_f32_e32 v32, v32
	v_exp_f32_e32 v30, v33
	v_exp_f32_e32 v36, v36
	v_exp_f32_e32 v35, v37
	s_waitcnt lgkmcnt(0)
	v_fma_f32 v28, v32, v128, v128
	v_fma_f32 v29, v30, v128, v128
	v_rcp_f32_e32 v28, v28
	v_rcp_f32_e32 v29, v29
	v_pk_mul_f32 v[30:31], v[20:21], v[130:131] op_sel_hi:[1,0]
	v_fma_f32 v34, v36, v128, v128
	v_exp_f32_e32 v30, v30
	v_pk_mul_f32 v[26:27], v[26:27], v[28:29]
	v_pk_mul_f32 v[28:29], v[22:23], v[130:131] op_sel_hi:[1,0]
	v_exp_f32_e32 v31, v31
	v_exp_f32_e32 v28, v28
	v_exp_f32_e32 v29, v29
	v_fma_f32 v35, v35, v128, v128
	v_fma_f32 v30, v30, v128, v128
	v_fma_f32 v31, v31, v128, v128
	v_fma_f32 v28, v28, v128, v128
	v_fma_f32 v29, v29, v128, v128
	v_rcp_f32_e32 v34, v34
	v_rcp_f32_e32 v35, v35
	v_rcp_f32_e32 v30, v30
	v_rcp_f32_e32 v31, v31
	v_rcp_f32_e32 v28, v28
	v_rcp_f32_e32 v29, v29
	v_pk_mul_f32 v[18:19], v[18:19], v[22:23]
	v_pk_mul_f32 v[16:17], v[16:17], v[20:21]
	v_pk_mul_f32 v[24:25], v[24:25], v[34:35]
	v_pk_mul_f32 v[20:21], v[16:17], v[30:31]
	v_pk_mul_f32 v[22:23], v[18:19], v[28:29]
	v_cvt_pk_bf16_f32 v16, v24, v25
	v_cvt_pk_bf16_f32 v17, v26, v27
	v_cvt_pk_bf16_f32 v18, v20, v21
	v_cvt_pk_bf16_f32 v19, v22, v23
	v_add_u32_e32 v21, 0xdc000, v112
	v_mov_b32_e32 v20, v131
	global_store_dwordx4 v21, v[16:19], s[18:19] nt
	v_pk_mul_f32 v[10:11], v[10:11], v[14:15]
	v_pk_mul_f32 v[22:23], v[12:13], v[20:21] op_sel_hi:[1,0]
	v_pk_mul_f32 v[16:17], v[14:15], v[20:21] op_sel_hi:[1,0]
	v_pk_mul_f32 v[8:9], v[8:9], v[12:13]
	v_exp_f32_e32 v16, v16
	v_exp_f32_e32 v14, v17
	v_exp_f32_e32 v22, v22
	v_exp_f32_e32 v19, v23
	v_fma_f32 v12, v16, v129, v129
	v_fma_f32 v13, v14, v129, v129
	v_rcp_f32_e32 v12, v12
	v_rcp_f32_e32 v13, v13
	v_pk_mul_f32 v[14:15], v[4:5], v[20:21] op_sel_hi:[1,0]
	v_fma_f32 v18, v22, v129, v129
	v_exp_f32_e32 v14, v14
	v_pk_mul_f32 v[10:11], v[10:11], v[12:13]
	v_pk_mul_f32 v[12:13], v[6:7], v[20:21] op_sel_hi:[1,0]
	v_exp_f32_e32 v15, v15
	v_exp_f32_e32 v12, v12
	v_exp_f32_e32 v13, v13
	v_fma_f32 v19, v19, v129, v129
	v_fma_f32 v14, v14, v129, v129
	v_fma_f32 v15, v15, v129, v129
	v_fma_f32 v12, v12, v129, v129
	v_fmac_f32_e32 v129, v13, v129
	v_rcp_f32_e32 v18, v18
	v_rcp_f32_e32 v19, v19
	v_rcp_f32_e32 v14, v14
	v_rcp_f32_e32 v15, v15
	v_rcp_f32_e32 v12, v12
	v_rcp_f32_e32 v13, v129
	v_pk_mul_f32 v[2:3], v[2:3], v[6:7]
	v_pk_mul_f32 v[0:1], v[0:1], v[4:5]
	v_pk_mul_f32 v[8:9], v[8:9], v[18:19]
	v_pk_mul_f32 v[4:5], v[0:1], v[14:15]
	v_pk_mul_f32 v[6:7], v[2:3], v[12:13]
	v_cvt_pk_bf16_f32 v0, v8, v9
	v_cvt_pk_bf16_f32 v1, v10, v11
	v_cvt_pk_bf16_f32 v2, v4, v5
	v_cvt_pk_bf16_f32 v3, v6, v7
	v_add_u32_e32 v4, 0xf2000, v112
	s_and_b64 vcc, exec, s[42:43]
	s_mov_b64 s[10:11], -1
	global_store_dwordx4 v4, v[0:3], s[18:19] nt
	s_cbranch_vccnz .LBB0_1133
	s_andn2_b64 vcc, exec, s[14:15]
	s_cbranch_vccnz .LBB0_1132
	s_mov_b32 s100, 1
	s_branch .LBB0_1132

.LBB0_1222:
	v_mov_b32_e32 v123, 0
	s_andn2_b64 vcc, exec, s[18:19]
	v_mov_b32_e32 v122, v123
	v_mov_b32_e32 v121, v123
	v_mov_b32_e32 v120, v123
	v_mov_b32_e32 v127, v123
	v_mov_b32_e32 v126, v123
	v_mov_b32_e32 v125, v123
	v_mov_b32_e32 v124, v123
	v_mov_b32_e32 v111, v123
	v_mov_b32_e32 v110, v123
	v_mov_b32_e32 v109, v123
	v_mov_b32_e32 v108, v123
	v_mov_b32_e32 v107, v123
	v_mov_b32_e32 v106, v123
	v_mov_b32_e32 v105, v123
	v_mov_b32_e32 v104, v123
	v_mov_b32_e32 v95, v123
	v_mov_b32_e32 v94, v123
	v_mov_b32_e32 v93, v123
	v_mov_b32_e32 v92, v123
	v_mov_b32_e32 v91, v123
	v_mov_b32_e32 v90, v123
	v_mov_b32_e32 v89, v123
	v_mov_b32_e32 v88, v123
	v_mov_b32_e32 v79, v123
	v_mov_b32_e32 v78, v123
	v_mov_b32_e32 v77, v123
	v_mov_b32_e32 v76, v123
	v_mov_b32_e32 v75, v123
	v_mov_b32_e32 v74, v123
	v_mov_b32_e32 v73, v123
	v_mov_b32_e32 v72, v123
	v_mov_b32_e32 v119, v123
	v_mov_b32_e32 v118, v123
	v_mov_b32_e32 v117, v123
	v_mov_b32_e32 v116, v123
	v_mov_b32_e32 v115, v123
	v_mov_b32_e32 v114, v123
	v_mov_b32_e32 v113, v123
	v_mov_b32_e32 v112, v123
	v_mov_b32_e32 v103, v123
	v_mov_b32_e32 v102, v123
	v_mov_b32_e32 v101, v123
	v_mov_b32_e32 v100, v123
	v_mov_b32_e32 v99, v123
	v_mov_b32_e32 v98, v123
	v_mov_b32_e32 v97, v123
	v_mov_b32_e32 v96, v123
	v_mov_b32_e32 v87, v123
	v_mov_b32_e32 v86, v123
	v_mov_b32_e32 v85, v123
	v_mov_b32_e32 v84, v123
	v_mov_b32_e32 v83, v123
	v_mov_b32_e32 v82, v123
	v_mov_b32_e32 v81, v123
	v_mov_b32_e32 v80, v123
	v_mov_b32_e32 v71, v123
	v_mov_b32_e32 v70, v123
	v_mov_b32_e32 v69, v123
	v_mov_b32_e32 v68, v123
	v_mov_b32_e32 v67, v123
	v_mov_b32_e32 v66, v123
	v_mov_b32_e32 v65, v123
	v_mov_b32_e32 v64, v123
	v_mov_b32_e32 v63, v123
	v_mov_b32_e32 v62, v123
	v_mov_b32_e32 v61, v123
	v_mov_b32_e32 v60, v123
	v_mov_b32_e32 v59, v123
	v_mov_b32_e32 v58, v123
	v_mov_b32_e32 v57, v123
	v_mov_b32_e32 v56, v123
	v_mov_b32_e32 v47, v123
	v_mov_b32_e32 v46, v123
	v_mov_b32_e32 v45, v123
	v_mov_b32_e32 v44, v123
	v_mov_b32_e32 v43, v123
	v_mov_b32_e32 v42, v123
	v_mov_b32_e32 v41, v123
	v_mov_b32_e32 v40, v123
	v_mov_b32_e32 v31, v123
	v_mov_b32_e32 v30, v123
	v_mov_b32_e32 v29, v123
	v_mov_b32_e32 v28, v123
	v_mov_b32_e32 v27, v123
	v_mov_b32_e32 v26, v123
	v_mov_b32_e32 v25, v123
	v_mov_b32_e32 v24, v123
	v_mov_b32_e32 v15, v123
	v_mov_b32_e32 v14, v123
	v_mov_b32_e32 v13, v123
	v_mov_b32_e32 v12, v123
	v_mov_b32_e32 v11, v123
	v_mov_b32_e32 v10, v123
	v_mov_b32_e32 v9, v123
	v_mov_b32_e32 v8, v123
	v_mov_b32_e32 v55, v123
	v_mov_b32_e32 v54, v123
	v_mov_b32_e32 v53, v123
	v_mov_b32_e32 v52, v123
	v_mov_b32_e32 v51, v123
	v_mov_b32_e32 v50, v123
	v_mov_b32_e32 v49, v123
	v_mov_b32_e32 v48, v123
	v_mov_b32_e32 v39, v123
	v_mov_b32_e32 v38, v123
	v_mov_b32_e32 v37, v123
	v_mov_b32_e32 v36, v123
	v_mov_b32_e32 v35, v123
	v_mov_b32_e32 v34, v123
	v_mov_b32_e32 v33, v123
	v_mov_b32_e32 v32, v123
	v_mov_b32_e32 v23, v123
	v_mov_b32_e32 v22, v123
	v_mov_b32_e32 v21, v123
	v_mov_b32_e32 v20, v123
	v_mov_b32_e32 v19, v123
	v_mov_b32_e32 v18, v123
	v_mov_b32_e32 v17, v123
	v_mov_b32_e32 v16, v123
	v_mov_b32_e32 v7, v123
	v_mov_b32_e32 v6, v123
	v_mov_b32_e32 v5, v123
	v_mov_b32_e32 v4, v123
	v_mov_b32_e32 v3, v123
	v_mov_b32_e32 v2, v123
	s_waitcnt lgkmcnt(0)
	v_mov_b32_e32 v1, v123
	v_mov_b32_e32 v0, v123
	s_cbranch_vccnz .LBB0_1226
	s_add_u32 s26, s26, 0x80
	s_addc_u32 s27, s27, 0
	s_add_u32 s10, s28, 0x100
	s_addc_u32 s11, s29, 0
	s_mov_b32 s28, 0
	s_cmp_lg_u32 s100, 0
	s_cbranch_scc0 .Llbb_11
	s_barrier
	s_mov_b32 s100, 0
.Llbb_11:
.LBB0_1224:
	s_add_i32 s44, s28, 2
	s_add_u32 s45, s26, 0x80
	s_addc_u32 s29, s27, 0
	s_add_i32 s62, 0, 0x10000
	s_cmp_eq_u32 s49, s28
	s_cselect_b32 s29, s23, s29
	s_cselect_b32 s28, s22, s45
	s_cselect_b32 s61, s25, s11
	s_cselect_b32 s60, s24, s10
	s_add_i32 s45, 0, 0x14000
	v_add_u32_e32 v140, s62, v199
	v_add_u32_e32 v166, s45, v199
	ds_read_b128 v[128:131], v140
	ds_read_b128 v[132:135], v140 offset:1024
	ds_read_b128 v[136:139], v140 offset:2048
	ds_read_b128 v[140:143], v140 offset:3072
	ds_read_b128 v[144:147], v166
	ds_read_b128 v[148:151], v166 offset:1024
	ds_read_b128 v[152:155], v166 offset:2048
	ds_read_b128 v[166:169], v166 offset:3072
	v_lshl_add_u64 v[178:179], s[26:27], 0, v[162:163]
	s_add_i32 m0, s35, 0xc000
	ds_read_b128 v[170:173], v206
	ds_read_b128 v[174:177], v206 offset:1024
	ds_read_b128 v[194:197], v206 offset:2048
	ds_read_b128 v[208:211], v206 offset:3072
	ds_read_b128 v[212:215], v206 offset:4096
	ds_read_b128 v[220:223], v206 offset:5120
	ds_read_b128 v[224:227], v206 offset:6144
	ds_read_b128 v[228:231], v206 offset:7168
	global_load_lds_dwordx4 v[178:179], off
	v_lshl_add_u64 v[178:179], s[26:27], 0, v[164:165]
	s_add_i32 m0, s35, 0xe000
	s_nop 0
	global_load_lds_dwordx4 v[178:179], off
	s_waitcnt vmcnt(8)
	s_waitcnt lgkmcnt(0)
	s_barrier
	s_waitcnt lgkmcnt(0)
	v_mfma_f32_16x16x32_bf16 v[120:123], v[128:131], v[170:173], v[120:123]
	v_mfma_f32_16x16x32_bf16 v[124:127], v[136:139], v[170:173], v[124:127]
	v_mfma_f32_16x16x32_bf16 v[108:111], v[128:131], v[194:197], v[108:111]
	v_mfma_f32_16x16x32_bf16 v[104:107], v[136:139], v[194:197], v[104:107]
	v_mfma_f32_16x16x32_bf16 v[92:95], v[128:131], v[212:215], v[92:95]
	v_mfma_f32_16x16x32_bf16 v[88:91], v[136:139], v[212:215], v[88:91]
	v_mfma_f32_16x16x32_bf16 v[76:79], v[128:131], v[224:227], v[76:79]
	v_mfma_f32_16x16x32_bf16 v[72:75], v[136:139], v[224:227], v[72:75]
	v_mfma_f32_16x16x32_bf16 v[120:123], v[132:135], v[174:177], v[120:123]
	v_mfma_f32_16x16x32_bf16 v[124:127], v[140:143], v[174:177], v[124:127]
	v_mfma_f32_16x16x32_bf16 v[108:111], v[132:135], v[208:211], v[108:111]
	v_mfma_f32_16x16x32_bf16 v[104:107], v[140:143], v[208:211], v[104:107]
	v_mfma_f32_16x16x32_bf16 v[92:95], v[132:135], v[220:223], v[92:95]
	v_mfma_f32_16x16x32_bf16 v[88:91], v[140:143], v[220:223], v[88:91]
	v_mfma_f32_16x16x32_bf16 v[76:79], v[132:135], v[228:231], v[76:79]
	v_mfma_f32_16x16x32_bf16 v[72:75], v[140:143], v[228:231], v[72:75]
	v_mfma_f32_16x16x32_bf16 v[116:119], v[144:147], v[170:173], v[116:119]
	v_mfma_f32_16x16x32_bf16 v[112:115], v[152:155], v[170:173], v[112:115]
	v_mfma_f32_16x16x32_bf16 v[100:103], v[144:147], v[194:197], v[100:103]
	v_mfma_f32_16x16x32_bf16 v[96:99], v[152:155], v[194:197], v[96:99]
	v_mfma_f32_16x16x32_bf16 v[84:87], v[144:147], v[212:215], v[84:87]
	v_mfma_f32_16x16x32_bf16 v[80:83], v[152:155], v[212:215], v[80:83]
	v_mfma_f32_16x16x32_bf16 v[68:71], v[144:147], v[224:227], v[68:71]
	v_mfma_f32_16x16x32_bf16 v[64:67], v[152:155], v[224:227], v[64:67]
	v_mfma_f32_16x16x32_bf16 v[116:119], v[148:151], v[174:177], v[116:119]
	v_mfma_f32_16x16x32_bf16 v[112:115], v[166:169], v[174:177], v[112:115]
	v_mfma_f32_16x16x32_bf16 v[100:103], v[148:151], v[208:211], v[100:103]
	v_mfma_f32_16x16x32_bf16 v[96:99], v[166:169], v[208:211], v[96:99]
	v_mfma_f32_16x16x32_bf16 v[84:87], v[148:151], v[220:223], v[84:87]
	v_mfma_f32_16x16x32_bf16 v[80:83], v[166:169], v[220:223], v[80:83]
	v_mfma_f32_16x16x32_bf16 v[68:71], v[148:151], v[228:231], v[68:71]
	v_mfma_f32_16x16x32_bf16 v[64:67], v[166:169], v[228:231], v[64:67]
	s_barrier
	s_add_i32 s62, s62, s34
	v_lshl_add_u64 v[178:179], s[60:61], 0, v[180:181]
	s_mov_b32 m0, s62
	ds_read_b128 v[170:173], v206 offset:16384
	ds_read_b128 v[174:177], v206 offset:17408
	ds_read_b128 v[194:197], v206 offset:18432
	ds_read_b128 v[208:211], v206 offset:19456
	ds_read_b128 v[212:215], v206 offset:20480
	ds_read_b128 v[220:223], v206 offset:21504
	ds_read_b128 v[224:227], v206 offset:22528
	ds_read_b128 v[228:231], v206 offset:23552
	global_load_lds_dwordx4 v[178:179], off
	s_add_i32 m0, s62, 0x2000
	v_lshl_add_u64 v[202:203], s[60:61], 0, v[156:157]
	s_add_u32 s60, s60, s6
	s_addc_u32 s61, s61, s7
	s_add_i32 s45, s45, s34
	global_load_lds_dwordx4 v[202:203], off
	v_lshl_add_u64 v[216:217], s[60:61], 0, v[180:181]
	s_mov_b32 m0, s45
	v_lshl_add_u64 v[232:233], s[60:61], 0, v[156:157]
	global_load_lds_dwordx4 v[216:217], off
	s_add_i32 m0, s45, 0x2000
	v_lshl_add_u64 v[234:235], s[28:29], 0, v[160:161]
	global_load_lds_dwordx4 v[232:233], off
	s_mov_b32 m0, s35
	v_lshl_add_u64 v[236:237], s[28:29], 0, v[158:159]
	global_load_lds_dwordx4 v[234:235], off
	s_mov_b32 m0, s36
	s_nop 0
	global_load_lds_dwordx4 v[236:237], off
	s_waitcnt vmcnt(8)
	s_waitcnt lgkmcnt(0)
	s_barrier
	s_waitcnt lgkmcnt(0)
	v_mfma_f32_16x16x32_bf16 v[60:63], v[128:131], v[170:173], v[60:63]
	v_mfma_f32_16x16x32_bf16 v[56:59], v[136:139], v[170:173], v[56:59]
	v_mfma_f32_16x16x32_bf16 v[44:47], v[128:131], v[194:197], v[44:47]
	v_mfma_f32_16x16x32_bf16 v[40:43], v[136:139], v[194:197], v[40:43]
	v_mfma_f32_16x16x32_bf16 v[28:31], v[128:131], v[212:215], v[28:31]
	v_mfma_f32_16x16x32_bf16 v[24:27], v[136:139], v[212:215], v[24:27]
	v_mfma_f32_16x16x32_bf16 v[12:15], v[128:131], v[224:227], v[12:15]
	v_mfma_f32_16x16x32_bf16 v[8:11], v[136:139], v[224:227], v[8:11]
	v_mfma_f32_16x16x32_bf16 v[60:63], v[132:135], v[174:177], v[60:63]
	v_mfma_f32_16x16x32_bf16 v[56:59], v[140:143], v[174:177], v[56:59]
	v_mfma_f32_16x16x32_bf16 v[44:47], v[132:135], v[208:211], v[44:47]
	v_mfma_f32_16x16x32_bf16 v[40:43], v[140:143], v[208:211], v[40:43]
	v_mfma_f32_16x16x32_bf16 v[28:31], v[132:135], v[220:223], v[28:31]
	v_mfma_f32_16x16x32_bf16 v[24:27], v[140:143], v[220:223], v[24:27]
	v_mfma_f32_16x16x32_bf16 v[12:15], v[132:135], v[228:231], v[12:15]
	v_mfma_f32_16x16x32_bf16 v[8:11], v[140:143], v[228:231], v[8:11]
	v_mfma_f32_16x16x32_bf16 v[52:55], v[144:147], v[170:173], v[52:55]
	v_mfma_f32_16x16x32_bf16 v[48:51], v[152:155], v[170:173], v[48:51]
	v_mfma_f32_16x16x32_bf16 v[36:39], v[144:147], v[194:197], v[36:39]
	v_mfma_f32_16x16x32_bf16 v[32:35], v[152:155], v[194:197], v[32:35]
	v_mfma_f32_16x16x32_bf16 v[20:23], v[144:147], v[212:215], v[20:23]
	v_mfma_f32_16x16x32_bf16 v[16:19], v[152:155], v[212:215], v[16:19]
	v_mfma_f32_16x16x32_bf16 v[4:7], v[144:147], v[224:227], v[4:7]
	v_mfma_f32_16x16x32_bf16 v[0:3], v[152:155], v[224:227], v[0:3]
	v_mfma_f32_16x16x32_bf16 v[52:55], v[148:151], v[174:177], v[52:55]
	v_mfma_f32_16x16x32_bf16 v[48:51], v[166:169], v[174:177], v[48:51]
	v_mfma_f32_16x16x32_bf16 v[36:39], v[148:151], v[208:211], v[36:39]
	v_mfma_f32_16x16x32_bf16 v[32:35], v[166:169], v[208:211], v[32:35]
	v_mfma_f32_16x16x32_bf16 v[20:23], v[148:151], v[220:223], v[20:23]
	v_mfma_f32_16x16x32_bf16 v[16:19], v[166:169], v[220:223], v[16:19]
	v_mfma_f32_16x16x32_bf16 v[4:7], v[148:151], v[228:231], v[4:7]
	v_mfma_f32_16x16x32_bf16 v[0:3], v[166:169], v[228:231], v[0:3]
	s_barrier
	s_add_i32 s45, 0, 0x18000
	s_add_i32 s60, 0, 0x1c000
	v_add_u32_e32 v140, s45, v199
	v_add_u32_e32 v166, s60, v199
	ds_read_b128 v[128:131], v140
	ds_read_b128 v[132:135], v140 offset:1024
	ds_read_b128 v[136:139], v140 offset:2048
	ds_read_b128 v[140:143], v140 offset:3072
	ds_read_b128 v[144:147], v166
	ds_read_b128 v[148:151], v166 offset:1024
	ds_read_b128 v[152:155], v166 offset:2048
	ds_read_b128 v[166:169], v166 offset:3072
	s_add_u32 s28, s28, s6
	s_addc_u32 s29, s29, s7
	s_mov_b32 m0, s37
	v_lshl_add_u64 v[238:239], s[28:29], 0, v[160:161]
	ds_read_b128 v[170:173], v206 offset:32768
	ds_read_b128 v[174:177], v206 offset:33792
	ds_read_b128 v[194:197], v206 offset:34816
	ds_read_b128 v[208:211], v206 offset:35840
	ds_read_b128 v[212:215], v206 offset:36864
	ds_read_b128 v[220:223], v206 offset:37888
	ds_read_b128 v[224:227], v206 offset:38912
	ds_read_b128 v[228:231], v206 offset:39936
	global_load_lds_dwordx4 v[238:239], off
	v_lshl_add_u64 v[238:239], s[28:29], 0, v[158:159]
	s_mov_b32 m0, s38
	s_nop 0
	global_load_lds_dwordx4 v[238:239], off
	s_waitcnt vmcnt(8)
	s_waitcnt lgkmcnt(0)
	s_barrier
	s_waitcnt lgkmcnt(0)
	v_mfma_f32_16x16x32_bf16 v[120:123], v[128:131], v[170:173], v[120:123]
	v_mfma_f32_16x16x32_bf16 v[124:127], v[136:139], v[170:173], v[124:127]
	v_mfma_f32_16x16x32_bf16 v[108:111], v[128:131], v[194:197], v[108:111]
	v_mfma_f32_16x16x32_bf16 v[104:107], v[136:139], v[194:197], v[104:107]
	v_mfma_f32_16x16x32_bf16 v[92:95], v[128:131], v[212:215], v[92:95]
	v_mfma_f32_16x16x32_bf16 v[88:91], v[136:139], v[212:215], v[88:91]
	v_mfma_f32_16x16x32_bf16 v[76:79], v[128:131], v[224:227], v[76:79]
	v_mfma_f32_16x16x32_bf16 v[72:75], v[136:139], v[224:227], v[72:75]
	v_mfma_f32_16x16x32_bf16 v[120:123], v[132:135], v[174:177], v[120:123]
	v_mfma_f32_16x16x32_bf16 v[124:127], v[140:143], v[174:177], v[124:127]
	v_mfma_f32_16x16x32_bf16 v[108:111], v[132:135], v[208:211], v[108:111]
	v_mfma_f32_16x16x32_bf16 v[104:107], v[140:143], v[208:211], v[104:107]
	v_mfma_f32_16x16x32_bf16 v[92:95], v[132:135], v[220:223], v[92:95]
	v_mfma_f32_16x16x32_bf16 v[88:91], v[140:143], v[220:223], v[88:91]
	v_mfma_f32_16x16x32_bf16 v[76:79], v[132:135], v[228:231], v[76:79]
	v_mfma_f32_16x16x32_bf16 v[72:75], v[140:143], v[228:231], v[72:75]
	v_mfma_f32_16x16x32_bf16 v[116:119], v[144:147], v[170:173], v[116:119]
	v_mfma_f32_16x16x32_bf16 v[112:115], v[152:155], v[170:173], v[112:115]
	v_mfma_f32_16x16x32_bf16 v[100:103], v[144:147], v[194:197], v[100:103]
	v_mfma_f32_16x16x32_bf16 v[96:99], v[152:155], v[194:197], v[96:99]
	v_mfma_f32_16x16x32_bf16 v[84:87], v[144:147], v[212:215], v[84:87]
	v_mfma_f32_16x16x32_bf16 v[80:83], v[152:155], v[212:215], v[80:83]
	v_mfma_f32_16x16x32_bf16 v[68:71], v[144:147], v[224:227], v[68:71]
	v_mfma_f32_16x16x32_bf16 v[64:67], v[152:155], v[224:227], v[64:67]
	v_mfma_f32_16x16x32_bf16 v[116:119], v[148:151], v[174:177], v[116:119]
	v_mfma_f32_16x16x32_bf16 v[112:115], v[166:169], v[174:177], v[112:115]
	v_mfma_f32_16x16x32_bf16 v[100:103], v[148:151], v[208:211], v[100:103]
	v_mfma_f32_16x16x32_bf16 v[96:99], v[166:169], v[208:211], v[96:99]
	v_mfma_f32_16x16x32_bf16 v[84:87], v[148:151], v[220:223], v[84:87]
	v_mfma_f32_16x16x32_bf16 v[80:83], v[166:169], v[220:223], v[80:83]
	v_mfma_f32_16x16x32_bf16 v[68:71], v[148:151], v[228:231], v[68:71]
	v_mfma_f32_16x16x32_bf16 v[64:67], v[166:169], v[228:231], v[64:67]
	s_barrier
	s_add_i32 s28, s45, s34
	v_lshl_add_u64 v[178:179], v[178:179], 0, s[12:13]
	s_mov_b32 m0, s28
	ds_read_b128 v[170:173], v206 offset:49152
	ds_read_b128 v[174:177], v206 offset:50176
	ds_read_b128 v[194:197], v206 offset:51200
	ds_read_b128 v[208:211], v206 offset:52224
	ds_read_b128 v[212:215], v206 offset:53248
	ds_read_b128 v[220:223], v206 offset:54272
	ds_read_b128 v[224:227], v206 offset:55296
	ds_read_b128 v[228:231], v206 offset:56320
	global_load_lds_dwordx4 v[178:179], off
	v_lshl_add_u64 v[178:179], v[202:203], 0, s[12:13]
	s_add_i32 m0, s28, 0x2000
	s_add_i32 s28, s60, s34
	global_load_lds_dwordx4 v[178:179], off
	v_lshl_add_u64 v[178:179], v[216:217], 0, s[12:13]
	s_mov_b32 m0, s28
	s_nop 0
	global_load_lds_dwordx4 v[178:179], off
	v_lshl_add_u64 v[178:179], v[232:233], 0, s[12:13]
	s_add_i32 m0, s28, 0x2000
	s_nop 0
	global_load_lds_dwordx4 v[178:179], off
	v_lshl_add_u64 v[178:179], v[234:235], 0, s[12:13]
	s_mov_b32 m0, s47
	s_nop 0
	global_load_lds_dwordx4 v[178:179], off
	v_lshl_add_u64 v[178:179], v[236:237], 0, s[12:13]
	s_mov_b32 m0, s48
	s_nop 0
	global_load_lds_dwordx4 v[178:179], off
	s_waitcnt vmcnt(8)
	s_waitcnt lgkmcnt(0)
	s_barrier
	s_waitcnt lgkmcnt(0)
	v_mfma_f32_16x16x32_bf16 v[60:63], v[128:131], v[170:173], v[60:63]
	v_mfma_f32_16x16x32_bf16 v[56:59], v[136:139], v[170:173], v[56:59]
	v_mfma_f32_16x16x32_bf16 v[44:47], v[128:131], v[194:197], v[44:47]
	v_mfma_f32_16x16x32_bf16 v[40:43], v[136:139], v[194:197], v[40:43]
	v_mfma_f32_16x16x32_bf16 v[28:31], v[128:131], v[212:215], v[28:31]
	v_mfma_f32_16x16x32_bf16 v[24:27], v[136:139], v[212:215], v[24:27]
	v_mfma_f32_16x16x32_bf16 v[12:15], v[128:131], v[224:227], v[12:15]
	v_mfma_f32_16x16x32_bf16 v[8:11], v[136:139], v[224:227], v[8:11]
	v_mfma_f32_16x16x32_bf16 v[60:63], v[132:135], v[174:177], v[60:63]
	v_mfma_f32_16x16x32_bf16 v[56:59], v[140:143], v[174:177], v[56:59]
	v_mfma_f32_16x16x32_bf16 v[44:47], v[132:135], v[208:211], v[44:47]
	v_mfma_f32_16x16x32_bf16 v[40:43], v[140:143], v[208:211], v[40:43]
	v_mfma_f32_16x16x32_bf16 v[28:31], v[132:135], v[220:223], v[28:31]
	v_mfma_f32_16x16x32_bf16 v[24:27], v[140:143], v[220:223], v[24:27]
	v_mfma_f32_16x16x32_bf16 v[12:15], v[132:135], v[228:231], v[12:15]
	v_mfma_f32_16x16x32_bf16 v[8:11], v[140:143], v[228:231], v[8:11]
	v_mfma_f32_16x16x32_bf16 v[52:55], v[144:147], v[170:173], v[52:55]
	v_mfma_f32_16x16x32_bf16 v[48:51], v[152:155], v[170:173], v[48:51]
	v_mfma_f32_16x16x32_bf16 v[36:39], v[144:147], v[194:197], v[36:39]
	v_mfma_f32_16x16x32_bf16 v[32:35], v[152:155], v[194:197], v[32:35]
	v_mfma_f32_16x16x32_bf16 v[20:23], v[144:147], v[212:215], v[20:23]
	v_mfma_f32_16x16x32_bf16 v[16:19], v[152:155], v[212:215], v[16:19]
	v_mfma_f32_16x16x32_bf16 v[4:7], v[144:147], v[224:227], v[4:7]
	v_mfma_f32_16x16x32_bf16 v[0:3], v[152:155], v[224:227], v[0:3]
	v_mfma_f32_16x16x32_bf16 v[52:55], v[148:151], v[174:177], v[52:55]
	v_mfma_f32_16x16x32_bf16 v[48:51], v[166:169], v[174:177], v[48:51]
	v_mfma_f32_16x16x32_bf16 v[36:39], v[148:151], v[208:211], v[36:39]
	v_mfma_f32_16x16x32_bf16 v[32:35], v[166:169], v[208:211], v[32:35]
	v_mfma_f32_16x16x32_bf16 v[20:23], v[148:151], v[220:223], v[20:23]
	v_mfma_f32_16x16x32_bf16 v[16:19], v[166:169], v[220:223], v[16:19]
	v_mfma_f32_16x16x32_bf16 v[4:7], v[148:151], v[228:231], v[4:7]
	v_mfma_f32_16x16x32_bf16 v[0:3], v[166:169], v[228:231], v[0:3]
	s_barrier
	s_add_u32 s26, s26, 0x100
	s_addc_u32 s27, s27, 0
	s_add_u32 s10, s10, 0x100
	s_addc_u32 s11, s11, 0
	s_cmp_ge_i32 s44, s46
	s_mov_b32 s28, s44
	s_cbranch_scc0 .LBB0_1224
	v_readlane_b32 s60, v253, 16
	v_readlane_b32 s61, v253, 17
